# v103 + k-loop back-edge: counter/pointer SALU block moved from after the loop-back barrier into the last MFMA segment (15 sites)
# speedup vs baseline: 1.0056x; 1.0014x over previous
; #define PG8_STAGE(bufoff, gbase, voff) do { _Pragma("unroll") for (int _i = 0; _i < 2; ++_i) \
;         __builtin_amdgcn_global_load_lds((const unsigned*)((const char*)(gbase) + (voff)[_i]), (PG8_LAS unsigned*)(lds + (bufoff) + ldsw + _i * 8192), 16, 0, 0); } while (0)
; #define PG8_LDA(dst, b, h) do { _Pragma("unroll") for (int m = 0; m < 4; ++m) _Pragma("unroll") for (int k = 0; k < 2; ++k) dst[m][k] = *(const PG8_LAS bf16x8*)(lds + PG8_SA(b, h) + aoff + m * 2048 + k * 1024); } while (0)
; #define PG8_LDB(dst, b, h) do { _Pragma("unroll") for (int n = 0; n < 2; ++n) _Pragma("unroll") for (int k = 0; k < 2; ++k) dst[n][k] = *(const PG8_LAS bf16x8*)(lds + PG8_SB(b, h) + boff + n * 2048 + k * 1024); } while (0)
; #define PG8_MMA(ai, bj, At, Bt) do { __builtin_amdgcn_s_setprio(1); _Pragma("unroll") for (int m = 0; m < 4; ++m) _Pragma("unroll") for (int n = 0; n < 2; ++n) _Pragma("unroll") for (int k = 0; k < 2; ++k) \
;         acc[ai][bj][m][n] = __builtin_amdgcn_mfma_f32_16x16x32_bf16(Bt[n][k], At[m][k], acc[ai][bj][m][n], 0, 0, 0); __builtin_amdgcn_s_setprio(0); } while (0)
; #define PG8_WAIT_V(n) asm volatile("s_waitcnt vmcnt(" #n ")" ::: "memory")
; #define PG8_WAIT_L(n) asm volatile("s_waitcnt lgkmcnt(" #n ")" ::: "memory")
; #define PG8_BAR __builtin_amdgcn_s_barrier()
; #define PG8_SCHED __builtin_amdgcn_sched_barrier(0)
; template <class Epi, class Sched>
; __device__ __forceinline__ void gemm_phase(PG8_LAS unsigned char* lds, PG8_LAS unsigned char* xl, const Gemm g, const Sched& S, const Epi& E) {
;     ...
;         const bool has_next = S.next(ui + 1, nxt);
;         const char* nA = has_next ? (const char*)g.A + nxt.aoff : cA; const char* nB = has_next ? (const char*)g.Bt + nxt.boff : cB;
; #pragma unroll 1
;         for (int t = 0; t < nt; t += 2) {
;             const bool last = (t == nt - 2);
;             const char* a1 = cA + (size_t)(t + 1) * kstep;
;             const char* a2 = last ? nA : cA + (size_t)(t + 2) * kstep; const char* b2 = last ? nB : cB + (size_t)(t + 2) * kstep;
;             const char* a3 = a2 + kstep; const char* b3 = b2 + kstep;
;             PG8_LDB(B0, 0, 0); PG8_LDB(B1, 0, 1); PG8_SCHED; PG8_LDA(At, 0, 0); PG8_STAGE(PG8_SA(1, 1), a1 + hsA, voffA);
;             PG8_WAIT_V(8); PG8_WAIT_L(0); PG8_BAR; PG8_MMA(0, 0, At, B0); PG8_MMA(0, 1, At, B1); PG8_BAR; PG8_SCHED;
.LBB0_101:
	s_add_u32 s20, s35, s16
	s_addc_u32 s21, s36, s17
	s_and_b64 s[22:23], s[4:5], exec
	s_cselect_b32 s73, s21, s29
	s_cselect_b32 s74, s20, s28
	s_add_u32 s22, s2, s18
	s_addc_u32 s23, s3, s19
	s_and_b64 s[30:31], s[4:5], exec
	s_cselect_b32 s75, s23, s27
	s_cselect_b32 s76, s22, s26
	s_add_u32 s77, s26, 0x100
	s_addc_u32 s78, s27, 0
	s_add_u32 s26, s28, 0x40080
	v_mov_b32_e32 v0, 0
	s_addc_u32 s27, s29, 0
	s_mov_b32 s79, -2
	ds_read_b128 v[148:151], v153
	ds_read_b128 v[158:161], v153 offset:1024
	ds_read_b128 v[162:165], v153 offset:2048
	ds_read_b128 v[166:169], v153 offset:3072
	ds_read_b128 v[170:173], v154
	ds_read_b128 v[174:177], v154 offset:1024
	ds_read_b128 v[178:181], v154 offset:2048
	ds_read_b128 v[182:185], v154 offset:3072
	s_add_u32 s28, s26, 0xfffc0080
	s_addc_u32 s29, s27, -1
	s_cmp_eq_u32 s79, 12
	s_cselect_b32 s31, s73, s29
	s_cselect_b32 s30, s74, s28
	s_cselect_b32 s29, s75, s78
	s_cselect_b32 s28, s76, s77
	v_lshl_add_u64 v[218:219], s[26:27], 0, v[142:143]
	s_add_i32 m0, s52, 0xc000
	ds_read_b128 v[186:189], v155
	ds_read_b128 v[190:193], v155 offset:1024
	ds_read_b128 v[194:197], v155 offset:2048
	ds_read_b128 v[198:201], v155 offset:3072
	ds_read_b128 v[202:205], v155 offset:4096
	ds_read_b128 v[206:209], v155 offset:5120
	ds_read_b128 v[210:213], v155 offset:6144
	ds_read_b128 v[214:217], v155 offset:7168
	global_load_lds_dwordx4 v[218:219], off
	v_lshl_add_u64 v[218:219], s[26:27], 0, v[140:141]
	s_add_i32 m0, s52, 0xe000
	s_nop 0
	global_load_lds_dwordx4 v[218:219], off
	s_waitcnt vmcnt(8)
	s_waitcnt lgkmcnt(0)
	s_barrier
	s_setprio 1
	s_waitcnt lgkmcnt(0)
	v_mfma_f32_16x16x32_bf16 v[124:127], v[148:151], v[186:189], 0
	v_mfma_f32_16x16x32_bf16 v[116:119], v[162:165], v[186:189], 0
	v_mfma_f32_16x16x32_bf16 v[108:111], v[148:151], v[194:197], 0
	v_mfma_f32_16x16x32_bf16 v[100:103], v[162:165], v[194:197], 0
	v_mfma_f32_16x16x32_bf16 v[92:95], v[148:151], v[202:205], 0
	v_mfma_f32_16x16x32_bf16 v[84:87], v[162:165], v[202:205], 0
	v_mfma_f32_16x16x32_bf16 v[76:79], v[148:151], v[210:213], 0
	v_mfma_f32_16x16x32_bf16 v[68:71], v[162:165], v[210:213], 0
	v_mfma_f32_16x16x32_bf16 v[124:127], v[158:161], v[190:193], v[124:127]
	v_mfma_f32_16x16x32_bf16 v[116:119], v[166:169], v[190:193], v[116:119]
	v_mfma_f32_16x16x32_bf16 v[108:111], v[158:161], v[198:201], v[108:111]
	v_mfma_f32_16x16x32_bf16 v[100:103], v[166:169], v[198:201], v[100:103]
	v_mfma_f32_16x16x32_bf16 v[92:95], v[158:161], v[206:209], v[92:95]
	v_mfma_f32_16x16x32_bf16 v[84:87], v[166:169], v[206:209], v[84:87]
	v_mfma_f32_16x16x32_bf16 v[76:79], v[158:161], v[214:217], v[76:79]
	v_mfma_f32_16x16x32_bf16 v[68:71], v[166:169], v[214:217], v[68:71]
	s_setprio 0
	s_setprio 1
	v_mfma_f32_16x16x32_bf16 v[120:123], v[170:173], v[186:189], 0
	v_mfma_f32_16x16x32_bf16 v[112:115], v[178:181], v[186:189], 0
	v_mfma_f32_16x16x32_bf16 v[104:107], v[170:173], v[194:197], 0
	v_mfma_f32_16x16x32_bf16 v[96:99], v[178:181], v[194:197], 0
	v_mfma_f32_16x16x32_bf16 v[88:91], v[170:173], v[202:205], 0
	v_mfma_f32_16x16x32_bf16 v[80:83], v[178:181], v[202:205], 0
	v_mfma_f32_16x16x32_bf16 v[72:75], v[170:173], v[210:213], 0
	v_mfma_f32_16x16x32_bf16 v[64:67], v[178:181], v[210:213], 0
	v_mfma_f32_16x16x32_bf16 v[120:123], v[174:177], v[190:193], v[120:123]
	v_mfma_f32_16x16x32_bf16 v[112:115], v[182:185], v[190:193], v[112:115]
	v_mfma_f32_16x16x32_bf16 v[104:107], v[174:177], v[198:201], v[104:107]
	v_mfma_f32_16x16x32_bf16 v[96:99], v[182:185], v[198:201], v[96:99]
	v_mfma_f32_16x16x32_bf16 v[88:91], v[174:177], v[206:209], v[88:91]
	v_mfma_f32_16x16x32_bf16 v[80:83], v[182:185], v[206:209], v[80:83]
	v_mfma_f32_16x16x32_bf16 v[72:75], v[174:177], v[214:217], v[72:75]
	v_mfma_f32_16x16x32_bf16 v[64:67], v[182:185], v[214:217], v[64:67]
	s_setprio 0
	s_barrier
	s_add_i32 s68, s60, s42
	v_lshl_add_u64 v[218:219], s[28:29], 0, v[132:133]
	s_mov_b32 m0, s68
	ds_read_b128 v[186:189], v155 offset:16384
	ds_read_b128 v[190:193], v155 offset:17408
	ds_read_b128 v[194:197], v155 offset:18432
	ds_read_b128 v[198:201], v155 offset:19456
	ds_read_b128 v[202:205], v155 offset:20480
	ds_read_b128 v[206:209], v155 offset:21504
	ds_read_b128 v[210:213], v155 offset:22528
	ds_read_b128 v[214:217], v155 offset:23552
	global_load_lds_dwordx4 v[218:219], off
	s_add_i32 m0, s68, 0x2000
	s_add_u32 s80, s28, 0x40000
	v_lshl_add_u64 v[222:223], s[28:29], 0, v[128:129]
	s_addc_u32 s81, s29, 0
	s_add_i32 s68, s61, s42
	global_load_lds_dwordx4 v[222:223], off
	v_lshl_add_u64 v[224:225], s[80:81], 0, v[132:133]
	s_mov_b32 m0, s68
	v_lshl_add_u64 v[226:227], s[30:31], 0, v[130:131]
	global_load_lds_dwordx4 v[224:225], off
	v_lshl_add_u64 v[224:225], s[80:81], 0, v[128:129]
	s_add_i32 m0, s68, 0x2000
	s_nop 0
	global_load_lds_dwordx4 v[224:225], off
	v_lshl_add_u64 v[224:225], s[30:31], 0, v[134:135]
	s_mov_b32 m0, s52
	s_nop 0
	global_load_lds_dwordx4 v[224:225], off
	s_mov_b32 m0, s53
	s_nop 0
	global_load_lds_dwordx4 v[226:227], off
	s_waitcnt vmcnt(8)
	s_waitcnt lgkmcnt(0)
	s_barrier
; #define PG8_STAGE(bufoff, gbase, voff) do { _Pragma("unroll") for (int _i = 0; _i < 2; ++_i) \
;         __builtin_amdgcn_global_load_lds((const unsigned*)((const char*)(gbase) + (voff)[_i]), (PG8_LAS unsigned*)(lds + (bufoff) + ldsw + _i * 8192), 16, 0, 0); } while (0)
; #define PG8_LDA(dst, b, h) do { _Pragma("unroll") for (int m = 0; m < 4; ++m) _Pragma("unroll") for (int k = 0; k < 2; ++k) dst[m][k] = *(const PG8_LAS bf16x8*)(lds + PG8_SA(b, h) + aoff + m * 2048 + k * 1024); } while (0)
; #define PG8_LDB(dst, b, h) do { _Pragma("unroll") for (int n = 0; n < 2; ++n) _Pragma("unroll") for (int k = 0; k < 2; ++k) dst[n][k] = *(const PG8_LAS bf16x8*)(lds + PG8_SB(b, h) + boff + n * 2048 + k * 1024); } while (0)
; #define PG8_MMA(ai, bj, At, Bt) do { __builtin_amdgcn_s_setprio(1); _Pragma("unroll") for (int m = 0; m < 4; ++m) _Pragma("unroll") for (int n = 0; n < 2; ++n) _Pragma("unroll") for (int k = 0; k < 2; ++k) \
;         acc[ai][bj][m][n] = __builtin_amdgcn_mfma_f32_16x16x32_bf16(Bt[n][k], At[m][k], acc[ai][bj][m][n], 0, 0, 0); __builtin_amdgcn_s_setprio(0); } while (0)
; #define PG8_WAIT_V(n) asm volatile("s_waitcnt vmcnt(" #n ")" ::: "memory")
; #define PG8_WAIT_L(n) asm volatile("s_waitcnt lgkmcnt(" #n ")" ::: "memory")
; #define PG8_BAR __builtin_amdgcn_s_barrier()
; #define PG8_SCHED __builtin_amdgcn_sched_barrier(0)
; template <class Epi, class Sched>
; __device__ __forceinline__ void gemm_phase(PG8_LAS unsigned char* lds, PG8_LAS unsigned char* xl, const Gemm g, const Sched& S, const Epi& E) {
;     ...
;             PG8_WAIT_V(8); PG8_WAIT_L(0); PG8_BAR; PG8_MMA(0, 0, At, B0); PG8_MMA(0, 1, At, B1); PG8_BAR; PG8_SCHED;
;             PG8_LDA(At, 0, 1); PG8_STAGE(PG8_SB(0, 0), b2, voffB); PG8_STAGE(PG8_SB(0, 1), b2 + hsB, voffB); PG8_STAGE(PG8_SA(0, 0), a2, voffA);
;             PG8_WAIT_V(8); PG8_WAIT_L(0); PG8_BAR; PG8_MMA(1, 0, At, B0); PG8_MMA(1, 1, At, B1); PG8_BAR; PG8_SCHED;
;             PG8_LDB(B0, 1, 0); PG8_LDB(B1, 1, 1); PG8_SCHED; PG8_LDA(At, 1, 0); PG8_STAGE(PG8_SA(0, 1), a2 + hsA, voffA);
;             PG8_WAIT_V(8); PG8_WAIT_L(0); PG8_BAR; PG8_MMA(0, 0, At, B0); PG8_MMA(0, 1, At, B1); PG8_BAR; PG8_SCHED;
	s_setprio 1
	s_waitcnt lgkmcnt(0)
	v_mfma_f32_16x16x32_bf16 v[60:63], v[148:151], v[186:189], 0
	v_mfma_f32_16x16x32_bf16 v[52:55], v[162:165], v[186:189], 0
	v_mfma_f32_16x16x32_bf16 v[44:47], v[148:151], v[194:197], 0
	v_mfma_f32_16x16x32_bf16 v[36:39], v[162:165], v[194:197], 0
	v_mfma_f32_16x16x32_bf16 v[28:31], v[148:151], v[202:205], 0
	v_mfma_f32_16x16x32_bf16 v[20:23], v[162:165], v[202:205], 0
	v_mfma_f32_16x16x32_bf16 v[12:15], v[148:151], v[210:213], 0
	v_mfma_f32_16x16x32_bf16 v[4:7], v[162:165], v[210:213], 0
	v_mfma_f32_16x16x32_bf16 v[60:63], v[158:161], v[190:193], v[60:63]
	v_mfma_f32_16x16x32_bf16 v[52:55], v[166:169], v[190:193], v[52:55]
	v_mfma_f32_16x16x32_bf16 v[44:47], v[158:161], v[198:201], v[44:47]
	v_mfma_f32_16x16x32_bf16 v[36:39], v[166:169], v[198:201], v[36:39]
	v_mfma_f32_16x16x32_bf16 v[28:31], v[158:161], v[206:209], v[28:31]
	v_mfma_f32_16x16x32_bf16 v[20:23], v[166:169], v[206:209], v[20:23]
	v_mfma_f32_16x16x32_bf16 v[12:15], v[158:161], v[214:217], v[12:15]
	v_mfma_f32_16x16x32_bf16 v[4:7], v[166:169], v[214:217], v[4:7]
	s_setprio 0
	s_setprio 1
	v_mfma_f32_16x16x32_bf16 v[56:59], v[170:173], v[186:189], 0
	v_mfma_f32_16x16x32_bf16 v[48:51], v[178:181], v[186:189], 0
	v_mfma_f32_16x16x32_bf16 v[40:43], v[170:173], v[194:197], 0
	v_mfma_f32_16x16x32_bf16 v[32:35], v[178:181], v[194:197], 0
	v_mfma_f32_16x16x32_bf16 v[24:27], v[170:173], v[202:205], 0
	v_mfma_f32_16x16x32_bf16 v[16:19], v[178:181], v[202:205], 0
	v_mfma_f32_16x16x32_bf16 v[8:11], v[170:173], v[210:213], 0
	v_mfma_f32_16x16x32_bf16 v[0:3], v[178:181], v[210:213], 0
	v_mfma_f32_16x16x32_bf16 v[56:59], v[174:177], v[190:193], v[56:59]
	v_mfma_f32_16x16x32_bf16 v[48:51], v[182:185], v[190:193], v[48:51]
	v_mfma_f32_16x16x32_bf16 v[40:43], v[174:177], v[198:201], v[40:43]
	v_mfma_f32_16x16x32_bf16 v[32:35], v[182:185], v[198:201], v[32:35]
	v_mfma_f32_16x16x32_bf16 v[24:27], v[174:177], v[206:209], v[24:27]
	v_mfma_f32_16x16x32_bf16 v[16:19], v[182:185], v[206:209], v[16:19]
	v_mfma_f32_16x16x32_bf16 v[8:11], v[174:177], v[214:217], v[8:11]
	v_mfma_f32_16x16x32_bf16 v[0:3], v[182:185], v[214:217], v[0:3]
	s_setprio 0
	s_barrier
	s_add_i32 s68, 0, 0x18000
	v_add_u32_e32 v136, s68, v152
	s_add_i32 s80, 0, 0x1c000
	ds_read_b128 v[148:151], v136
	ds_read_b128 v[158:161], v136 offset:1024
	ds_read_b128 v[162:165], v136 offset:2048
	ds_read_b128 v[166:169], v136 offset:3072
	v_add_u32_e32 v136, s80, v152
	ds_read_b128 v[170:173], v136
	ds_read_b128 v[174:177], v136 offset:1024
	ds_read_b128 v[178:181], v136 offset:2048
	ds_read_b128 v[182:185], v136 offset:3072
	s_add_u32 s30, s30, 0x40000
	s_addc_u32 s31, s31, 0
	s_mov_b32 m0, s54
	v_lshl_add_u64 v[228:229], s[30:31], 0, v[134:135]
	ds_read_b128 v[186:189], v155 offset:32768
	ds_read_b128 v[190:193], v155 offset:33792
	ds_read_b128 v[194:197], v155 offset:34816
	ds_read_b128 v[198:201], v155 offset:35840
	ds_read_b128 v[202:205], v155 offset:36864
	ds_read_b128 v[206:209], v155 offset:37888
	ds_read_b128 v[210:213], v155 offset:38912
	ds_read_b128 v[214:217], v155 offset:39936
	global_load_lds_dwordx4 v[228:229], off
	v_lshl_add_u64 v[228:229], s[30:31], 0, v[130:131]
	s_mov_b32 m0, s55
	s_nop 0
	global_load_lds_dwordx4 v[228:229], off
	s_waitcnt vmcnt(8)
	s_waitcnt lgkmcnt(0)
	s_barrier
	s_setprio 1
	s_waitcnt lgkmcnt(0)
	v_mfma_f32_16x16x32_bf16 v[124:127], v[148:151], v[186:189], v[124:127]
	v_mfma_f32_16x16x32_bf16 v[116:119], v[162:165], v[186:189], v[116:119]
	v_mfma_f32_16x16x32_bf16 v[108:111], v[148:151], v[194:197], v[108:111]
	v_mfma_f32_16x16x32_bf16 v[100:103], v[162:165], v[194:197], v[100:103]
	v_mfma_f32_16x16x32_bf16 v[92:95], v[148:151], v[202:205], v[92:95]
	v_mfma_f32_16x16x32_bf16 v[84:87], v[162:165], v[202:205], v[84:87]
	v_mfma_f32_16x16x32_bf16 v[76:79], v[148:151], v[210:213], v[76:79]
	v_mfma_f32_16x16x32_bf16 v[68:71], v[162:165], v[210:213], v[68:71]
	v_mfma_f32_16x16x32_bf16 v[124:127], v[158:161], v[190:193], v[124:127]
	v_mfma_f32_16x16x32_bf16 v[116:119], v[166:169], v[190:193], v[116:119]
	v_mfma_f32_16x16x32_bf16 v[108:111], v[158:161], v[198:201], v[108:111]
	v_mfma_f32_16x16x32_bf16 v[100:103], v[166:169], v[198:201], v[100:103]
	v_mfma_f32_16x16x32_bf16 v[92:95], v[158:161], v[206:209], v[92:95]
	v_mfma_f32_16x16x32_bf16 v[84:87], v[166:169], v[206:209], v[84:87]
	v_mfma_f32_16x16x32_bf16 v[76:79], v[158:161], v[214:217], v[76:79]
	v_mfma_f32_16x16x32_bf16 v[68:71], v[166:169], v[214:217], v[68:71]
	s_setprio 0
	s_setprio 1
	v_mfma_f32_16x16x32_bf16 v[120:123], v[170:173], v[186:189], v[120:123]
	v_mfma_f32_16x16x32_bf16 v[112:115], v[178:181], v[186:189], v[112:115]
	v_mfma_f32_16x16x32_bf16 v[104:107], v[170:173], v[194:197], v[104:107]
	v_mfma_f32_16x16x32_bf16 v[96:99], v[178:181], v[194:197], v[96:99]
	v_mfma_f32_16x16x32_bf16 v[88:91], v[170:173], v[202:205], v[88:91]
	v_mfma_f32_16x16x32_bf16 v[80:83], v[178:181], v[202:205], v[80:83]
	v_mfma_f32_16x16x32_bf16 v[72:75], v[170:173], v[210:213], v[72:75]
	v_mfma_f32_16x16x32_bf16 v[64:67], v[178:181], v[210:213], v[64:67]
	v_mfma_f32_16x16x32_bf16 v[120:123], v[174:177], v[190:193], v[120:123]
	v_mfma_f32_16x16x32_bf16 v[112:115], v[182:185], v[190:193], v[112:115]
	v_mfma_f32_16x16x32_bf16 v[104:107], v[174:177], v[198:201], v[104:107]
	v_mfma_f32_16x16x32_bf16 v[96:99], v[182:185], v[198:201], v[96:99]
	v_mfma_f32_16x16x32_bf16 v[88:91], v[174:177], v[206:209], v[88:91]
	v_mfma_f32_16x16x32_bf16 v[80:83], v[182:185], v[206:209], v[80:83]
	v_mfma_f32_16x16x32_bf16 v[72:75], v[174:177], v[214:217], v[72:75]
	v_mfma_f32_16x16x32_bf16 v[64:67], v[182:185], v[214:217], v[64:67]
	s_setprio 0
	s_barrier
; #define PG8_STAGE(bufoff, gbase, voff) do { _Pragma("unroll") for (int _i = 0; _i < 2; ++_i) \
;         __builtin_amdgcn_global_load_lds((const unsigned*)((const char*)(gbase) + (voff)[_i]), (PG8_LAS unsigned*)(lds + (bufoff) + ldsw + _i * 8192), 16, 0, 0); } while (0)
; #define PG8_LDA(dst, b, h) do { _Pragma("unroll") for (int m = 0; m < 4; ++m) _Pragma("unroll") for (int k = 0; k < 2; ++k) dst[m][k] = *(const PG8_LAS bf16x8*)(lds + PG8_SA(b, h) + aoff + m * 2048 + k * 1024); } while (0)
; #define PG8_LDB(dst, b, h) do { _Pragma("unroll") for (int n = 0; n < 2; ++n) _Pragma("unroll") for (int k = 0; k < 2; ++k) dst[n][k] = *(const PG8_LAS bf16x8*)(lds + PG8_SB(b, h) + boff + n * 2048 + k * 1024); } while (0)
; #define PG8_MMA(ai, bj, At, Bt) do { __builtin_amdgcn_s_setprio(1); _Pragma("unroll") for (int m = 0; m < 4; ++m) _Pragma("unroll") for (int n = 0; n < 2; ++n) _Pragma("unroll") for (int k = 0; k < 2; ++k) \
;         acc[ai][bj][m][n] = __builtin_amdgcn_mfma_f32_16x16x32_bf16(Bt[n][k], At[m][k], acc[ai][bj][m][n], 0, 0, 0); __builtin_amdgcn_s_setprio(0); } while (0)
; #define PG8_WAIT_V(n) asm volatile("s_waitcnt vmcnt(" #n ")" ::: "memory")
; template <class Epi, class Sched>
; __device__ __forceinline__ void gemm_phase(PG8_LAS unsigned char* lds, PG8_LAS unsigned char* xl, const Gemm g, const Sched& S, const Epi& E) {
;     ...
;             PG8_LDB(B0, 0, 0); PG8_LDB(B1, 0, 1); PG8_SCHED; PG8_LDA(At, 0, 0); PG8_STAGE(PG8_SA(1, 1), a1 + hsA, voffA);
;             PG8_WAIT_V(8); PG8_WAIT_L(0); PG8_BAR; PG8_MMA(0, 0, At, B0); PG8_MMA(0, 1, At, B1); PG8_BAR; PG8_SCHED;
;             PG8_LDA(At, 0, 1); PG8_STAGE(PG8_SB(0, 0), b2, voffB); PG8_STAGE(PG8_SB(0, 1), b2 + hsB, voffB); PG8_STAGE(PG8_SA(0, 0), a2, voffA);
;             PG8_WAIT_V(8); PG8_WAIT_L(0); PG8_BAR; PG8_MMA(1, 0, At, B0); PG8_MMA(1, 1, At, B1); PG8_BAR; PG8_SCHED;
;             PG8_LDB(B0, 1, 0); PG8_LDB(B1, 1, 1); PG8_SCHED; PG8_LDA(At, 1, 0); PG8_STAGE(PG8_SA(0, 1), a2 + hsA, voffA);
;             PG8_WAIT_V(8); PG8_WAIT_L(0); PG8_BAR; PG8_MMA(0, 0, At, B0); PG8_MMA(0, 1, At, B1); PG8_BAR; PG8_SCHED;
;             PG8_LDA(At, 1, 1); PG8_STAGE(PG8_SB(1, 0), b3, voffB); PG8_STAGE(PG8_SB(1, 1), b3 + hsB, voffB); PG8_STAGE(PG8_SA(1, 0), a3, voffA);
;             PG8_WAIT_V(8); PG8_WAIT_L(0); PG8_BAR; PG8_MMA(1, 0, At, B0); PG8_MMA(1, 1, At, B1); PG8_BAR; PG8_SCHED;
	s_add_i32 s30, s68, s42
	v_lshl_add_u64 v[218:219], v[218:219], 0, s[12:13]
	s_mov_b32 m0, s30
	ds_read_b128 v[186:189], v155 offset:49152
	ds_read_b128 v[190:193], v155 offset:50176
	ds_read_b128 v[194:197], v155 offset:51200
	ds_read_b128 v[198:201], v155 offset:52224
	ds_read_b128 v[202:205], v155 offset:53248
	ds_read_b128 v[206:209], v155 offset:54272
	ds_read_b128 v[210:213], v155 offset:55296
	ds_read_b128 v[214:217], v155 offset:56320
	global_load_lds_dwordx4 v[218:219], off
	s_add_i32 m0, s30, 0x2000
	s_add_u32 s28, s28, 0x40080
	v_lshl_add_u64 v[218:219], v[222:223], 0, s[12:13]
	s_addc_u32 s29, s29, 0
	s_add_i32 s30, s80, s42
	global_load_lds_dwordx4 v[218:219], off
	v_lshl_add_u64 v[218:219], s[28:29], 0, v[132:133]
	s_mov_b32 m0, s30
	s_nop 0
	global_load_lds_dwordx4 v[218:219], off
	v_lshl_add_u64 v[218:219], s[28:29], 0, v[128:129]
	s_add_i32 m0, s30, 0x2000
	s_nop 0
	global_load_lds_dwordx4 v[218:219], off
	v_lshl_add_u64 v[218:219], v[224:225], 0, s[12:13]
	s_mov_b32 m0, s58
	s_nop 0
	global_load_lds_dwordx4 v[218:219], off
	v_lshl_add_u64 v[218:219], v[226:227], 0, s[12:13]
	s_mov_b32 m0, s59
	s_nop 0
	global_load_lds_dwordx4 v[218:219], off
	s_waitcnt vmcnt(8)
	s_waitcnt lgkmcnt(0)
	s_barrier
	s_setprio 1
	s_waitcnt lgkmcnt(0)
	v_mfma_f32_16x16x32_bf16 v[60:63], v[148:151], v[186:189], v[60:63]
	v_mfma_f32_16x16x32_bf16 v[52:55], v[162:165], v[186:189], v[52:55]
	v_mfma_f32_16x16x32_bf16 v[44:47], v[148:151], v[194:197], v[44:47]
	v_mfma_f32_16x16x32_bf16 v[36:39], v[162:165], v[194:197], v[36:39]
	v_mfma_f32_16x16x32_bf16 v[28:31], v[148:151], v[202:205], v[28:31]
	v_mfma_f32_16x16x32_bf16 v[20:23], v[162:165], v[202:205], v[20:23]
	v_mfma_f32_16x16x32_bf16 v[12:15], v[148:151], v[210:213], v[12:15]
	v_mfma_f32_16x16x32_bf16 v[4:7], v[162:165], v[210:213], v[4:7]
	v_mfma_f32_16x16x32_bf16 v[60:63], v[158:161], v[190:193], v[60:63]
	v_mfma_f32_16x16x32_bf16 v[52:55], v[166:169], v[190:193], v[52:55]
	v_mfma_f32_16x16x32_bf16 v[44:47], v[158:161], v[198:201], v[44:47]
	v_mfma_f32_16x16x32_bf16 v[36:39], v[166:169], v[198:201], v[36:39]
	v_mfma_f32_16x16x32_bf16 v[28:31], v[158:161], v[206:209], v[28:31]
	v_mfma_f32_16x16x32_bf16 v[20:23], v[166:169], v[206:209], v[20:23]
	v_mfma_f32_16x16x32_bf16 v[12:15], v[158:161], v[214:217], v[12:15]
	v_mfma_f32_16x16x32_bf16 v[4:7], v[166:169], v[214:217], v[4:7]
	s_setprio 0
	s_setprio 1
	v_mfma_f32_16x16x32_bf16 v[56:59], v[170:173], v[186:189], v[56:59]
	s_add_i32 s79, s79, 2
	v_mfma_f32_16x16x32_bf16 v[48:51], v[178:181], v[186:189], v[48:51]
	s_add_u32 s77, s77, 0x100
	v_mfma_f32_16x16x32_bf16 v[40:43], v[170:173], v[194:197], v[40:43]
	s_addc_u32 s78, s78, 0
	v_mfma_f32_16x16x32_bf16 v[32:35], v[178:181], v[194:197], v[32:35]
	s_add_u32 s26, s26, 0x100
	v_mfma_f32_16x16x32_bf16 v[24:27], v[170:173], v[202:205], v[24:27]
	s_addc_u32 s27, s27, 0
	v_mfma_f32_16x16x32_bf16 v[16:19], v[178:181], v[202:205], v[16:19]
	s_cmp_gt_u32 s79, 13
	v_mfma_f32_16x16x32_bf16 v[8:11], v[170:173], v[210:213], v[8:11]
	v_mfma_f32_16x16x32_bf16 v[0:3], v[178:181], v[210:213], v[0:3]
	v_mfma_f32_16x16x32_bf16 v[56:59], v[174:177], v[190:193], v[56:59]
	v_mfma_f32_16x16x32_bf16 v[48:51], v[182:185], v[190:193], v[48:51]
	v_mfma_f32_16x16x32_bf16 v[40:43], v[174:177], v[198:201], v[40:43]
	v_mfma_f32_16x16x32_bf16 v[32:35], v[182:185], v[198:201], v[32:35]
	v_mfma_f32_16x16x32_bf16 v[24:27], v[174:177], v[206:209], v[24:27]
	v_mfma_f32_16x16x32_bf16 v[16:19], v[182:185], v[206:209], v[16:19]
	v_mfma_f32_16x16x32_bf16 v[8:11], v[174:177], v[214:217], v[8:11]
	v_mfma_f32_16x16x32_bf16 v[0:3], v[182:185], v[214:217], v[0:3]
	s_setprio 0
	s_barrier
	s_cbranch_scc1 .Lpeel_after_P1
.LBB0_102:
	ds_read_b128 v[148:151], v153
	ds_read_b128 v[158:161], v153 offset:1024
	ds_read_b128 v[162:165], v153 offset:2048
	ds_read_b128 v[166:169], v153 offset:3072
	ds_read_b128 v[170:173], v154
	ds_read_b128 v[174:177], v154 offset:1024
	ds_read_b128 v[178:181], v154 offset:2048
	ds_read_b128 v[182:185], v154 offset:3072
	s_add_u32 s28, s26, 0xfffc0080
	s_addc_u32 s29, s27, -1
	s_cmp_eq_u32 s79, 12
	s_cselect_b32 s31, s73, s29
	s_cselect_b32 s30, s74, s28
	s_cselect_b32 s29, s75, s78
	s_cselect_b32 s28, s76, s77
	v_lshl_add_u64 v[218:219], s[26:27], 0, v[142:143]
	s_add_i32 m0, s52, 0xc000
	ds_read_b128 v[186:189], v155
	ds_read_b128 v[190:193], v155 offset:1024
	ds_read_b128 v[194:197], v155 offset:2048
	ds_read_b128 v[198:201], v155 offset:3072
	ds_read_b128 v[202:205], v155 offset:4096
	ds_read_b128 v[206:209], v155 offset:5120
	ds_read_b128 v[210:213], v155 offset:6144
	ds_read_b128 v[214:217], v155 offset:7168
	global_load_lds_dwordx4 v[218:219], off
	v_lshl_add_u64 v[218:219], s[26:27], 0, v[140:141]
	s_add_i32 m0, s52, 0xe000
	s_nop 0
	global_load_lds_dwordx4 v[218:219], off
	s_waitcnt vmcnt(8)
	s_waitcnt lgkmcnt(0)
	s_barrier
; #define PG8_STAGE(bufoff, gbase, voff) do { _Pragma("unroll") for (int _i = 0; _i < 2; ++_i) \
;         __builtin_amdgcn_global_load_lds((const unsigned*)((const char*)(gbase) + (voff)[_i]), (PG8_LAS unsigned*)(lds + (bufoff) + ldsw + _i * 8192), 16, 0, 0); } while (0)
; #define PG8_LDA(dst, b, h) do { _Pragma("unroll") for (int m = 0; m < 4; ++m) _Pragma("unroll") for (int k = 0; k < 2; ++k) dst[m][k] = *(const PG8_LAS bf16x8*)(lds + PG8_SA(b, h) + aoff + m * 2048 + k * 1024); } while (0)
; #define PG8_LDB(dst, b, h) do { _Pragma("unroll") for (int n = 0; n < 2; ++n) _Pragma("unroll") for (int k = 0; k < 2; ++k) dst[n][k] = *(const PG8_LAS bf16x8*)(lds + PG8_SB(b, h) + boff + n * 2048 + k * 1024); } while (0)
; #define PG8_MMA(ai, bj, At, Bt) do { __builtin_amdgcn_s_setprio(1); _Pragma("unroll") for (int m = 0; m < 4; ++m) _Pragma("unroll") for (int n = 0; n < 2; ++n) _Pragma("unroll") for (int k = 0; k < 2; ++k) \
;         acc[ai][bj][m][n] = __builtin_amdgcn_mfma_f32_16x16x32_bf16(Bt[n][k], At[m][k], acc[ai][bj][m][n], 0, 0, 0); __builtin_amdgcn_s_setprio(0); } while (0)
; #define PG8_WAIT_V(n) asm volatile("s_waitcnt vmcnt(" #n ")" ::: "memory")
; #define PG8_WAIT_L(n) asm volatile("s_waitcnt lgkmcnt(" #n ")" ::: "memory")
; #define PG8_BAR __builtin_amdgcn_s_barrier()
; #define PG8_SCHED __builtin_amdgcn_sched_barrier(0)
; template <class Epi, class Sched>
; __device__ __forceinline__ void gemm_phase(PG8_LAS unsigned char* lds, PG8_LAS unsigned char* xl, const Gemm g, const Sched& S, const Epi& E) {
;     ...
;             PG8_LDB(B0, 0, 0); PG8_LDB(B1, 0, 1); PG8_SCHED; PG8_LDA(At, 0, 0); PG8_STAGE(PG8_SA(1, 1), a1 + hsA, voffA);
;             PG8_WAIT_V(8); PG8_WAIT_L(0); PG8_BAR; PG8_MMA(0, 0, At, B0); PG8_MMA(0, 1, At, B1); PG8_BAR; PG8_SCHED;
;             PG8_LDA(At, 0, 1); PG8_STAGE(PG8_SB(0, 0), b2, voffB); PG8_STAGE(PG8_SB(0, 1), b2 + hsB, voffB); PG8_STAGE(PG8_SA(0, 0), a2, voffA);
;             PG8_WAIT_V(8); PG8_WAIT_L(0); PG8_BAR; PG8_MMA(1, 0, At, B0); PG8_MMA(1, 1, At, B1); PG8_BAR; PG8_SCHED;
;             PG8_LDB(B0, 1, 0); PG8_LDB(B1, 1, 1); PG8_SCHED; PG8_LDA(At, 1, 0); PG8_STAGE(PG8_SA(0, 1), a2 + hsA, voffA);
;             PG8_WAIT_V(8); PG8_WAIT_L(0); PG8_BAR; PG8_MMA(0, 0, At, B0); PG8_MMA(0, 1, At, B1); PG8_BAR; PG8_SCHED;
	s_setprio 1
	s_waitcnt lgkmcnt(0)
	v_mfma_f32_16x16x32_bf16 v[124:127], v[148:151], v[186:189], v[124:127]
	v_mfma_f32_16x16x32_bf16 v[116:119], v[162:165], v[186:189], v[116:119]
	v_mfma_f32_16x16x32_bf16 v[108:111], v[148:151], v[194:197], v[108:111]
	v_mfma_f32_16x16x32_bf16 v[100:103], v[162:165], v[194:197], v[100:103]
	v_mfma_f32_16x16x32_bf16 v[92:95], v[148:151], v[202:205], v[92:95]
	v_mfma_f32_16x16x32_bf16 v[84:87], v[162:165], v[202:205], v[84:87]
	v_mfma_f32_16x16x32_bf16 v[76:79], v[148:151], v[210:213], v[76:79]
	v_mfma_f32_16x16x32_bf16 v[68:71], v[162:165], v[210:213], v[68:71]
	v_mfma_f32_16x16x32_bf16 v[124:127], v[158:161], v[190:193], v[124:127]
	v_mfma_f32_16x16x32_bf16 v[116:119], v[166:169], v[190:193], v[116:119]
	v_mfma_f32_16x16x32_bf16 v[108:111], v[158:161], v[198:201], v[108:111]
	v_mfma_f32_16x16x32_bf16 v[100:103], v[166:169], v[198:201], v[100:103]
	v_mfma_f32_16x16x32_bf16 v[92:95], v[158:161], v[206:209], v[92:95]
	v_mfma_f32_16x16x32_bf16 v[84:87], v[166:169], v[206:209], v[84:87]
	v_mfma_f32_16x16x32_bf16 v[76:79], v[158:161], v[214:217], v[76:79]
	v_mfma_f32_16x16x32_bf16 v[68:71], v[166:169], v[214:217], v[68:71]
	s_setprio 0
	s_setprio 1
	v_mfma_f32_16x16x32_bf16 v[120:123], v[170:173], v[186:189], v[120:123]
	v_mfma_f32_16x16x32_bf16 v[112:115], v[178:181], v[186:189], v[112:115]
	v_mfma_f32_16x16x32_bf16 v[104:107], v[170:173], v[194:197], v[104:107]
	v_mfma_f32_16x16x32_bf16 v[96:99], v[178:181], v[194:197], v[96:99]
	v_mfma_f32_16x16x32_bf16 v[88:91], v[170:173], v[202:205], v[88:91]
	v_mfma_f32_16x16x32_bf16 v[80:83], v[178:181], v[202:205], v[80:83]
	v_mfma_f32_16x16x32_bf16 v[72:75], v[170:173], v[210:213], v[72:75]
	v_mfma_f32_16x16x32_bf16 v[64:67], v[178:181], v[210:213], v[64:67]
	v_mfma_f32_16x16x32_bf16 v[120:123], v[174:177], v[190:193], v[120:123]
	v_mfma_f32_16x16x32_bf16 v[112:115], v[182:185], v[190:193], v[112:115]
	v_mfma_f32_16x16x32_bf16 v[104:107], v[174:177], v[198:201], v[104:107]
	v_mfma_f32_16x16x32_bf16 v[96:99], v[182:185], v[198:201], v[96:99]
	v_mfma_f32_16x16x32_bf16 v[88:91], v[174:177], v[206:209], v[88:91]
	v_mfma_f32_16x16x32_bf16 v[80:83], v[182:185], v[206:209], v[80:83]
	v_mfma_f32_16x16x32_bf16 v[72:75], v[174:177], v[214:217], v[72:75]
	v_mfma_f32_16x16x32_bf16 v[64:67], v[182:185], v[214:217], v[64:67]
	s_setprio 0
	s_barrier
	s_add_i32 s68, s60, s42
	v_lshl_add_u64 v[218:219], s[28:29], 0, v[132:133]
	s_mov_b32 m0, s68
	ds_read_b128 v[186:189], v155 offset:16384
	ds_read_b128 v[190:193], v155 offset:17408
	ds_read_b128 v[194:197], v155 offset:18432
	ds_read_b128 v[198:201], v155 offset:19456
	ds_read_b128 v[202:205], v155 offset:20480
	ds_read_b128 v[206:209], v155 offset:21504
	ds_read_b128 v[210:213], v155 offset:22528
	ds_read_b128 v[214:217], v155 offset:23552
	global_load_lds_dwordx4 v[218:219], off
	s_add_i32 m0, s68, 0x2000
	s_add_u32 s80, s28, 0x40000
	v_lshl_add_u64 v[222:223], s[28:29], 0, v[128:129]
	s_addc_u32 s81, s29, 0
	s_add_i32 s68, s61, s42
	global_load_lds_dwordx4 v[222:223], off
	v_lshl_add_u64 v[224:225], s[80:81], 0, v[132:133]
	s_mov_b32 m0, s68
	v_lshl_add_u64 v[226:227], s[30:31], 0, v[130:131]
	global_load_lds_dwordx4 v[224:225], off
	v_lshl_add_u64 v[224:225], s[80:81], 0, v[128:129]
	s_add_i32 m0, s68, 0x2000
	s_nop 0
	global_load_lds_dwordx4 v[224:225], off
	v_lshl_add_u64 v[224:225], s[30:31], 0, v[134:135]
	s_mov_b32 m0, s52
	s_nop 0
	global_load_lds_dwordx4 v[224:225], off
	s_mov_b32 m0, s53
	s_nop 0
	global_load_lds_dwordx4 v[226:227], off
	s_waitcnt vmcnt(8)
	s_waitcnt lgkmcnt(0)
	s_barrier
	s_setprio 1
	s_waitcnt lgkmcnt(0)
	v_mfma_f32_16x16x32_bf16 v[60:63], v[148:151], v[186:189], v[60:63]
	v_mfma_f32_16x16x32_bf16 v[52:55], v[162:165], v[186:189], v[52:55]
	v_mfma_f32_16x16x32_bf16 v[44:47], v[148:151], v[194:197], v[44:47]
	v_mfma_f32_16x16x32_bf16 v[36:39], v[162:165], v[194:197], v[36:39]
	v_mfma_f32_16x16x32_bf16 v[28:31], v[148:151], v[202:205], v[28:31]
	v_mfma_f32_16x16x32_bf16 v[20:23], v[162:165], v[202:205], v[20:23]
	v_mfma_f32_16x16x32_bf16 v[12:15], v[148:151], v[210:213], v[12:15]
	v_mfma_f32_16x16x32_bf16 v[4:7], v[162:165], v[210:213], v[4:7]
	v_mfma_f32_16x16x32_bf16 v[60:63], v[158:161], v[190:193], v[60:63]
	v_mfma_f32_16x16x32_bf16 v[52:55], v[166:169], v[190:193], v[52:55]
	v_mfma_f32_16x16x32_bf16 v[44:47], v[158:161], v[198:201], v[44:47]
	v_mfma_f32_16x16x32_bf16 v[36:39], v[166:169], v[198:201], v[36:39]
	v_mfma_f32_16x16x32_bf16 v[28:31], v[158:161], v[206:209], v[28:31]
	v_mfma_f32_16x16x32_bf16 v[20:23], v[166:169], v[206:209], v[20:23]
	v_mfma_f32_16x16x32_bf16 v[12:15], v[158:161], v[214:217], v[12:15]
	v_mfma_f32_16x16x32_bf16 v[4:7], v[166:169], v[214:217], v[4:7]
	s_setprio 0
	s_setprio 1
	v_mfma_f32_16x16x32_bf16 v[56:59], v[170:173], v[186:189], v[56:59]
	v_mfma_f32_16x16x32_bf16 v[48:51], v[178:181], v[186:189], v[48:51]
	v_mfma_f32_16x16x32_bf16 v[40:43], v[170:173], v[194:197], v[40:43]
	v_mfma_f32_16x16x32_bf16 v[32:35], v[178:181], v[194:197], v[32:35]
	v_mfma_f32_16x16x32_bf16 v[24:27], v[170:173], v[202:205], v[24:27]
	v_mfma_f32_16x16x32_bf16 v[16:19], v[178:181], v[202:205], v[16:19]
	v_mfma_f32_16x16x32_bf16 v[8:11], v[170:173], v[210:213], v[8:11]
	v_mfma_f32_16x16x32_bf16 v[0:3], v[178:181], v[210:213], v[0:3]
	v_mfma_f32_16x16x32_bf16 v[56:59], v[174:177], v[190:193], v[56:59]
	v_mfma_f32_16x16x32_bf16 v[48:51], v[182:185], v[190:193], v[48:51]
	v_mfma_f32_16x16x32_bf16 v[40:43], v[174:177], v[198:201], v[40:43]
	v_mfma_f32_16x16x32_bf16 v[32:35], v[182:185], v[198:201], v[32:35]
	v_mfma_f32_16x16x32_bf16 v[24:27], v[174:177], v[206:209], v[24:27]
	v_mfma_f32_16x16x32_bf16 v[16:19], v[182:185], v[206:209], v[16:19]
	v_mfma_f32_16x16x32_bf16 v[8:11], v[174:177], v[214:217], v[8:11]
	v_mfma_f32_16x16x32_bf16 v[0:3], v[182:185], v[214:217], v[0:3]
	s_setprio 0
	s_barrier
; #define PG8_STAGE(bufoff, gbase, voff) do { _Pragma("unroll") for (int _i = 0; _i < 2; ++_i) \
;         __builtin_amdgcn_global_load_lds((const unsigned*)((const char*)(gbase) + (voff)[_i]), (PG8_LAS unsigned*)(lds + (bufoff) + ldsw + _i * 8192), 16, 0, 0); } while (0)
; #define PG8_LDA(dst, b, h) do { _Pragma("unroll") for (int m = 0; m < 4; ++m) _Pragma("unroll") for (int k = 0; k < 2; ++k) dst[m][k] = *(const PG8_LAS bf16x8*)(lds + PG8_SA(b, h) + aoff + m * 2048 + k * 1024); } while (0)
; #define PG8_LDB(dst, b, h) do { _Pragma("unroll") for (int n = 0; n < 2; ++n) _Pragma("unroll") for (int k = 0; k < 2; ++k) dst[n][k] = *(const PG8_LAS bf16x8*)(lds + PG8_SB(b, h) + boff + n * 2048 + k * 1024); } while (0)
; #define PG8_MMA(ai, bj, At, Bt) do { __builtin_amdgcn_s_setprio(1); _Pragma("unroll") for (int m = 0; m < 4; ++m) _Pragma("unroll") for (int n = 0; n < 2; ++n) _Pragma("unroll") for (int k = 0; k < 2; ++k) \
;         acc[ai][bj][m][n] = __builtin_amdgcn_mfma_f32_16x16x32_bf16(Bt[n][k], At[m][k], acc[ai][bj][m][n], 0, 0, 0); __builtin_amdgcn_s_setprio(0); } while (0)
; #define PG8_WAIT_V(n) asm volatile("s_waitcnt vmcnt(" #n ")" ::: "memory")
; #define PG8_WAIT_L(n) asm volatile("s_waitcnt lgkmcnt(" #n ")" ::: "memory")
; #define PG8_BAR __builtin_amdgcn_s_barrier()
; #define PG8_SCHED __builtin_amdgcn_sched_barrier(0)
; template <class Epi, class Sched>
; __device__ __forceinline__ void gemm_phase(PG8_LAS unsigned char* lds, PG8_LAS unsigned char* xl, const Gemm g, const Sched& S, const Epi& E) {
;     ...
;             PG8_LDB(B0, 1, 0); PG8_LDB(B1, 1, 1); PG8_SCHED; PG8_LDA(At, 1, 0); PG8_STAGE(PG8_SA(0, 1), a2 + hsA, voffA);
;             PG8_WAIT_V(8); PG8_WAIT_L(0); PG8_BAR; PG8_MMA(0, 0, At, B0); PG8_MMA(0, 1, At, B1); PG8_BAR; PG8_SCHED;
;             PG8_LDA(At, 1, 1); PG8_STAGE(PG8_SB(1, 0), b3, voffB); PG8_STAGE(PG8_SB(1, 1), b3 + hsB, voffB); PG8_STAGE(PG8_SA(1, 0), a3, voffA);
;             PG8_WAIT_V(8); PG8_WAIT_L(0); PG8_BAR; PG8_MMA(1, 0, At, B0); PG8_MMA(1, 1, At, B1); PG8_BAR; PG8_SCHED;
	s_add_i32 s68, 0, 0x18000
	v_add_u32_e32 v136, s68, v152
	s_add_i32 s80, 0, 0x1c000
	ds_read_b128 v[148:151], v136
	ds_read_b128 v[158:161], v136 offset:1024
	ds_read_b128 v[162:165], v136 offset:2048
	ds_read_b128 v[166:169], v136 offset:3072
	v_add_u32_e32 v136, s80, v152
	ds_read_b128 v[170:173], v136
	ds_read_b128 v[174:177], v136 offset:1024
	ds_read_b128 v[178:181], v136 offset:2048
	ds_read_b128 v[182:185], v136 offset:3072
	s_add_u32 s30, s30, 0x40000
	s_addc_u32 s31, s31, 0
	s_mov_b32 m0, s54
	v_lshl_add_u64 v[228:229], s[30:31], 0, v[134:135]
	ds_read_b128 v[186:189], v155 offset:32768
	ds_read_b128 v[190:193], v155 offset:33792
	ds_read_b128 v[194:197], v155 offset:34816
	ds_read_b128 v[198:201], v155 offset:35840
	ds_read_b128 v[202:205], v155 offset:36864
	ds_read_b128 v[206:209], v155 offset:37888
	ds_read_b128 v[210:213], v155 offset:38912
	ds_read_b128 v[214:217], v155 offset:39936
	global_load_lds_dwordx4 v[228:229], off
	v_lshl_add_u64 v[228:229], s[30:31], 0, v[130:131]
	s_mov_b32 m0, s55
	s_nop 0
	global_load_lds_dwordx4 v[228:229], off
	s_waitcnt vmcnt(8)
	s_waitcnt lgkmcnt(0)
	s_barrier
	s_setprio 1
	s_waitcnt lgkmcnt(0)
	v_mfma_f32_16x16x32_bf16 v[124:127], v[148:151], v[186:189], v[124:127]
	v_mfma_f32_16x16x32_bf16 v[116:119], v[162:165], v[186:189], v[116:119]
	v_mfma_f32_16x16x32_bf16 v[108:111], v[148:151], v[194:197], v[108:111]
	v_mfma_f32_16x16x32_bf16 v[100:103], v[162:165], v[194:197], v[100:103]
	v_mfma_f32_16x16x32_bf16 v[92:95], v[148:151], v[202:205], v[92:95]
	v_mfma_f32_16x16x32_bf16 v[84:87], v[162:165], v[202:205], v[84:87]
	v_mfma_f32_16x16x32_bf16 v[76:79], v[148:151], v[210:213], v[76:79]
	v_mfma_f32_16x16x32_bf16 v[68:71], v[162:165], v[210:213], v[68:71]
	v_mfma_f32_16x16x32_bf16 v[124:127], v[158:161], v[190:193], v[124:127]
	v_mfma_f32_16x16x32_bf16 v[116:119], v[166:169], v[190:193], v[116:119]
	v_mfma_f32_16x16x32_bf16 v[108:111], v[158:161], v[198:201], v[108:111]
	v_mfma_f32_16x16x32_bf16 v[100:103], v[166:169], v[198:201], v[100:103]
	v_mfma_f32_16x16x32_bf16 v[92:95], v[158:161], v[206:209], v[92:95]
	v_mfma_f32_16x16x32_bf16 v[84:87], v[166:169], v[206:209], v[84:87]
	v_mfma_f32_16x16x32_bf16 v[76:79], v[158:161], v[214:217], v[76:79]
	v_mfma_f32_16x16x32_bf16 v[68:71], v[166:169], v[214:217], v[68:71]
	s_setprio 0
	s_setprio 1
	v_mfma_f32_16x16x32_bf16 v[120:123], v[170:173], v[186:189], v[120:123]
	v_mfma_f32_16x16x32_bf16 v[112:115], v[178:181], v[186:189], v[112:115]
	v_mfma_f32_16x16x32_bf16 v[104:107], v[170:173], v[194:197], v[104:107]
	v_mfma_f32_16x16x32_bf16 v[96:99], v[178:181], v[194:197], v[96:99]
	v_mfma_f32_16x16x32_bf16 v[88:91], v[170:173], v[202:205], v[88:91]
	v_mfma_f32_16x16x32_bf16 v[80:83], v[178:181], v[202:205], v[80:83]
	v_mfma_f32_16x16x32_bf16 v[72:75], v[170:173], v[210:213], v[72:75]
	v_mfma_f32_16x16x32_bf16 v[64:67], v[178:181], v[210:213], v[64:67]
	v_mfma_f32_16x16x32_bf16 v[120:123], v[174:177], v[190:193], v[120:123]
	v_mfma_f32_16x16x32_bf16 v[112:115], v[182:185], v[190:193], v[112:115]
	v_mfma_f32_16x16x32_bf16 v[104:107], v[174:177], v[198:201], v[104:107]
	v_mfma_f32_16x16x32_bf16 v[96:99], v[182:185], v[198:201], v[96:99]
	v_mfma_f32_16x16x32_bf16 v[88:91], v[174:177], v[206:209], v[88:91]
	v_mfma_f32_16x16x32_bf16 v[80:83], v[182:185], v[206:209], v[80:83]
	v_mfma_f32_16x16x32_bf16 v[72:75], v[174:177], v[214:217], v[72:75]
	v_mfma_f32_16x16x32_bf16 v[64:67], v[182:185], v[214:217], v[64:67]
	s_setprio 0
	s_barrier
; #define PG8_STAGE(bufoff, gbase, voff) do { _Pragma("unroll") for (int _i = 0; _i < 2; ++_i) \
;         __builtin_amdgcn_global_load_lds((const unsigned*)((const char*)(gbase) + (voff)[_i]), (PG8_LAS unsigned*)(lds + (bufoff) + ldsw + _i * 8192), 16, 0, 0); } while (0)
; #define PG8_LDA(dst, b, h) do { _Pragma("unroll") for (int m = 0; m < 4; ++m) _Pragma("unroll") for (int k = 0; k < 2; ++k) dst[m][k] = *(const PG8_LAS bf16x8*)(lds + PG8_SA(b, h) + aoff + m * 2048 + k * 1024); } while (0)
; #define PG8_MMA(ai, bj, At, Bt) do { __builtin_amdgcn_s_setprio(1); _Pragma("unroll") for (int m = 0; m < 4; ++m) _Pragma("unroll") for (int n = 0; n < 2; ++n) _Pragma("unroll") for (int k = 0; k < 2; ++k) \
;         acc[ai][bj][m][n] = __builtin_amdgcn_mfma_f32_16x16x32_bf16(Bt[n][k], At[m][k], acc[ai][bj][m][n], 0, 0, 0); __builtin_amdgcn_s_setprio(0); } while (0)
; #define PG8_WAIT_V(n) asm volatile("s_waitcnt vmcnt(" #n ")" ::: "memory")
; #define PG8_WAIT_L(n) asm volatile("s_waitcnt lgkmcnt(" #n ")" ::: "memory")
; #define PG8_BAR __builtin_amdgcn_s_barrier()
; #define PG8_SCHED __builtin_amdgcn_sched_barrier(0)
; template <class Epi, class Sched>
; __device__ __forceinline__ void gemm_phase(PG8_LAS unsigned char* lds, PG8_LAS unsigned char* xl, const Gemm g, const Sched& S, const Epi& E) {
;     ...
;             PG8_LDA(At, 1, 1); PG8_STAGE(PG8_SB(1, 0), b3, voffB); PG8_STAGE(PG8_SB(1, 1), b3 + hsB, voffB); PG8_STAGE(PG8_SA(1, 0), a3, voffA);
;             PG8_WAIT_V(8); PG8_WAIT_L(0); PG8_BAR; PG8_MMA(1, 0, At, B0); PG8_MMA(1, 1, At, B1); PG8_BAR; PG8_SCHED;
;         }
	s_add_i32 s30, s68, s42
	v_lshl_add_u64 v[218:219], v[218:219], 0, s[12:13]
	s_mov_b32 m0, s30
	ds_read_b128 v[186:189], v155 offset:49152
	ds_read_b128 v[190:193], v155 offset:50176
	ds_read_b128 v[194:197], v155 offset:51200
	ds_read_b128 v[198:201], v155 offset:52224
	ds_read_b128 v[202:205], v155 offset:53248
	ds_read_b128 v[206:209], v155 offset:54272
	ds_read_b128 v[210:213], v155 offset:55296
	ds_read_b128 v[214:217], v155 offset:56320
	global_load_lds_dwordx4 v[218:219], off
	s_add_i32 m0, s30, 0x2000
	s_add_u32 s28, s28, 0x40080
	v_lshl_add_u64 v[218:219], v[222:223], 0, s[12:13]
	s_addc_u32 s29, s29, 0
	s_add_i32 s30, s80, s42
	global_load_lds_dwordx4 v[218:219], off
	v_lshl_add_u64 v[218:219], s[28:29], 0, v[132:133]
	s_mov_b32 m0, s30
	s_nop 0
	global_load_lds_dwordx4 v[218:219], off
	v_lshl_add_u64 v[218:219], s[28:29], 0, v[128:129]
	s_add_i32 m0, s30, 0x2000
	s_nop 0
	global_load_lds_dwordx4 v[218:219], off
	v_lshl_add_u64 v[218:219], v[224:225], 0, s[12:13]
	s_mov_b32 m0, s58
	s_nop 0
	global_load_lds_dwordx4 v[218:219], off
	v_lshl_add_u64 v[218:219], v[226:227], 0, s[12:13]
	s_mov_b32 m0, s59
	s_nop 0
	global_load_lds_dwordx4 v[218:219], off
	s_waitcnt vmcnt(8)
	s_waitcnt lgkmcnt(0)
	s_barrier
	s_setprio 1
	s_waitcnt lgkmcnt(0)
	v_mfma_f32_16x16x32_bf16 v[60:63], v[148:151], v[186:189], v[60:63]
	v_mfma_f32_16x16x32_bf16 v[52:55], v[162:165], v[186:189], v[52:55]
	v_mfma_f32_16x16x32_bf16 v[44:47], v[148:151], v[194:197], v[44:47]
	v_mfma_f32_16x16x32_bf16 v[36:39], v[162:165], v[194:197], v[36:39]
	v_mfma_f32_16x16x32_bf16 v[28:31], v[148:151], v[202:205], v[28:31]
	v_mfma_f32_16x16x32_bf16 v[20:23], v[162:165], v[202:205], v[20:23]
	v_mfma_f32_16x16x32_bf16 v[12:15], v[148:151], v[210:213], v[12:15]
	v_mfma_f32_16x16x32_bf16 v[4:7], v[162:165], v[210:213], v[4:7]
	v_mfma_f32_16x16x32_bf16 v[60:63], v[158:161], v[190:193], v[60:63]
	v_mfma_f32_16x16x32_bf16 v[52:55], v[166:169], v[190:193], v[52:55]
	v_mfma_f32_16x16x32_bf16 v[44:47], v[158:161], v[198:201], v[44:47]
	v_mfma_f32_16x16x32_bf16 v[36:39], v[166:169], v[198:201], v[36:39]
	v_mfma_f32_16x16x32_bf16 v[28:31], v[158:161], v[206:209], v[28:31]
	v_mfma_f32_16x16x32_bf16 v[20:23], v[166:169], v[206:209], v[20:23]
	v_mfma_f32_16x16x32_bf16 v[12:15], v[158:161], v[214:217], v[12:15]
	v_mfma_f32_16x16x32_bf16 v[4:7], v[166:169], v[214:217], v[4:7]
	s_setprio 0
	s_setprio 1
	v_mfma_f32_16x16x32_bf16 v[56:59], v[170:173], v[186:189], v[56:59]
	s_add_i32 s79, s79, 2
	v_mfma_f32_16x16x32_bf16 v[48:51], v[178:181], v[186:189], v[48:51]
	s_add_u32 s77, s77, 0x100
	v_mfma_f32_16x16x32_bf16 v[40:43], v[170:173], v[194:197], v[40:43]
	s_addc_u32 s78, s78, 0
	v_mfma_f32_16x16x32_bf16 v[32:35], v[178:181], v[194:197], v[32:35]
	s_add_u32 s26, s26, 0x100
	v_mfma_f32_16x16x32_bf16 v[24:27], v[170:173], v[202:205], v[24:27]
	s_addc_u32 s27, s27, 0
	v_mfma_f32_16x16x32_bf16 v[16:19], v[178:181], v[202:205], v[16:19]
	s_cmp_gt_u32 s79, 13
	v_mfma_f32_16x16x32_bf16 v[8:11], v[170:173], v[210:213], v[8:11]
	v_mfma_f32_16x16x32_bf16 v[0:3], v[178:181], v[210:213], v[0:3]
	v_mfma_f32_16x16x32_bf16 v[56:59], v[174:177], v[190:193], v[56:59]
	v_mfma_f32_16x16x32_bf16 v[48:51], v[182:185], v[190:193], v[48:51]
	v_mfma_f32_16x16x32_bf16 v[40:43], v[174:177], v[198:201], v[40:43]
	v_mfma_f32_16x16x32_bf16 v[32:35], v[182:185], v[198:201], v[32:35]
	v_mfma_f32_16x16x32_bf16 v[24:27], v[174:177], v[206:209], v[24:27]
	v_mfma_f32_16x16x32_bf16 v[16:19], v[182:185], v[206:209], v[16:19]
	v_mfma_f32_16x16x32_bf16 v[8:11], v[174:177], v[214:217], v[8:11]
	v_mfma_f32_16x16x32_bf16 v[0:3], v[182:185], v[214:217], v[0:3]
	s_setprio 0
	s_barrier
	s_cbranch_scc0 .LBB0_102

; #define PG8_STAGE(bufoff, gbase, voff) do { _Pragma("unroll") for (int _i = 0; _i < 2; ++_i) \
;         __builtin_amdgcn_global_load_lds((const unsigned*)((const char*)(gbase) + (voff)[_i]), (PG8_LAS unsigned*)(lds + (bufoff) + ldsw + _i * 8192), 16, 0, 0); } while (0)
; #define PG8_LDA(dst, b, h) do { _Pragma("unroll") for (int m = 0; m < 4; ++m) _Pragma("unroll") for (int k = 0; k < 2; ++k) dst[m][k] = *(const PG8_LAS bf16x8*)(lds + PG8_SA(b, h) + aoff + m * 2048 + k * 1024); } while (0)
; #define PG8_LDB(dst, b, h) do { _Pragma("unroll") for (int n = 0; n < 2; ++n) _Pragma("unroll") for (int k = 0; k < 2; ++k) dst[n][k] = *(const PG8_LAS bf16x8*)(lds + PG8_SB(b, h) + boff + n * 2048 + k * 1024); } while (0)
; #define PG8_MMA(ai, bj, At, Bt) do { __builtin_amdgcn_s_setprio(1); _Pragma("unroll") for (int m = 0; m < 4; ++m) _Pragma("unroll") for (int n = 0; n < 2; ++n) _Pragma("unroll") for (int k = 0; k < 2; ++k) \
;         acc[ai][bj][m][n] = __builtin_amdgcn_mfma_f32_16x16x32_bf16(Bt[n][k], At[m][k], acc[ai][bj][m][n], 0, 0, 0); __builtin_amdgcn_s_setprio(0); } while (0)
; #define PG8_WAIT_V(n) asm volatile("s_waitcnt vmcnt(" #n ")" ::: "memory")
; #define PG8_WAIT_L(n) asm volatile("s_waitcnt lgkmcnt(" #n ")" ::: "memory")
; #define PG8_BAR __builtin_amdgcn_s_barrier()
; #define PG8_SCHED __builtin_amdgcn_sched_barrier(0)
; template <class Epi, class Sched>
; __device__ __forceinline__ void gemm_phase(PG8_LAS unsigned char* lds, PG8_LAS unsigned char* xl, const Gemm g, const Sched& S, const Epi& E) {
;     ...
;         const bool has_next = S.next(ui + 1, nxt);
;         const char* nA = has_next ? (const char*)g.A + nxt.aoff : cA; const char* nB = has_next ? (const char*)g.Bt + nxt.boff : cB;
; #pragma unroll 1
;         for (int t = 0; t < nt; t += 2) {
;             const bool last = (t == nt - 2);
;             const char* a1 = cA + (size_t)(t + 1) * kstep;
;             const char* a2 = last ? nA : cA + (size_t)(t + 2) * kstep; const char* b2 = last ? nB : cB + (size_t)(t + 2) * kstep;
;             const char* a3 = a2 + kstep; const char* b3 = b2 + kstep;
;             PG8_LDB(B0, 0, 0); PG8_LDB(B1, 0, 1); PG8_SCHED; PG8_LDA(At, 0, 0); PG8_STAGE(PG8_SA(1, 1), a1 + hsA, voffA);
;             PG8_WAIT_V(8); PG8_WAIT_L(0); PG8_BAR; PG8_MMA(0, 0, At, B0); PG8_MMA(0, 1, At, B1); PG8_BAR; PG8_SCHED;
.LBB0_129:
	s_add_u32 s18, s35, s14
	s_addc_u32 s19, s36, s15
	s_and_b64 s[20:21], s[4:5], exec
	s_cselect_b32 s70, s19, s29
	s_cselect_b32 s72, s18, s28
	s_add_u32 s20, s37, s16
	s_addc_u32 s21, s42, s17
	s_and_b64 s[30:31], s[4:5], exec
	s_cselect_b32 s73, s21, s27
	s_cselect_b32 s74, s20, s26
	s_add_u32 s75, s26, 0x100
	s_addc_u32 s76, s27, 0
	s_add_u32 s26, s28, 0x40080
	v_mov_b32_e32 v0, 0
	s_addc_u32 s27, s29, 0
	s_mov_b32 s77, -2
	ds_read_b128 v[154:157], v150
	ds_read_b128 v[158:161], v150 offset:1024
	ds_read_b128 v[162:165], v150 offset:2048
	ds_read_b128 v[166:169], v150 offset:3072
	ds_read_b128 v[170:173], v151
	ds_read_b128 v[174:177], v151 offset:1024
	ds_read_b128 v[178:181], v151 offset:2048
	ds_read_b128 v[182:185], v151 offset:3072
	s_add_u32 s28, s26, 0xfffc0080
	s_addc_u32 s29, s27, -1
	s_cmp_eq_u32 s77, 12
	s_cselect_b32 s31, s70, s29
	s_cselect_b32 s30, s72, s28
	s_cselect_b32 s29, s73, s76
	s_cselect_b32 s28, s74, s75
	v_lshl_add_u64 v[146:147], s[26:27], 0, v[140:141]
	s_add_i32 m0, s46, 0xc000
	ds_read_b128 v[186:189], v152
	ds_read_b128 v[190:193], v152 offset:1024
	ds_read_b128 v[194:197], v152 offset:2048
	ds_read_b128 v[198:201], v152 offset:3072
	ds_read_b128 v[202:205], v152 offset:4096
	ds_read_b128 v[206:209], v152 offset:5120
	ds_read_b128 v[210:213], v152 offset:6144
	ds_read_b128 v[214:217], v152 offset:7168
	global_load_lds_dwordx4 v[146:147], off
	v_lshl_add_u64 v[146:147], s[26:27], 0, v[138:139]
	s_add_i32 m0, s46, 0xe000
	s_nop 0
	global_load_lds_dwordx4 v[146:147], off
	s_waitcnt vmcnt(8)
	s_waitcnt lgkmcnt(0)
	s_barrier
	s_setprio 1
	s_waitcnt lgkmcnt(0)
	v_mfma_f32_16x16x32_bf16 v[124:127], v[154:157], v[186:189], 0
	v_mfma_f32_16x16x32_bf16 v[120:123], v[162:165], v[186:189], 0
	v_mfma_f32_16x16x32_bf16 v[116:119], v[154:157], v[194:197], 0
	v_mfma_f32_16x16x32_bf16 v[108:111], v[162:165], v[194:197], 0
	v_mfma_f32_16x16x32_bf16 v[100:103], v[154:157], v[202:205], 0
	v_mfma_f32_16x16x32_bf16 v[92:95], v[162:165], v[202:205], 0
	v_mfma_f32_16x16x32_bf16 v[84:87], v[154:157], v[210:213], 0
	v_mfma_f32_16x16x32_bf16 v[76:79], v[162:165], v[210:213], 0
	v_mfma_f32_16x16x32_bf16 v[124:127], v[158:161], v[190:193], v[124:127]
	v_mfma_f32_16x16x32_bf16 v[120:123], v[166:169], v[190:193], v[120:123]
	v_mfma_f32_16x16x32_bf16 v[116:119], v[158:161], v[198:201], v[116:119]
	v_mfma_f32_16x16x32_bf16 v[108:111], v[166:169], v[198:201], v[108:111]
	v_mfma_f32_16x16x32_bf16 v[100:103], v[158:161], v[206:209], v[100:103]
	v_mfma_f32_16x16x32_bf16 v[92:95], v[166:169], v[206:209], v[92:95]
	v_mfma_f32_16x16x32_bf16 v[84:87], v[158:161], v[214:217], v[84:87]
	v_mfma_f32_16x16x32_bf16 v[76:79], v[166:169], v[214:217], v[76:79]
	s_setprio 0
	s_setprio 1
	v_mfma_f32_16x16x32_bf16 v[112:115], v[170:173], v[186:189], 0
	v_mfma_f32_16x16x32_bf16 v[104:107], v[178:181], v[186:189], 0
	v_mfma_f32_16x16x32_bf16 v[96:99], v[170:173], v[194:197], 0
	v_mfma_f32_16x16x32_bf16 v[88:91], v[178:181], v[194:197], 0
	v_mfma_f32_16x16x32_bf16 v[80:83], v[170:173], v[202:205], 0
	v_mfma_f32_16x16x32_bf16 v[72:75], v[178:181], v[202:205], 0
	v_mfma_f32_16x16x32_bf16 v[68:71], v[170:173], v[210:213], 0
	v_mfma_f32_16x16x32_bf16 v[64:67], v[178:181], v[210:213], 0
	v_mfma_f32_16x16x32_bf16 v[112:115], v[174:177], v[190:193], v[112:115]
	v_mfma_f32_16x16x32_bf16 v[104:107], v[182:185], v[190:193], v[104:107]
	v_mfma_f32_16x16x32_bf16 v[96:99], v[174:177], v[198:201], v[96:99]
	v_mfma_f32_16x16x32_bf16 v[88:91], v[182:185], v[198:201], v[88:91]
	v_mfma_f32_16x16x32_bf16 v[80:83], v[174:177], v[206:209], v[80:83]
	v_mfma_f32_16x16x32_bf16 v[72:75], v[182:185], v[206:209], v[72:75]
	v_mfma_f32_16x16x32_bf16 v[68:71], v[174:177], v[214:217], v[68:71]
	v_mfma_f32_16x16x32_bf16 v[64:67], v[182:185], v[214:217], v[64:67]
	s_setprio 0
	s_barrier
	s_add_i32 s68, s57, s43
	v_lshl_add_u64 v[146:147], s[28:29], 0, v[130:131]
	s_mov_b32 m0, s68
	ds_read_b128 v[186:189], v152 offset:16384
	ds_read_b128 v[190:193], v152 offset:17408
	ds_read_b128 v[194:197], v152 offset:18432
	ds_read_b128 v[198:201], v152 offset:19456
	ds_read_b128 v[202:205], v152 offset:20480
	ds_read_b128 v[206:209], v152 offset:21504
	ds_read_b128 v[210:213], v152 offset:22528
	ds_read_b128 v[214:217], v152 offset:23552
	global_load_lds_dwordx4 v[146:147], off
	s_add_i32 m0, s68, 0x2000
	s_add_u32 s78, s28, 0x40000
	v_lshl_add_u64 v[218:219], s[28:29], 0, v[134:135]
	s_addc_u32 s79, s29, 0
	s_add_i32 s68, s58, s43
	global_load_lds_dwordx4 v[218:219], off
	v_lshl_add_u64 v[222:223], s[78:79], 0, v[130:131]
	s_mov_b32 m0, s68
	v_lshl_add_u64 v[224:225], s[30:31], 0, v[132:133]
	global_load_lds_dwordx4 v[222:223], off
	v_lshl_add_u64 v[222:223], s[78:79], 0, v[134:135]
	s_add_i32 m0, s68, 0x2000
	s_nop 0
	global_load_lds_dwordx4 v[222:223], off
	v_lshl_add_u64 v[222:223], s[30:31], 0, v[128:129]
	s_mov_b32 m0, s46
	s_nop 0
	global_load_lds_dwordx4 v[222:223], off
	s_mov_b32 m0, s47
	s_nop 0
	global_load_lds_dwordx4 v[224:225], off
	s_waitcnt vmcnt(8)
	s_waitcnt lgkmcnt(0)
	s_barrier
; #define PG8_STAGE(bufoff, gbase, voff) do { _Pragma("unroll") for (int _i = 0; _i < 2; ++_i) \
;         __builtin_amdgcn_global_load_lds((const unsigned*)((const char*)(gbase) + (voff)[_i]), (PG8_LAS unsigned*)(lds + (bufoff) + ldsw + _i * 8192), 16, 0, 0); } while (0)
; #define PG8_LDA(dst, b, h) do { _Pragma("unroll") for (int m = 0; m < 4; ++m) _Pragma("unroll") for (int k = 0; k < 2; ++k) dst[m][k] = *(const PG8_LAS bf16x8*)(lds + PG8_SA(b, h) + aoff + m * 2048 + k * 1024); } while (0)
; #define PG8_LDB(dst, b, h) do { _Pragma("unroll") for (int n = 0; n < 2; ++n) _Pragma("unroll") for (int k = 0; k < 2; ++k) dst[n][k] = *(const PG8_LAS bf16x8*)(lds + PG8_SB(b, h) + boff + n * 2048 + k * 1024); } while (0)
; #define PG8_MMA(ai, bj, At, Bt) do { __builtin_amdgcn_s_setprio(1); _Pragma("unroll") for (int m = 0; m < 4; ++m) _Pragma("unroll") for (int n = 0; n < 2; ++n) _Pragma("unroll") for (int k = 0; k < 2; ++k) \
;         acc[ai][bj][m][n] = __builtin_amdgcn_mfma_f32_16x16x32_bf16(Bt[n][k], At[m][k], acc[ai][bj][m][n], 0, 0, 0); __builtin_amdgcn_s_setprio(0); } while (0)
; #define PG8_WAIT_V(n) asm volatile("s_waitcnt vmcnt(" #n ")" ::: "memory")
; #define PG8_WAIT_L(n) asm volatile("s_waitcnt lgkmcnt(" #n ")" ::: "memory")
; #define PG8_BAR __builtin_amdgcn_s_barrier()
; #define PG8_SCHED __builtin_amdgcn_sched_barrier(0)
; template <class Epi, class Sched>
; __device__ __forceinline__ void gemm_phase(PG8_LAS unsigned char* lds, PG8_LAS unsigned char* xl, const Gemm g, const Sched& S, const Epi& E) {
;     ...
;             PG8_WAIT_V(8); PG8_WAIT_L(0); PG8_BAR; PG8_MMA(0, 0, At, B0); PG8_MMA(0, 1, At, B1); PG8_BAR; PG8_SCHED;
;             PG8_LDA(At, 0, 1); PG8_STAGE(PG8_SB(0, 0), b2, voffB); PG8_STAGE(PG8_SB(0, 1), b2 + hsB, voffB); PG8_STAGE(PG8_SA(0, 0), a2, voffA);
;             PG8_WAIT_V(8); PG8_WAIT_L(0); PG8_BAR; PG8_MMA(1, 0, At, B0); PG8_MMA(1, 1, At, B1); PG8_BAR; PG8_SCHED;
;             PG8_LDB(B0, 1, 0); PG8_LDB(B1, 1, 1); PG8_SCHED; PG8_LDA(At, 1, 0); PG8_STAGE(PG8_SA(0, 1), a2 + hsA, voffA);
;             PG8_WAIT_V(8); PG8_WAIT_L(0); PG8_BAR; PG8_MMA(0, 0, At, B0); PG8_MMA(0, 1, At, B1); PG8_BAR; PG8_SCHED;
	s_setprio 1
	s_waitcnt lgkmcnt(0)
	v_mfma_f32_16x16x32_bf16 v[60:63], v[154:157], v[186:189], 0
	v_mfma_f32_16x16x32_bf16 v[56:59], v[162:165], v[186:189], 0
	v_mfma_f32_16x16x32_bf16 v[52:55], v[154:157], v[194:197], 0
	v_mfma_f32_16x16x32_bf16 v[44:47], v[162:165], v[194:197], 0
	v_mfma_f32_16x16x32_bf16 v[36:39], v[154:157], v[202:205], 0
	v_mfma_f32_16x16x32_bf16 v[28:31], v[162:165], v[202:205], 0
	v_mfma_f32_16x16x32_bf16 v[20:23], v[154:157], v[210:213], 0
	v_mfma_f32_16x16x32_bf16 v[12:15], v[162:165], v[210:213], 0
	v_mfma_f32_16x16x32_bf16 v[60:63], v[158:161], v[190:193], v[60:63]
	v_mfma_f32_16x16x32_bf16 v[56:59], v[166:169], v[190:193], v[56:59]
	v_mfma_f32_16x16x32_bf16 v[52:55], v[158:161], v[198:201], v[52:55]
	v_mfma_f32_16x16x32_bf16 v[44:47], v[166:169], v[198:201], v[44:47]
	v_mfma_f32_16x16x32_bf16 v[36:39], v[158:161], v[206:209], v[36:39]
	v_mfma_f32_16x16x32_bf16 v[28:31], v[166:169], v[206:209], v[28:31]
	v_mfma_f32_16x16x32_bf16 v[20:23], v[158:161], v[214:217], v[20:23]
	v_mfma_f32_16x16x32_bf16 v[12:15], v[166:169], v[214:217], v[12:15]
	s_setprio 0
	s_setprio 1
	v_mfma_f32_16x16x32_bf16 v[48:51], v[170:173], v[186:189], 0
	v_mfma_f32_16x16x32_bf16 v[40:43], v[178:181], v[186:189], 0
	v_mfma_f32_16x16x32_bf16 v[32:35], v[170:173], v[194:197], 0
	v_mfma_f32_16x16x32_bf16 v[24:27], v[178:181], v[194:197], 0
	v_mfma_f32_16x16x32_bf16 v[16:19], v[170:173], v[202:205], 0
	v_mfma_f32_16x16x32_bf16 v[8:11], v[178:181], v[202:205], 0
	v_mfma_f32_16x16x32_bf16 v[4:7], v[170:173], v[210:213], 0
	v_mfma_f32_16x16x32_bf16 v[0:3], v[178:181], v[210:213], 0
	v_mfma_f32_16x16x32_bf16 v[48:51], v[174:177], v[190:193], v[48:51]
	v_mfma_f32_16x16x32_bf16 v[40:43], v[182:185], v[190:193], v[40:43]
	v_mfma_f32_16x16x32_bf16 v[32:35], v[174:177], v[198:201], v[32:35]
	v_mfma_f32_16x16x32_bf16 v[24:27], v[182:185], v[198:201], v[24:27]
	v_mfma_f32_16x16x32_bf16 v[16:19], v[174:177], v[206:209], v[16:19]
	v_mfma_f32_16x16x32_bf16 v[8:11], v[182:185], v[206:209], v[8:11]
	v_mfma_f32_16x16x32_bf16 v[4:7], v[174:177], v[214:217], v[4:7]
	v_mfma_f32_16x16x32_bf16 v[0:3], v[182:185], v[214:217], v[0:3]
	s_setprio 0
	s_barrier
	s_add_i32 s68, 0, 0x18000
	v_add_u32_e32 v153, s68, v149
	s_add_i32 s78, 0, 0x1c000
	ds_read_b128 v[154:157], v153
	ds_read_b128 v[158:161], v153 offset:1024
	ds_read_b128 v[162:165], v153 offset:2048
	ds_read_b128 v[166:169], v153 offset:3072
	v_add_u32_e32 v153, s78, v149
	ds_read_b128 v[170:173], v153
	ds_read_b128 v[174:177], v153 offset:1024
	ds_read_b128 v[178:181], v153 offset:2048
	ds_read_b128 v[182:185], v153 offset:3072
	s_add_u32 s30, s30, 0x40000
	s_addc_u32 s31, s31, 0
	s_mov_b32 m0, s52
	v_lshl_add_u64 v[226:227], s[30:31], 0, v[128:129]
	ds_read_b128 v[186:189], v152 offset:32768
	ds_read_b128 v[190:193], v152 offset:33792
	ds_read_b128 v[194:197], v152 offset:34816
	ds_read_b128 v[198:201], v152 offset:35840
	ds_read_b128 v[202:205], v152 offset:36864
	ds_read_b128 v[206:209], v152 offset:37888
	ds_read_b128 v[210:213], v152 offset:38912
	ds_read_b128 v[214:217], v152 offset:39936
	global_load_lds_dwordx4 v[226:227], off
	v_lshl_add_u64 v[226:227], s[30:31], 0, v[132:133]
	s_mov_b32 m0, s53
	s_nop 0
	global_load_lds_dwordx4 v[226:227], off
	s_waitcnt vmcnt(8)
	s_waitcnt lgkmcnt(0)
	s_barrier
	s_setprio 1
	s_waitcnt lgkmcnt(0)
	v_mfma_f32_16x16x32_bf16 v[124:127], v[154:157], v[186:189], v[124:127]
	v_mfma_f32_16x16x32_bf16 v[120:123], v[162:165], v[186:189], v[120:123]
	v_mfma_f32_16x16x32_bf16 v[116:119], v[154:157], v[194:197], v[116:119]
	v_mfma_f32_16x16x32_bf16 v[108:111], v[162:165], v[194:197], v[108:111]
	v_mfma_f32_16x16x32_bf16 v[100:103], v[154:157], v[202:205], v[100:103]
	v_mfma_f32_16x16x32_bf16 v[92:95], v[162:165], v[202:205], v[92:95]
	v_mfma_f32_16x16x32_bf16 v[84:87], v[154:157], v[210:213], v[84:87]
	v_mfma_f32_16x16x32_bf16 v[76:79], v[162:165], v[210:213], v[76:79]
	v_mfma_f32_16x16x32_bf16 v[124:127], v[158:161], v[190:193], v[124:127]
	v_mfma_f32_16x16x32_bf16 v[120:123], v[166:169], v[190:193], v[120:123]
	v_mfma_f32_16x16x32_bf16 v[116:119], v[158:161], v[198:201], v[116:119]
	v_mfma_f32_16x16x32_bf16 v[108:111], v[166:169], v[198:201], v[108:111]
	v_mfma_f32_16x16x32_bf16 v[100:103], v[158:161], v[206:209], v[100:103]
	v_mfma_f32_16x16x32_bf16 v[92:95], v[166:169], v[206:209], v[92:95]
	v_mfma_f32_16x16x32_bf16 v[84:87], v[158:161], v[214:217], v[84:87]
	v_mfma_f32_16x16x32_bf16 v[76:79], v[166:169], v[214:217], v[76:79]
	s_setprio 0
	s_setprio 1
	v_mfma_f32_16x16x32_bf16 v[112:115], v[170:173], v[186:189], v[112:115]
	v_mfma_f32_16x16x32_bf16 v[104:107], v[178:181], v[186:189], v[104:107]
	v_mfma_f32_16x16x32_bf16 v[96:99], v[170:173], v[194:197], v[96:99]
	v_mfma_f32_16x16x32_bf16 v[88:91], v[178:181], v[194:197], v[88:91]
	v_mfma_f32_16x16x32_bf16 v[80:83], v[170:173], v[202:205], v[80:83]
	v_mfma_f32_16x16x32_bf16 v[72:75], v[178:181], v[202:205], v[72:75]
	v_mfma_f32_16x16x32_bf16 v[68:71], v[170:173], v[210:213], v[68:71]
	v_mfma_f32_16x16x32_bf16 v[64:67], v[178:181], v[210:213], v[64:67]
	v_mfma_f32_16x16x32_bf16 v[112:115], v[174:177], v[190:193], v[112:115]
	v_mfma_f32_16x16x32_bf16 v[104:107], v[182:185], v[190:193], v[104:107]
	v_mfma_f32_16x16x32_bf16 v[96:99], v[174:177], v[198:201], v[96:99]
	v_mfma_f32_16x16x32_bf16 v[88:91], v[182:185], v[198:201], v[88:91]
	v_mfma_f32_16x16x32_bf16 v[80:83], v[174:177], v[206:209], v[80:83]
	v_mfma_f32_16x16x32_bf16 v[72:75], v[182:185], v[206:209], v[72:75]
	v_mfma_f32_16x16x32_bf16 v[68:71], v[174:177], v[214:217], v[68:71]
	v_mfma_f32_16x16x32_bf16 v[64:67], v[182:185], v[214:217], v[64:67]
	s_setprio 0
	s_barrier
; #define PG8_STAGE(bufoff, gbase, voff) do { _Pragma("unroll") for (int _i = 0; _i < 2; ++_i) \
;         __builtin_amdgcn_global_load_lds((const unsigned*)((const char*)(gbase) + (voff)[_i]), (PG8_LAS unsigned*)(lds + (bufoff) + ldsw + _i * 8192), 16, 0, 0); } while (0)
; #define PG8_LDA(dst, b, h) do { _Pragma("unroll") for (int m = 0; m < 4; ++m) _Pragma("unroll") for (int k = 0; k < 2; ++k) dst[m][k] = *(const PG8_LAS bf16x8*)(lds + PG8_SA(b, h) + aoff + m * 2048 + k * 1024); } while (0)
; #define PG8_LDB(dst, b, h) do { _Pragma("unroll") for (int n = 0; n < 2; ++n) _Pragma("unroll") for (int k = 0; k < 2; ++k) dst[n][k] = *(const PG8_LAS bf16x8*)(lds + PG8_SB(b, h) + boff + n * 2048 + k * 1024); } while (0)
; #define PG8_MMA(ai, bj, At, Bt) do { __builtin_amdgcn_s_setprio(1); _Pragma("unroll") for (int m = 0; m < 4; ++m) _Pragma("unroll") for (int n = 0; n < 2; ++n) _Pragma("unroll") for (int k = 0; k < 2; ++k) \
;         acc[ai][bj][m][n] = __builtin_amdgcn_mfma_f32_16x16x32_bf16(Bt[n][k], At[m][k], acc[ai][bj][m][n], 0, 0, 0); __builtin_amdgcn_s_setprio(0); } while (0)
; #define PG8_WAIT_V(n) asm volatile("s_waitcnt vmcnt(" #n ")" ::: "memory")
; #define PG8_WAIT_L(n) asm volatile("s_waitcnt lgkmcnt(" #n ")" ::: "memory")
; #define PG8_BAR __builtin_amdgcn_s_barrier()
; #define PG8_SCHED __builtin_amdgcn_sched_barrier(0)
; template <class Epi, class Sched>
; __device__ __forceinline__ void gemm_phase(PG8_LAS unsigned char* lds, PG8_LAS unsigned char* xl, const Gemm g, const Sched& S, const Epi& E) {
;     ...
;         for (int t = 0; t < nt; t += 2) {
;             const bool last = (t == nt - 2);
;             const char* a1 = cA + (size_t)(t + 1) * kstep;
;             const char* a2 = last ? nA : cA + (size_t)(t + 2) * kstep; const char* b2 = last ? nB : cB + (size_t)(t + 2) * kstep;
;             const char* a3 = a2 + kstep; const char* b3 = b2 + kstep;
;             PG8_LDB(B0, 0, 0); PG8_LDB(B1, 0, 1); PG8_SCHED; PG8_LDA(At, 0, 0); PG8_STAGE(PG8_SA(1, 1), a1 + hsA, voffA);
;     ...
;             PG8_LDA(At, 1, 1); PG8_STAGE(PG8_SB(1, 0), b3, voffB); PG8_STAGE(PG8_SB(1, 1), b3 + hsB, voffB); PG8_STAGE(PG8_SA(1, 0), a3, voffA);
;             PG8_WAIT_V(8); PG8_WAIT_L(0); PG8_BAR; PG8_MMA(1, 0, At, B0); PG8_MMA(1, 1, At, B1); PG8_BAR; PG8_SCHED;
	s_add_i32 s30, s68, s43
	v_lshl_add_u64 v[146:147], v[146:147], 0, s[10:11]
	s_mov_b32 m0, s30
	ds_read_b128 v[186:189], v152 offset:49152
	ds_read_b128 v[190:193], v152 offset:50176
	ds_read_b128 v[194:197], v152 offset:51200
	ds_read_b128 v[198:201], v152 offset:52224
	ds_read_b128 v[202:205], v152 offset:53248
	ds_read_b128 v[206:209], v152 offset:54272
	ds_read_b128 v[210:213], v152 offset:55296
	ds_read_b128 v[214:217], v152 offset:56320
	global_load_lds_dwordx4 v[146:147], off
	s_add_i32 m0, s30, 0x2000
	s_add_u32 s28, s28, 0x40080
	v_lshl_add_u64 v[146:147], v[218:219], 0, s[10:11]
	s_addc_u32 s29, s29, 0
	s_add_i32 s30, s78, s43
	global_load_lds_dwordx4 v[146:147], off
	v_lshl_add_u64 v[146:147], s[28:29], 0, v[130:131]
	s_mov_b32 m0, s30
	s_nop 0
	global_load_lds_dwordx4 v[146:147], off
	v_lshl_add_u64 v[146:147], s[28:29], 0, v[134:135]
	s_add_i32 m0, s30, 0x2000
	s_nop 0
	global_load_lds_dwordx4 v[146:147], off
	v_lshl_add_u64 v[146:147], v[222:223], 0, s[10:11]
	s_mov_b32 m0, s55
	s_nop 0
	global_load_lds_dwordx4 v[146:147], off
	v_lshl_add_u64 v[146:147], v[224:225], 0, s[10:11]
	s_mov_b32 m0, s56
	s_nop 0
	global_load_lds_dwordx4 v[146:147], off
	s_waitcnt vmcnt(8)
	s_waitcnt lgkmcnt(0)
	s_barrier
	s_setprio 1
	s_waitcnt lgkmcnt(0)
	v_mfma_f32_16x16x32_bf16 v[60:63], v[154:157], v[186:189], v[60:63]
	v_mfma_f32_16x16x32_bf16 v[56:59], v[162:165], v[186:189], v[56:59]
	v_mfma_f32_16x16x32_bf16 v[52:55], v[154:157], v[194:197], v[52:55]
	v_mfma_f32_16x16x32_bf16 v[44:47], v[162:165], v[194:197], v[44:47]
	v_mfma_f32_16x16x32_bf16 v[36:39], v[154:157], v[202:205], v[36:39]
	v_mfma_f32_16x16x32_bf16 v[28:31], v[162:165], v[202:205], v[28:31]
	v_mfma_f32_16x16x32_bf16 v[20:23], v[154:157], v[210:213], v[20:23]
	v_mfma_f32_16x16x32_bf16 v[12:15], v[162:165], v[210:213], v[12:15]
	v_mfma_f32_16x16x32_bf16 v[60:63], v[158:161], v[190:193], v[60:63]
	v_mfma_f32_16x16x32_bf16 v[56:59], v[166:169], v[190:193], v[56:59]
	v_mfma_f32_16x16x32_bf16 v[52:55], v[158:161], v[198:201], v[52:55]
	v_mfma_f32_16x16x32_bf16 v[44:47], v[166:169], v[198:201], v[44:47]
	v_mfma_f32_16x16x32_bf16 v[36:39], v[158:161], v[206:209], v[36:39]
	v_mfma_f32_16x16x32_bf16 v[28:31], v[166:169], v[206:209], v[28:31]
	v_mfma_f32_16x16x32_bf16 v[20:23], v[158:161], v[214:217], v[20:23]
	v_mfma_f32_16x16x32_bf16 v[12:15], v[166:169], v[214:217], v[12:15]
	s_setprio 0
	s_setprio 1
	v_mfma_f32_16x16x32_bf16 v[48:51], v[170:173], v[186:189], v[48:51]
	s_add_i32 s77, s77, 2
	v_mfma_f32_16x16x32_bf16 v[40:43], v[178:181], v[186:189], v[40:43]
	s_add_u32 s75, s75, 0x100
	v_mfma_f32_16x16x32_bf16 v[32:35], v[170:173], v[194:197], v[32:35]
	s_addc_u32 s76, s76, 0
	v_mfma_f32_16x16x32_bf16 v[24:27], v[178:181], v[194:197], v[24:27]
	s_add_u32 s26, s26, 0x100
	v_mfma_f32_16x16x32_bf16 v[16:19], v[170:173], v[202:205], v[16:19]
	s_addc_u32 s27, s27, 0
	v_mfma_f32_16x16x32_bf16 v[8:11], v[178:181], v[202:205], v[8:11]
	s_cmp_gt_u32 s77, 13
	v_mfma_f32_16x16x32_bf16 v[4:7], v[170:173], v[210:213], v[4:7]
	v_mfma_f32_16x16x32_bf16 v[0:3], v[178:181], v[210:213], v[0:3]
	v_mfma_f32_16x16x32_bf16 v[48:51], v[174:177], v[190:193], v[48:51]
	v_mfma_f32_16x16x32_bf16 v[40:43], v[182:185], v[190:193], v[40:43]
	v_mfma_f32_16x16x32_bf16 v[32:35], v[174:177], v[198:201], v[32:35]
	v_mfma_f32_16x16x32_bf16 v[24:27], v[182:185], v[198:201], v[24:27]
	v_mfma_f32_16x16x32_bf16 v[16:19], v[174:177], v[206:209], v[16:19]
	v_mfma_f32_16x16x32_bf16 v[8:11], v[182:185], v[206:209], v[8:11]
	v_mfma_f32_16x16x32_bf16 v[4:7], v[174:177], v[214:217], v[4:7]
	v_mfma_f32_16x16x32_bf16 v[0:3], v[182:185], v[214:217], v[0:3]
	s_setprio 0
	s_barrier
	s_cbranch_scc1 .Lpeel_after_P11
.LBB0_130:
	ds_read_b128 v[154:157], v150
	ds_read_b128 v[158:161], v150 offset:1024
	ds_read_b128 v[162:165], v150 offset:2048
	ds_read_b128 v[166:169], v150 offset:3072
	ds_read_b128 v[170:173], v151
	ds_read_b128 v[174:177], v151 offset:1024
	ds_read_b128 v[178:181], v151 offset:2048
	ds_read_b128 v[182:185], v151 offset:3072
	s_add_u32 s28, s26, 0xfffc0080
	s_addc_u32 s29, s27, -1
	s_cmp_eq_u32 s77, 12
	s_cselect_b32 s31, s70, s29
	s_cselect_b32 s30, s72, s28
	s_cselect_b32 s29, s73, s76
	s_cselect_b32 s28, s74, s75
	v_lshl_add_u64 v[146:147], s[26:27], 0, v[140:141]
	s_add_i32 m0, s46, 0xc000
	ds_read_b128 v[186:189], v152
	ds_read_b128 v[190:193], v152 offset:1024
	ds_read_b128 v[194:197], v152 offset:2048
	ds_read_b128 v[198:201], v152 offset:3072
	ds_read_b128 v[202:205], v152 offset:4096
	ds_read_b128 v[206:209], v152 offset:5120
	ds_read_b128 v[210:213], v152 offset:6144
	ds_read_b128 v[214:217], v152 offset:7168
	global_load_lds_dwordx4 v[146:147], off
	v_lshl_add_u64 v[146:147], s[26:27], 0, v[138:139]
	s_add_i32 m0, s46, 0xe000
	s_nop 0
	global_load_lds_dwordx4 v[146:147], off
	s_waitcnt vmcnt(8)
	s_waitcnt lgkmcnt(0)
	s_barrier
; #define PG8_STAGE(bufoff, gbase, voff) do { _Pragma("unroll") for (int _i = 0; _i < 2; ++_i) \
;         __builtin_amdgcn_global_load_lds((const unsigned*)((const char*)(gbase) + (voff)[_i]), (PG8_LAS unsigned*)(lds + (bufoff) + ldsw + _i * 8192), 16, 0, 0); } while (0)
; #define PG8_LDA(dst, b, h) do { _Pragma("unroll") for (int m = 0; m < 4; ++m) _Pragma("unroll") for (int k = 0; k < 2; ++k) dst[m][k] = *(const PG8_LAS bf16x8*)(lds + PG8_SA(b, h) + aoff + m * 2048 + k * 1024); } while (0)
; #define PG8_MMA(ai, bj, At, Bt) do { __builtin_amdgcn_s_setprio(1); _Pragma("unroll") for (int m = 0; m < 4; ++m) _Pragma("unroll") for (int n = 0; n < 2; ++n) _Pragma("unroll") for (int k = 0; k < 2; ++k) \
;         acc[ai][bj][m][n] = __builtin_amdgcn_mfma_f32_16x16x32_bf16(Bt[n][k], At[m][k], acc[ai][bj][m][n], 0, 0, 0); __builtin_amdgcn_s_setprio(0); } while (0)
; #define PG8_WAIT_V(n) asm volatile("s_waitcnt vmcnt(" #n ")" ::: "memory")
; #define PG8_WAIT_L(n) asm volatile("s_waitcnt lgkmcnt(" #n ")" ::: "memory")
; #define PG8_BAR __builtin_amdgcn_s_barrier()
; #define PG8_SCHED __builtin_amdgcn_sched_barrier(0)
; template <class Epi, class Sched>
; __device__ __forceinline__ void gemm_phase(PG8_LAS unsigned char* lds, PG8_LAS unsigned char* xl, const Gemm g, const Sched& S, const Epi& E) {
;     ...
;             PG8_WAIT_V(8); PG8_WAIT_L(0); PG8_BAR; PG8_MMA(0, 0, At, B0); PG8_MMA(0, 1, At, B1); PG8_BAR; PG8_SCHED;
;             PG8_LDA(At, 0, 1); PG8_STAGE(PG8_SB(0, 0), b2, voffB); PG8_STAGE(PG8_SB(0, 1), b2 + hsB, voffB); PG8_STAGE(PG8_SA(0, 0), a2, voffA);
;             PG8_WAIT_V(8); PG8_WAIT_L(0); PG8_BAR; PG8_MMA(1, 0, At, B0); PG8_MMA(1, 1, At, B1); PG8_BAR; PG8_SCHED;
	s_setprio 1
	s_waitcnt lgkmcnt(0)
	v_mfma_f32_16x16x32_bf16 v[124:127], v[154:157], v[186:189], v[124:127]
	v_mfma_f32_16x16x32_bf16 v[120:123], v[162:165], v[186:189], v[120:123]
	v_mfma_f32_16x16x32_bf16 v[116:119], v[154:157], v[194:197], v[116:119]
	v_mfma_f32_16x16x32_bf16 v[108:111], v[162:165], v[194:197], v[108:111]
	v_mfma_f32_16x16x32_bf16 v[100:103], v[154:157], v[202:205], v[100:103]
	v_mfma_f32_16x16x32_bf16 v[92:95], v[162:165], v[202:205], v[92:95]
	v_mfma_f32_16x16x32_bf16 v[84:87], v[154:157], v[210:213], v[84:87]
	v_mfma_f32_16x16x32_bf16 v[76:79], v[162:165], v[210:213], v[76:79]
	v_mfma_f32_16x16x32_bf16 v[124:127], v[158:161], v[190:193], v[124:127]
	v_mfma_f32_16x16x32_bf16 v[120:123], v[166:169], v[190:193], v[120:123]
	v_mfma_f32_16x16x32_bf16 v[116:119], v[158:161], v[198:201], v[116:119]
	v_mfma_f32_16x16x32_bf16 v[108:111], v[166:169], v[198:201], v[108:111]
	v_mfma_f32_16x16x32_bf16 v[100:103], v[158:161], v[206:209], v[100:103]
	v_mfma_f32_16x16x32_bf16 v[92:95], v[166:169], v[206:209], v[92:95]
	v_mfma_f32_16x16x32_bf16 v[84:87], v[158:161], v[214:217], v[84:87]
	v_mfma_f32_16x16x32_bf16 v[76:79], v[166:169], v[214:217], v[76:79]
	s_setprio 0
	s_setprio 1
	v_mfma_f32_16x16x32_bf16 v[112:115], v[170:173], v[186:189], v[112:115]
	v_mfma_f32_16x16x32_bf16 v[104:107], v[178:181], v[186:189], v[104:107]
	v_mfma_f32_16x16x32_bf16 v[96:99], v[170:173], v[194:197], v[96:99]
	v_mfma_f32_16x16x32_bf16 v[88:91], v[178:181], v[194:197], v[88:91]
	v_mfma_f32_16x16x32_bf16 v[80:83], v[170:173], v[202:205], v[80:83]
	v_mfma_f32_16x16x32_bf16 v[72:75], v[178:181], v[202:205], v[72:75]
	v_mfma_f32_16x16x32_bf16 v[68:71], v[170:173], v[210:213], v[68:71]
	v_mfma_f32_16x16x32_bf16 v[64:67], v[178:181], v[210:213], v[64:67]
	v_mfma_f32_16x16x32_bf16 v[112:115], v[174:177], v[190:193], v[112:115]
	v_mfma_f32_16x16x32_bf16 v[104:107], v[182:185], v[190:193], v[104:107]
	v_mfma_f32_16x16x32_bf16 v[96:99], v[174:177], v[198:201], v[96:99]
	v_mfma_f32_16x16x32_bf16 v[88:91], v[182:185], v[198:201], v[88:91]
	v_mfma_f32_16x16x32_bf16 v[80:83], v[174:177], v[206:209], v[80:83]
	v_mfma_f32_16x16x32_bf16 v[72:75], v[182:185], v[206:209], v[72:75]
	v_mfma_f32_16x16x32_bf16 v[68:71], v[174:177], v[214:217], v[68:71]
	v_mfma_f32_16x16x32_bf16 v[64:67], v[182:185], v[214:217], v[64:67]
	s_setprio 0
	s_barrier
	s_add_i32 s68, s57, s43
	v_lshl_add_u64 v[146:147], s[28:29], 0, v[130:131]
	s_mov_b32 m0, s68
	ds_read_b128 v[186:189], v152 offset:16384
	ds_read_b128 v[190:193], v152 offset:17408
	ds_read_b128 v[194:197], v152 offset:18432
	ds_read_b128 v[198:201], v152 offset:19456
	ds_read_b128 v[202:205], v152 offset:20480
	ds_read_b128 v[206:209], v152 offset:21504
	ds_read_b128 v[210:213], v152 offset:22528
	ds_read_b128 v[214:217], v152 offset:23552
	global_load_lds_dwordx4 v[146:147], off
	s_add_i32 m0, s68, 0x2000
	s_add_u32 s78, s28, 0x40000
	v_lshl_add_u64 v[218:219], s[28:29], 0, v[134:135]
	s_addc_u32 s79, s29, 0
	s_add_i32 s68, s58, s43
	global_load_lds_dwordx4 v[218:219], off
	v_lshl_add_u64 v[222:223], s[78:79], 0, v[130:131]
	s_mov_b32 m0, s68
	v_lshl_add_u64 v[224:225], s[30:31], 0, v[132:133]
	global_load_lds_dwordx4 v[222:223], off
	v_lshl_add_u64 v[222:223], s[78:79], 0, v[134:135]
	s_add_i32 m0, s68, 0x2000
	s_nop 0
	global_load_lds_dwordx4 v[222:223], off
	v_lshl_add_u64 v[222:223], s[30:31], 0, v[128:129]
	s_mov_b32 m0, s46
	s_nop 0
	global_load_lds_dwordx4 v[222:223], off
	s_mov_b32 m0, s47
	s_nop 0
	global_load_lds_dwordx4 v[224:225], off
	s_waitcnt vmcnt(8)
	s_waitcnt lgkmcnt(0)
	s_barrier
	s_setprio 1
	s_waitcnt lgkmcnt(0)
	v_mfma_f32_16x16x32_bf16 v[60:63], v[154:157], v[186:189], v[60:63]
	v_mfma_f32_16x16x32_bf16 v[56:59], v[162:165], v[186:189], v[56:59]
	v_mfma_f32_16x16x32_bf16 v[52:55], v[154:157], v[194:197], v[52:55]
	v_mfma_f32_16x16x32_bf16 v[44:47], v[162:165], v[194:197], v[44:47]
	v_mfma_f32_16x16x32_bf16 v[36:39], v[154:157], v[202:205], v[36:39]
	v_mfma_f32_16x16x32_bf16 v[28:31], v[162:165], v[202:205], v[28:31]
	v_mfma_f32_16x16x32_bf16 v[20:23], v[154:157], v[210:213], v[20:23]
	v_mfma_f32_16x16x32_bf16 v[12:15], v[162:165], v[210:213], v[12:15]
	v_mfma_f32_16x16x32_bf16 v[60:63], v[158:161], v[190:193], v[60:63]
	v_mfma_f32_16x16x32_bf16 v[56:59], v[166:169], v[190:193], v[56:59]
	v_mfma_f32_16x16x32_bf16 v[52:55], v[158:161], v[198:201], v[52:55]
	v_mfma_f32_16x16x32_bf16 v[44:47], v[166:169], v[198:201], v[44:47]
	v_mfma_f32_16x16x32_bf16 v[36:39], v[158:161], v[206:209], v[36:39]
	v_mfma_f32_16x16x32_bf16 v[28:31], v[166:169], v[206:209], v[28:31]
	v_mfma_f32_16x16x32_bf16 v[20:23], v[158:161], v[214:217], v[20:23]
	v_mfma_f32_16x16x32_bf16 v[12:15], v[166:169], v[214:217], v[12:15]
	s_setprio 0
	s_setprio 1
	v_mfma_f32_16x16x32_bf16 v[48:51], v[170:173], v[186:189], v[48:51]
	v_mfma_f32_16x16x32_bf16 v[40:43], v[178:181], v[186:189], v[40:43]
	v_mfma_f32_16x16x32_bf16 v[32:35], v[170:173], v[194:197], v[32:35]
	v_mfma_f32_16x16x32_bf16 v[24:27], v[178:181], v[194:197], v[24:27]
	v_mfma_f32_16x16x32_bf16 v[16:19], v[170:173], v[202:205], v[16:19]
	v_mfma_f32_16x16x32_bf16 v[8:11], v[178:181], v[202:205], v[8:11]
	v_mfma_f32_16x16x32_bf16 v[4:7], v[170:173], v[210:213], v[4:7]
	v_mfma_f32_16x16x32_bf16 v[0:3], v[178:181], v[210:213], v[0:3]
	v_mfma_f32_16x16x32_bf16 v[48:51], v[174:177], v[190:193], v[48:51]
	v_mfma_f32_16x16x32_bf16 v[40:43], v[182:185], v[190:193], v[40:43]
	v_mfma_f32_16x16x32_bf16 v[32:35], v[174:177], v[198:201], v[32:35]
	v_mfma_f32_16x16x32_bf16 v[24:27], v[182:185], v[198:201], v[24:27]
	v_mfma_f32_16x16x32_bf16 v[16:19], v[174:177], v[206:209], v[16:19]
	v_mfma_f32_16x16x32_bf16 v[8:11], v[182:185], v[206:209], v[8:11]
	v_mfma_f32_16x16x32_bf16 v[4:7], v[174:177], v[214:217], v[4:7]
	v_mfma_f32_16x16x32_bf16 v[0:3], v[182:185], v[214:217], v[0:3]
	s_setprio 0
	s_barrier
; #define PG8_STAGE(bufoff, gbase, voff) do { _Pragma("unroll") for (int _i = 0; _i < 2; ++_i) \
;         __builtin_amdgcn_global_load_lds((const unsigned*)((const char*)(gbase) + (voff)[_i]), (PG8_LAS unsigned*)(lds + (bufoff) + ldsw + _i * 8192), 16, 0, 0); } while (0)
; #define PG8_LDA(dst, b, h) do { _Pragma("unroll") for (int m = 0; m < 4; ++m) _Pragma("unroll") for (int k = 0; k < 2; ++k) dst[m][k] = *(const PG8_LAS bf16x8*)(lds + PG8_SA(b, h) + aoff + m * 2048 + k * 1024); } while (0)
; #define PG8_LDB(dst, b, h) do { _Pragma("unroll") for (int n = 0; n < 2; ++n) _Pragma("unroll") for (int k = 0; k < 2; ++k) dst[n][k] = *(const PG8_LAS bf16x8*)(lds + PG8_SB(b, h) + boff + n * 2048 + k * 1024); } while (0)
; #define PG8_MMA(ai, bj, At, Bt) do { __builtin_amdgcn_s_setprio(1); _Pragma("unroll") for (int m = 0; m < 4; ++m) _Pragma("unroll") for (int n = 0; n < 2; ++n) _Pragma("unroll") for (int k = 0; k < 2; ++k) \
;         acc[ai][bj][m][n] = __builtin_amdgcn_mfma_f32_16x16x32_bf16(Bt[n][k], At[m][k], acc[ai][bj][m][n], 0, 0, 0); __builtin_amdgcn_s_setprio(0); } while (0)
; #define PG8_WAIT_V(n) asm volatile("s_waitcnt vmcnt(" #n ")" ::: "memory")
; #define PG8_WAIT_L(n) asm volatile("s_waitcnt lgkmcnt(" #n ")" ::: "memory")
; #define PG8_BAR __builtin_amdgcn_s_barrier()
; #define PG8_SCHED __builtin_amdgcn_sched_barrier(0)
; template <class Epi, class Sched>
; __device__ __forceinline__ void gemm_phase(PG8_LAS unsigned char* lds, PG8_LAS unsigned char* xl, const Gemm g, const Sched& S, const Epi& E) {
;     ...
;             PG8_LDB(B0, 1, 0); PG8_LDB(B1, 1, 1); PG8_SCHED; PG8_LDA(At, 1, 0); PG8_STAGE(PG8_SA(0, 1), a2 + hsA, voffA);
;             PG8_WAIT_V(8); PG8_WAIT_L(0); PG8_BAR; PG8_MMA(0, 0, At, B0); PG8_MMA(0, 1, At, B1); PG8_BAR; PG8_SCHED;
	s_add_i32 s68, 0, 0x18000
	v_add_u32_e32 v153, s68, v149
	s_add_i32 s78, 0, 0x1c000
	ds_read_b128 v[154:157], v153
	ds_read_b128 v[158:161], v153 offset:1024
	ds_read_b128 v[162:165], v153 offset:2048
	ds_read_b128 v[166:169], v153 offset:3072
	v_add_u32_e32 v153, s78, v149
	ds_read_b128 v[170:173], v153
	ds_read_b128 v[174:177], v153 offset:1024
	ds_read_b128 v[178:181], v153 offset:2048
	ds_read_b128 v[182:185], v153 offset:3072
	s_add_u32 s30, s30, 0x40000
	s_addc_u32 s31, s31, 0
	s_mov_b32 m0, s52
	v_lshl_add_u64 v[226:227], s[30:31], 0, v[128:129]
	ds_read_b128 v[186:189], v152 offset:32768
	ds_read_b128 v[190:193], v152 offset:33792
	ds_read_b128 v[194:197], v152 offset:34816
	ds_read_b128 v[198:201], v152 offset:35840
	ds_read_b128 v[202:205], v152 offset:36864
	ds_read_b128 v[206:209], v152 offset:37888
	ds_read_b128 v[210:213], v152 offset:38912
	ds_read_b128 v[214:217], v152 offset:39936
	global_load_lds_dwordx4 v[226:227], off
	v_lshl_add_u64 v[226:227], s[30:31], 0, v[132:133]
	s_mov_b32 m0, s53
	s_nop 0
	global_load_lds_dwordx4 v[226:227], off
	s_waitcnt vmcnt(8)
	s_waitcnt lgkmcnt(0)
	s_barrier
	s_setprio 1
	s_waitcnt lgkmcnt(0)
	v_mfma_f32_16x16x32_bf16 v[124:127], v[154:157], v[186:189], v[124:127]
	v_mfma_f32_16x16x32_bf16 v[120:123], v[162:165], v[186:189], v[120:123]
	v_mfma_f32_16x16x32_bf16 v[116:119], v[154:157], v[194:197], v[116:119]
	v_mfma_f32_16x16x32_bf16 v[108:111], v[162:165], v[194:197], v[108:111]
	v_mfma_f32_16x16x32_bf16 v[100:103], v[154:157], v[202:205], v[100:103]
	v_mfma_f32_16x16x32_bf16 v[92:95], v[162:165], v[202:205], v[92:95]
	v_mfma_f32_16x16x32_bf16 v[84:87], v[154:157], v[210:213], v[84:87]
	v_mfma_f32_16x16x32_bf16 v[76:79], v[162:165], v[210:213], v[76:79]
	v_mfma_f32_16x16x32_bf16 v[124:127], v[158:161], v[190:193], v[124:127]
	v_mfma_f32_16x16x32_bf16 v[120:123], v[166:169], v[190:193], v[120:123]
	v_mfma_f32_16x16x32_bf16 v[116:119], v[158:161], v[198:201], v[116:119]
	v_mfma_f32_16x16x32_bf16 v[108:111], v[166:169], v[198:201], v[108:111]
	v_mfma_f32_16x16x32_bf16 v[100:103], v[158:161], v[206:209], v[100:103]
	v_mfma_f32_16x16x32_bf16 v[92:95], v[166:169], v[206:209], v[92:95]
	v_mfma_f32_16x16x32_bf16 v[84:87], v[158:161], v[214:217], v[84:87]
	v_mfma_f32_16x16x32_bf16 v[76:79], v[166:169], v[214:217], v[76:79]
	s_setprio 0
	s_setprio 1
	v_mfma_f32_16x16x32_bf16 v[112:115], v[170:173], v[186:189], v[112:115]
	v_mfma_f32_16x16x32_bf16 v[104:107], v[178:181], v[186:189], v[104:107]
	v_mfma_f32_16x16x32_bf16 v[96:99], v[170:173], v[194:197], v[96:99]
	v_mfma_f32_16x16x32_bf16 v[88:91], v[178:181], v[194:197], v[88:91]
	v_mfma_f32_16x16x32_bf16 v[80:83], v[170:173], v[202:205], v[80:83]
	v_mfma_f32_16x16x32_bf16 v[72:75], v[178:181], v[202:205], v[72:75]
	v_mfma_f32_16x16x32_bf16 v[68:71], v[170:173], v[210:213], v[68:71]
	v_mfma_f32_16x16x32_bf16 v[64:67], v[178:181], v[210:213], v[64:67]
	v_mfma_f32_16x16x32_bf16 v[112:115], v[174:177], v[190:193], v[112:115]
	v_mfma_f32_16x16x32_bf16 v[104:107], v[182:185], v[190:193], v[104:107]
	v_mfma_f32_16x16x32_bf16 v[96:99], v[174:177], v[198:201], v[96:99]
	v_mfma_f32_16x16x32_bf16 v[88:91], v[182:185], v[198:201], v[88:91]
	v_mfma_f32_16x16x32_bf16 v[80:83], v[174:177], v[206:209], v[80:83]
	v_mfma_f32_16x16x32_bf16 v[72:75], v[182:185], v[206:209], v[72:75]
	v_mfma_f32_16x16x32_bf16 v[68:71], v[174:177], v[214:217], v[68:71]
	v_mfma_f32_16x16x32_bf16 v[64:67], v[182:185], v[214:217], v[64:67]
	s_setprio 0
	s_barrier
; #define PG8_STAGE(bufoff, gbase, voff) do { _Pragma("unroll") for (int _i = 0; _i < 2; ++_i) \
;         __builtin_amdgcn_global_load_lds((const unsigned*)((const char*)(gbase) + (voff)[_i]), (PG8_LAS unsigned*)(lds + (bufoff) + ldsw + _i * 8192), 16, 0, 0); } while (0)
; #define PG8_LDA(dst, b, h) do { _Pragma("unroll") for (int m = 0; m < 4; ++m) _Pragma("unroll") for (int k = 0; k < 2; ++k) dst[m][k] = *(const PG8_LAS bf16x8*)(lds + PG8_SA(b, h) + aoff + m * 2048 + k * 1024); } while (0)
; #define PG8_MMA(ai, bj, At, Bt) do { __builtin_amdgcn_s_setprio(1); _Pragma("unroll") for (int m = 0; m < 4; ++m) _Pragma("unroll") for (int n = 0; n < 2; ++n) _Pragma("unroll") for (int k = 0; k < 2; ++k) \
;         acc[ai][bj][m][n] = __builtin_amdgcn_mfma_f32_16x16x32_bf16(Bt[n][k], At[m][k], acc[ai][bj][m][n], 0, 0, 0); __builtin_amdgcn_s_setprio(0); } while (0)
; #define PG8_WAIT_V(n) asm volatile("s_waitcnt vmcnt(" #n ")" ::: "memory")
; #define PG8_WAIT_L(n) asm volatile("s_waitcnt lgkmcnt(" #n ")" ::: "memory")
; #define PG8_BAR __builtin_amdgcn_s_barrier()
; #define PG8_SCHED __builtin_amdgcn_sched_barrier(0)
; template <class Epi, class Sched>
; __device__ __forceinline__ void gemm_phase(PG8_LAS unsigned char* lds, PG8_LAS unsigned char* xl, const Gemm g, const Sched& S, const Epi& E) {
;     ...
;             PG8_LDA(At, 1, 1); PG8_STAGE(PG8_SB(1, 0), b3, voffB); PG8_STAGE(PG8_SB(1, 1), b3 + hsB, voffB); PG8_STAGE(PG8_SA(1, 0), a3, voffA);
;             PG8_WAIT_V(8); PG8_WAIT_L(0); PG8_BAR; PG8_MMA(1, 0, At, B0); PG8_MMA(1, 1, At, B1); PG8_BAR; PG8_SCHED;
	s_add_i32 s30, s68, s43
	v_lshl_add_u64 v[146:147], v[146:147], 0, s[10:11]
	s_mov_b32 m0, s30
	ds_read_b128 v[186:189], v152 offset:49152
	ds_read_b128 v[190:193], v152 offset:50176
	ds_read_b128 v[194:197], v152 offset:51200
	ds_read_b128 v[198:201], v152 offset:52224
	ds_read_b128 v[202:205], v152 offset:53248
	ds_read_b128 v[206:209], v152 offset:54272
	ds_read_b128 v[210:213], v152 offset:55296
	ds_read_b128 v[214:217], v152 offset:56320
	global_load_lds_dwordx4 v[146:147], off
	s_add_i32 m0, s30, 0x2000
	s_add_u32 s28, s28, 0x40080
	v_lshl_add_u64 v[146:147], v[218:219], 0, s[10:11]
	s_addc_u32 s29, s29, 0
	s_add_i32 s30, s78, s43
	global_load_lds_dwordx4 v[146:147], off
	v_lshl_add_u64 v[146:147], s[28:29], 0, v[130:131]
	s_mov_b32 m0, s30
	s_nop 0
	global_load_lds_dwordx4 v[146:147], off
	v_lshl_add_u64 v[146:147], s[28:29], 0, v[134:135]
	s_add_i32 m0, s30, 0x2000
	s_nop 0
	global_load_lds_dwordx4 v[146:147], off
	v_lshl_add_u64 v[146:147], v[222:223], 0, s[10:11]
	s_mov_b32 m0, s55
	s_nop 0
	global_load_lds_dwordx4 v[146:147], off
	v_lshl_add_u64 v[146:147], v[224:225], 0, s[10:11]
	s_mov_b32 m0, s56
	s_nop 0
	global_load_lds_dwordx4 v[146:147], off
	s_waitcnt vmcnt(8)
	s_waitcnt lgkmcnt(0)
	s_barrier
	s_setprio 1
	s_waitcnt lgkmcnt(0)
	v_mfma_f32_16x16x32_bf16 v[60:63], v[154:157], v[186:189], v[60:63]
	v_mfma_f32_16x16x32_bf16 v[56:59], v[162:165], v[186:189], v[56:59]
	v_mfma_f32_16x16x32_bf16 v[52:55], v[154:157], v[194:197], v[52:55]
	v_mfma_f32_16x16x32_bf16 v[44:47], v[162:165], v[194:197], v[44:47]
	v_mfma_f32_16x16x32_bf16 v[36:39], v[154:157], v[202:205], v[36:39]
	v_mfma_f32_16x16x32_bf16 v[28:31], v[162:165], v[202:205], v[28:31]
	v_mfma_f32_16x16x32_bf16 v[20:23], v[154:157], v[210:213], v[20:23]
	v_mfma_f32_16x16x32_bf16 v[12:15], v[162:165], v[210:213], v[12:15]
	v_mfma_f32_16x16x32_bf16 v[60:63], v[158:161], v[190:193], v[60:63]
	v_mfma_f32_16x16x32_bf16 v[56:59], v[166:169], v[190:193], v[56:59]
	v_mfma_f32_16x16x32_bf16 v[52:55], v[158:161], v[198:201], v[52:55]
	v_mfma_f32_16x16x32_bf16 v[44:47], v[166:169], v[198:201], v[44:47]
	v_mfma_f32_16x16x32_bf16 v[36:39], v[158:161], v[206:209], v[36:39]
	v_mfma_f32_16x16x32_bf16 v[28:31], v[166:169], v[206:209], v[28:31]
	v_mfma_f32_16x16x32_bf16 v[20:23], v[158:161], v[214:217], v[20:23]
	v_mfma_f32_16x16x32_bf16 v[12:15], v[166:169], v[214:217], v[12:15]
	s_setprio 0
	s_setprio 1
	v_mfma_f32_16x16x32_bf16 v[48:51], v[170:173], v[186:189], v[48:51]
	s_add_i32 s77, s77, 2
	v_mfma_f32_16x16x32_bf16 v[40:43], v[178:181], v[186:189], v[40:43]
	s_add_u32 s75, s75, 0x100
	v_mfma_f32_16x16x32_bf16 v[32:35], v[170:173], v[194:197], v[32:35]
	s_addc_u32 s76, s76, 0
	v_mfma_f32_16x16x32_bf16 v[24:27], v[178:181], v[194:197], v[24:27]
	s_add_u32 s26, s26, 0x100
	v_mfma_f32_16x16x32_bf16 v[16:19], v[170:173], v[202:205], v[16:19]
	s_addc_u32 s27, s27, 0
	v_mfma_f32_16x16x32_bf16 v[8:11], v[178:181], v[202:205], v[8:11]
	s_cmp_gt_u32 s77, 13
	v_mfma_f32_16x16x32_bf16 v[4:7], v[170:173], v[210:213], v[4:7]
	v_mfma_f32_16x16x32_bf16 v[0:3], v[178:181], v[210:213], v[0:3]
	v_mfma_f32_16x16x32_bf16 v[48:51], v[174:177], v[190:193], v[48:51]
	v_mfma_f32_16x16x32_bf16 v[40:43], v[182:185], v[190:193], v[40:43]
	v_mfma_f32_16x16x32_bf16 v[32:35], v[174:177], v[198:201], v[32:35]
	v_mfma_f32_16x16x32_bf16 v[24:27], v[182:185], v[198:201], v[24:27]
	v_mfma_f32_16x16x32_bf16 v[16:19], v[174:177], v[206:209], v[16:19]
	v_mfma_f32_16x16x32_bf16 v[8:11], v[182:185], v[206:209], v[8:11]
	v_mfma_f32_16x16x32_bf16 v[4:7], v[174:177], v[214:217], v[4:7]
	v_mfma_f32_16x16x32_bf16 v[0:3], v[182:185], v[214:217], v[0:3]
	s_setprio 0
	s_barrier
	s_cbranch_scc0 .LBB0_130

; #define PG8_STAGE(bufoff, gbase, voff) do { _Pragma("unroll") for (int _i = 0; _i < 2; ++_i) \
;         __builtin_amdgcn_global_load_lds((const unsigned*)((const char*)(gbase) + (voff)[_i]), (PG8_LAS unsigned*)(lds + (bufoff) + ldsw + _i * 8192), 16, 0, 0); } while (0)
; #define PG8_LDA(dst, b, h) do { _Pragma("unroll") for (int m = 0; m < 4; ++m) _Pragma("unroll") for (int k = 0; k < 2; ++k) dst[m][k] = *(const PG8_LAS bf16x8*)(lds + PG8_SA(b, h) + aoff + m * 2048 + k * 1024); } while (0)
; #define PG8_LDB(dst, b, h) do { _Pragma("unroll") for (int n = 0; n < 2; ++n) _Pragma("unroll") for (int k = 0; k < 2; ++k) dst[n][k] = *(const PG8_LAS bf16x8*)(lds + PG8_SB(b, h) + boff + n * 2048 + k * 1024); } while (0)
; #define PG8_MMA(ai, bj, At, Bt) do { __builtin_amdgcn_s_setprio(1); _Pragma("unroll") for (int m = 0; m < 4; ++m) _Pragma("unroll") for (int n = 0; n < 2; ++n) _Pragma("unroll") for (int k = 0; k < 2; ++k) \
;         acc[ai][bj][m][n] = __builtin_amdgcn_mfma_f32_16x16x32_bf16(Bt[n][k], At[m][k], acc[ai][bj][m][n], 0, 0, 0); __builtin_amdgcn_s_setprio(0); } while (0)
; #define PG8_WAIT_V(n) asm volatile("s_waitcnt vmcnt(" #n ")" ::: "memory")
; #define PG8_WAIT_L(n) asm volatile("s_waitcnt lgkmcnt(" #n ")" ::: "memory")
; template <class Epi, class Sched>
; __device__ __forceinline__ void gemm_phase(PG8_LAS unsigned char* lds, PG8_LAS unsigned char* xl, const Gemm g, const Sched& S, const Epi& E) {
;     ...
;         const bool has_next = S.next(ui + 1, nxt);
;         const char* nA = has_next ? (const char*)g.A + nxt.aoff : cA; const char* nB = has_next ? (const char*)g.Bt + nxt.boff : cB;
; #pragma unroll 1
;         for (int t = 0; t < nt; t += 2) {
;             const bool last = (t == nt - 2);
;             const char* a1 = cA + (size_t)(t + 1) * kstep;
;             const char* a2 = last ? nA : cA + (size_t)(t + 2) * kstep; const char* b2 = last ? nB : cB + (size_t)(t + 2) * kstep;
;             const char* a3 = a2 + kstep; const char* b3 = b2 + kstep;
;             PG8_LDB(B0, 0, 0); PG8_LDB(B1, 0, 1); PG8_SCHED; PG8_LDA(At, 0, 0); PG8_STAGE(PG8_SA(1, 1), a1 + hsA, voffA);
;             PG8_WAIT_V(8); PG8_WAIT_L(0); PG8_BAR; PG8_MMA(0, 0, At, B0); PG8_MMA(0, 1, At, B1); PG8_BAR; PG8_SCHED;
;             PG8_LDA(At, 0, 1); PG8_STAGE(PG8_SB(0, 0), b2, voffB); PG8_STAGE(PG8_SB(0, 1), b2 + hsB, voffB); PG8_STAGE(PG8_SA(0, 0), a2, voffA);
.LBB0_470:
	s_add_u32 s26, s43, s20
	s_addc_u32 s27, s50, s21
	s_and_b64 s[28:29], s[8:9], exec
	s_cselect_b32 s33, s27, s35
	s_cselect_b32 s46, s26, s34
	s_add_u32 s28, s51, s22
	s_addc_u32 s29, s52, s23
	s_and_b64 s[36:37], s[8:9], exec
	s_cselect_b32 s47, s29, s31
	s_cselect_b32 s70, s28, s30
	s_add_u32 s72, s30, 0x100
	s_addc_u32 s73, s31, 0
	s_add_u32 s30, s34, 0x40080
	v_mov_b32_e32 v0, 0
	s_addc_u32 s31, s35, 0
	s_mov_b32 s74, -2
	s_waitcnt lgkmcnt(0)
	ds_read_b128 v[168:171], v156
	ds_read_b128 v[172:175], v156 offset:1024
	ds_read_b128 v[180:183], v156 offset:2048
	ds_read_b128 v[184:187], v156 offset:3072
	ds_read_b128 v[188:191], v157
	ds_read_b128 v[192:195], v157 offset:1024
	ds_read_b128 v[196:199], v157 offset:2048
	ds_read_b128 v[200:203], v157 offset:3072
	s_add_u32 s34, s30, 0xfffc0080
	s_addc_u32 s35, s31, -1
	s_cmp_eq_u32 s74, 12
	s_cselect_b32 s37, s33, s35
	s_cselect_b32 s36, s46, s34
	s_cselect_b32 s35, s47, s73
	s_cselect_b32 s34, s70, s72
	v_lshl_add_u64 v[144:145], s[30:31], 0, v[138:139]
	s_add_i32 m0, s56, 0xc000
	ds_read_b128 v[204:207], v158
	ds_read_b128 v[208:211], v158 offset:1024
	ds_read_b128 v[212:215], v158 offset:2048
	ds_read_b128 v[216:219], v158 offset:3072
	ds_read_b128 v[222:225], v158 offset:4096
	ds_read_b128 v[226:229], v158 offset:5120
	ds_read_b128 v[230:233], v158 offset:6144
	ds_read_b128 v[234:237], v158 offset:7168
	global_load_lds_dwordx4 v[144:145], off
	v_lshl_add_u64 v[144:145], s[30:31], 0, v[136:137]
	s_add_i32 m0, s56, 0xe000
	s_nop 0
	global_load_lds_dwordx4 v[144:145], off
	s_waitcnt vmcnt(8)
	s_waitcnt lgkmcnt(0)
	s_barrier
	s_setprio 1
	s_waitcnt lgkmcnt(0)
	v_mfma_f32_16x16x32_bf16 v[124:127], v[168:171], v[204:207], 0
	v_mfma_f32_16x16x32_bf16 v[120:123], v[180:183], v[204:207], 0
	v_mfma_f32_16x16x32_bf16 v[108:111], v[168:171], v[212:215], 0
	v_mfma_f32_16x16x32_bf16 v[104:107], v[180:183], v[212:215], 0
	v_mfma_f32_16x16x32_bf16 v[92:95], v[168:171], v[222:225], 0
	v_mfma_f32_16x16x32_bf16 v[88:91], v[180:183], v[222:225], 0
	v_mfma_f32_16x16x32_bf16 v[76:79], v[168:171], v[230:233], 0
	v_mfma_f32_16x16x32_bf16 v[72:75], v[180:183], v[230:233], 0
	v_mfma_f32_16x16x32_bf16 v[124:127], v[172:175], v[208:211], v[124:127]
	v_mfma_f32_16x16x32_bf16 v[120:123], v[184:187], v[208:211], v[120:123]
	v_mfma_f32_16x16x32_bf16 v[108:111], v[172:175], v[216:219], v[108:111]
	v_mfma_f32_16x16x32_bf16 v[104:107], v[184:187], v[216:219], v[104:107]
	v_mfma_f32_16x16x32_bf16 v[92:95], v[172:175], v[226:229], v[92:95]
	v_mfma_f32_16x16x32_bf16 v[88:91], v[184:187], v[226:229], v[88:91]
	v_mfma_f32_16x16x32_bf16 v[76:79], v[172:175], v[234:237], v[76:79]
	v_mfma_f32_16x16x32_bf16 v[72:75], v[184:187], v[234:237], v[72:75]
	s_setprio 0
	s_setprio 1
	v_mfma_f32_16x16x32_bf16 v[116:119], v[188:191], v[204:207], 0
	v_mfma_f32_16x16x32_bf16 v[112:115], v[196:199], v[204:207], 0
	v_mfma_f32_16x16x32_bf16 v[100:103], v[188:191], v[212:215], 0
	v_mfma_f32_16x16x32_bf16 v[96:99], v[196:199], v[212:215], 0
	v_mfma_f32_16x16x32_bf16 v[84:87], v[188:191], v[222:225], 0
	v_mfma_f32_16x16x32_bf16 v[80:83], v[196:199], v[222:225], 0
	v_mfma_f32_16x16x32_bf16 v[68:71], v[188:191], v[230:233], 0
	v_mfma_f32_16x16x32_bf16 v[64:67], v[196:199], v[230:233], 0
	v_mfma_f32_16x16x32_bf16 v[116:119], v[192:195], v[208:211], v[116:119]
	v_mfma_f32_16x16x32_bf16 v[112:115], v[200:203], v[208:211], v[112:115]
	v_mfma_f32_16x16x32_bf16 v[100:103], v[192:195], v[216:219], v[100:103]
	v_mfma_f32_16x16x32_bf16 v[96:99], v[200:203], v[216:219], v[96:99]
	v_mfma_f32_16x16x32_bf16 v[84:87], v[192:195], v[226:229], v[84:87]
	v_mfma_f32_16x16x32_bf16 v[80:83], v[200:203], v[226:229], v[80:83]
	v_mfma_f32_16x16x32_bf16 v[68:71], v[192:195], v[234:237], v[68:71]
	v_mfma_f32_16x16x32_bf16 v[64:67], v[200:203], v[234:237], v[64:67]
	s_setprio 0
	s_barrier
	s_add_i32 s68, s64, s55
	v_lshl_add_u64 v[144:145], s[34:35], 0, v[130:131]
	s_mov_b32 m0, s68
	ds_read_b128 v[204:207], v158 offset:16384
	ds_read_b128 v[208:211], v158 offset:17408
	ds_read_b128 v[212:215], v158 offset:18432
	ds_read_b128 v[216:219], v158 offset:19456
	ds_read_b128 v[222:225], v158 offset:20480
	ds_read_b128 v[226:229], v158 offset:21504
	ds_read_b128 v[230:233], v158 offset:22528
	ds_read_b128 v[234:237], v158 offset:23552
	global_load_lds_dwordx4 v[144:145], off
	s_add_i32 m0, s68, 0x2000
	s_add_u32 s76, s34, 0x40000
	v_lshl_add_u64 v[176:177], s[34:35], 0, v[134:135]
	s_addc_u32 s77, s35, 0
	s_add_i32 s68, s65, s55
	global_load_lds_dwordx4 v[176:177], off
	v_lshl_add_u64 v[238:239], s[76:77], 0, v[130:131]
	s_mov_b32 m0, s68
	v_lshl_add_u64 v[240:241], s[36:37], 0, v[132:133]
	global_load_lds_dwordx4 v[238:239], off
	v_lshl_add_u64 v[238:239], s[76:77], 0, v[134:135]
	s_add_i32 m0, s68, 0x2000
	s_nop 0
	global_load_lds_dwordx4 v[238:239], off
	v_lshl_add_u64 v[238:239], s[36:37], 0, v[128:129]
	s_mov_b32 m0, s56
	s_nop 0
	global_load_lds_dwordx4 v[238:239], off
	s_mov_b32 m0, s57
	s_nop 0
	global_load_lds_dwordx4 v[240:241], off
	s_waitcnt vmcnt(8)
	s_waitcnt lgkmcnt(0)
	s_barrier
; #define PG8_STAGE(bufoff, gbase, voff) do { _Pragma("unroll") for (int _i = 0; _i < 2; ++_i) \
;         __builtin_amdgcn_global_load_lds((const unsigned*)((const char*)(gbase) + (voff)[_i]), (PG8_LAS unsigned*)(lds + (bufoff) + ldsw + _i * 8192), 16, 0, 0); } while (0)
; #define PG8_LDA(dst, b, h) do { _Pragma("unroll") for (int m = 0; m < 4; ++m) _Pragma("unroll") for (int k = 0; k < 2; ++k) dst[m][k] = *(const PG8_LAS bf16x8*)(lds + PG8_SA(b, h) + aoff + m * 2048 + k * 1024); } while (0)
; #define PG8_LDB(dst, b, h) do { _Pragma("unroll") for (int n = 0; n < 2; ++n) _Pragma("unroll") for (int k = 0; k < 2; ++k) dst[n][k] = *(const PG8_LAS bf16x8*)(lds + PG8_SB(b, h) + boff + n * 2048 + k * 1024); } while (0)
; #define PG8_MMA(ai, bj, At, Bt) do { __builtin_amdgcn_s_setprio(1); _Pragma("unroll") for (int m = 0; m < 4; ++m) _Pragma("unroll") for (int n = 0; n < 2; ++n) _Pragma("unroll") for (int k = 0; k < 2; ++k) \
;         acc[ai][bj][m][n] = __builtin_amdgcn_mfma_f32_16x16x32_bf16(Bt[n][k], At[m][k], acc[ai][bj][m][n], 0, 0, 0); __builtin_amdgcn_s_setprio(0); } while (0)
; #define PG8_WAIT_V(n) asm volatile("s_waitcnt vmcnt(" #n ")" ::: "memory")
; #define PG8_WAIT_L(n) asm volatile("s_waitcnt lgkmcnt(" #n ")" ::: "memory")
; #define PG8_BAR __builtin_amdgcn_s_barrier()
; #define PG8_SCHED __builtin_amdgcn_sched_barrier(0)
; template <class Epi, class Sched>
; __device__ __forceinline__ void gemm_phase(PG8_LAS unsigned char* lds, PG8_LAS unsigned char* xl, const Gemm g, const Sched& S, const Epi& E) {
;     ...
;             PG8_WAIT_V(8); PG8_WAIT_L(0); PG8_BAR; PG8_MMA(1, 0, At, B0); PG8_MMA(1, 1, At, B1); PG8_BAR; PG8_SCHED;
;             PG8_LDB(B0, 1, 0); PG8_LDB(B1, 1, 1); PG8_SCHED; PG8_LDA(At, 1, 0); PG8_STAGE(PG8_SA(0, 1), a2 + hsA, voffA);
;             PG8_WAIT_V(8); PG8_WAIT_L(0); PG8_BAR; PG8_MMA(0, 0, At, B0); PG8_MMA(0, 1, At, B1); PG8_BAR; PG8_SCHED;
	s_setprio 1
	s_waitcnt lgkmcnt(0)
	v_mfma_f32_16x16x32_bf16 v[60:63], v[168:171], v[204:207], 0
	v_mfma_f32_16x16x32_bf16 v[56:59], v[180:183], v[204:207], 0
	v_mfma_f32_16x16x32_bf16 v[44:47], v[168:171], v[212:215], 0
	v_mfma_f32_16x16x32_bf16 v[40:43], v[180:183], v[212:215], 0
	v_mfma_f32_16x16x32_bf16 v[28:31], v[168:171], v[222:225], 0
	v_mfma_f32_16x16x32_bf16 v[24:27], v[180:183], v[222:225], 0
	v_mfma_f32_16x16x32_bf16 v[12:15], v[168:171], v[230:233], 0
	v_mfma_f32_16x16x32_bf16 v[8:11], v[180:183], v[230:233], 0
	v_mfma_f32_16x16x32_bf16 v[60:63], v[172:175], v[208:211], v[60:63]
	v_mfma_f32_16x16x32_bf16 v[56:59], v[184:187], v[208:211], v[56:59]
	v_mfma_f32_16x16x32_bf16 v[44:47], v[172:175], v[216:219], v[44:47]
	v_mfma_f32_16x16x32_bf16 v[40:43], v[184:187], v[216:219], v[40:43]
	v_mfma_f32_16x16x32_bf16 v[28:31], v[172:175], v[226:229], v[28:31]
	v_mfma_f32_16x16x32_bf16 v[24:27], v[184:187], v[226:229], v[24:27]
	v_mfma_f32_16x16x32_bf16 v[12:15], v[172:175], v[234:237], v[12:15]
	v_mfma_f32_16x16x32_bf16 v[8:11], v[184:187], v[234:237], v[8:11]
	s_setprio 0
	s_setprio 1
	v_mfma_f32_16x16x32_bf16 v[52:55], v[188:191], v[204:207], 0
	v_mfma_f32_16x16x32_bf16 v[48:51], v[196:199], v[204:207], 0
	v_mfma_f32_16x16x32_bf16 v[36:39], v[188:191], v[212:215], 0
	v_mfma_f32_16x16x32_bf16 v[32:35], v[196:199], v[212:215], 0
	v_mfma_f32_16x16x32_bf16 v[20:23], v[188:191], v[222:225], 0
	v_mfma_f32_16x16x32_bf16 v[16:19], v[196:199], v[222:225], 0
	v_mfma_f32_16x16x32_bf16 v[4:7], v[188:191], v[230:233], 0
	v_mfma_f32_16x16x32_bf16 v[0:3], v[196:199], v[230:233], 0
	v_mfma_f32_16x16x32_bf16 v[52:55], v[192:195], v[208:211], v[52:55]
	v_mfma_f32_16x16x32_bf16 v[48:51], v[200:203], v[208:211], v[48:51]
	v_mfma_f32_16x16x32_bf16 v[36:39], v[192:195], v[216:219], v[36:39]
	v_mfma_f32_16x16x32_bf16 v[32:35], v[200:203], v[216:219], v[32:35]
	v_mfma_f32_16x16x32_bf16 v[20:23], v[192:195], v[226:229], v[20:23]
	v_mfma_f32_16x16x32_bf16 v[16:19], v[200:203], v[226:229], v[16:19]
	v_mfma_f32_16x16x32_bf16 v[4:7], v[192:195], v[234:237], v[4:7]
	v_mfma_f32_16x16x32_bf16 v[0:3], v[200:203], v[234:237], v[0:3]
	s_setprio 0
	s_barrier
	s_add_i32 s68, 0, 0x18000
	v_add_u32_e32 v179, s68, v147
	s_add_i32 s75, 0, 0x1c000
	ds_read_b128 v[168:171], v179
	ds_read_b128 v[172:175], v179 offset:1024
	ds_read_b128 v[180:183], v179 offset:2048
	ds_read_b128 v[184:187], v179 offset:3072
	v_add_u32_e32 v179, s75, v147
	ds_read_b128 v[188:191], v179
	ds_read_b128 v[192:195], v179 offset:1024
	ds_read_b128 v[196:199], v179 offset:2048
	ds_read_b128 v[200:203], v179 offset:3072
	s_add_u32 s36, s36, 0x40000
	s_addc_u32 s37, s37, 0
	s_mov_b32 m0, s58
	v_lshl_add_u64 v[242:243], s[36:37], 0, v[128:129]
	ds_read_b128 v[204:207], v158 offset:32768
	ds_read_b128 v[208:211], v158 offset:33792
	ds_read_b128 v[212:215], v158 offset:34816
	ds_read_b128 v[216:219], v158 offset:35840
	ds_read_b128 v[222:225], v158 offset:36864
	ds_read_b128 v[226:229], v158 offset:37888
	ds_read_b128 v[230:233], v158 offset:38912
	ds_read_b128 v[234:237], v158 offset:39936
	global_load_lds_dwordx4 v[242:243], off
	v_lshl_add_u64 v[242:243], s[36:37], 0, v[132:133]
	s_mov_b32 m0, s59
	s_nop 0
	global_load_lds_dwordx4 v[242:243], off
	s_waitcnt vmcnt(8)
	s_waitcnt lgkmcnt(0)
	s_barrier
	s_setprio 1
	s_waitcnt lgkmcnt(0)
	v_mfma_f32_16x16x32_bf16 v[124:127], v[168:171], v[204:207], v[124:127]
	v_mfma_f32_16x16x32_bf16 v[120:123], v[180:183], v[204:207], v[120:123]
	v_mfma_f32_16x16x32_bf16 v[108:111], v[168:171], v[212:215], v[108:111]
	v_mfma_f32_16x16x32_bf16 v[104:107], v[180:183], v[212:215], v[104:107]
	v_mfma_f32_16x16x32_bf16 v[92:95], v[168:171], v[222:225], v[92:95]
	v_mfma_f32_16x16x32_bf16 v[88:91], v[180:183], v[222:225], v[88:91]
	v_mfma_f32_16x16x32_bf16 v[76:79], v[168:171], v[230:233], v[76:79]
	v_mfma_f32_16x16x32_bf16 v[72:75], v[180:183], v[230:233], v[72:75]
	v_mfma_f32_16x16x32_bf16 v[124:127], v[172:175], v[208:211], v[124:127]
	v_mfma_f32_16x16x32_bf16 v[120:123], v[184:187], v[208:211], v[120:123]
	v_mfma_f32_16x16x32_bf16 v[108:111], v[172:175], v[216:219], v[108:111]
	v_mfma_f32_16x16x32_bf16 v[104:107], v[184:187], v[216:219], v[104:107]
	v_mfma_f32_16x16x32_bf16 v[92:95], v[172:175], v[226:229], v[92:95]
	v_mfma_f32_16x16x32_bf16 v[88:91], v[184:187], v[226:229], v[88:91]
	v_mfma_f32_16x16x32_bf16 v[76:79], v[172:175], v[234:237], v[76:79]
	v_mfma_f32_16x16x32_bf16 v[72:75], v[184:187], v[234:237], v[72:75]
	s_setprio 0
	s_setprio 1
	v_mfma_f32_16x16x32_bf16 v[116:119], v[188:191], v[204:207], v[116:119]
	v_mfma_f32_16x16x32_bf16 v[112:115], v[196:199], v[204:207], v[112:115]
	v_mfma_f32_16x16x32_bf16 v[100:103], v[188:191], v[212:215], v[100:103]
	v_mfma_f32_16x16x32_bf16 v[96:99], v[196:199], v[212:215], v[96:99]
	v_mfma_f32_16x16x32_bf16 v[84:87], v[188:191], v[222:225], v[84:87]
	v_mfma_f32_16x16x32_bf16 v[80:83], v[196:199], v[222:225], v[80:83]
	v_mfma_f32_16x16x32_bf16 v[68:71], v[188:191], v[230:233], v[68:71]
	v_mfma_f32_16x16x32_bf16 v[64:67], v[196:199], v[230:233], v[64:67]
	v_mfma_f32_16x16x32_bf16 v[116:119], v[192:195], v[208:211], v[116:119]
	v_mfma_f32_16x16x32_bf16 v[112:115], v[200:203], v[208:211], v[112:115]
	v_mfma_f32_16x16x32_bf16 v[100:103], v[192:195], v[216:219], v[100:103]
	v_mfma_f32_16x16x32_bf16 v[96:99], v[200:203], v[216:219], v[96:99]
	v_mfma_f32_16x16x32_bf16 v[84:87], v[192:195], v[226:229], v[84:87]
	v_mfma_f32_16x16x32_bf16 v[80:83], v[200:203], v[226:229], v[80:83]
	v_mfma_f32_16x16x32_bf16 v[68:71], v[192:195], v[234:237], v[68:71]
	v_mfma_f32_16x16x32_bf16 v[64:67], v[200:203], v[234:237], v[64:67]
	s_setprio 0
	s_barrier
; #define PG8_STAGE(bufoff, gbase, voff) do { _Pragma("unroll") for (int _i = 0; _i < 2; ++_i) \
;         __builtin_amdgcn_global_load_lds((const unsigned*)((const char*)(gbase) + (voff)[_i]), (PG8_LAS unsigned*)(lds + (bufoff) + ldsw + _i * 8192), 16, 0, 0); } while (0)
; #define PG8_LDA(dst, b, h) do { _Pragma("unroll") for (int m = 0; m < 4; ++m) _Pragma("unroll") for (int k = 0; k < 2; ++k) dst[m][k] = *(const PG8_LAS bf16x8*)(lds + PG8_SA(b, h) + aoff + m * 2048 + k * 1024); } while (0)
; #define PG8_LDB(dst, b, h) do { _Pragma("unroll") for (int n = 0; n < 2; ++n) _Pragma("unroll") for (int k = 0; k < 2; ++k) dst[n][k] = *(const PG8_LAS bf16x8*)(lds + PG8_SB(b, h) + boff + n * 2048 + k * 1024); } while (0)
; #define PG8_MMA(ai, bj, At, Bt) do { __builtin_amdgcn_s_setprio(1); _Pragma("unroll") for (int m = 0; m < 4; ++m) _Pragma("unroll") for (int n = 0; n < 2; ++n) _Pragma("unroll") for (int k = 0; k < 2; ++k) \
;         acc[ai][bj][m][n] = __builtin_amdgcn_mfma_f32_16x16x32_bf16(Bt[n][k], At[m][k], acc[ai][bj][m][n], 0, 0, 0); __builtin_amdgcn_s_setprio(0); } while (0)
; #define PG8_WAIT_V(n) asm volatile("s_waitcnt vmcnt(" #n ")" ::: "memory")
; #define PG8_WAIT_L(n) asm volatile("s_waitcnt lgkmcnt(" #n ")" ::: "memory")
; #define PG8_BAR __builtin_amdgcn_s_barrier()
; #define PG8_SCHED __builtin_amdgcn_sched_barrier(0)
; template <class Epi, class Sched>
; __device__ __forceinline__ void gemm_phase(PG8_LAS unsigned char* lds, PG8_LAS unsigned char* xl, const Gemm g, const Sched& S, const Epi& E) {
;     ...
;         for (int t = 0; t < nt; t += 2) {
;             const bool last = (t == nt - 2);
;             const char* a1 = cA + (size_t)(t + 1) * kstep;
;             const char* a2 = last ? nA : cA + (size_t)(t + 2) * kstep; const char* b2 = last ? nB : cB + (size_t)(t + 2) * kstep;
;             const char* a3 = a2 + kstep; const char* b3 = b2 + kstep;
;             PG8_LDB(B0, 0, 0); PG8_LDB(B1, 0, 1); PG8_SCHED; PG8_LDA(At, 0, 0); PG8_STAGE(PG8_SA(1, 1), a1 + hsA, voffA);
;     ...
;             PG8_LDA(At, 1, 1); PG8_STAGE(PG8_SB(1, 0), b3, voffB); PG8_STAGE(PG8_SB(1, 1), b3 + hsB, voffB); PG8_STAGE(PG8_SA(1, 0), a3, voffA);
;             PG8_WAIT_V(8); PG8_WAIT_L(0); PG8_BAR; PG8_MMA(1, 0, At, B0); PG8_MMA(1, 1, At, B1); PG8_BAR; PG8_SCHED;
	s_add_i32 s36, s68, s55
	v_lshl_add_u64 v[144:145], v[144:145], 0, s[16:17]
	s_mov_b32 m0, s36
	ds_read_b128 v[204:207], v158 offset:49152
	ds_read_b128 v[208:211], v158 offset:50176
	ds_read_b128 v[212:215], v158 offset:51200
	ds_read_b128 v[216:219], v158 offset:52224
	ds_read_b128 v[222:225], v158 offset:53248
	ds_read_b128 v[226:229], v158 offset:54272
	ds_read_b128 v[230:233], v158 offset:55296
	ds_read_b128 v[234:237], v158 offset:56320
	global_load_lds_dwordx4 v[144:145], off
	s_add_i32 m0, s36, 0x2000
	s_add_u32 s34, s34, 0x40080
	v_lshl_add_u64 v[144:145], v[176:177], 0, s[16:17]
	s_addc_u32 s35, s35, 0
	s_add_i32 s36, s75, s55
	global_load_lds_dwordx4 v[144:145], off
	v_lshl_add_u64 v[144:145], s[34:35], 0, v[130:131]
	s_mov_b32 m0, s36
	s_nop 0
	global_load_lds_dwordx4 v[144:145], off
	v_lshl_add_u64 v[144:145], s[34:35], 0, v[134:135]
	s_add_i32 m0, s36, 0x2000
	s_nop 0
	global_load_lds_dwordx4 v[144:145], off
	v_lshl_add_u64 v[144:145], v[238:239], 0, s[16:17]
	s_mov_b32 m0, s61
	s_nop 0
	global_load_lds_dwordx4 v[144:145], off
	v_lshl_add_u64 v[144:145], v[240:241], 0, s[16:17]
	s_mov_b32 m0, s62
	s_nop 0
	global_load_lds_dwordx4 v[144:145], off
	s_waitcnt vmcnt(8)
	s_waitcnt lgkmcnt(0)
	s_barrier
	s_setprio 1
	s_waitcnt lgkmcnt(0)
	v_mfma_f32_16x16x32_bf16 v[60:63], v[168:171], v[204:207], v[60:63]
	v_mfma_f32_16x16x32_bf16 v[56:59], v[180:183], v[204:207], v[56:59]
	v_mfma_f32_16x16x32_bf16 v[44:47], v[168:171], v[212:215], v[44:47]
	v_mfma_f32_16x16x32_bf16 v[40:43], v[180:183], v[212:215], v[40:43]
	v_mfma_f32_16x16x32_bf16 v[28:31], v[168:171], v[222:225], v[28:31]
	v_mfma_f32_16x16x32_bf16 v[24:27], v[180:183], v[222:225], v[24:27]
	v_mfma_f32_16x16x32_bf16 v[12:15], v[168:171], v[230:233], v[12:15]
	v_mfma_f32_16x16x32_bf16 v[8:11], v[180:183], v[230:233], v[8:11]
	v_mfma_f32_16x16x32_bf16 v[60:63], v[172:175], v[208:211], v[60:63]
	v_mfma_f32_16x16x32_bf16 v[56:59], v[184:187], v[208:211], v[56:59]
	v_mfma_f32_16x16x32_bf16 v[44:47], v[172:175], v[216:219], v[44:47]
	v_mfma_f32_16x16x32_bf16 v[40:43], v[184:187], v[216:219], v[40:43]
	v_mfma_f32_16x16x32_bf16 v[28:31], v[172:175], v[226:229], v[28:31]
	v_mfma_f32_16x16x32_bf16 v[24:27], v[184:187], v[226:229], v[24:27]
	v_mfma_f32_16x16x32_bf16 v[12:15], v[172:175], v[234:237], v[12:15]
	v_mfma_f32_16x16x32_bf16 v[8:11], v[184:187], v[234:237], v[8:11]
	s_setprio 0
	s_setprio 1
	v_mfma_f32_16x16x32_bf16 v[52:55], v[188:191], v[204:207], v[52:55]
	s_add_i32 s74, s74, 2
	v_mfma_f32_16x16x32_bf16 v[48:51], v[196:199], v[204:207], v[48:51]
	s_add_u32 s72, s72, 0x100
	v_mfma_f32_16x16x32_bf16 v[36:39], v[188:191], v[212:215], v[36:39]
	s_addc_u32 s73, s73, 0
	v_mfma_f32_16x16x32_bf16 v[32:35], v[196:199], v[212:215], v[32:35]
	s_add_u32 s30, s30, 0x100
	v_mfma_f32_16x16x32_bf16 v[20:23], v[188:191], v[222:225], v[20:23]
	s_addc_u32 s31, s31, 0
	v_mfma_f32_16x16x32_bf16 v[16:19], v[196:199], v[222:225], v[16:19]
	s_cmp_gt_u32 s74, 13
	v_mfma_f32_16x16x32_bf16 v[4:7], v[188:191], v[230:233], v[4:7]
	v_mfma_f32_16x16x32_bf16 v[0:3], v[196:199], v[230:233], v[0:3]
	v_mfma_f32_16x16x32_bf16 v[52:55], v[192:195], v[208:211], v[52:55]
	v_mfma_f32_16x16x32_bf16 v[48:51], v[200:203], v[208:211], v[48:51]
	v_mfma_f32_16x16x32_bf16 v[36:39], v[192:195], v[216:219], v[36:39]
	v_mfma_f32_16x16x32_bf16 v[32:35], v[200:203], v[216:219], v[32:35]
	v_mfma_f32_16x16x32_bf16 v[20:23], v[192:195], v[226:229], v[20:23]
	v_mfma_f32_16x16x32_bf16 v[16:19], v[200:203], v[226:229], v[16:19]
	v_mfma_f32_16x16x32_bf16 v[4:7], v[192:195], v[234:237], v[4:7]
	v_mfma_f32_16x16x32_bf16 v[0:3], v[200:203], v[234:237], v[0:3]
	s_setprio 0
	s_barrier
	s_cbranch_scc1 .Lpeel_after_P3
.LBB0_471:
	ds_read_b128 v[168:171], v156
	ds_read_b128 v[172:175], v156 offset:1024
	ds_read_b128 v[180:183], v156 offset:2048
	ds_read_b128 v[184:187], v156 offset:3072
	ds_read_b128 v[188:191], v157
	ds_read_b128 v[192:195], v157 offset:1024
	ds_read_b128 v[196:199], v157 offset:2048
	ds_read_b128 v[200:203], v157 offset:3072
	s_add_u32 s34, s30, 0xfffc0080
	s_addc_u32 s35, s31, -1
	s_cmp_eq_u32 s74, 12
	s_cselect_b32 s37, s33, s35
	s_cselect_b32 s36, s46, s34
	s_cselect_b32 s35, s47, s73
	s_cselect_b32 s34, s70, s72
	v_lshl_add_u64 v[144:145], s[30:31], 0, v[138:139]
	s_add_i32 m0, s56, 0xc000
	ds_read_b128 v[204:207], v158
	ds_read_b128 v[208:211], v158 offset:1024
	ds_read_b128 v[212:215], v158 offset:2048
	ds_read_b128 v[216:219], v158 offset:3072
	ds_read_b128 v[222:225], v158 offset:4096
	ds_read_b128 v[226:229], v158 offset:5120
	ds_read_b128 v[230:233], v158 offset:6144
	ds_read_b128 v[234:237], v158 offset:7168
	global_load_lds_dwordx4 v[144:145], off
	v_lshl_add_u64 v[144:145], s[30:31], 0, v[136:137]
	s_add_i32 m0, s56, 0xe000
	s_nop 0
	global_load_lds_dwordx4 v[144:145], off
	s_waitcnt vmcnt(8)
	s_waitcnt lgkmcnt(0)
	s_barrier
; #define PG8_STAGE(bufoff, gbase, voff) do { _Pragma("unroll") for (int _i = 0; _i < 2; ++_i) \
;         __builtin_amdgcn_global_load_lds((const unsigned*)((const char*)(gbase) + (voff)[_i]), (PG8_LAS unsigned*)(lds + (bufoff) + ldsw + _i * 8192), 16, 0, 0); } while (0)
; #define PG8_LDA(dst, b, h) do { _Pragma("unroll") for (int m = 0; m < 4; ++m) _Pragma("unroll") for (int k = 0; k < 2; ++k) dst[m][k] = *(const PG8_LAS bf16x8*)(lds + PG8_SA(b, h) + aoff + m * 2048 + k * 1024); } while (0)
; #define PG8_MMA(ai, bj, At, Bt) do { __builtin_amdgcn_s_setprio(1); _Pragma("unroll") for (int m = 0; m < 4; ++m) _Pragma("unroll") for (int n = 0; n < 2; ++n) _Pragma("unroll") for (int k = 0; k < 2; ++k) \
;         acc[ai][bj][m][n] = __builtin_amdgcn_mfma_f32_16x16x32_bf16(Bt[n][k], At[m][k], acc[ai][bj][m][n], 0, 0, 0); __builtin_amdgcn_s_setprio(0); } while (0)
; #define PG8_WAIT_V(n) asm volatile("s_waitcnt vmcnt(" #n ")" ::: "memory")
; #define PG8_WAIT_L(n) asm volatile("s_waitcnt lgkmcnt(" #n ")" ::: "memory")
; #define PG8_BAR __builtin_amdgcn_s_barrier()
; #define PG8_SCHED __builtin_amdgcn_sched_barrier(0)
; template <class Epi, class Sched>
; __device__ __forceinline__ void gemm_phase(PG8_LAS unsigned char* lds, PG8_LAS unsigned char* xl, const Gemm g, const Sched& S, const Epi& E) {
;     ...
;             PG8_WAIT_V(8); PG8_WAIT_L(0); PG8_BAR; PG8_MMA(0, 0, At, B0); PG8_MMA(0, 1, At, B1); PG8_BAR; PG8_SCHED;
;             PG8_LDA(At, 0, 1); PG8_STAGE(PG8_SB(0, 0), b2, voffB); PG8_STAGE(PG8_SB(0, 1), b2 + hsB, voffB); PG8_STAGE(PG8_SA(0, 0), a2, voffA);
;             PG8_WAIT_V(8); PG8_WAIT_L(0); PG8_BAR; PG8_MMA(1, 0, At, B0); PG8_MMA(1, 1, At, B1); PG8_BAR; PG8_SCHED;
	s_setprio 1
	s_waitcnt lgkmcnt(0)
	v_mfma_f32_16x16x32_bf16 v[124:127], v[168:171], v[204:207], v[124:127]
	v_mfma_f32_16x16x32_bf16 v[120:123], v[180:183], v[204:207], v[120:123]
	v_mfma_f32_16x16x32_bf16 v[108:111], v[168:171], v[212:215], v[108:111]
	v_mfma_f32_16x16x32_bf16 v[104:107], v[180:183], v[212:215], v[104:107]
	v_mfma_f32_16x16x32_bf16 v[92:95], v[168:171], v[222:225], v[92:95]
	v_mfma_f32_16x16x32_bf16 v[88:91], v[180:183], v[222:225], v[88:91]
	v_mfma_f32_16x16x32_bf16 v[76:79], v[168:171], v[230:233], v[76:79]
	v_mfma_f32_16x16x32_bf16 v[72:75], v[180:183], v[230:233], v[72:75]
	v_mfma_f32_16x16x32_bf16 v[124:127], v[172:175], v[208:211], v[124:127]
	v_mfma_f32_16x16x32_bf16 v[120:123], v[184:187], v[208:211], v[120:123]
	v_mfma_f32_16x16x32_bf16 v[108:111], v[172:175], v[216:219], v[108:111]
	v_mfma_f32_16x16x32_bf16 v[104:107], v[184:187], v[216:219], v[104:107]
	v_mfma_f32_16x16x32_bf16 v[92:95], v[172:175], v[226:229], v[92:95]
	v_mfma_f32_16x16x32_bf16 v[88:91], v[184:187], v[226:229], v[88:91]
	v_mfma_f32_16x16x32_bf16 v[76:79], v[172:175], v[234:237], v[76:79]
	v_mfma_f32_16x16x32_bf16 v[72:75], v[184:187], v[234:237], v[72:75]
	s_setprio 0
	s_setprio 1
	v_mfma_f32_16x16x32_bf16 v[116:119], v[188:191], v[204:207], v[116:119]
	v_mfma_f32_16x16x32_bf16 v[112:115], v[196:199], v[204:207], v[112:115]
	v_mfma_f32_16x16x32_bf16 v[100:103], v[188:191], v[212:215], v[100:103]
	v_mfma_f32_16x16x32_bf16 v[96:99], v[196:199], v[212:215], v[96:99]
	v_mfma_f32_16x16x32_bf16 v[84:87], v[188:191], v[222:225], v[84:87]
	v_mfma_f32_16x16x32_bf16 v[80:83], v[196:199], v[222:225], v[80:83]
	v_mfma_f32_16x16x32_bf16 v[68:71], v[188:191], v[230:233], v[68:71]
	v_mfma_f32_16x16x32_bf16 v[64:67], v[196:199], v[230:233], v[64:67]
	v_mfma_f32_16x16x32_bf16 v[116:119], v[192:195], v[208:211], v[116:119]
	v_mfma_f32_16x16x32_bf16 v[112:115], v[200:203], v[208:211], v[112:115]
	v_mfma_f32_16x16x32_bf16 v[100:103], v[192:195], v[216:219], v[100:103]
	v_mfma_f32_16x16x32_bf16 v[96:99], v[200:203], v[216:219], v[96:99]
	v_mfma_f32_16x16x32_bf16 v[84:87], v[192:195], v[226:229], v[84:87]
	v_mfma_f32_16x16x32_bf16 v[80:83], v[200:203], v[226:229], v[80:83]
	v_mfma_f32_16x16x32_bf16 v[68:71], v[192:195], v[234:237], v[68:71]
	v_mfma_f32_16x16x32_bf16 v[64:67], v[200:203], v[234:237], v[64:67]
	s_setprio 0
	s_barrier
	s_add_i32 s68, s64, s55
	v_lshl_add_u64 v[144:145], s[34:35], 0, v[130:131]
	s_mov_b32 m0, s68
	ds_read_b128 v[204:207], v158 offset:16384
	ds_read_b128 v[208:211], v158 offset:17408
	ds_read_b128 v[212:215], v158 offset:18432
	ds_read_b128 v[216:219], v158 offset:19456
	ds_read_b128 v[222:225], v158 offset:20480
	ds_read_b128 v[226:229], v158 offset:21504
	ds_read_b128 v[230:233], v158 offset:22528
	ds_read_b128 v[234:237], v158 offset:23552
	global_load_lds_dwordx4 v[144:145], off
	s_add_i32 m0, s68, 0x2000
	s_add_u32 s76, s34, 0x40000
	v_lshl_add_u64 v[176:177], s[34:35], 0, v[134:135]
	s_addc_u32 s77, s35, 0
	s_add_i32 s68, s65, s55
	global_load_lds_dwordx4 v[176:177], off
	v_lshl_add_u64 v[238:239], s[76:77], 0, v[130:131]
	s_mov_b32 m0, s68
	v_lshl_add_u64 v[240:241], s[36:37], 0, v[132:133]
	global_load_lds_dwordx4 v[238:239], off
	v_lshl_add_u64 v[238:239], s[76:77], 0, v[134:135]
	s_add_i32 m0, s68, 0x2000
	s_nop 0
	global_load_lds_dwordx4 v[238:239], off
	v_lshl_add_u64 v[238:239], s[36:37], 0, v[128:129]
	s_mov_b32 m0, s56
	s_nop 0
	global_load_lds_dwordx4 v[238:239], off
	s_mov_b32 m0, s57
	s_nop 0
	global_load_lds_dwordx4 v[240:241], off
	s_waitcnt vmcnt(8)
	s_waitcnt lgkmcnt(0)
	s_barrier
	s_setprio 1
	s_waitcnt lgkmcnt(0)
	v_mfma_f32_16x16x32_bf16 v[60:63], v[168:171], v[204:207], v[60:63]
	v_mfma_f32_16x16x32_bf16 v[56:59], v[180:183], v[204:207], v[56:59]
	v_mfma_f32_16x16x32_bf16 v[44:47], v[168:171], v[212:215], v[44:47]
	v_mfma_f32_16x16x32_bf16 v[40:43], v[180:183], v[212:215], v[40:43]
	v_mfma_f32_16x16x32_bf16 v[28:31], v[168:171], v[222:225], v[28:31]
	v_mfma_f32_16x16x32_bf16 v[24:27], v[180:183], v[222:225], v[24:27]
	v_mfma_f32_16x16x32_bf16 v[12:15], v[168:171], v[230:233], v[12:15]
	v_mfma_f32_16x16x32_bf16 v[8:11], v[180:183], v[230:233], v[8:11]
	v_mfma_f32_16x16x32_bf16 v[60:63], v[172:175], v[208:211], v[60:63]
	v_mfma_f32_16x16x32_bf16 v[56:59], v[184:187], v[208:211], v[56:59]
	v_mfma_f32_16x16x32_bf16 v[44:47], v[172:175], v[216:219], v[44:47]
	v_mfma_f32_16x16x32_bf16 v[40:43], v[184:187], v[216:219], v[40:43]
	v_mfma_f32_16x16x32_bf16 v[28:31], v[172:175], v[226:229], v[28:31]
	v_mfma_f32_16x16x32_bf16 v[24:27], v[184:187], v[226:229], v[24:27]
	v_mfma_f32_16x16x32_bf16 v[12:15], v[172:175], v[234:237], v[12:15]
	v_mfma_f32_16x16x32_bf16 v[8:11], v[184:187], v[234:237], v[8:11]
	s_setprio 0
	s_setprio 1
	v_mfma_f32_16x16x32_bf16 v[52:55], v[188:191], v[204:207], v[52:55]
	v_mfma_f32_16x16x32_bf16 v[48:51], v[196:199], v[204:207], v[48:51]
	v_mfma_f32_16x16x32_bf16 v[36:39], v[188:191], v[212:215], v[36:39]
	v_mfma_f32_16x16x32_bf16 v[32:35], v[196:199], v[212:215], v[32:35]
	v_mfma_f32_16x16x32_bf16 v[20:23], v[188:191], v[222:225], v[20:23]
	v_mfma_f32_16x16x32_bf16 v[16:19], v[196:199], v[222:225], v[16:19]
	v_mfma_f32_16x16x32_bf16 v[4:7], v[188:191], v[230:233], v[4:7]
	v_mfma_f32_16x16x32_bf16 v[0:3], v[196:199], v[230:233], v[0:3]
	v_mfma_f32_16x16x32_bf16 v[52:55], v[192:195], v[208:211], v[52:55]
	v_mfma_f32_16x16x32_bf16 v[48:51], v[200:203], v[208:211], v[48:51]
	v_mfma_f32_16x16x32_bf16 v[36:39], v[192:195], v[216:219], v[36:39]
	v_mfma_f32_16x16x32_bf16 v[32:35], v[200:203], v[216:219], v[32:35]
	v_mfma_f32_16x16x32_bf16 v[20:23], v[192:195], v[226:229], v[20:23]
	v_mfma_f32_16x16x32_bf16 v[16:19], v[200:203], v[226:229], v[16:19]
	v_mfma_f32_16x16x32_bf16 v[4:7], v[192:195], v[234:237], v[4:7]
	v_mfma_f32_16x16x32_bf16 v[0:3], v[200:203], v[234:237], v[0:3]
	s_setprio 0
	s_barrier
; #define PG8_STAGE(bufoff, gbase, voff) do { _Pragma("unroll") for (int _i = 0; _i < 2; ++_i) \
;         __builtin_amdgcn_global_load_lds((const unsigned*)((const char*)(gbase) + (voff)[_i]), (PG8_LAS unsigned*)(lds + (bufoff) + ldsw + _i * 8192), 16, 0, 0); } while (0)
; #define PG8_LDA(dst, b, h) do { _Pragma("unroll") for (int m = 0; m < 4; ++m) _Pragma("unroll") for (int k = 0; k < 2; ++k) dst[m][k] = *(const PG8_LAS bf16x8*)(lds + PG8_SA(b, h) + aoff + m * 2048 + k * 1024); } while (0)
; #define PG8_LDB(dst, b, h) do { _Pragma("unroll") for (int n = 0; n < 2; ++n) _Pragma("unroll") for (int k = 0; k < 2; ++k) dst[n][k] = *(const PG8_LAS bf16x8*)(lds + PG8_SB(b, h) + boff + n * 2048 + k * 1024); } while (0)
; #define PG8_MMA(ai, bj, At, Bt) do { __builtin_amdgcn_s_setprio(1); _Pragma("unroll") for (int m = 0; m < 4; ++m) _Pragma("unroll") for (int n = 0; n < 2; ++n) _Pragma("unroll") for (int k = 0; k < 2; ++k) \
;         acc[ai][bj][m][n] = __builtin_amdgcn_mfma_f32_16x16x32_bf16(Bt[n][k], At[m][k], acc[ai][bj][m][n], 0, 0, 0); __builtin_amdgcn_s_setprio(0); } while (0)
; #define PG8_WAIT_V(n) asm volatile("s_waitcnt vmcnt(" #n ")" ::: "memory")
; #define PG8_WAIT_L(n) asm volatile("s_waitcnt lgkmcnt(" #n ")" ::: "memory")
; #define PG8_BAR __builtin_amdgcn_s_barrier()
; #define PG8_SCHED __builtin_amdgcn_sched_barrier(0)
; template <class Epi, class Sched>
; __device__ __forceinline__ void gemm_phase(PG8_LAS unsigned char* lds, PG8_LAS unsigned char* xl, const Gemm g, const Sched& S, const Epi& E) {
;     ...
;             PG8_LDB(B0, 1, 0); PG8_LDB(B1, 1, 1); PG8_SCHED; PG8_LDA(At, 1, 0); PG8_STAGE(PG8_SA(0, 1), a2 + hsA, voffA);
;             PG8_WAIT_V(8); PG8_WAIT_L(0); PG8_BAR; PG8_MMA(0, 0, At, B0); PG8_MMA(0, 1, At, B1); PG8_BAR; PG8_SCHED;
	s_add_i32 s68, 0, 0x18000
	v_add_u32_e32 v179, s68, v147
	s_add_i32 s75, 0, 0x1c000
	ds_read_b128 v[168:171], v179
	ds_read_b128 v[172:175], v179 offset:1024
	ds_read_b128 v[180:183], v179 offset:2048
	ds_read_b128 v[184:187], v179 offset:3072
	v_add_u32_e32 v179, s75, v147
	ds_read_b128 v[188:191], v179
	ds_read_b128 v[192:195], v179 offset:1024
	ds_read_b128 v[196:199], v179 offset:2048
	ds_read_b128 v[200:203], v179 offset:3072
	s_add_u32 s36, s36, 0x40000
	s_addc_u32 s37, s37, 0
	s_mov_b32 m0, s58
	v_lshl_add_u64 v[242:243], s[36:37], 0, v[128:129]
	ds_read_b128 v[204:207], v158 offset:32768
	ds_read_b128 v[208:211], v158 offset:33792
	ds_read_b128 v[212:215], v158 offset:34816
	ds_read_b128 v[216:219], v158 offset:35840
	ds_read_b128 v[222:225], v158 offset:36864
	ds_read_b128 v[226:229], v158 offset:37888
	ds_read_b128 v[230:233], v158 offset:38912
	ds_read_b128 v[234:237], v158 offset:39936
	global_load_lds_dwordx4 v[242:243], off
	v_lshl_add_u64 v[242:243], s[36:37], 0, v[132:133]
	s_mov_b32 m0, s59
	s_nop 0
	global_load_lds_dwordx4 v[242:243], off
	s_waitcnt vmcnt(8)
	s_waitcnt lgkmcnt(0)
	s_barrier
	s_setprio 1
	s_waitcnt lgkmcnt(0)
	v_mfma_f32_16x16x32_bf16 v[124:127], v[168:171], v[204:207], v[124:127]
	v_mfma_f32_16x16x32_bf16 v[120:123], v[180:183], v[204:207], v[120:123]
	v_mfma_f32_16x16x32_bf16 v[108:111], v[168:171], v[212:215], v[108:111]
	v_mfma_f32_16x16x32_bf16 v[104:107], v[180:183], v[212:215], v[104:107]
	v_mfma_f32_16x16x32_bf16 v[92:95], v[168:171], v[222:225], v[92:95]
	v_mfma_f32_16x16x32_bf16 v[88:91], v[180:183], v[222:225], v[88:91]
	v_mfma_f32_16x16x32_bf16 v[76:79], v[168:171], v[230:233], v[76:79]
	v_mfma_f32_16x16x32_bf16 v[72:75], v[180:183], v[230:233], v[72:75]
	v_mfma_f32_16x16x32_bf16 v[124:127], v[172:175], v[208:211], v[124:127]
	v_mfma_f32_16x16x32_bf16 v[120:123], v[184:187], v[208:211], v[120:123]
	v_mfma_f32_16x16x32_bf16 v[108:111], v[172:175], v[216:219], v[108:111]
	v_mfma_f32_16x16x32_bf16 v[104:107], v[184:187], v[216:219], v[104:107]
	v_mfma_f32_16x16x32_bf16 v[92:95], v[172:175], v[226:229], v[92:95]
	v_mfma_f32_16x16x32_bf16 v[88:91], v[184:187], v[226:229], v[88:91]
	v_mfma_f32_16x16x32_bf16 v[76:79], v[172:175], v[234:237], v[76:79]
	v_mfma_f32_16x16x32_bf16 v[72:75], v[184:187], v[234:237], v[72:75]
	s_setprio 0
	s_setprio 1
	v_mfma_f32_16x16x32_bf16 v[116:119], v[188:191], v[204:207], v[116:119]
	v_mfma_f32_16x16x32_bf16 v[112:115], v[196:199], v[204:207], v[112:115]
	v_mfma_f32_16x16x32_bf16 v[100:103], v[188:191], v[212:215], v[100:103]
	v_mfma_f32_16x16x32_bf16 v[96:99], v[196:199], v[212:215], v[96:99]
	v_mfma_f32_16x16x32_bf16 v[84:87], v[188:191], v[222:225], v[84:87]
	v_mfma_f32_16x16x32_bf16 v[80:83], v[196:199], v[222:225], v[80:83]
	v_mfma_f32_16x16x32_bf16 v[68:71], v[188:191], v[230:233], v[68:71]
	v_mfma_f32_16x16x32_bf16 v[64:67], v[196:199], v[230:233], v[64:67]
	v_mfma_f32_16x16x32_bf16 v[116:119], v[192:195], v[208:211], v[116:119]
	v_mfma_f32_16x16x32_bf16 v[112:115], v[200:203], v[208:211], v[112:115]
	v_mfma_f32_16x16x32_bf16 v[100:103], v[192:195], v[216:219], v[100:103]
	v_mfma_f32_16x16x32_bf16 v[96:99], v[200:203], v[216:219], v[96:99]
	v_mfma_f32_16x16x32_bf16 v[84:87], v[192:195], v[226:229], v[84:87]
	v_mfma_f32_16x16x32_bf16 v[80:83], v[200:203], v[226:229], v[80:83]
	v_mfma_f32_16x16x32_bf16 v[68:71], v[192:195], v[234:237], v[68:71]
	v_mfma_f32_16x16x32_bf16 v[64:67], v[200:203], v[234:237], v[64:67]
	s_setprio 0
	s_barrier
; #define PG8_STAGE(bufoff, gbase, voff) do { _Pragma("unroll") for (int _i = 0; _i < 2; ++_i) \
;         __builtin_amdgcn_global_load_lds((const unsigned*)((const char*)(gbase) + (voff)[_i]), (PG8_LAS unsigned*)(lds + (bufoff) + ldsw + _i * 8192), 16, 0, 0); } while (0)
; #define PG8_LDA(dst, b, h) do { _Pragma("unroll") for (int m = 0; m < 4; ++m) _Pragma("unroll") for (int k = 0; k < 2; ++k) dst[m][k] = *(const PG8_LAS bf16x8*)(lds + PG8_SA(b, h) + aoff + m * 2048 + k * 1024); } while (0)
; #define PG8_MMA(ai, bj, At, Bt) do { __builtin_amdgcn_s_setprio(1); _Pragma("unroll") for (int m = 0; m < 4; ++m) _Pragma("unroll") for (int n = 0; n < 2; ++n) _Pragma("unroll") for (int k = 0; k < 2; ++k) \
;         acc[ai][bj][m][n] = __builtin_amdgcn_mfma_f32_16x16x32_bf16(Bt[n][k], At[m][k], acc[ai][bj][m][n], 0, 0, 0); __builtin_amdgcn_s_setprio(0); } while (0)
; #define PG8_WAIT_V(n) asm volatile("s_waitcnt vmcnt(" #n ")" ::: "memory")
; #define PG8_WAIT_L(n) asm volatile("s_waitcnt lgkmcnt(" #n ")" ::: "memory")
; #define PG8_BAR __builtin_amdgcn_s_barrier()
; #define PG8_SCHED __builtin_amdgcn_sched_barrier(0)
; template <class Epi, class Sched>
; __device__ __forceinline__ void gemm_phase(PG8_LAS unsigned char* lds, PG8_LAS unsigned char* xl, const Gemm g, const Sched& S, const Epi& E) {
;     ...
;             PG8_LDA(At, 1, 1); PG8_STAGE(PG8_SB(1, 0), b3, voffB); PG8_STAGE(PG8_SB(1, 1), b3 + hsB, voffB); PG8_STAGE(PG8_SA(1, 0), a3, voffA);
;             PG8_WAIT_V(8); PG8_WAIT_L(0); PG8_BAR; PG8_MMA(1, 0, At, B0); PG8_MMA(1, 1, At, B1); PG8_BAR; PG8_SCHED;
	s_add_i32 s36, s68, s55
	v_lshl_add_u64 v[144:145], v[144:145], 0, s[16:17]
	s_mov_b32 m0, s36
	ds_read_b128 v[204:207], v158 offset:49152
	ds_read_b128 v[208:211], v158 offset:50176
	ds_read_b128 v[212:215], v158 offset:51200
	ds_read_b128 v[216:219], v158 offset:52224
	ds_read_b128 v[222:225], v158 offset:53248
	ds_read_b128 v[226:229], v158 offset:54272
	ds_read_b128 v[230:233], v158 offset:55296
	ds_read_b128 v[234:237], v158 offset:56320
	global_load_lds_dwordx4 v[144:145], off
	s_add_i32 m0, s36, 0x2000
	s_add_u32 s34, s34, 0x40080
	v_lshl_add_u64 v[144:145], v[176:177], 0, s[16:17]
	s_addc_u32 s35, s35, 0
	s_add_i32 s36, s75, s55
	global_load_lds_dwordx4 v[144:145], off
	v_lshl_add_u64 v[144:145], s[34:35], 0, v[130:131]
	s_mov_b32 m0, s36
	s_nop 0
	global_load_lds_dwordx4 v[144:145], off
	v_lshl_add_u64 v[144:145], s[34:35], 0, v[134:135]
	s_add_i32 m0, s36, 0x2000
	s_nop 0
	global_load_lds_dwordx4 v[144:145], off
	v_lshl_add_u64 v[144:145], v[238:239], 0, s[16:17]
	s_mov_b32 m0, s61
	s_nop 0
	global_load_lds_dwordx4 v[144:145], off
	v_lshl_add_u64 v[144:145], v[240:241], 0, s[16:17]
	s_mov_b32 m0, s62
	s_nop 0
	global_load_lds_dwordx4 v[144:145], off
	s_waitcnt vmcnt(8)
	s_waitcnt lgkmcnt(0)
	s_barrier
	s_setprio 1
	s_waitcnt lgkmcnt(0)
	v_mfma_f32_16x16x32_bf16 v[60:63], v[168:171], v[204:207], v[60:63]
	v_mfma_f32_16x16x32_bf16 v[56:59], v[180:183], v[204:207], v[56:59]
	v_mfma_f32_16x16x32_bf16 v[44:47], v[168:171], v[212:215], v[44:47]
	v_mfma_f32_16x16x32_bf16 v[40:43], v[180:183], v[212:215], v[40:43]
	v_mfma_f32_16x16x32_bf16 v[28:31], v[168:171], v[222:225], v[28:31]
	v_mfma_f32_16x16x32_bf16 v[24:27], v[180:183], v[222:225], v[24:27]
	v_mfma_f32_16x16x32_bf16 v[12:15], v[168:171], v[230:233], v[12:15]
	v_mfma_f32_16x16x32_bf16 v[8:11], v[180:183], v[230:233], v[8:11]
	v_mfma_f32_16x16x32_bf16 v[60:63], v[172:175], v[208:211], v[60:63]
	v_mfma_f32_16x16x32_bf16 v[56:59], v[184:187], v[208:211], v[56:59]
	v_mfma_f32_16x16x32_bf16 v[44:47], v[172:175], v[216:219], v[44:47]
	v_mfma_f32_16x16x32_bf16 v[40:43], v[184:187], v[216:219], v[40:43]
	v_mfma_f32_16x16x32_bf16 v[28:31], v[172:175], v[226:229], v[28:31]
	v_mfma_f32_16x16x32_bf16 v[24:27], v[184:187], v[226:229], v[24:27]
	v_mfma_f32_16x16x32_bf16 v[12:15], v[172:175], v[234:237], v[12:15]
	v_mfma_f32_16x16x32_bf16 v[8:11], v[184:187], v[234:237], v[8:11]
	s_setprio 0
	s_setprio 1
	v_mfma_f32_16x16x32_bf16 v[52:55], v[188:191], v[204:207], v[52:55]
	s_add_i32 s74, s74, 2
	v_mfma_f32_16x16x32_bf16 v[48:51], v[196:199], v[204:207], v[48:51]
	s_add_u32 s72, s72, 0x100
	v_mfma_f32_16x16x32_bf16 v[36:39], v[188:191], v[212:215], v[36:39]
	s_addc_u32 s73, s73, 0
	v_mfma_f32_16x16x32_bf16 v[32:35], v[196:199], v[212:215], v[32:35]
	s_add_u32 s30, s30, 0x100
	v_mfma_f32_16x16x32_bf16 v[20:23], v[188:191], v[222:225], v[20:23]
	s_addc_u32 s31, s31, 0
	v_mfma_f32_16x16x32_bf16 v[16:19], v[196:199], v[222:225], v[16:19]
	s_cmp_gt_u32 s74, 13
	v_mfma_f32_16x16x32_bf16 v[4:7], v[188:191], v[230:233], v[4:7]
	v_mfma_f32_16x16x32_bf16 v[0:3], v[196:199], v[230:233], v[0:3]
	v_mfma_f32_16x16x32_bf16 v[52:55], v[192:195], v[208:211], v[52:55]
	v_mfma_f32_16x16x32_bf16 v[48:51], v[200:203], v[208:211], v[48:51]
	v_mfma_f32_16x16x32_bf16 v[36:39], v[192:195], v[216:219], v[36:39]
	v_mfma_f32_16x16x32_bf16 v[32:35], v[200:203], v[216:219], v[32:35]
	v_mfma_f32_16x16x32_bf16 v[20:23], v[192:195], v[226:229], v[20:23]
	v_mfma_f32_16x16x32_bf16 v[16:19], v[200:203], v[226:229], v[16:19]
	v_mfma_f32_16x16x32_bf16 v[4:7], v[192:195], v[234:237], v[4:7]
	v_mfma_f32_16x16x32_bf16 v[0:3], v[200:203], v[234:237], v[0:3]
	s_setprio 0
	s_barrier
	s_cbranch_scc0 .LBB0_471

; #define PG8_STAGE(bufoff, gbase, voff) do { _Pragma("unroll") for (int _i = 0; _i < 2; ++_i) \
;         __builtin_amdgcn_global_load_lds((const unsigned*)((const char*)(gbase) + (voff)[_i]), (PG8_LAS unsigned*)(lds + (bufoff) + ldsw + _i * 8192), 16, 0, 0); } while (0)
; #define PG8_LDA(dst, b, h) do { _Pragma("unroll") for (int m = 0; m < 4; ++m) _Pragma("unroll") for (int k = 0; k < 2; ++k) dst[m][k] = *(const PG8_LAS bf16x8*)(lds + PG8_SA(b, h) + aoff + m * 2048 + k * 1024); } while (0)
; #define PG8_LDB(dst, b, h) do { _Pragma("unroll") for (int n = 0; n < 2; ++n) _Pragma("unroll") for (int k = 0; k < 2; ++k) dst[n][k] = *(const PG8_LAS bf16x8*)(lds + PG8_SB(b, h) + boff + n * 2048 + k * 1024); } while (0)
; #define PG8_MMA(ai, bj, At, Bt) do { __builtin_amdgcn_s_setprio(1); _Pragma("unroll") for (int m = 0; m < 4; ++m) _Pragma("unroll") for (int n = 0; n < 2; ++n) _Pragma("unroll") for (int k = 0; k < 2; ++k) \
;         acc[ai][bj][m][n] = __builtin_amdgcn_mfma_f32_16x16x32_bf16(Bt[n][k], At[m][k], acc[ai][bj][m][n], 0, 0, 0); __builtin_amdgcn_s_setprio(0); } while (0)
; #define PG8_WAIT_V(n) asm volatile("s_waitcnt vmcnt(" #n ")" ::: "memory")
; #define PG8_WAIT_L(n) asm volatile("s_waitcnt lgkmcnt(" #n ")" ::: "memory")
; template <class Epi, class Sched>
; __device__ __forceinline__ void gemm_phase(PG8_LAS unsigned char* lds, PG8_LAS unsigned char* xl, const Gemm g, const Sched& S, const Epi& E) {
;     ...
;         const bool has_next = S.next(ui + 1, nxt);
;         const char* nA = has_next ? (const char*)g.A + nxt.aoff : cA; const char* nB = has_next ? (const char*)g.Bt + nxt.boff : cB;
; #pragma unroll 1
;         for (int t = 0; t < nt; t += 2) {
;             const bool last = (t == nt - 2);
;             const char* a1 = cA + (size_t)(t + 1) * kstep;
;             const char* a2 = last ? nA : cA + (size_t)(t + 2) * kstep; const char* b2 = last ? nB : cB + (size_t)(t + 2) * kstep;
;             const char* a3 = a2 + kstep; const char* b3 = b2 + kstep;
;             PG8_LDB(B0, 0, 0); PG8_LDB(B1, 0, 1); PG8_SCHED; PG8_LDA(At, 0, 0); PG8_STAGE(PG8_SA(1, 1), a1 + hsA, voffA);
;             PG8_WAIT_V(8); PG8_WAIT_L(0); PG8_BAR; PG8_MMA(0, 0, At, B0); PG8_MMA(0, 1, At, B1); PG8_BAR; PG8_SCHED;
;             PG8_LDA(At, 0, 1); PG8_STAGE(PG8_SB(0, 0), b2, voffB); PG8_STAGE(PG8_SB(0, 1), b2 + hsB, voffB); PG8_STAGE(PG8_SA(0, 0), a2, voffA);
.LBB0_576:
	s_add_u32 s34, s43, s28
	s_addc_u32 s35, s55, s29
	s_and_b64 s[36:37], s[10:11], exec
	s_cselect_b32 s13, s35, s51
	s_cselect_b32 s33, s34, s50
	s_add_u32 s36, s56, s30
	s_addc_u32 s37, s57, s31
	s_and_b64 s[46:47], s[10:11], exec
	s_cselect_b32 s46, s37, s3
	s_cselect_b32 s47, s36, s2
	s_add_u32 s79, s2, 0x100
	s_addc_u32 s80, s3, 0
	s_add_u32 s2, s50, 0x40080
	v_mov_b32_e32 v0, 0
	s_addc_u32 s3, s51, 0
	s_mov_b32 s81, -2
	ds_read_b128 v[146:149], v181
	ds_read_b128 v[150:153], v181 offset:1024
	ds_read_b128 v[188:191], v181 offset:2048
	ds_read_b128 v[192:195], v181 offset:3072
	ds_read_b128 v[196:199], v182
	ds_read_b128 v[200:203], v182 offset:1024
	ds_read_b128 v[204:207], v182 offset:2048
	ds_read_b128 v[208:211], v182 offset:3072
	s_add_u32 s50, s2, 0xfffc0080
	s_addc_u32 s51, s3, -1
	s_cmp_eq_u32 s81, 12
	s_cselect_b32 s53, s13, s51
	s_cselect_b32 s52, s33, s50
	s_cselect_b32 s51, s46, s80
	s_cselect_b32 s50, s47, s79
	v_lshl_add_u64 v[246:247], s[2:3], 0, v[140:141]
	s_add_i32 m0, s60, 0xc000
	ds_read_b128 v[212:215], v183
	ds_read_b128 v[216:219], v183 offset:1024
	ds_read_b128 v[222:225], v183 offset:2048
	ds_read_b128 v[226:229], v183 offset:3072
	ds_read_b128 v[230:233], v183 offset:4096
	ds_read_b128 v[234:237], v183 offset:5120
	ds_read_b128 v[238:241], v183 offset:6144
	ds_read_b128 v[242:245], v183 offset:7168
	global_load_lds_dwordx4 v[246:247], off
	v_lshl_add_u64 v[246:247], s[2:3], 0, v[138:139]
	s_add_i32 m0, s60, 0xe000
	s_nop 0
	global_load_lds_dwordx4 v[246:247], off
	s_waitcnt vmcnt(8)
	s_waitcnt lgkmcnt(0)
	s_barrier
	s_setprio 1
	s_waitcnt lgkmcnt(0)
	v_mfma_f32_16x16x32_bf16 v[124:127], v[146:149], v[212:215], 0
	v_mfma_f32_16x16x32_bf16 v[120:123], v[188:191], v[212:215], 0
	v_mfma_f32_16x16x32_bf16 v[108:111], v[146:149], v[222:225], 0
	v_mfma_f32_16x16x32_bf16 v[104:107], v[188:191], v[222:225], 0
	v_mfma_f32_16x16x32_bf16 v[92:95], v[146:149], v[230:233], 0
	v_mfma_f32_16x16x32_bf16 v[88:91], v[188:191], v[230:233], 0
	v_mfma_f32_16x16x32_bf16 v[76:79], v[146:149], v[238:241], 0
	v_mfma_f32_16x16x32_bf16 v[72:75], v[188:191], v[238:241], 0
	v_mfma_f32_16x16x32_bf16 v[124:127], v[150:153], v[216:219], v[124:127]
	v_mfma_f32_16x16x32_bf16 v[120:123], v[192:195], v[216:219], v[120:123]
	v_mfma_f32_16x16x32_bf16 v[108:111], v[150:153], v[226:229], v[108:111]
	v_mfma_f32_16x16x32_bf16 v[104:107], v[192:195], v[226:229], v[104:107]
	v_mfma_f32_16x16x32_bf16 v[92:95], v[150:153], v[234:237], v[92:95]
	v_mfma_f32_16x16x32_bf16 v[88:91], v[192:195], v[234:237], v[88:91]
	v_mfma_f32_16x16x32_bf16 v[76:79], v[150:153], v[242:245], v[76:79]
	v_mfma_f32_16x16x32_bf16 v[72:75], v[192:195], v[242:245], v[72:75]
	s_setprio 0
	s_setprio 1
	v_mfma_f32_16x16x32_bf16 v[116:119], v[196:199], v[212:215], 0
	v_mfma_f32_16x16x32_bf16 v[112:115], v[204:207], v[212:215], 0
	v_mfma_f32_16x16x32_bf16 v[100:103], v[196:199], v[222:225], 0
	v_mfma_f32_16x16x32_bf16 v[96:99], v[204:207], v[222:225], 0
	v_mfma_f32_16x16x32_bf16 v[84:87], v[196:199], v[230:233], 0
	v_mfma_f32_16x16x32_bf16 v[80:83], v[204:207], v[230:233], 0
	v_mfma_f32_16x16x32_bf16 v[68:71], v[196:199], v[238:241], 0
	v_mfma_f32_16x16x32_bf16 v[64:67], v[204:207], v[238:241], 0
	v_mfma_f32_16x16x32_bf16 v[116:119], v[200:203], v[216:219], v[116:119]
	v_mfma_f32_16x16x32_bf16 v[112:115], v[208:211], v[216:219], v[112:115]
	v_mfma_f32_16x16x32_bf16 v[100:103], v[200:203], v[226:229], v[100:103]
	v_mfma_f32_16x16x32_bf16 v[96:99], v[208:211], v[226:229], v[96:99]
	v_mfma_f32_16x16x32_bf16 v[84:87], v[200:203], v[234:237], v[84:87]
	v_mfma_f32_16x16x32_bf16 v[80:83], v[208:211], v[234:237], v[80:83]
	v_mfma_f32_16x16x32_bf16 v[68:71], v[200:203], v[242:245], v[68:71]
	v_mfma_f32_16x16x32_bf16 v[64:67], v[208:211], v[242:245], v[64:67]
	s_setprio 0
	s_barrier
	s_add_i32 s68, s72, s59
	v_lshl_add_u64 v[246:247], s[50:51], 0, v[130:131]
	s_mov_b32 m0, s68
	ds_read_b128 v[212:215], v183 offset:16384
	ds_read_b128 v[216:219], v183 offset:17408
	ds_read_b128 v[222:225], v183 offset:18432
	ds_read_b128 v[226:229], v183 offset:19456
	ds_read_b128 v[230:233], v183 offset:20480
	ds_read_b128 v[234:237], v183 offset:21504
	ds_read_b128 v[238:241], v183 offset:22528
	ds_read_b128 v[242:245], v183 offset:23552
	global_load_lds_dwordx4 v[246:247], off
	s_add_i32 m0, s68, 0x2000
	s_add_u32 s82, s50, 0x40000
	v_lshl_add_u64 v[248:249], s[50:51], 0, v[134:135]
	s_addc_u32 s83, s51, 0
	s_add_i32 s68, s73, s59
	global_load_lds_dwordx4 v[248:249], off
	v_lshl_add_u64 v[250:251], s[82:83], 0, v[130:131]
	s_mov_b32 m0, s68
	v_lshl_add_u64 v[252:253], s[52:53], 0, v[132:133]
	global_load_lds_dwordx4 v[250:251], off
	v_lshl_add_u64 v[250:251], s[82:83], 0, v[134:135]
	s_add_i32 m0, s68, 0x2000
	s_nop 0
	global_load_lds_dwordx4 v[250:251], off
	v_lshl_add_u64 v[250:251], s[52:53], 0, v[128:129]
	s_mov_b32 m0, s60
	s_nop 0
	global_load_lds_dwordx4 v[250:251], off
	s_mov_b32 m0, s61
	s_nop 0
	global_load_lds_dwordx4 v[252:253], off
	s_waitcnt vmcnt(8)
	s_waitcnt lgkmcnt(0)
	s_barrier
; #define PG8_STAGE(bufoff, gbase, voff) do { _Pragma("unroll") for (int _i = 0; _i < 2; ++_i) \
;         __builtin_amdgcn_global_load_lds((const unsigned*)((const char*)(gbase) + (voff)[_i]), (PG8_LAS unsigned*)(lds + (bufoff) + ldsw + _i * 8192), 16, 0, 0); } while (0)
; #define PG8_LDA(dst, b, h) do { _Pragma("unroll") for (int m = 0; m < 4; ++m) _Pragma("unroll") for (int k = 0; k < 2; ++k) dst[m][k] = *(const PG8_LAS bf16x8*)(lds + PG8_SA(b, h) + aoff + m * 2048 + k * 1024); } while (0)
; #define PG8_LDB(dst, b, h) do { _Pragma("unroll") for (int n = 0; n < 2; ++n) _Pragma("unroll") for (int k = 0; k < 2; ++k) dst[n][k] = *(const PG8_LAS bf16x8*)(lds + PG8_SB(b, h) + boff + n * 2048 + k * 1024); } while (0)
; #define PG8_MMA(ai, bj, At, Bt) do { __builtin_amdgcn_s_setprio(1); _Pragma("unroll") for (int m = 0; m < 4; ++m) _Pragma("unroll") for (int n = 0; n < 2; ++n) _Pragma("unroll") for (int k = 0; k < 2; ++k) \
;         acc[ai][bj][m][n] = __builtin_amdgcn_mfma_f32_16x16x32_bf16(Bt[n][k], At[m][k], acc[ai][bj][m][n], 0, 0, 0); __builtin_amdgcn_s_setprio(0); } while (0)
; #define PG8_WAIT_V(n) asm volatile("s_waitcnt vmcnt(" #n ")" ::: "memory")
; #define PG8_WAIT_L(n) asm volatile("s_waitcnt lgkmcnt(" #n ")" ::: "memory")
; #define PG8_BAR __builtin_amdgcn_s_barrier()
; #define PG8_SCHED __builtin_amdgcn_sched_barrier(0)
; template <class Epi, class Sched>
; __device__ __forceinline__ void gemm_phase(PG8_LAS unsigned char* lds, PG8_LAS unsigned char* xl, const Gemm g, const Sched& S, const Epi& E) {
;     ...
;             PG8_WAIT_V(8); PG8_WAIT_L(0); PG8_BAR; PG8_MMA(1, 0, At, B0); PG8_MMA(1, 1, At, B1); PG8_BAR; PG8_SCHED;
;             PG8_LDB(B0, 1, 0); PG8_LDB(B1, 1, 1); PG8_SCHED; PG8_LDA(At, 1, 0); PG8_STAGE(PG8_SA(0, 1), a2 + hsA, voffA);
;             PG8_WAIT_V(8); PG8_WAIT_L(0); PG8_BAR; PG8_MMA(0, 0, At, B0); PG8_MMA(0, 1, At, B1); PG8_BAR; PG8_SCHED;
	s_setprio 1
	s_waitcnt lgkmcnt(0)
	v_mfma_f32_16x16x32_bf16 v[60:63], v[146:149], v[212:215], 0
	v_mfma_f32_16x16x32_bf16 v[56:59], v[188:191], v[212:215], 0
	v_mfma_f32_16x16x32_bf16 v[44:47], v[146:149], v[222:225], 0
	v_mfma_f32_16x16x32_bf16 v[40:43], v[188:191], v[222:225], 0
	v_mfma_f32_16x16x32_bf16 v[28:31], v[146:149], v[230:233], 0
	v_mfma_f32_16x16x32_bf16 v[24:27], v[188:191], v[230:233], 0
	v_mfma_f32_16x16x32_bf16 v[12:15], v[146:149], v[238:241], 0
	v_mfma_f32_16x16x32_bf16 v[8:11], v[188:191], v[238:241], 0
	v_mfma_f32_16x16x32_bf16 v[60:63], v[150:153], v[216:219], v[60:63]
	v_mfma_f32_16x16x32_bf16 v[56:59], v[192:195], v[216:219], v[56:59]
	v_mfma_f32_16x16x32_bf16 v[44:47], v[150:153], v[226:229], v[44:47]
	v_mfma_f32_16x16x32_bf16 v[40:43], v[192:195], v[226:229], v[40:43]
	v_mfma_f32_16x16x32_bf16 v[28:31], v[150:153], v[234:237], v[28:31]
	v_mfma_f32_16x16x32_bf16 v[24:27], v[192:195], v[234:237], v[24:27]
	v_mfma_f32_16x16x32_bf16 v[12:15], v[150:153], v[242:245], v[12:15]
	v_mfma_f32_16x16x32_bf16 v[8:11], v[192:195], v[242:245], v[8:11]
	s_setprio 0
	s_setprio 1
	v_mfma_f32_16x16x32_bf16 v[52:55], v[196:199], v[212:215], 0
	v_mfma_f32_16x16x32_bf16 v[48:51], v[204:207], v[212:215], 0
	v_mfma_f32_16x16x32_bf16 v[36:39], v[196:199], v[222:225], 0
	v_mfma_f32_16x16x32_bf16 v[32:35], v[204:207], v[222:225], 0
	v_mfma_f32_16x16x32_bf16 v[20:23], v[196:199], v[230:233], 0
	v_mfma_f32_16x16x32_bf16 v[16:19], v[204:207], v[230:233], 0
	v_mfma_f32_16x16x32_bf16 v[4:7], v[196:199], v[238:241], 0
	v_mfma_f32_16x16x32_bf16 v[0:3], v[204:207], v[238:241], 0
	v_mfma_f32_16x16x32_bf16 v[52:55], v[200:203], v[216:219], v[52:55]
	v_mfma_f32_16x16x32_bf16 v[48:51], v[208:211], v[216:219], v[48:51]
	v_mfma_f32_16x16x32_bf16 v[36:39], v[200:203], v[226:229], v[36:39]
	v_mfma_f32_16x16x32_bf16 v[32:35], v[208:211], v[226:229], v[32:35]
	v_mfma_f32_16x16x32_bf16 v[20:23], v[200:203], v[234:237], v[20:23]
	v_mfma_f32_16x16x32_bf16 v[16:19], v[208:211], v[234:237], v[16:19]
	v_mfma_f32_16x16x32_bf16 v[4:7], v[200:203], v[242:245], v[4:7]
	v_mfma_f32_16x16x32_bf16 v[0:3], v[208:211], v[242:245], v[0:3]
	s_setprio 0
	s_barrier
	s_add_i32 s68, 0, 0x18000
	v_add_u32_e32 v184, s68, v156
	s_add_i32 s82, 0, 0x1c000
	ds_read_b128 v[146:149], v184
	ds_read_b128 v[150:153], v184 offset:1024
	ds_read_b128 v[188:191], v184 offset:2048
	ds_read_b128 v[192:195], v184 offset:3072
	v_add_u32_e32 v184, s82, v156
	ds_read_b128 v[196:199], v184
	ds_read_b128 v[200:203], v184 offset:1024
	ds_read_b128 v[204:207], v184 offset:2048
	ds_read_b128 v[208:211], v184 offset:3072
	s_add_u32 s52, s52, 0x40000
	s_addc_u32 s53, s53, 0
	s_mov_b32 m0, s62
	v_lshl_add_u64 v[184:185], s[52:53], 0, v[128:129]
	ds_read_b128 v[212:215], v183 offset:32768
	ds_read_b128 v[216:219], v183 offset:33792
	ds_read_b128 v[222:225], v183 offset:34816
	ds_read_b128 v[226:229], v183 offset:35840
	ds_read_b128 v[230:233], v183 offset:36864
	ds_read_b128 v[234:237], v183 offset:37888
	ds_read_b128 v[238:241], v183 offset:38912
	ds_read_b128 v[242:245], v183 offset:39936
	global_load_lds_dwordx4 v[184:185], off
	v_lshl_add_u64 v[184:185], s[52:53], 0, v[132:133]
	s_mov_b32 m0, s63
	s_nop 0
	global_load_lds_dwordx4 v[184:185], off
	s_waitcnt vmcnt(8)
	s_waitcnt lgkmcnt(0)
	s_barrier
	s_setprio 1
	s_waitcnt lgkmcnt(0)
	v_mfma_f32_16x16x32_bf16 v[124:127], v[146:149], v[212:215], v[124:127]
	v_mfma_f32_16x16x32_bf16 v[120:123], v[188:191], v[212:215], v[120:123]
	v_mfma_f32_16x16x32_bf16 v[108:111], v[146:149], v[222:225], v[108:111]
	v_mfma_f32_16x16x32_bf16 v[104:107], v[188:191], v[222:225], v[104:107]
	v_mfma_f32_16x16x32_bf16 v[92:95], v[146:149], v[230:233], v[92:95]
	v_mfma_f32_16x16x32_bf16 v[88:91], v[188:191], v[230:233], v[88:91]
	v_mfma_f32_16x16x32_bf16 v[76:79], v[146:149], v[238:241], v[76:79]
	v_mfma_f32_16x16x32_bf16 v[72:75], v[188:191], v[238:241], v[72:75]
	v_mfma_f32_16x16x32_bf16 v[124:127], v[150:153], v[216:219], v[124:127]
	v_mfma_f32_16x16x32_bf16 v[120:123], v[192:195], v[216:219], v[120:123]
	v_mfma_f32_16x16x32_bf16 v[108:111], v[150:153], v[226:229], v[108:111]
	v_mfma_f32_16x16x32_bf16 v[104:107], v[192:195], v[226:229], v[104:107]
	v_mfma_f32_16x16x32_bf16 v[92:95], v[150:153], v[234:237], v[92:95]
	v_mfma_f32_16x16x32_bf16 v[88:91], v[192:195], v[234:237], v[88:91]
	v_mfma_f32_16x16x32_bf16 v[76:79], v[150:153], v[242:245], v[76:79]
	v_mfma_f32_16x16x32_bf16 v[72:75], v[192:195], v[242:245], v[72:75]
	s_setprio 0
	s_setprio 1
	v_mfma_f32_16x16x32_bf16 v[116:119], v[196:199], v[212:215], v[116:119]
	v_mfma_f32_16x16x32_bf16 v[112:115], v[204:207], v[212:215], v[112:115]
	v_mfma_f32_16x16x32_bf16 v[100:103], v[196:199], v[222:225], v[100:103]
	v_mfma_f32_16x16x32_bf16 v[96:99], v[204:207], v[222:225], v[96:99]
	v_mfma_f32_16x16x32_bf16 v[84:87], v[196:199], v[230:233], v[84:87]
	v_mfma_f32_16x16x32_bf16 v[80:83], v[204:207], v[230:233], v[80:83]
	v_mfma_f32_16x16x32_bf16 v[68:71], v[196:199], v[238:241], v[68:71]
	v_mfma_f32_16x16x32_bf16 v[64:67], v[204:207], v[238:241], v[64:67]
	v_mfma_f32_16x16x32_bf16 v[116:119], v[200:203], v[216:219], v[116:119]
	v_mfma_f32_16x16x32_bf16 v[112:115], v[208:211], v[216:219], v[112:115]
	v_mfma_f32_16x16x32_bf16 v[100:103], v[200:203], v[226:229], v[100:103]
	v_mfma_f32_16x16x32_bf16 v[96:99], v[208:211], v[226:229], v[96:99]
	v_mfma_f32_16x16x32_bf16 v[84:87], v[200:203], v[234:237], v[84:87]
	v_mfma_f32_16x16x32_bf16 v[80:83], v[208:211], v[234:237], v[80:83]
	v_mfma_f32_16x16x32_bf16 v[68:71], v[200:203], v[242:245], v[68:71]
	v_mfma_f32_16x16x32_bf16 v[64:67], v[208:211], v[242:245], v[64:67]
	s_setprio 0
	s_barrier
; #define PG8_STAGE(bufoff, gbase, voff) do { _Pragma("unroll") for (int _i = 0; _i < 2; ++_i) \
;         __builtin_amdgcn_global_load_lds((const unsigned*)((const char*)(gbase) + (voff)[_i]), (PG8_LAS unsigned*)(lds + (bufoff) + ldsw + _i * 8192), 16, 0, 0); } while (0)
; #define PG8_LDA(dst, b, h) do { _Pragma("unroll") for (int m = 0; m < 4; ++m) _Pragma("unroll") for (int k = 0; k < 2; ++k) dst[m][k] = *(const PG8_LAS bf16x8*)(lds + PG8_SA(b, h) + aoff + m * 2048 + k * 1024); } while (0)
; #define PG8_LDB(dst, b, h) do { _Pragma("unroll") for (int n = 0; n < 2; ++n) _Pragma("unroll") for (int k = 0; k < 2; ++k) dst[n][k] = *(const PG8_LAS bf16x8*)(lds + PG8_SB(b, h) + boff + n * 2048 + k * 1024); } while (0)
; #define PG8_MMA(ai, bj, At, Bt) do { __builtin_amdgcn_s_setprio(1); _Pragma("unroll") for (int m = 0; m < 4; ++m) _Pragma("unroll") for (int n = 0; n < 2; ++n) _Pragma("unroll") for (int k = 0; k < 2; ++k) \
;         acc[ai][bj][m][n] = __builtin_amdgcn_mfma_f32_16x16x32_bf16(Bt[n][k], At[m][k], acc[ai][bj][m][n], 0, 0, 0); __builtin_amdgcn_s_setprio(0); } while (0)
; #define PG8_WAIT_V(n) asm volatile("s_waitcnt vmcnt(" #n ")" ::: "memory")
; #define PG8_WAIT_L(n) asm volatile("s_waitcnt lgkmcnt(" #n ")" ::: "memory")
; #define PG8_BAR __builtin_amdgcn_s_barrier()
; #define PG8_SCHED __builtin_amdgcn_sched_barrier(0)
; template <class Epi, class Sched>
; __device__ __forceinline__ void gemm_phase(PG8_LAS unsigned char* lds, PG8_LAS unsigned char* xl, const Gemm g, const Sched& S, const Epi& E) {
;     ...
;         for (int t = 0; t < nt; t += 2) {
;             const bool last = (t == nt - 2);
;             const char* a1 = cA + (size_t)(t + 1) * kstep;
;             const char* a2 = last ? nA : cA + (size_t)(t + 2) * kstep; const char* b2 = last ? nB : cB + (size_t)(t + 2) * kstep;
;             const char* a3 = a2 + kstep; const char* b3 = b2 + kstep;
;             PG8_LDB(B0, 0, 0); PG8_LDB(B1, 0, 1); PG8_SCHED; PG8_LDA(At, 0, 0); PG8_STAGE(PG8_SA(1, 1), a1 + hsA, voffA);
;     ...
;             PG8_LDA(At, 1, 1); PG8_STAGE(PG8_SB(1, 0), b3, voffB); PG8_STAGE(PG8_SB(1, 1), b3 + hsB, voffB); PG8_STAGE(PG8_SA(1, 0), a3, voffA);
;             PG8_WAIT_V(8); PG8_WAIT_L(0); PG8_BAR; PG8_MMA(1, 0, At, B0); PG8_MMA(1, 1, At, B1); PG8_BAR; PG8_SCHED;
	s_add_i32 s52, s68, s59
	v_lshl_add_u64 v[184:185], v[246:247], 0, s[20:21]
	s_mov_b32 m0, s52
	ds_read_b128 v[212:215], v183 offset:49152
	ds_read_b128 v[216:219], v183 offset:50176
	ds_read_b128 v[222:225], v183 offset:51200
	ds_read_b128 v[226:229], v183 offset:52224
	ds_read_b128 v[230:233], v183 offset:53248
	ds_read_b128 v[234:237], v183 offset:54272
	ds_read_b128 v[238:241], v183 offset:55296
	ds_read_b128 v[242:245], v183 offset:56320
	global_load_lds_dwordx4 v[184:185], off
	s_add_i32 m0, s52, 0x2000
	s_add_u32 s50, s50, 0x40080
	v_lshl_add_u64 v[184:185], v[248:249], 0, s[20:21]
	s_addc_u32 s51, s51, 0
	s_add_i32 s52, s82, s59
	global_load_lds_dwordx4 v[184:185], off
	v_lshl_add_u64 v[184:185], s[50:51], 0, v[130:131]
	s_mov_b32 m0, s52
	s_nop 0
	global_load_lds_dwordx4 v[184:185], off
	v_lshl_add_u64 v[184:185], s[50:51], 0, v[134:135]
	s_add_i32 m0, s52, 0x2000
	s_nop 0
	global_load_lds_dwordx4 v[184:185], off
	v_lshl_add_u64 v[184:185], v[250:251], 0, s[20:21]
	s_mov_b32 m0, s65
	s_nop 0
	global_load_lds_dwordx4 v[184:185], off
	v_lshl_add_u64 v[184:185], v[252:253], 0, s[20:21]
	s_mov_b32 m0, s66
	s_nop 0
	global_load_lds_dwordx4 v[184:185], off
	s_waitcnt vmcnt(8)
	s_waitcnt lgkmcnt(0)
	s_barrier
	s_setprio 1
	s_waitcnt lgkmcnt(0)
	v_mfma_f32_16x16x32_bf16 v[60:63], v[146:149], v[212:215], v[60:63]
	v_mfma_f32_16x16x32_bf16 v[56:59], v[188:191], v[212:215], v[56:59]
	v_mfma_f32_16x16x32_bf16 v[44:47], v[146:149], v[222:225], v[44:47]
	v_mfma_f32_16x16x32_bf16 v[40:43], v[188:191], v[222:225], v[40:43]
	v_mfma_f32_16x16x32_bf16 v[28:31], v[146:149], v[230:233], v[28:31]
	v_mfma_f32_16x16x32_bf16 v[24:27], v[188:191], v[230:233], v[24:27]
	v_mfma_f32_16x16x32_bf16 v[12:15], v[146:149], v[238:241], v[12:15]
	v_mfma_f32_16x16x32_bf16 v[8:11], v[188:191], v[238:241], v[8:11]
	v_mfma_f32_16x16x32_bf16 v[60:63], v[150:153], v[216:219], v[60:63]
	v_mfma_f32_16x16x32_bf16 v[56:59], v[192:195], v[216:219], v[56:59]
	v_mfma_f32_16x16x32_bf16 v[44:47], v[150:153], v[226:229], v[44:47]
	v_mfma_f32_16x16x32_bf16 v[40:43], v[192:195], v[226:229], v[40:43]
	v_mfma_f32_16x16x32_bf16 v[28:31], v[150:153], v[234:237], v[28:31]
	v_mfma_f32_16x16x32_bf16 v[24:27], v[192:195], v[234:237], v[24:27]
	v_mfma_f32_16x16x32_bf16 v[12:15], v[150:153], v[242:245], v[12:15]
	v_mfma_f32_16x16x32_bf16 v[8:11], v[192:195], v[242:245], v[8:11]
	s_setprio 0
	s_setprio 1
	v_mfma_f32_16x16x32_bf16 v[52:55], v[196:199], v[212:215], v[52:55]
	s_add_i32 s81, s81, 2
	v_mfma_f32_16x16x32_bf16 v[48:51], v[204:207], v[212:215], v[48:51]
	s_add_u32 s79, s79, 0x100
	v_mfma_f32_16x16x32_bf16 v[36:39], v[196:199], v[222:225], v[36:39]
	s_addc_u32 s80, s80, 0
	v_mfma_f32_16x16x32_bf16 v[32:35], v[204:207], v[222:225], v[32:35]
	s_add_u32 s2, s2, 0x100
	v_mfma_f32_16x16x32_bf16 v[20:23], v[196:199], v[230:233], v[20:23]
	s_addc_u32 s3, s3, 0
	v_mfma_f32_16x16x32_bf16 v[16:19], v[204:207], v[230:233], v[16:19]
	s_cmp_gt_u32 s81, 13
	v_mfma_f32_16x16x32_bf16 v[4:7], v[196:199], v[238:241], v[4:7]
	v_mfma_f32_16x16x32_bf16 v[0:3], v[204:207], v[238:241], v[0:3]
	v_mfma_f32_16x16x32_bf16 v[52:55], v[200:203], v[216:219], v[52:55]
	v_mfma_f32_16x16x32_bf16 v[48:51], v[208:211], v[216:219], v[48:51]
	v_mfma_f32_16x16x32_bf16 v[36:39], v[200:203], v[226:229], v[36:39]
	v_mfma_f32_16x16x32_bf16 v[32:35], v[208:211], v[226:229], v[32:35]
	v_mfma_f32_16x16x32_bf16 v[20:23], v[200:203], v[234:237], v[20:23]
	v_mfma_f32_16x16x32_bf16 v[16:19], v[208:211], v[234:237], v[16:19]
	v_mfma_f32_16x16x32_bf16 v[4:7], v[200:203], v[242:245], v[4:7]
	v_mfma_f32_16x16x32_bf16 v[0:3], v[208:211], v[242:245], v[0:3]
	s_setprio 0
	s_barrier
	s_cbranch_scc1 .Lpeel_after_P4
.LBB0_577:
	ds_read_b128 v[146:149], v181
	ds_read_b128 v[150:153], v181 offset:1024
	ds_read_b128 v[188:191], v181 offset:2048
	ds_read_b128 v[192:195], v181 offset:3072
	ds_read_b128 v[196:199], v182
	ds_read_b128 v[200:203], v182 offset:1024
	ds_read_b128 v[204:207], v182 offset:2048
	ds_read_b128 v[208:211], v182 offset:3072
	s_add_u32 s50, s2, 0xfffc0080
	s_addc_u32 s51, s3, -1
	s_cmp_eq_u32 s81, 12
	s_cselect_b32 s53, s13, s51
	s_cselect_b32 s52, s33, s50
	s_cselect_b32 s51, s46, s80
	s_cselect_b32 s50, s47, s79
	v_lshl_add_u64 v[246:247], s[2:3], 0, v[140:141]
	s_add_i32 m0, s60, 0xc000
	ds_read_b128 v[212:215], v183
	ds_read_b128 v[216:219], v183 offset:1024
	ds_read_b128 v[222:225], v183 offset:2048
	ds_read_b128 v[226:229], v183 offset:3072
	ds_read_b128 v[230:233], v183 offset:4096
	ds_read_b128 v[234:237], v183 offset:5120
	ds_read_b128 v[238:241], v183 offset:6144
	ds_read_b128 v[242:245], v183 offset:7168
	global_load_lds_dwordx4 v[246:247], off
	v_lshl_add_u64 v[246:247], s[2:3], 0, v[138:139]
	s_add_i32 m0, s60, 0xe000
	s_nop 0
	global_load_lds_dwordx4 v[246:247], off
	s_waitcnt vmcnt(8)
	s_waitcnt lgkmcnt(0)
	s_barrier
; #define PG8_STAGE(bufoff, gbase, voff) do { _Pragma("unroll") for (int _i = 0; _i < 2; ++_i) \
;         __builtin_amdgcn_global_load_lds((const unsigned*)((const char*)(gbase) + (voff)[_i]), (PG8_LAS unsigned*)(lds + (bufoff) + ldsw + _i * 8192), 16, 0, 0); } while (0)
; #define PG8_LDA(dst, b, h) do { _Pragma("unroll") for (int m = 0; m < 4; ++m) _Pragma("unroll") for (int k = 0; k < 2; ++k) dst[m][k] = *(const PG8_LAS bf16x8*)(lds + PG8_SA(b, h) + aoff + m * 2048 + k * 1024); } while (0)
; #define PG8_MMA(ai, bj, At, Bt) do { __builtin_amdgcn_s_setprio(1); _Pragma("unroll") for (int m = 0; m < 4; ++m) _Pragma("unroll") for (int n = 0; n < 2; ++n) _Pragma("unroll") for (int k = 0; k < 2; ++k) \
;         acc[ai][bj][m][n] = __builtin_amdgcn_mfma_f32_16x16x32_bf16(Bt[n][k], At[m][k], acc[ai][bj][m][n], 0, 0, 0); __builtin_amdgcn_s_setprio(0); } while (0)
; #define PG8_WAIT_V(n) asm volatile("s_waitcnt vmcnt(" #n ")" ::: "memory")
; #define PG8_WAIT_L(n) asm volatile("s_waitcnt lgkmcnt(" #n ")" ::: "memory")
; #define PG8_BAR __builtin_amdgcn_s_barrier()
; #define PG8_SCHED __builtin_amdgcn_sched_barrier(0)
; template <class Epi, class Sched>
; __device__ __forceinline__ void gemm_phase(PG8_LAS unsigned char* lds, PG8_LAS unsigned char* xl, const Gemm g, const Sched& S, const Epi& E) {
;     ...
;             PG8_WAIT_V(8); PG8_WAIT_L(0); PG8_BAR; PG8_MMA(0, 0, At, B0); PG8_MMA(0, 1, At, B1); PG8_BAR; PG8_SCHED;
;             PG8_LDA(At, 0, 1); PG8_STAGE(PG8_SB(0, 0), b2, voffB); PG8_STAGE(PG8_SB(0, 1), b2 + hsB, voffB); PG8_STAGE(PG8_SA(0, 0), a2, voffA);
;             PG8_WAIT_V(8); PG8_WAIT_L(0); PG8_BAR; PG8_MMA(1, 0, At, B0); PG8_MMA(1, 1, At, B1); PG8_BAR; PG8_SCHED;
	s_setprio 1
	s_waitcnt lgkmcnt(0)
	v_mfma_f32_16x16x32_bf16 v[124:127], v[146:149], v[212:215], v[124:127]
	v_mfma_f32_16x16x32_bf16 v[120:123], v[188:191], v[212:215], v[120:123]
	v_mfma_f32_16x16x32_bf16 v[108:111], v[146:149], v[222:225], v[108:111]
	v_mfma_f32_16x16x32_bf16 v[104:107], v[188:191], v[222:225], v[104:107]
	v_mfma_f32_16x16x32_bf16 v[92:95], v[146:149], v[230:233], v[92:95]
	v_mfma_f32_16x16x32_bf16 v[88:91], v[188:191], v[230:233], v[88:91]
	v_mfma_f32_16x16x32_bf16 v[76:79], v[146:149], v[238:241], v[76:79]
	v_mfma_f32_16x16x32_bf16 v[72:75], v[188:191], v[238:241], v[72:75]
	v_mfma_f32_16x16x32_bf16 v[124:127], v[150:153], v[216:219], v[124:127]
	v_mfma_f32_16x16x32_bf16 v[120:123], v[192:195], v[216:219], v[120:123]
	v_mfma_f32_16x16x32_bf16 v[108:111], v[150:153], v[226:229], v[108:111]
	v_mfma_f32_16x16x32_bf16 v[104:107], v[192:195], v[226:229], v[104:107]
	v_mfma_f32_16x16x32_bf16 v[92:95], v[150:153], v[234:237], v[92:95]
	v_mfma_f32_16x16x32_bf16 v[88:91], v[192:195], v[234:237], v[88:91]
	v_mfma_f32_16x16x32_bf16 v[76:79], v[150:153], v[242:245], v[76:79]
	v_mfma_f32_16x16x32_bf16 v[72:75], v[192:195], v[242:245], v[72:75]
	s_setprio 0
	s_setprio 1
	v_mfma_f32_16x16x32_bf16 v[116:119], v[196:199], v[212:215], v[116:119]
	v_mfma_f32_16x16x32_bf16 v[112:115], v[204:207], v[212:215], v[112:115]
	v_mfma_f32_16x16x32_bf16 v[100:103], v[196:199], v[222:225], v[100:103]
	v_mfma_f32_16x16x32_bf16 v[96:99], v[204:207], v[222:225], v[96:99]
	v_mfma_f32_16x16x32_bf16 v[84:87], v[196:199], v[230:233], v[84:87]
	v_mfma_f32_16x16x32_bf16 v[80:83], v[204:207], v[230:233], v[80:83]
	v_mfma_f32_16x16x32_bf16 v[68:71], v[196:199], v[238:241], v[68:71]
	v_mfma_f32_16x16x32_bf16 v[64:67], v[204:207], v[238:241], v[64:67]
	v_mfma_f32_16x16x32_bf16 v[116:119], v[200:203], v[216:219], v[116:119]
	v_mfma_f32_16x16x32_bf16 v[112:115], v[208:211], v[216:219], v[112:115]
	v_mfma_f32_16x16x32_bf16 v[100:103], v[200:203], v[226:229], v[100:103]
	v_mfma_f32_16x16x32_bf16 v[96:99], v[208:211], v[226:229], v[96:99]
	v_mfma_f32_16x16x32_bf16 v[84:87], v[200:203], v[234:237], v[84:87]
	v_mfma_f32_16x16x32_bf16 v[80:83], v[208:211], v[234:237], v[80:83]
	v_mfma_f32_16x16x32_bf16 v[68:71], v[200:203], v[242:245], v[68:71]
	v_mfma_f32_16x16x32_bf16 v[64:67], v[208:211], v[242:245], v[64:67]
	s_setprio 0
	s_barrier
	s_add_i32 s68, s72, s59
	v_lshl_add_u64 v[246:247], s[50:51], 0, v[130:131]
	s_mov_b32 m0, s68
	ds_read_b128 v[212:215], v183 offset:16384
	ds_read_b128 v[216:219], v183 offset:17408
	ds_read_b128 v[222:225], v183 offset:18432
	ds_read_b128 v[226:229], v183 offset:19456
	ds_read_b128 v[230:233], v183 offset:20480
	ds_read_b128 v[234:237], v183 offset:21504
	ds_read_b128 v[238:241], v183 offset:22528
	ds_read_b128 v[242:245], v183 offset:23552
	global_load_lds_dwordx4 v[246:247], off
	s_add_i32 m0, s68, 0x2000
	s_add_u32 s82, s50, 0x40000
	v_lshl_add_u64 v[248:249], s[50:51], 0, v[134:135]
	s_addc_u32 s83, s51, 0
	s_add_i32 s68, s73, s59
	global_load_lds_dwordx4 v[248:249], off
	v_lshl_add_u64 v[250:251], s[82:83], 0, v[130:131]
	s_mov_b32 m0, s68
	v_lshl_add_u64 v[252:253], s[52:53], 0, v[132:133]
	global_load_lds_dwordx4 v[250:251], off
	v_lshl_add_u64 v[250:251], s[82:83], 0, v[134:135]
	s_add_i32 m0, s68, 0x2000
	s_nop 0
	global_load_lds_dwordx4 v[250:251], off
	v_lshl_add_u64 v[250:251], s[52:53], 0, v[128:129]
	s_mov_b32 m0, s60
	s_nop 0
	global_load_lds_dwordx4 v[250:251], off
	s_mov_b32 m0, s61
	s_nop 0
	global_load_lds_dwordx4 v[252:253], off
	s_waitcnt vmcnt(8)
	s_waitcnt lgkmcnt(0)
	s_barrier
	s_setprio 1
	s_waitcnt lgkmcnt(0)
	v_mfma_f32_16x16x32_bf16 v[60:63], v[146:149], v[212:215], v[60:63]
	v_mfma_f32_16x16x32_bf16 v[56:59], v[188:191], v[212:215], v[56:59]
	v_mfma_f32_16x16x32_bf16 v[44:47], v[146:149], v[222:225], v[44:47]
	v_mfma_f32_16x16x32_bf16 v[40:43], v[188:191], v[222:225], v[40:43]
	v_mfma_f32_16x16x32_bf16 v[28:31], v[146:149], v[230:233], v[28:31]
	v_mfma_f32_16x16x32_bf16 v[24:27], v[188:191], v[230:233], v[24:27]
	v_mfma_f32_16x16x32_bf16 v[12:15], v[146:149], v[238:241], v[12:15]
	v_mfma_f32_16x16x32_bf16 v[8:11], v[188:191], v[238:241], v[8:11]
	v_mfma_f32_16x16x32_bf16 v[60:63], v[150:153], v[216:219], v[60:63]
	v_mfma_f32_16x16x32_bf16 v[56:59], v[192:195], v[216:219], v[56:59]
	v_mfma_f32_16x16x32_bf16 v[44:47], v[150:153], v[226:229], v[44:47]
	v_mfma_f32_16x16x32_bf16 v[40:43], v[192:195], v[226:229], v[40:43]
	v_mfma_f32_16x16x32_bf16 v[28:31], v[150:153], v[234:237], v[28:31]
	v_mfma_f32_16x16x32_bf16 v[24:27], v[192:195], v[234:237], v[24:27]
	v_mfma_f32_16x16x32_bf16 v[12:15], v[150:153], v[242:245], v[12:15]
	v_mfma_f32_16x16x32_bf16 v[8:11], v[192:195], v[242:245], v[8:11]
	s_setprio 0
	s_setprio 1
	v_mfma_f32_16x16x32_bf16 v[52:55], v[196:199], v[212:215], v[52:55]
	v_mfma_f32_16x16x32_bf16 v[48:51], v[204:207], v[212:215], v[48:51]
	v_mfma_f32_16x16x32_bf16 v[36:39], v[196:199], v[222:225], v[36:39]
	v_mfma_f32_16x16x32_bf16 v[32:35], v[204:207], v[222:225], v[32:35]
	v_mfma_f32_16x16x32_bf16 v[20:23], v[196:199], v[230:233], v[20:23]
	v_mfma_f32_16x16x32_bf16 v[16:19], v[204:207], v[230:233], v[16:19]
	v_mfma_f32_16x16x32_bf16 v[4:7], v[196:199], v[238:241], v[4:7]
	v_mfma_f32_16x16x32_bf16 v[0:3], v[204:207], v[238:241], v[0:3]
	v_mfma_f32_16x16x32_bf16 v[52:55], v[200:203], v[216:219], v[52:55]
	v_mfma_f32_16x16x32_bf16 v[48:51], v[208:211], v[216:219], v[48:51]
	v_mfma_f32_16x16x32_bf16 v[36:39], v[200:203], v[226:229], v[36:39]
	v_mfma_f32_16x16x32_bf16 v[32:35], v[208:211], v[226:229], v[32:35]
	v_mfma_f32_16x16x32_bf16 v[20:23], v[200:203], v[234:237], v[20:23]
	v_mfma_f32_16x16x32_bf16 v[16:19], v[208:211], v[234:237], v[16:19]
	v_mfma_f32_16x16x32_bf16 v[4:7], v[200:203], v[242:245], v[4:7]
	v_mfma_f32_16x16x32_bf16 v[0:3], v[208:211], v[242:245], v[0:3]
	s_setprio 0
	s_barrier
; #define PG8_STAGE(bufoff, gbase, voff) do { _Pragma("unroll") for (int _i = 0; _i < 2; ++_i) \
;         __builtin_amdgcn_global_load_lds((const unsigned*)((const char*)(gbase) + (voff)[_i]), (PG8_LAS unsigned*)(lds + (bufoff) + ldsw + _i * 8192), 16, 0, 0); } while (0)
; #define PG8_LDA(dst, b, h) do { _Pragma("unroll") for (int m = 0; m < 4; ++m) _Pragma("unroll") for (int k = 0; k < 2; ++k) dst[m][k] = *(const PG8_LAS bf16x8*)(lds + PG8_SA(b, h) + aoff + m * 2048 + k * 1024); } while (0)
; #define PG8_LDB(dst, b, h) do { _Pragma("unroll") for (int n = 0; n < 2; ++n) _Pragma("unroll") for (int k = 0; k < 2; ++k) dst[n][k] = *(const PG8_LAS bf16x8*)(lds + PG8_SB(b, h) + boff + n * 2048 + k * 1024); } while (0)
; #define PG8_MMA(ai, bj, At, Bt) do { __builtin_amdgcn_s_setprio(1); _Pragma("unroll") for (int m = 0; m < 4; ++m) _Pragma("unroll") for (int n = 0; n < 2; ++n) _Pragma("unroll") for (int k = 0; k < 2; ++k) \
;         acc[ai][bj][m][n] = __builtin_amdgcn_mfma_f32_16x16x32_bf16(Bt[n][k], At[m][k], acc[ai][bj][m][n], 0, 0, 0); __builtin_amdgcn_s_setprio(0); } while (0)
; #define PG8_WAIT_V(n) asm volatile("s_waitcnt vmcnt(" #n ")" ::: "memory")
; #define PG8_WAIT_L(n) asm volatile("s_waitcnt lgkmcnt(" #n ")" ::: "memory")
; #define PG8_BAR __builtin_amdgcn_s_barrier()
; #define PG8_SCHED __builtin_amdgcn_sched_barrier(0)
; template <class Epi, class Sched>
; __device__ __forceinline__ void gemm_phase(PG8_LAS unsigned char* lds, PG8_LAS unsigned char* xl, const Gemm g, const Sched& S, const Epi& E) {
;     ...
;             PG8_LDB(B0, 1, 0); PG8_LDB(B1, 1, 1); PG8_SCHED; PG8_LDA(At, 1, 0); PG8_STAGE(PG8_SA(0, 1), a2 + hsA, voffA);
;             PG8_WAIT_V(8); PG8_WAIT_L(0); PG8_BAR; PG8_MMA(0, 0, At, B0); PG8_MMA(0, 1, At, B1); PG8_BAR; PG8_SCHED;
	s_add_i32 s68, 0, 0x18000
	v_add_u32_e32 v184, s68, v156
	s_add_i32 s82, 0, 0x1c000
	ds_read_b128 v[146:149], v184
	ds_read_b128 v[150:153], v184 offset:1024
	ds_read_b128 v[188:191], v184 offset:2048
	ds_read_b128 v[192:195], v184 offset:3072
	v_add_u32_e32 v184, s82, v156
	ds_read_b128 v[196:199], v184
	ds_read_b128 v[200:203], v184 offset:1024
	ds_read_b128 v[204:207], v184 offset:2048
	ds_read_b128 v[208:211], v184 offset:3072
	s_add_u32 s52, s52, 0x40000
	s_addc_u32 s53, s53, 0
	s_mov_b32 m0, s62
	v_lshl_add_u64 v[184:185], s[52:53], 0, v[128:129]
	ds_read_b128 v[212:215], v183 offset:32768
	ds_read_b128 v[216:219], v183 offset:33792
	ds_read_b128 v[222:225], v183 offset:34816
	ds_read_b128 v[226:229], v183 offset:35840
	ds_read_b128 v[230:233], v183 offset:36864
	ds_read_b128 v[234:237], v183 offset:37888
	ds_read_b128 v[238:241], v183 offset:38912
	ds_read_b128 v[242:245], v183 offset:39936
	global_load_lds_dwordx4 v[184:185], off
	v_lshl_add_u64 v[184:185], s[52:53], 0, v[132:133]
	s_mov_b32 m0, s63
	s_nop 0
	global_load_lds_dwordx4 v[184:185], off
	s_waitcnt vmcnt(8)
	s_waitcnt lgkmcnt(0)
	s_barrier
	s_setprio 1
	s_waitcnt lgkmcnt(0)
	v_mfma_f32_16x16x32_bf16 v[124:127], v[146:149], v[212:215], v[124:127]
	v_mfma_f32_16x16x32_bf16 v[120:123], v[188:191], v[212:215], v[120:123]
	v_mfma_f32_16x16x32_bf16 v[108:111], v[146:149], v[222:225], v[108:111]
	v_mfma_f32_16x16x32_bf16 v[104:107], v[188:191], v[222:225], v[104:107]
	v_mfma_f32_16x16x32_bf16 v[92:95], v[146:149], v[230:233], v[92:95]
	v_mfma_f32_16x16x32_bf16 v[88:91], v[188:191], v[230:233], v[88:91]
	v_mfma_f32_16x16x32_bf16 v[76:79], v[146:149], v[238:241], v[76:79]
	v_mfma_f32_16x16x32_bf16 v[72:75], v[188:191], v[238:241], v[72:75]
	v_mfma_f32_16x16x32_bf16 v[124:127], v[150:153], v[216:219], v[124:127]
	v_mfma_f32_16x16x32_bf16 v[120:123], v[192:195], v[216:219], v[120:123]
	v_mfma_f32_16x16x32_bf16 v[108:111], v[150:153], v[226:229], v[108:111]
	v_mfma_f32_16x16x32_bf16 v[104:107], v[192:195], v[226:229], v[104:107]
	v_mfma_f32_16x16x32_bf16 v[92:95], v[150:153], v[234:237], v[92:95]
	v_mfma_f32_16x16x32_bf16 v[88:91], v[192:195], v[234:237], v[88:91]
	v_mfma_f32_16x16x32_bf16 v[76:79], v[150:153], v[242:245], v[76:79]
	v_mfma_f32_16x16x32_bf16 v[72:75], v[192:195], v[242:245], v[72:75]
	s_setprio 0
	s_setprio 1
	v_mfma_f32_16x16x32_bf16 v[116:119], v[196:199], v[212:215], v[116:119]
	v_mfma_f32_16x16x32_bf16 v[112:115], v[204:207], v[212:215], v[112:115]
	v_mfma_f32_16x16x32_bf16 v[100:103], v[196:199], v[222:225], v[100:103]
	v_mfma_f32_16x16x32_bf16 v[96:99], v[204:207], v[222:225], v[96:99]
	v_mfma_f32_16x16x32_bf16 v[84:87], v[196:199], v[230:233], v[84:87]
	v_mfma_f32_16x16x32_bf16 v[80:83], v[204:207], v[230:233], v[80:83]
	v_mfma_f32_16x16x32_bf16 v[68:71], v[196:199], v[238:241], v[68:71]
	v_mfma_f32_16x16x32_bf16 v[64:67], v[204:207], v[238:241], v[64:67]
	v_mfma_f32_16x16x32_bf16 v[116:119], v[200:203], v[216:219], v[116:119]
	v_mfma_f32_16x16x32_bf16 v[112:115], v[208:211], v[216:219], v[112:115]
	v_mfma_f32_16x16x32_bf16 v[100:103], v[200:203], v[226:229], v[100:103]
	v_mfma_f32_16x16x32_bf16 v[96:99], v[208:211], v[226:229], v[96:99]
	v_mfma_f32_16x16x32_bf16 v[84:87], v[200:203], v[234:237], v[84:87]
	v_mfma_f32_16x16x32_bf16 v[80:83], v[208:211], v[234:237], v[80:83]
	v_mfma_f32_16x16x32_bf16 v[68:71], v[200:203], v[242:245], v[68:71]
	v_mfma_f32_16x16x32_bf16 v[64:67], v[208:211], v[242:245], v[64:67]
	s_setprio 0
	s_barrier
; #define PG8_STAGE(bufoff, gbase, voff) do { _Pragma("unroll") for (int _i = 0; _i < 2; ++_i) \
;         __builtin_amdgcn_global_load_lds((const unsigned*)((const char*)(gbase) + (voff)[_i]), (PG8_LAS unsigned*)(lds + (bufoff) + ldsw + _i * 8192), 16, 0, 0); } while (0)
; #define PG8_LDA(dst, b, h) do { _Pragma("unroll") for (int m = 0; m < 4; ++m) _Pragma("unroll") for (int k = 0; k < 2; ++k) dst[m][k] = *(const PG8_LAS bf16x8*)(lds + PG8_SA(b, h) + aoff + m * 2048 + k * 1024); } while (0)
; #define PG8_MMA(ai, bj, At, Bt) do { __builtin_amdgcn_s_setprio(1); _Pragma("unroll") for (int m = 0; m < 4; ++m) _Pragma("unroll") for (int n = 0; n < 2; ++n) _Pragma("unroll") for (int k = 0; k < 2; ++k) \
;         acc[ai][bj][m][n] = __builtin_amdgcn_mfma_f32_16x16x32_bf16(Bt[n][k], At[m][k], acc[ai][bj][m][n], 0, 0, 0); __builtin_amdgcn_s_setprio(0); } while (0)
; #define PG8_WAIT_V(n) asm volatile("s_waitcnt vmcnt(" #n ")" ::: "memory")
; #define PG8_WAIT_L(n) asm volatile("s_waitcnt lgkmcnt(" #n ")" ::: "memory")
; #define PG8_BAR __builtin_amdgcn_s_barrier()
; #define PG8_SCHED __builtin_amdgcn_sched_barrier(0)
; template <class Epi, class Sched>
; __device__ __forceinline__ void gemm_phase(PG8_LAS unsigned char* lds, PG8_LAS unsigned char* xl, const Gemm g, const Sched& S, const Epi& E) {
;     ...
;             PG8_LDA(At, 1, 1); PG8_STAGE(PG8_SB(1, 0), b3, voffB); PG8_STAGE(PG8_SB(1, 1), b3 + hsB, voffB); PG8_STAGE(PG8_SA(1, 0), a3, voffA);
;             PG8_WAIT_V(8); PG8_WAIT_L(0); PG8_BAR; PG8_MMA(1, 0, At, B0); PG8_MMA(1, 1, At, B1); PG8_BAR; PG8_SCHED;
	s_add_i32 s52, s68, s59
	v_lshl_add_u64 v[184:185], v[246:247], 0, s[20:21]
	s_mov_b32 m0, s52
	ds_read_b128 v[212:215], v183 offset:49152
	ds_read_b128 v[216:219], v183 offset:50176
	ds_read_b128 v[222:225], v183 offset:51200
	ds_read_b128 v[226:229], v183 offset:52224
	ds_read_b128 v[230:233], v183 offset:53248
	ds_read_b128 v[234:237], v183 offset:54272
	ds_read_b128 v[238:241], v183 offset:55296
	ds_read_b128 v[242:245], v183 offset:56320
	global_load_lds_dwordx4 v[184:185], off
	s_add_i32 m0, s52, 0x2000
	s_add_u32 s50, s50, 0x40080
	v_lshl_add_u64 v[184:185], v[248:249], 0, s[20:21]
	s_addc_u32 s51, s51, 0
	s_add_i32 s52, s82, s59
	global_load_lds_dwordx4 v[184:185], off
	v_lshl_add_u64 v[184:185], s[50:51], 0, v[130:131]
	s_mov_b32 m0, s52
	s_nop 0
	global_load_lds_dwordx4 v[184:185], off
	v_lshl_add_u64 v[184:185], s[50:51], 0, v[134:135]
	s_add_i32 m0, s52, 0x2000
	s_nop 0
	global_load_lds_dwordx4 v[184:185], off
	v_lshl_add_u64 v[184:185], v[250:251], 0, s[20:21]
	s_mov_b32 m0, s65
	s_nop 0
	global_load_lds_dwordx4 v[184:185], off
	v_lshl_add_u64 v[184:185], v[252:253], 0, s[20:21]
	s_mov_b32 m0, s66
	s_nop 0
	global_load_lds_dwordx4 v[184:185], off
	s_waitcnt vmcnt(8)
	s_waitcnt lgkmcnt(0)
	s_barrier
	s_setprio 1
	s_waitcnt lgkmcnt(0)
	v_mfma_f32_16x16x32_bf16 v[60:63], v[146:149], v[212:215], v[60:63]
	v_mfma_f32_16x16x32_bf16 v[56:59], v[188:191], v[212:215], v[56:59]
	v_mfma_f32_16x16x32_bf16 v[44:47], v[146:149], v[222:225], v[44:47]
	v_mfma_f32_16x16x32_bf16 v[40:43], v[188:191], v[222:225], v[40:43]
	v_mfma_f32_16x16x32_bf16 v[28:31], v[146:149], v[230:233], v[28:31]
	v_mfma_f32_16x16x32_bf16 v[24:27], v[188:191], v[230:233], v[24:27]
	v_mfma_f32_16x16x32_bf16 v[12:15], v[146:149], v[238:241], v[12:15]
	v_mfma_f32_16x16x32_bf16 v[8:11], v[188:191], v[238:241], v[8:11]
	v_mfma_f32_16x16x32_bf16 v[60:63], v[150:153], v[216:219], v[60:63]
	v_mfma_f32_16x16x32_bf16 v[56:59], v[192:195], v[216:219], v[56:59]
	v_mfma_f32_16x16x32_bf16 v[44:47], v[150:153], v[226:229], v[44:47]
	v_mfma_f32_16x16x32_bf16 v[40:43], v[192:195], v[226:229], v[40:43]
	v_mfma_f32_16x16x32_bf16 v[28:31], v[150:153], v[234:237], v[28:31]
	v_mfma_f32_16x16x32_bf16 v[24:27], v[192:195], v[234:237], v[24:27]
	v_mfma_f32_16x16x32_bf16 v[12:15], v[150:153], v[242:245], v[12:15]
	v_mfma_f32_16x16x32_bf16 v[8:11], v[192:195], v[242:245], v[8:11]
	s_setprio 0
	s_setprio 1
	v_mfma_f32_16x16x32_bf16 v[52:55], v[196:199], v[212:215], v[52:55]
	s_add_i32 s81, s81, 2
	v_mfma_f32_16x16x32_bf16 v[48:51], v[204:207], v[212:215], v[48:51]
	s_add_u32 s79, s79, 0x100
	v_mfma_f32_16x16x32_bf16 v[36:39], v[196:199], v[222:225], v[36:39]
	s_addc_u32 s80, s80, 0
	v_mfma_f32_16x16x32_bf16 v[32:35], v[204:207], v[222:225], v[32:35]
	s_add_u32 s2, s2, 0x100
	v_mfma_f32_16x16x32_bf16 v[20:23], v[196:199], v[230:233], v[20:23]
	s_addc_u32 s3, s3, 0
	v_mfma_f32_16x16x32_bf16 v[16:19], v[204:207], v[230:233], v[16:19]
	s_cmp_gt_u32 s81, 13
	v_mfma_f32_16x16x32_bf16 v[4:7], v[196:199], v[238:241], v[4:7]
	v_mfma_f32_16x16x32_bf16 v[0:3], v[204:207], v[238:241], v[0:3]
	v_mfma_f32_16x16x32_bf16 v[52:55], v[200:203], v[216:219], v[52:55]
	v_mfma_f32_16x16x32_bf16 v[48:51], v[208:211], v[216:219], v[48:51]
	v_mfma_f32_16x16x32_bf16 v[36:39], v[200:203], v[226:229], v[36:39]
	v_mfma_f32_16x16x32_bf16 v[32:35], v[208:211], v[226:229], v[32:35]
	v_mfma_f32_16x16x32_bf16 v[20:23], v[200:203], v[234:237], v[20:23]
	v_mfma_f32_16x16x32_bf16 v[16:19], v[208:211], v[234:237], v[16:19]
	v_mfma_f32_16x16x32_bf16 v[4:7], v[200:203], v[242:245], v[4:7]
	v_mfma_f32_16x16x32_bf16 v[0:3], v[208:211], v[242:245], v[0:3]
	s_setprio 0
	s_barrier
	s_cbranch_scc0 .LBB0_577

; #define PG8_STAGE(bufoff, gbase, voff) do { _Pragma("unroll") for (int _i = 0; _i < 2; ++_i) \
;         __builtin_amdgcn_global_load_lds((const unsigned*)((const char*)(gbase) + (voff)[_i]), (PG8_LAS unsigned*)(lds + (bufoff) + ldsw + _i * 8192), 16, 0, 0); } while (0)
; #define PG8_LDA(dst, b, h) do { _Pragma("unroll") for (int m = 0; m < 4; ++m) _Pragma("unroll") for (int k = 0; k < 2; ++k) dst[m][k] = *(const PG8_LAS bf16x8*)(lds + PG8_SA(b, h) + aoff + m * 2048 + k * 1024); } while (0)
; #define PG8_LDB(dst, b, h) do { _Pragma("unroll") for (int n = 0; n < 2; ++n) _Pragma("unroll") for (int k = 0; k < 2; ++k) dst[n][k] = *(const PG8_LAS bf16x8*)(lds + PG8_SB(b, h) + boff + n * 2048 + k * 1024); } while (0)
; #define PG8_MMA(ai, bj, At, Bt) do { __builtin_amdgcn_s_setprio(1); _Pragma("unroll") for (int m = 0; m < 4; ++m) _Pragma("unroll") for (int n = 0; n < 2; ++n) _Pragma("unroll") for (int k = 0; k < 2; ++k) \
;         acc[ai][bj][m][n] = __builtin_amdgcn_mfma_f32_16x16x32_bf16(Bt[n][k], At[m][k], acc[ai][bj][m][n], 0, 0, 0); __builtin_amdgcn_s_setprio(0); } while (0)
; #define PG8_WAIT_V(n) asm volatile("s_waitcnt vmcnt(" #n ")" ::: "memory")
; #define PG8_WAIT_L(n) asm volatile("s_waitcnt lgkmcnt(" #n ")" ::: "memory")
; template <class Epi, class Sched>
; __device__ __forceinline__ void gemm_phase(PG8_LAS unsigned char* lds, PG8_LAS unsigned char* xl, const Gemm g, const Sched& S, const Epi& E) {
;     ...
;         const bool has_next = S.next(ui + 1, nxt);
;         const char* nA = has_next ? (const char*)g.A + nxt.aoff : cA; const char* nB = has_next ? (const char*)g.Bt + nxt.boff : cB;
; #pragma unroll 1
;         for (int t = 0; t < nt; t += 2) {
;             const bool last = (t == nt - 2);
;             const char* a1 = cA + (size_t)(t + 1) * kstep;
;             const char* a2 = last ? nA : cA + (size_t)(t + 2) * kstep; const char* b2 = last ? nB : cB + (size_t)(t + 2) * kstep;
;             const char* a3 = a2 + kstep; const char* b3 = b2 + kstep;
;             PG8_LDB(B0, 0, 0); PG8_LDB(B1, 0, 1); PG8_SCHED; PG8_LDA(At, 0, 0); PG8_STAGE(PG8_SA(1, 1), a1 + hsA, voffA);
;             PG8_WAIT_V(8); PG8_WAIT_L(0); PG8_BAR; PG8_MMA(0, 0, At, B0); PG8_MMA(0, 1, At, B1); PG8_BAR; PG8_SCHED;
;             PG8_LDA(At, 0, 1); PG8_STAGE(PG8_SB(0, 0), b2, voffB); PG8_STAGE(PG8_SB(0, 1), b2 + hsB, voffB); PG8_STAGE(PG8_SA(0, 0), a2, voffA);
.LBB0_724:
	s_add_u32 s26, s43, s20
	s_addc_u32 s27, s50, s21
	s_and_b64 s[28:29], s[8:9], exec
	s_cselect_b32 s33, s27, s35
	s_cselect_b32 s46, s26, s34
	s_add_u32 s28, s51, s22
	s_addc_u32 s29, s52, s23
	s_and_b64 s[36:37], s[8:9], exec
	s_cselect_b32 s47, s29, s31
	s_cselect_b32 s72, s28, s30
	s_add_u32 s73, s30, 0x100
	s_addc_u32 s74, s31, 0
	s_add_u32 s30, s34, 0x40080
	v_mov_b32_e32 v0, 0
	s_addc_u32 s31, s35, 0
	s_mov_b32 s75, -2
	s_waitcnt lgkmcnt(0)
	ds_read_b128 v[170:173], v157
	ds_read_b128 v[174:177], v157 offset:1024
	ds_read_b128 v[180:183], v157 offset:2048
	ds_read_b128 v[184:187], v157 offset:3072
	ds_read_b128 v[188:191], v158
	ds_read_b128 v[192:195], v158 offset:1024
	ds_read_b128 v[196:199], v158 offset:2048
	ds_read_b128 v[200:203], v158 offset:3072
	s_add_u32 s34, s30, 0xfffc0080
	s_addc_u32 s35, s31, -1
	s_cmp_eq_u32 s75, 12
	s_cselect_b32 s37, s33, s35
	s_cselect_b32 s36, s46, s34
	s_cselect_b32 s35, s47, s74
	s_cselect_b32 s34, s72, s73
	v_lshl_add_u64 v[144:145], s[30:31], 0, v[138:139]
	s_add_i32 m0, s57, 0xc000
	ds_read_b128 v[204:207], v159
	ds_read_b128 v[208:211], v159 offset:1024
	ds_read_b128 v[212:215], v159 offset:2048
	ds_read_b128 v[216:219], v159 offset:3072
	ds_read_b128 v[222:225], v159 offset:4096
	ds_read_b128 v[226:229], v159 offset:5120
	ds_read_b128 v[230:233], v159 offset:6144
	ds_read_b128 v[234:237], v159 offset:7168
	global_load_lds_dwordx4 v[144:145], off
	v_lshl_add_u64 v[144:145], s[30:31], 0, v[136:137]
	s_add_i32 m0, s57, 0xe000
	s_nop 0
	global_load_lds_dwordx4 v[144:145], off
	s_waitcnt vmcnt(8)
	s_waitcnt lgkmcnt(0)
	s_barrier
	s_setprio 1
	s_waitcnt lgkmcnt(0)
	v_mfma_f32_16x16x32_bf16 v[124:127], v[170:173], v[204:207], 0
	v_mfma_f32_16x16x32_bf16 v[120:123], v[180:183], v[204:207], 0
	v_mfma_f32_16x16x32_bf16 v[108:111], v[170:173], v[212:215], 0
	v_mfma_f32_16x16x32_bf16 v[104:107], v[180:183], v[212:215], 0
	v_mfma_f32_16x16x32_bf16 v[92:95], v[170:173], v[222:225], 0
	v_mfma_f32_16x16x32_bf16 v[88:91], v[180:183], v[222:225], 0
	v_mfma_f32_16x16x32_bf16 v[76:79], v[170:173], v[230:233], 0
	v_mfma_f32_16x16x32_bf16 v[72:75], v[180:183], v[230:233], 0
	v_mfma_f32_16x16x32_bf16 v[124:127], v[174:177], v[208:211], v[124:127]
	v_mfma_f32_16x16x32_bf16 v[120:123], v[184:187], v[208:211], v[120:123]
	v_mfma_f32_16x16x32_bf16 v[108:111], v[174:177], v[216:219], v[108:111]
	v_mfma_f32_16x16x32_bf16 v[104:107], v[184:187], v[216:219], v[104:107]
	v_mfma_f32_16x16x32_bf16 v[92:95], v[174:177], v[226:229], v[92:95]
	v_mfma_f32_16x16x32_bf16 v[88:91], v[184:187], v[226:229], v[88:91]
	v_mfma_f32_16x16x32_bf16 v[76:79], v[174:177], v[234:237], v[76:79]
	v_mfma_f32_16x16x32_bf16 v[72:75], v[184:187], v[234:237], v[72:75]
	s_setprio 0
	s_setprio 1
	v_mfma_f32_16x16x32_bf16 v[116:119], v[188:191], v[204:207], 0
	v_mfma_f32_16x16x32_bf16 v[112:115], v[196:199], v[204:207], 0
	v_mfma_f32_16x16x32_bf16 v[100:103], v[188:191], v[212:215], 0
	v_mfma_f32_16x16x32_bf16 v[96:99], v[196:199], v[212:215], 0
	v_mfma_f32_16x16x32_bf16 v[84:87], v[188:191], v[222:225], 0
	v_mfma_f32_16x16x32_bf16 v[80:83], v[196:199], v[222:225], 0
	v_mfma_f32_16x16x32_bf16 v[68:71], v[188:191], v[230:233], 0
	v_mfma_f32_16x16x32_bf16 v[64:67], v[196:199], v[230:233], 0
	v_mfma_f32_16x16x32_bf16 v[116:119], v[192:195], v[208:211], v[116:119]
	v_mfma_f32_16x16x32_bf16 v[112:115], v[200:203], v[208:211], v[112:115]
	v_mfma_f32_16x16x32_bf16 v[100:103], v[192:195], v[216:219], v[100:103]
	v_mfma_f32_16x16x32_bf16 v[96:99], v[200:203], v[216:219], v[96:99]
	v_mfma_f32_16x16x32_bf16 v[84:87], v[192:195], v[226:229], v[84:87]
	v_mfma_f32_16x16x32_bf16 v[80:83], v[200:203], v[226:229], v[80:83]
	v_mfma_f32_16x16x32_bf16 v[68:71], v[192:195], v[234:237], v[68:71]
	v_mfma_f32_16x16x32_bf16 v[64:67], v[200:203], v[234:237], v[64:67]
	s_setprio 0
	s_barrier
	s_add_i32 s68, s65, s56
	v_lshl_add_u64 v[144:145], s[34:35], 0, v[130:131]
	s_mov_b32 m0, s68
	ds_read_b128 v[204:207], v159 offset:16384
	ds_read_b128 v[208:211], v159 offset:17408
	ds_read_b128 v[212:215], v159 offset:18432
	ds_read_b128 v[216:219], v159 offset:19456
	ds_read_b128 v[222:225], v159 offset:20480
	ds_read_b128 v[226:229], v159 offset:21504
	ds_read_b128 v[230:233], v159 offset:22528
	ds_read_b128 v[234:237], v159 offset:23552
	global_load_lds_dwordx4 v[144:145], off
	s_add_i32 m0, s68, 0x2000
	s_add_u32 s76, s34, 0x40000
	v_lshl_add_u64 v[238:239], s[34:35], 0, v[134:135]
	s_addc_u32 s77, s35, 0
	s_add_i32 s68, s66, s56
	global_load_lds_dwordx4 v[238:239], off
	v_lshl_add_u64 v[240:241], s[76:77], 0, v[130:131]
	s_mov_b32 m0, s68
	v_lshl_add_u64 v[242:243], s[36:37], 0, v[132:133]
	global_load_lds_dwordx4 v[240:241], off
	v_lshl_add_u64 v[240:241], s[76:77], 0, v[134:135]
	s_add_i32 m0, s68, 0x2000
	s_nop 0
	global_load_lds_dwordx4 v[240:241], off
	v_lshl_add_u64 v[240:241], s[36:37], 0, v[128:129]
	s_mov_b32 m0, s57
	s_nop 0
	global_load_lds_dwordx4 v[240:241], off
	s_mov_b32 m0, s58
	s_nop 0
	global_load_lds_dwordx4 v[242:243], off
	s_waitcnt vmcnt(8)
	s_waitcnt lgkmcnt(0)
	s_barrier
; #define PG8_STAGE(bufoff, gbase, voff) do { _Pragma("unroll") for (int _i = 0; _i < 2; ++_i) \
;         __builtin_amdgcn_global_load_lds((const unsigned*)((const char*)(gbase) + (voff)[_i]), (PG8_LAS unsigned*)(lds + (bufoff) + ldsw + _i * 8192), 16, 0, 0); } while (0)
; #define PG8_LDA(dst, b, h) do { _Pragma("unroll") for (int m = 0; m < 4; ++m) _Pragma("unroll") for (int k = 0; k < 2; ++k) dst[m][k] = *(const PG8_LAS bf16x8*)(lds + PG8_SA(b, h) + aoff + m * 2048 + k * 1024); } while (0)
; #define PG8_LDB(dst, b, h) do { _Pragma("unroll") for (int n = 0; n < 2; ++n) _Pragma("unroll") for (int k = 0; k < 2; ++k) dst[n][k] = *(const PG8_LAS bf16x8*)(lds + PG8_SB(b, h) + boff + n * 2048 + k * 1024); } while (0)
; #define PG8_MMA(ai, bj, At, Bt) do { __builtin_amdgcn_s_setprio(1); _Pragma("unroll") for (int m = 0; m < 4; ++m) _Pragma("unroll") for (int n = 0; n < 2; ++n) _Pragma("unroll") for (int k = 0; k < 2; ++k) \
;         acc[ai][bj][m][n] = __builtin_amdgcn_mfma_f32_16x16x32_bf16(Bt[n][k], At[m][k], acc[ai][bj][m][n], 0, 0, 0); __builtin_amdgcn_s_setprio(0); } while (0)
; #define PG8_WAIT_V(n) asm volatile("s_waitcnt vmcnt(" #n ")" ::: "memory")
; #define PG8_WAIT_L(n) asm volatile("s_waitcnt lgkmcnt(" #n ")" ::: "memory")
; #define PG8_BAR __builtin_amdgcn_s_barrier()
; #define PG8_SCHED __builtin_amdgcn_sched_barrier(0)
; template <class Epi, class Sched>
; __device__ __forceinline__ void gemm_phase(PG8_LAS unsigned char* lds, PG8_LAS unsigned char* xl, const Gemm g, const Sched& S, const Epi& E) {
;     ...
;             PG8_WAIT_V(8); PG8_WAIT_L(0); PG8_BAR; PG8_MMA(1, 0, At, B0); PG8_MMA(1, 1, At, B1); PG8_BAR; PG8_SCHED;
;             PG8_LDB(B0, 1, 0); PG8_LDB(B1, 1, 1); PG8_SCHED; PG8_LDA(At, 1, 0); PG8_STAGE(PG8_SA(0, 1), a2 + hsA, voffA);
;             PG8_WAIT_V(8); PG8_WAIT_L(0); PG8_BAR; PG8_MMA(0, 0, At, B0); PG8_MMA(0, 1, At, B1); PG8_BAR; PG8_SCHED;
	s_setprio 1
	s_waitcnt lgkmcnt(0)
	v_mfma_f32_16x16x32_bf16 v[60:63], v[170:173], v[204:207], 0
	v_mfma_f32_16x16x32_bf16 v[56:59], v[180:183], v[204:207], 0
	v_mfma_f32_16x16x32_bf16 v[44:47], v[170:173], v[212:215], 0
	v_mfma_f32_16x16x32_bf16 v[40:43], v[180:183], v[212:215], 0
	v_mfma_f32_16x16x32_bf16 v[28:31], v[170:173], v[222:225], 0
	v_mfma_f32_16x16x32_bf16 v[24:27], v[180:183], v[222:225], 0
	v_mfma_f32_16x16x32_bf16 v[12:15], v[170:173], v[230:233], 0
	v_mfma_f32_16x16x32_bf16 v[8:11], v[180:183], v[230:233], 0
	v_mfma_f32_16x16x32_bf16 v[60:63], v[174:177], v[208:211], v[60:63]
	v_mfma_f32_16x16x32_bf16 v[56:59], v[184:187], v[208:211], v[56:59]
	v_mfma_f32_16x16x32_bf16 v[44:47], v[174:177], v[216:219], v[44:47]
	v_mfma_f32_16x16x32_bf16 v[40:43], v[184:187], v[216:219], v[40:43]
	v_mfma_f32_16x16x32_bf16 v[28:31], v[174:177], v[226:229], v[28:31]
	v_mfma_f32_16x16x32_bf16 v[24:27], v[184:187], v[226:229], v[24:27]
	v_mfma_f32_16x16x32_bf16 v[12:15], v[174:177], v[234:237], v[12:15]
	v_mfma_f32_16x16x32_bf16 v[8:11], v[184:187], v[234:237], v[8:11]
	s_setprio 0
	s_setprio 1
	v_mfma_f32_16x16x32_bf16 v[52:55], v[188:191], v[204:207], 0
	v_mfma_f32_16x16x32_bf16 v[48:51], v[196:199], v[204:207], 0
	v_mfma_f32_16x16x32_bf16 v[36:39], v[188:191], v[212:215], 0
	v_mfma_f32_16x16x32_bf16 v[32:35], v[196:199], v[212:215], 0
	v_mfma_f32_16x16x32_bf16 v[20:23], v[188:191], v[222:225], 0
	v_mfma_f32_16x16x32_bf16 v[16:19], v[196:199], v[222:225], 0
	v_mfma_f32_16x16x32_bf16 v[4:7], v[188:191], v[230:233], 0
	v_mfma_f32_16x16x32_bf16 v[0:3], v[196:199], v[230:233], 0
	v_mfma_f32_16x16x32_bf16 v[52:55], v[192:195], v[208:211], v[52:55]
	v_mfma_f32_16x16x32_bf16 v[48:51], v[200:203], v[208:211], v[48:51]
	v_mfma_f32_16x16x32_bf16 v[36:39], v[192:195], v[216:219], v[36:39]
	v_mfma_f32_16x16x32_bf16 v[32:35], v[200:203], v[216:219], v[32:35]
	v_mfma_f32_16x16x32_bf16 v[20:23], v[192:195], v[226:229], v[20:23]
	v_mfma_f32_16x16x32_bf16 v[16:19], v[200:203], v[226:229], v[16:19]
	v_mfma_f32_16x16x32_bf16 v[4:7], v[192:195], v[234:237], v[4:7]
	v_mfma_f32_16x16x32_bf16 v[0:3], v[200:203], v[234:237], v[0:3]
	s_setprio 0
	s_barrier
	s_add_i32 s68, 0, 0x18000
	v_add_u32_e32 v169, s68, v147
	s_add_i32 s76, 0, 0x1c000
	ds_read_b128 v[170:173], v169
	ds_read_b128 v[174:177], v169 offset:1024
	ds_read_b128 v[180:183], v169 offset:2048
	ds_read_b128 v[184:187], v169 offset:3072
	v_add_u32_e32 v169, s76, v147
	ds_read_b128 v[188:191], v169
	ds_read_b128 v[192:195], v169 offset:1024
	ds_read_b128 v[196:199], v169 offset:2048
	ds_read_b128 v[200:203], v169 offset:3072
	s_add_u32 s36, s36, 0x40000
	s_addc_u32 s37, s37, 0
	s_mov_b32 m0, s59
	v_lshl_add_u64 v[244:245], s[36:37], 0, v[128:129]
	ds_read_b128 v[204:207], v159 offset:32768
	ds_read_b128 v[208:211], v159 offset:33792
	ds_read_b128 v[212:215], v159 offset:34816
	ds_read_b128 v[216:219], v159 offset:35840
	ds_read_b128 v[222:225], v159 offset:36864
	ds_read_b128 v[226:229], v159 offset:37888
	ds_read_b128 v[230:233], v159 offset:38912
	ds_read_b128 v[234:237], v159 offset:39936
	global_load_lds_dwordx4 v[244:245], off
	v_lshl_add_u64 v[244:245], s[36:37], 0, v[132:133]
	s_mov_b32 m0, s60
	s_nop 0
	global_load_lds_dwordx4 v[244:245], off
	s_waitcnt vmcnt(8)
	s_waitcnt lgkmcnt(0)
	s_barrier
	s_setprio 1
	s_waitcnt lgkmcnt(0)
	v_mfma_f32_16x16x32_bf16 v[124:127], v[170:173], v[204:207], v[124:127]
	v_mfma_f32_16x16x32_bf16 v[120:123], v[180:183], v[204:207], v[120:123]
	v_mfma_f32_16x16x32_bf16 v[108:111], v[170:173], v[212:215], v[108:111]
	v_mfma_f32_16x16x32_bf16 v[104:107], v[180:183], v[212:215], v[104:107]
	v_mfma_f32_16x16x32_bf16 v[92:95], v[170:173], v[222:225], v[92:95]
	v_mfma_f32_16x16x32_bf16 v[88:91], v[180:183], v[222:225], v[88:91]
	v_mfma_f32_16x16x32_bf16 v[76:79], v[170:173], v[230:233], v[76:79]
	v_mfma_f32_16x16x32_bf16 v[72:75], v[180:183], v[230:233], v[72:75]
	v_mfma_f32_16x16x32_bf16 v[124:127], v[174:177], v[208:211], v[124:127]
	v_mfma_f32_16x16x32_bf16 v[120:123], v[184:187], v[208:211], v[120:123]
	v_mfma_f32_16x16x32_bf16 v[108:111], v[174:177], v[216:219], v[108:111]
	v_mfma_f32_16x16x32_bf16 v[104:107], v[184:187], v[216:219], v[104:107]
	v_mfma_f32_16x16x32_bf16 v[92:95], v[174:177], v[226:229], v[92:95]
	v_mfma_f32_16x16x32_bf16 v[88:91], v[184:187], v[226:229], v[88:91]
	v_mfma_f32_16x16x32_bf16 v[76:79], v[174:177], v[234:237], v[76:79]
	v_mfma_f32_16x16x32_bf16 v[72:75], v[184:187], v[234:237], v[72:75]
	s_setprio 0
	s_setprio 1
	v_mfma_f32_16x16x32_bf16 v[116:119], v[188:191], v[204:207], v[116:119]
	v_mfma_f32_16x16x32_bf16 v[112:115], v[196:199], v[204:207], v[112:115]
	v_mfma_f32_16x16x32_bf16 v[100:103], v[188:191], v[212:215], v[100:103]
	v_mfma_f32_16x16x32_bf16 v[96:99], v[196:199], v[212:215], v[96:99]
	v_mfma_f32_16x16x32_bf16 v[84:87], v[188:191], v[222:225], v[84:87]
	v_mfma_f32_16x16x32_bf16 v[80:83], v[196:199], v[222:225], v[80:83]
	v_mfma_f32_16x16x32_bf16 v[68:71], v[188:191], v[230:233], v[68:71]
	v_mfma_f32_16x16x32_bf16 v[64:67], v[196:199], v[230:233], v[64:67]
	v_mfma_f32_16x16x32_bf16 v[116:119], v[192:195], v[208:211], v[116:119]
	v_mfma_f32_16x16x32_bf16 v[112:115], v[200:203], v[208:211], v[112:115]
	v_mfma_f32_16x16x32_bf16 v[100:103], v[192:195], v[216:219], v[100:103]
	v_mfma_f32_16x16x32_bf16 v[96:99], v[200:203], v[216:219], v[96:99]
	v_mfma_f32_16x16x32_bf16 v[84:87], v[192:195], v[226:229], v[84:87]
	v_mfma_f32_16x16x32_bf16 v[80:83], v[200:203], v[226:229], v[80:83]
	v_mfma_f32_16x16x32_bf16 v[68:71], v[192:195], v[234:237], v[68:71]
	v_mfma_f32_16x16x32_bf16 v[64:67], v[200:203], v[234:237], v[64:67]
	s_setprio 0
	s_barrier
; #define PG8_STAGE(bufoff, gbase, voff) do { _Pragma("unroll") for (int _i = 0; _i < 2; ++_i) \
;         __builtin_amdgcn_global_load_lds((const unsigned*)((const char*)(gbase) + (voff)[_i]), (PG8_LAS unsigned*)(lds + (bufoff) + ldsw + _i * 8192), 16, 0, 0); } while (0)
; #define PG8_LDA(dst, b, h) do { _Pragma("unroll") for (int m = 0; m < 4; ++m) _Pragma("unroll") for (int k = 0; k < 2; ++k) dst[m][k] = *(const PG8_LAS bf16x8*)(lds + PG8_SA(b, h) + aoff + m * 2048 + k * 1024); } while (0)
; #define PG8_LDB(dst, b, h) do { _Pragma("unroll") for (int n = 0; n < 2; ++n) _Pragma("unroll") for (int k = 0; k < 2; ++k) dst[n][k] = *(const PG8_LAS bf16x8*)(lds + PG8_SB(b, h) + boff + n * 2048 + k * 1024); } while (0)
; #define PG8_MMA(ai, bj, At, Bt) do { __builtin_amdgcn_s_setprio(1); _Pragma("unroll") for (int m = 0; m < 4; ++m) _Pragma("unroll") for (int n = 0; n < 2; ++n) _Pragma("unroll") for (int k = 0; k < 2; ++k) \
;         acc[ai][bj][m][n] = __builtin_amdgcn_mfma_f32_16x16x32_bf16(Bt[n][k], At[m][k], acc[ai][bj][m][n], 0, 0, 0); __builtin_amdgcn_s_setprio(0); } while (0)
; #define PG8_WAIT_V(n) asm volatile("s_waitcnt vmcnt(" #n ")" ::: "memory")
; #define PG8_WAIT_L(n) asm volatile("s_waitcnt lgkmcnt(" #n ")" ::: "memory")
; #define PG8_BAR __builtin_amdgcn_s_barrier()
; #define PG8_SCHED __builtin_amdgcn_sched_barrier(0)
; template <class Epi, class Sched>
; __device__ __forceinline__ void gemm_phase(PG8_LAS unsigned char* lds, PG8_LAS unsigned char* xl, const Gemm g, const Sched& S, const Epi& E) {
;     ...
;         for (int t = 0; t < nt; t += 2) {
;             const bool last = (t == nt - 2);
;             const char* a1 = cA + (size_t)(t + 1) * kstep;
;             const char* a2 = last ? nA : cA + (size_t)(t + 2) * kstep; const char* b2 = last ? nB : cB + (size_t)(t + 2) * kstep;
;             const char* a3 = a2 + kstep; const char* b3 = b2 + kstep;
;             PG8_LDB(B0, 0, 0); PG8_LDB(B1, 0, 1); PG8_SCHED; PG8_LDA(At, 0, 0); PG8_STAGE(PG8_SA(1, 1), a1 + hsA, voffA);
;     ...
;             PG8_LDA(At, 1, 1); PG8_STAGE(PG8_SB(1, 0), b3, voffB); PG8_STAGE(PG8_SB(1, 1), b3 + hsB, voffB); PG8_STAGE(PG8_SA(1, 0), a3, voffA);
;             PG8_WAIT_V(8); PG8_WAIT_L(0); PG8_BAR; PG8_MMA(1, 0, At, B0); PG8_MMA(1, 1, At, B1); PG8_BAR; PG8_SCHED;
	s_add_i32 s36, s68, s56
	v_lshl_add_u64 v[144:145], v[144:145], 0, s[16:17]
	s_mov_b32 m0, s36
	ds_read_b128 v[204:207], v159 offset:49152
	ds_read_b128 v[208:211], v159 offset:50176
	ds_read_b128 v[212:215], v159 offset:51200
	ds_read_b128 v[216:219], v159 offset:52224
	ds_read_b128 v[222:225], v159 offset:53248
	ds_read_b128 v[226:229], v159 offset:54272
	ds_read_b128 v[230:233], v159 offset:55296
	ds_read_b128 v[234:237], v159 offset:56320
	global_load_lds_dwordx4 v[144:145], off
	s_add_i32 m0, s36, 0x2000
	s_add_u32 s34, s34, 0x40080
	v_lshl_add_u64 v[144:145], v[238:239], 0, s[16:17]
	s_addc_u32 s35, s35, 0
	s_add_i32 s36, s76, s56
	global_load_lds_dwordx4 v[144:145], off
	v_lshl_add_u64 v[144:145], s[34:35], 0, v[130:131]
	s_mov_b32 m0, s36
	s_nop 0
	global_load_lds_dwordx4 v[144:145], off
	v_lshl_add_u64 v[144:145], s[34:35], 0, v[134:135]
	s_add_i32 m0, s36, 0x2000
	s_nop 0
	global_load_lds_dwordx4 v[144:145], off
	v_lshl_add_u64 v[144:145], v[240:241], 0, s[16:17]
	s_mov_b32 m0, s62
	s_nop 0
	global_load_lds_dwordx4 v[144:145], off
	v_lshl_add_u64 v[144:145], v[242:243], 0, s[16:17]
	s_mov_b32 m0, s63
	s_nop 0
	global_load_lds_dwordx4 v[144:145], off
	s_waitcnt vmcnt(8)
	s_waitcnt lgkmcnt(0)
	s_barrier
	s_setprio 1
	s_waitcnt lgkmcnt(0)
	v_mfma_f32_16x16x32_bf16 v[60:63], v[170:173], v[204:207], v[60:63]
	v_mfma_f32_16x16x32_bf16 v[56:59], v[180:183], v[204:207], v[56:59]
	v_mfma_f32_16x16x32_bf16 v[44:47], v[170:173], v[212:215], v[44:47]
	v_mfma_f32_16x16x32_bf16 v[40:43], v[180:183], v[212:215], v[40:43]
	v_mfma_f32_16x16x32_bf16 v[28:31], v[170:173], v[222:225], v[28:31]
	v_mfma_f32_16x16x32_bf16 v[24:27], v[180:183], v[222:225], v[24:27]
	v_mfma_f32_16x16x32_bf16 v[12:15], v[170:173], v[230:233], v[12:15]
	v_mfma_f32_16x16x32_bf16 v[8:11], v[180:183], v[230:233], v[8:11]
	v_mfma_f32_16x16x32_bf16 v[60:63], v[174:177], v[208:211], v[60:63]
	v_mfma_f32_16x16x32_bf16 v[56:59], v[184:187], v[208:211], v[56:59]
	v_mfma_f32_16x16x32_bf16 v[44:47], v[174:177], v[216:219], v[44:47]
	v_mfma_f32_16x16x32_bf16 v[40:43], v[184:187], v[216:219], v[40:43]
	v_mfma_f32_16x16x32_bf16 v[28:31], v[174:177], v[226:229], v[28:31]
	v_mfma_f32_16x16x32_bf16 v[24:27], v[184:187], v[226:229], v[24:27]
	v_mfma_f32_16x16x32_bf16 v[12:15], v[174:177], v[234:237], v[12:15]
	v_mfma_f32_16x16x32_bf16 v[8:11], v[184:187], v[234:237], v[8:11]
	s_setprio 0
	s_setprio 1
	v_mfma_f32_16x16x32_bf16 v[52:55], v[188:191], v[204:207], v[52:55]
	s_add_i32 s75, s75, 2
	v_mfma_f32_16x16x32_bf16 v[48:51], v[196:199], v[204:207], v[48:51]
	s_add_u32 s73, s73, 0x100
	v_mfma_f32_16x16x32_bf16 v[36:39], v[188:191], v[212:215], v[36:39]
	s_addc_u32 s74, s74, 0
	v_mfma_f32_16x16x32_bf16 v[32:35], v[196:199], v[212:215], v[32:35]
	s_add_u32 s30, s30, 0x100
	v_mfma_f32_16x16x32_bf16 v[20:23], v[188:191], v[222:225], v[20:23]
	s_addc_u32 s31, s31, 0
	v_mfma_f32_16x16x32_bf16 v[16:19], v[196:199], v[222:225], v[16:19]
	s_cmp_gt_u32 s75, 13
	v_mfma_f32_16x16x32_bf16 v[4:7], v[188:191], v[230:233], v[4:7]
	v_mfma_f32_16x16x32_bf16 v[0:3], v[196:199], v[230:233], v[0:3]
	v_mfma_f32_16x16x32_bf16 v[52:55], v[192:195], v[208:211], v[52:55]
	v_mfma_f32_16x16x32_bf16 v[48:51], v[200:203], v[208:211], v[48:51]
	v_mfma_f32_16x16x32_bf16 v[36:39], v[192:195], v[216:219], v[36:39]
	v_mfma_f32_16x16x32_bf16 v[32:35], v[200:203], v[216:219], v[32:35]
	v_mfma_f32_16x16x32_bf16 v[20:23], v[192:195], v[226:229], v[20:23]
	v_mfma_f32_16x16x32_bf16 v[16:19], v[200:203], v[226:229], v[16:19]
	v_mfma_f32_16x16x32_bf16 v[4:7], v[192:195], v[234:237], v[4:7]
	v_mfma_f32_16x16x32_bf16 v[0:3], v[200:203], v[234:237], v[0:3]
	s_setprio 0
	s_barrier
	s_cbranch_scc1 .Lpeel_after_P7
.LBB0_725:
	ds_read_b128 v[170:173], v157
	ds_read_b128 v[174:177], v157 offset:1024
	ds_read_b128 v[180:183], v157 offset:2048
	ds_read_b128 v[184:187], v157 offset:3072
	ds_read_b128 v[188:191], v158
	ds_read_b128 v[192:195], v158 offset:1024
	ds_read_b128 v[196:199], v158 offset:2048
	ds_read_b128 v[200:203], v158 offset:3072
	s_add_u32 s34, s30, 0xfffc0080
	s_addc_u32 s35, s31, -1
	s_cmp_eq_u32 s75, 12
	s_cselect_b32 s37, s33, s35
	s_cselect_b32 s36, s46, s34
	s_cselect_b32 s35, s47, s74
	s_cselect_b32 s34, s72, s73
	v_lshl_add_u64 v[144:145], s[30:31], 0, v[138:139]
	s_add_i32 m0, s57, 0xc000
	ds_read_b128 v[204:207], v159
	ds_read_b128 v[208:211], v159 offset:1024
	ds_read_b128 v[212:215], v159 offset:2048
	ds_read_b128 v[216:219], v159 offset:3072
	ds_read_b128 v[222:225], v159 offset:4096
	ds_read_b128 v[226:229], v159 offset:5120
	ds_read_b128 v[230:233], v159 offset:6144
	ds_read_b128 v[234:237], v159 offset:7168
	global_load_lds_dwordx4 v[144:145], off
	v_lshl_add_u64 v[144:145], s[30:31], 0, v[136:137]
	s_add_i32 m0, s57, 0xe000
	s_nop 0
	global_load_lds_dwordx4 v[144:145], off
	s_waitcnt vmcnt(8)
	s_waitcnt lgkmcnt(0)
	s_barrier
; #define PG8_STAGE(bufoff, gbase, voff) do { _Pragma("unroll") for (int _i = 0; _i < 2; ++_i) \
;         __builtin_amdgcn_global_load_lds((const unsigned*)((const char*)(gbase) + (voff)[_i]), (PG8_LAS unsigned*)(lds + (bufoff) + ldsw + _i * 8192), 16, 0, 0); } while (0)
; #define PG8_LDA(dst, b, h) do { _Pragma("unroll") for (int m = 0; m < 4; ++m) _Pragma("unroll") for (int k = 0; k < 2; ++k) dst[m][k] = *(const PG8_LAS bf16x8*)(lds + PG8_SA(b, h) + aoff + m * 2048 + k * 1024); } while (0)
; #define PG8_MMA(ai, bj, At, Bt) do { __builtin_amdgcn_s_setprio(1); _Pragma("unroll") for (int m = 0; m < 4; ++m) _Pragma("unroll") for (int n = 0; n < 2; ++n) _Pragma("unroll") for (int k = 0; k < 2; ++k) \
;         acc[ai][bj][m][n] = __builtin_amdgcn_mfma_f32_16x16x32_bf16(Bt[n][k], At[m][k], acc[ai][bj][m][n], 0, 0, 0); __builtin_amdgcn_s_setprio(0); } while (0)
; #define PG8_WAIT_V(n) asm volatile("s_waitcnt vmcnt(" #n ")" ::: "memory")
; #define PG8_WAIT_L(n) asm volatile("s_waitcnt lgkmcnt(" #n ")" ::: "memory")
; #define PG8_BAR __builtin_amdgcn_s_barrier()
; #define PG8_SCHED __builtin_amdgcn_sched_barrier(0)
; template <class Epi, class Sched>
; __device__ __forceinline__ void gemm_phase(PG8_LAS unsigned char* lds, PG8_LAS unsigned char* xl, const Gemm g, const Sched& S, const Epi& E) {
;     ...
;             PG8_WAIT_V(8); PG8_WAIT_L(0); PG8_BAR; PG8_MMA(0, 0, At, B0); PG8_MMA(0, 1, At, B1); PG8_BAR; PG8_SCHED;
;             PG8_LDA(At, 0, 1); PG8_STAGE(PG8_SB(0, 0), b2, voffB); PG8_STAGE(PG8_SB(0, 1), b2 + hsB, voffB); PG8_STAGE(PG8_SA(0, 0), a2, voffA);
;             PG8_WAIT_V(8); PG8_WAIT_L(0); PG8_BAR; PG8_MMA(1, 0, At, B0); PG8_MMA(1, 1, At, B1); PG8_BAR; PG8_SCHED;
	s_setprio 1
	s_waitcnt lgkmcnt(0)
	v_mfma_f32_16x16x32_bf16 v[124:127], v[170:173], v[204:207], v[124:127]
	v_mfma_f32_16x16x32_bf16 v[120:123], v[180:183], v[204:207], v[120:123]
	v_mfma_f32_16x16x32_bf16 v[108:111], v[170:173], v[212:215], v[108:111]
	v_mfma_f32_16x16x32_bf16 v[104:107], v[180:183], v[212:215], v[104:107]
	v_mfma_f32_16x16x32_bf16 v[92:95], v[170:173], v[222:225], v[92:95]
	v_mfma_f32_16x16x32_bf16 v[88:91], v[180:183], v[222:225], v[88:91]
	v_mfma_f32_16x16x32_bf16 v[76:79], v[170:173], v[230:233], v[76:79]
	v_mfma_f32_16x16x32_bf16 v[72:75], v[180:183], v[230:233], v[72:75]
	v_mfma_f32_16x16x32_bf16 v[124:127], v[174:177], v[208:211], v[124:127]
	v_mfma_f32_16x16x32_bf16 v[120:123], v[184:187], v[208:211], v[120:123]
	v_mfma_f32_16x16x32_bf16 v[108:111], v[174:177], v[216:219], v[108:111]
	v_mfma_f32_16x16x32_bf16 v[104:107], v[184:187], v[216:219], v[104:107]
	v_mfma_f32_16x16x32_bf16 v[92:95], v[174:177], v[226:229], v[92:95]
	v_mfma_f32_16x16x32_bf16 v[88:91], v[184:187], v[226:229], v[88:91]
	v_mfma_f32_16x16x32_bf16 v[76:79], v[174:177], v[234:237], v[76:79]
	v_mfma_f32_16x16x32_bf16 v[72:75], v[184:187], v[234:237], v[72:75]
	s_setprio 0
	s_setprio 1
	v_mfma_f32_16x16x32_bf16 v[116:119], v[188:191], v[204:207], v[116:119]
	v_mfma_f32_16x16x32_bf16 v[112:115], v[196:199], v[204:207], v[112:115]
	v_mfma_f32_16x16x32_bf16 v[100:103], v[188:191], v[212:215], v[100:103]
	v_mfma_f32_16x16x32_bf16 v[96:99], v[196:199], v[212:215], v[96:99]
	v_mfma_f32_16x16x32_bf16 v[84:87], v[188:191], v[222:225], v[84:87]
	v_mfma_f32_16x16x32_bf16 v[80:83], v[196:199], v[222:225], v[80:83]
	v_mfma_f32_16x16x32_bf16 v[68:71], v[188:191], v[230:233], v[68:71]
	v_mfma_f32_16x16x32_bf16 v[64:67], v[196:199], v[230:233], v[64:67]
	v_mfma_f32_16x16x32_bf16 v[116:119], v[192:195], v[208:211], v[116:119]
	v_mfma_f32_16x16x32_bf16 v[112:115], v[200:203], v[208:211], v[112:115]
	v_mfma_f32_16x16x32_bf16 v[100:103], v[192:195], v[216:219], v[100:103]
	v_mfma_f32_16x16x32_bf16 v[96:99], v[200:203], v[216:219], v[96:99]
	v_mfma_f32_16x16x32_bf16 v[84:87], v[192:195], v[226:229], v[84:87]
	v_mfma_f32_16x16x32_bf16 v[80:83], v[200:203], v[226:229], v[80:83]
	v_mfma_f32_16x16x32_bf16 v[68:71], v[192:195], v[234:237], v[68:71]
	v_mfma_f32_16x16x32_bf16 v[64:67], v[200:203], v[234:237], v[64:67]
	s_setprio 0
	s_barrier
	s_add_i32 s68, s65, s56
	v_lshl_add_u64 v[144:145], s[34:35], 0, v[130:131]
	s_mov_b32 m0, s68
	ds_read_b128 v[204:207], v159 offset:16384
	ds_read_b128 v[208:211], v159 offset:17408
	ds_read_b128 v[212:215], v159 offset:18432
	ds_read_b128 v[216:219], v159 offset:19456
	ds_read_b128 v[222:225], v159 offset:20480
	ds_read_b128 v[226:229], v159 offset:21504
	ds_read_b128 v[230:233], v159 offset:22528
	ds_read_b128 v[234:237], v159 offset:23552
	global_load_lds_dwordx4 v[144:145], off
	s_add_i32 m0, s68, 0x2000
	s_add_u32 s76, s34, 0x40000
	v_lshl_add_u64 v[238:239], s[34:35], 0, v[134:135]
	s_addc_u32 s77, s35, 0
	s_add_i32 s68, s66, s56
	global_load_lds_dwordx4 v[238:239], off
	v_lshl_add_u64 v[240:241], s[76:77], 0, v[130:131]
	s_mov_b32 m0, s68
	v_lshl_add_u64 v[242:243], s[36:37], 0, v[132:133]
	global_load_lds_dwordx4 v[240:241], off
	v_lshl_add_u64 v[240:241], s[76:77], 0, v[134:135]
	s_add_i32 m0, s68, 0x2000
	s_nop 0
	global_load_lds_dwordx4 v[240:241], off
	v_lshl_add_u64 v[240:241], s[36:37], 0, v[128:129]
	s_mov_b32 m0, s57
	s_nop 0
	global_load_lds_dwordx4 v[240:241], off
	s_mov_b32 m0, s58
	s_nop 0
	global_load_lds_dwordx4 v[242:243], off
	s_waitcnt vmcnt(8)
	s_waitcnt lgkmcnt(0)
	s_barrier
	s_setprio 1
	s_waitcnt lgkmcnt(0)
	v_mfma_f32_16x16x32_bf16 v[60:63], v[170:173], v[204:207], v[60:63]
	v_mfma_f32_16x16x32_bf16 v[56:59], v[180:183], v[204:207], v[56:59]
	v_mfma_f32_16x16x32_bf16 v[44:47], v[170:173], v[212:215], v[44:47]
	v_mfma_f32_16x16x32_bf16 v[40:43], v[180:183], v[212:215], v[40:43]
	v_mfma_f32_16x16x32_bf16 v[28:31], v[170:173], v[222:225], v[28:31]
	v_mfma_f32_16x16x32_bf16 v[24:27], v[180:183], v[222:225], v[24:27]
	v_mfma_f32_16x16x32_bf16 v[12:15], v[170:173], v[230:233], v[12:15]
	v_mfma_f32_16x16x32_bf16 v[8:11], v[180:183], v[230:233], v[8:11]
	v_mfma_f32_16x16x32_bf16 v[60:63], v[174:177], v[208:211], v[60:63]
	v_mfma_f32_16x16x32_bf16 v[56:59], v[184:187], v[208:211], v[56:59]
	v_mfma_f32_16x16x32_bf16 v[44:47], v[174:177], v[216:219], v[44:47]
	v_mfma_f32_16x16x32_bf16 v[40:43], v[184:187], v[216:219], v[40:43]
	v_mfma_f32_16x16x32_bf16 v[28:31], v[174:177], v[226:229], v[28:31]
	v_mfma_f32_16x16x32_bf16 v[24:27], v[184:187], v[226:229], v[24:27]
	v_mfma_f32_16x16x32_bf16 v[12:15], v[174:177], v[234:237], v[12:15]
	v_mfma_f32_16x16x32_bf16 v[8:11], v[184:187], v[234:237], v[8:11]
	s_setprio 0
	s_setprio 1
	v_mfma_f32_16x16x32_bf16 v[52:55], v[188:191], v[204:207], v[52:55]
	v_mfma_f32_16x16x32_bf16 v[48:51], v[196:199], v[204:207], v[48:51]
	v_mfma_f32_16x16x32_bf16 v[36:39], v[188:191], v[212:215], v[36:39]
	v_mfma_f32_16x16x32_bf16 v[32:35], v[196:199], v[212:215], v[32:35]
	v_mfma_f32_16x16x32_bf16 v[20:23], v[188:191], v[222:225], v[20:23]
	v_mfma_f32_16x16x32_bf16 v[16:19], v[196:199], v[222:225], v[16:19]
	v_mfma_f32_16x16x32_bf16 v[4:7], v[188:191], v[230:233], v[4:7]
	v_mfma_f32_16x16x32_bf16 v[0:3], v[196:199], v[230:233], v[0:3]
	v_mfma_f32_16x16x32_bf16 v[52:55], v[192:195], v[208:211], v[52:55]
	v_mfma_f32_16x16x32_bf16 v[48:51], v[200:203], v[208:211], v[48:51]
	v_mfma_f32_16x16x32_bf16 v[36:39], v[192:195], v[216:219], v[36:39]
	v_mfma_f32_16x16x32_bf16 v[32:35], v[200:203], v[216:219], v[32:35]
	v_mfma_f32_16x16x32_bf16 v[20:23], v[192:195], v[226:229], v[20:23]
	v_mfma_f32_16x16x32_bf16 v[16:19], v[200:203], v[226:229], v[16:19]
	v_mfma_f32_16x16x32_bf16 v[4:7], v[192:195], v[234:237], v[4:7]
	v_mfma_f32_16x16x32_bf16 v[0:3], v[200:203], v[234:237], v[0:3]
	s_setprio 0
	s_barrier
; #define PG8_STAGE(bufoff, gbase, voff) do { _Pragma("unroll") for (int _i = 0; _i < 2; ++_i) \
;         __builtin_amdgcn_global_load_lds((const unsigned*)((const char*)(gbase) + (voff)[_i]), (PG8_LAS unsigned*)(lds + (bufoff) + ldsw + _i * 8192), 16, 0, 0); } while (0)
; #define PG8_LDA(dst, b, h) do { _Pragma("unroll") for (int m = 0; m < 4; ++m) _Pragma("unroll") for (int k = 0; k < 2; ++k) dst[m][k] = *(const PG8_LAS bf16x8*)(lds + PG8_SA(b, h) + aoff + m * 2048 + k * 1024); } while (0)
; #define PG8_LDB(dst, b, h) do { _Pragma("unroll") for (int n = 0; n < 2; ++n) _Pragma("unroll") for (int k = 0; k < 2; ++k) dst[n][k] = *(const PG8_LAS bf16x8*)(lds + PG8_SB(b, h) + boff + n * 2048 + k * 1024); } while (0)
; #define PG8_MMA(ai, bj, At, Bt) do { __builtin_amdgcn_s_setprio(1); _Pragma("unroll") for (int m = 0; m < 4; ++m) _Pragma("unroll") for (int n = 0; n < 2; ++n) _Pragma("unroll") for (int k = 0; k < 2; ++k) \
;         acc[ai][bj][m][n] = __builtin_amdgcn_mfma_f32_16x16x32_bf16(Bt[n][k], At[m][k], acc[ai][bj][m][n], 0, 0, 0); __builtin_amdgcn_s_setprio(0); } while (0)
; #define PG8_WAIT_V(n) asm volatile("s_waitcnt vmcnt(" #n ")" ::: "memory")
; #define PG8_WAIT_L(n) asm volatile("s_waitcnt lgkmcnt(" #n ")" ::: "memory")
; #define PG8_BAR __builtin_amdgcn_s_barrier()
; #define PG8_SCHED __builtin_amdgcn_sched_barrier(0)
; template <class Epi, class Sched>
; __device__ __forceinline__ void gemm_phase(PG8_LAS unsigned char* lds, PG8_LAS unsigned char* xl, const Gemm g, const Sched& S, const Epi& E) {
;     ...
;             PG8_LDB(B0, 1, 0); PG8_LDB(B1, 1, 1); PG8_SCHED; PG8_LDA(At, 1, 0); PG8_STAGE(PG8_SA(0, 1), a2 + hsA, voffA);
;             PG8_WAIT_V(8); PG8_WAIT_L(0); PG8_BAR; PG8_MMA(0, 0, At, B0); PG8_MMA(0, 1, At, B1); PG8_BAR; PG8_SCHED;
	s_add_i32 s68, 0, 0x18000
	v_add_u32_e32 v169, s68, v147
	s_add_i32 s76, 0, 0x1c000
	ds_read_b128 v[170:173], v169
	ds_read_b128 v[174:177], v169 offset:1024
	ds_read_b128 v[180:183], v169 offset:2048
	ds_read_b128 v[184:187], v169 offset:3072
	v_add_u32_e32 v169, s76, v147
	ds_read_b128 v[188:191], v169
	ds_read_b128 v[192:195], v169 offset:1024
	ds_read_b128 v[196:199], v169 offset:2048
	ds_read_b128 v[200:203], v169 offset:3072
	s_add_u32 s36, s36, 0x40000
	s_addc_u32 s37, s37, 0
	s_mov_b32 m0, s59
	v_lshl_add_u64 v[244:245], s[36:37], 0, v[128:129]
	ds_read_b128 v[204:207], v159 offset:32768
	ds_read_b128 v[208:211], v159 offset:33792
	ds_read_b128 v[212:215], v159 offset:34816
	ds_read_b128 v[216:219], v159 offset:35840
	ds_read_b128 v[222:225], v159 offset:36864
	ds_read_b128 v[226:229], v159 offset:37888
	ds_read_b128 v[230:233], v159 offset:38912
	ds_read_b128 v[234:237], v159 offset:39936
	global_load_lds_dwordx4 v[244:245], off
	v_lshl_add_u64 v[244:245], s[36:37], 0, v[132:133]
	s_mov_b32 m0, s60
	s_nop 0
	global_load_lds_dwordx4 v[244:245], off
	s_waitcnt vmcnt(8)
	s_waitcnt lgkmcnt(0)
	s_barrier
	s_setprio 1
	s_waitcnt lgkmcnt(0)
	v_mfma_f32_16x16x32_bf16 v[124:127], v[170:173], v[204:207], v[124:127]
	v_mfma_f32_16x16x32_bf16 v[120:123], v[180:183], v[204:207], v[120:123]
	v_mfma_f32_16x16x32_bf16 v[108:111], v[170:173], v[212:215], v[108:111]
	v_mfma_f32_16x16x32_bf16 v[104:107], v[180:183], v[212:215], v[104:107]
	v_mfma_f32_16x16x32_bf16 v[92:95], v[170:173], v[222:225], v[92:95]
	v_mfma_f32_16x16x32_bf16 v[88:91], v[180:183], v[222:225], v[88:91]
	v_mfma_f32_16x16x32_bf16 v[76:79], v[170:173], v[230:233], v[76:79]
	v_mfma_f32_16x16x32_bf16 v[72:75], v[180:183], v[230:233], v[72:75]
	v_mfma_f32_16x16x32_bf16 v[124:127], v[174:177], v[208:211], v[124:127]
	v_mfma_f32_16x16x32_bf16 v[120:123], v[184:187], v[208:211], v[120:123]
	v_mfma_f32_16x16x32_bf16 v[108:111], v[174:177], v[216:219], v[108:111]
	v_mfma_f32_16x16x32_bf16 v[104:107], v[184:187], v[216:219], v[104:107]
	v_mfma_f32_16x16x32_bf16 v[92:95], v[174:177], v[226:229], v[92:95]
	v_mfma_f32_16x16x32_bf16 v[88:91], v[184:187], v[226:229], v[88:91]
	v_mfma_f32_16x16x32_bf16 v[76:79], v[174:177], v[234:237], v[76:79]
	v_mfma_f32_16x16x32_bf16 v[72:75], v[184:187], v[234:237], v[72:75]
	s_setprio 0
	s_setprio 1
	v_mfma_f32_16x16x32_bf16 v[116:119], v[188:191], v[204:207], v[116:119]
	v_mfma_f32_16x16x32_bf16 v[112:115], v[196:199], v[204:207], v[112:115]
	v_mfma_f32_16x16x32_bf16 v[100:103], v[188:191], v[212:215], v[100:103]
	v_mfma_f32_16x16x32_bf16 v[96:99], v[196:199], v[212:215], v[96:99]
	v_mfma_f32_16x16x32_bf16 v[84:87], v[188:191], v[222:225], v[84:87]
	v_mfma_f32_16x16x32_bf16 v[80:83], v[196:199], v[222:225], v[80:83]
	v_mfma_f32_16x16x32_bf16 v[68:71], v[188:191], v[230:233], v[68:71]
	v_mfma_f32_16x16x32_bf16 v[64:67], v[196:199], v[230:233], v[64:67]
	v_mfma_f32_16x16x32_bf16 v[116:119], v[192:195], v[208:211], v[116:119]
	v_mfma_f32_16x16x32_bf16 v[112:115], v[200:203], v[208:211], v[112:115]
	v_mfma_f32_16x16x32_bf16 v[100:103], v[192:195], v[216:219], v[100:103]
	v_mfma_f32_16x16x32_bf16 v[96:99], v[200:203], v[216:219], v[96:99]
	v_mfma_f32_16x16x32_bf16 v[84:87], v[192:195], v[226:229], v[84:87]
	v_mfma_f32_16x16x32_bf16 v[80:83], v[200:203], v[226:229], v[80:83]
	v_mfma_f32_16x16x32_bf16 v[68:71], v[192:195], v[234:237], v[68:71]
	v_mfma_f32_16x16x32_bf16 v[64:67], v[200:203], v[234:237], v[64:67]
	s_setprio 0
	s_barrier
; #define PG8_STAGE(bufoff, gbase, voff) do { _Pragma("unroll") for (int _i = 0; _i < 2; ++_i) \
;         __builtin_amdgcn_global_load_lds((const unsigned*)((const char*)(gbase) + (voff)[_i]), (PG8_LAS unsigned*)(lds + (bufoff) + ldsw + _i * 8192), 16, 0, 0); } while (0)
; #define PG8_LDA(dst, b, h) do { _Pragma("unroll") for (int m = 0; m < 4; ++m) _Pragma("unroll") for (int k = 0; k < 2; ++k) dst[m][k] = *(const PG8_LAS bf16x8*)(lds + PG8_SA(b, h) + aoff + m * 2048 + k * 1024); } while (0)
; #define PG8_MMA(ai, bj, At, Bt) do { __builtin_amdgcn_s_setprio(1); _Pragma("unroll") for (int m = 0; m < 4; ++m) _Pragma("unroll") for (int n = 0; n < 2; ++n) _Pragma("unroll") for (int k = 0; k < 2; ++k) \
;         acc[ai][bj][m][n] = __builtin_amdgcn_mfma_f32_16x16x32_bf16(Bt[n][k], At[m][k], acc[ai][bj][m][n], 0, 0, 0); __builtin_amdgcn_s_setprio(0); } while (0)
; #define PG8_WAIT_V(n) asm volatile("s_waitcnt vmcnt(" #n ")" ::: "memory")
; #define PG8_WAIT_L(n) asm volatile("s_waitcnt lgkmcnt(" #n ")" ::: "memory")
; #define PG8_BAR __builtin_amdgcn_s_barrier()
; #define PG8_SCHED __builtin_amdgcn_sched_barrier(0)
; template <class Epi, class Sched>
; __device__ __forceinline__ void gemm_phase(PG8_LAS unsigned char* lds, PG8_LAS unsigned char* xl, const Gemm g, const Sched& S, const Epi& E) {
;     ...
;             PG8_LDA(At, 1, 1); PG8_STAGE(PG8_SB(1, 0), b3, voffB); PG8_STAGE(PG8_SB(1, 1), b3 + hsB, voffB); PG8_STAGE(PG8_SA(1, 0), a3, voffA);
;             PG8_WAIT_V(8); PG8_WAIT_L(0); PG8_BAR; PG8_MMA(1, 0, At, B0); PG8_MMA(1, 1, At, B1); PG8_BAR; PG8_SCHED;
	s_add_i32 s36, s68, s56
	v_lshl_add_u64 v[144:145], v[144:145], 0, s[16:17]
	s_mov_b32 m0, s36
	ds_read_b128 v[204:207], v159 offset:49152
	ds_read_b128 v[208:211], v159 offset:50176
	ds_read_b128 v[212:215], v159 offset:51200
	ds_read_b128 v[216:219], v159 offset:52224
	ds_read_b128 v[222:225], v159 offset:53248
	ds_read_b128 v[226:229], v159 offset:54272
	ds_read_b128 v[230:233], v159 offset:55296
	ds_read_b128 v[234:237], v159 offset:56320
	global_load_lds_dwordx4 v[144:145], off
	s_add_i32 m0, s36, 0x2000
	s_add_u32 s34, s34, 0x40080
	v_lshl_add_u64 v[144:145], v[238:239], 0, s[16:17]
	s_addc_u32 s35, s35, 0
	s_add_i32 s36, s76, s56
	global_load_lds_dwordx4 v[144:145], off
	v_lshl_add_u64 v[144:145], s[34:35], 0, v[130:131]
	s_mov_b32 m0, s36
	s_nop 0
	global_load_lds_dwordx4 v[144:145], off
	v_lshl_add_u64 v[144:145], s[34:35], 0, v[134:135]
	s_add_i32 m0, s36, 0x2000
	s_nop 0
	global_load_lds_dwordx4 v[144:145], off
	v_lshl_add_u64 v[144:145], v[240:241], 0, s[16:17]
	s_mov_b32 m0, s62
	s_nop 0
	global_load_lds_dwordx4 v[144:145], off
	v_lshl_add_u64 v[144:145], v[242:243], 0, s[16:17]
	s_mov_b32 m0, s63
	s_nop 0
	global_load_lds_dwordx4 v[144:145], off
	s_waitcnt vmcnt(8)
	s_waitcnt lgkmcnt(0)
	s_barrier
	s_setprio 1
	s_waitcnt lgkmcnt(0)
	v_mfma_f32_16x16x32_bf16 v[60:63], v[170:173], v[204:207], v[60:63]
	v_mfma_f32_16x16x32_bf16 v[56:59], v[180:183], v[204:207], v[56:59]
	v_mfma_f32_16x16x32_bf16 v[44:47], v[170:173], v[212:215], v[44:47]
	v_mfma_f32_16x16x32_bf16 v[40:43], v[180:183], v[212:215], v[40:43]
	v_mfma_f32_16x16x32_bf16 v[28:31], v[170:173], v[222:225], v[28:31]
	v_mfma_f32_16x16x32_bf16 v[24:27], v[180:183], v[222:225], v[24:27]
	v_mfma_f32_16x16x32_bf16 v[12:15], v[170:173], v[230:233], v[12:15]
	v_mfma_f32_16x16x32_bf16 v[8:11], v[180:183], v[230:233], v[8:11]
	v_mfma_f32_16x16x32_bf16 v[60:63], v[174:177], v[208:211], v[60:63]
	v_mfma_f32_16x16x32_bf16 v[56:59], v[184:187], v[208:211], v[56:59]
	v_mfma_f32_16x16x32_bf16 v[44:47], v[174:177], v[216:219], v[44:47]
	v_mfma_f32_16x16x32_bf16 v[40:43], v[184:187], v[216:219], v[40:43]
	v_mfma_f32_16x16x32_bf16 v[28:31], v[174:177], v[226:229], v[28:31]
	v_mfma_f32_16x16x32_bf16 v[24:27], v[184:187], v[226:229], v[24:27]
	v_mfma_f32_16x16x32_bf16 v[12:15], v[174:177], v[234:237], v[12:15]
	v_mfma_f32_16x16x32_bf16 v[8:11], v[184:187], v[234:237], v[8:11]
	s_setprio 0
	s_setprio 1
	v_mfma_f32_16x16x32_bf16 v[52:55], v[188:191], v[204:207], v[52:55]
	s_add_i32 s75, s75, 2
	v_mfma_f32_16x16x32_bf16 v[48:51], v[196:199], v[204:207], v[48:51]
	s_add_u32 s73, s73, 0x100
	v_mfma_f32_16x16x32_bf16 v[36:39], v[188:191], v[212:215], v[36:39]
	s_addc_u32 s74, s74, 0
	v_mfma_f32_16x16x32_bf16 v[32:35], v[196:199], v[212:215], v[32:35]
	s_add_u32 s30, s30, 0x100
	v_mfma_f32_16x16x32_bf16 v[20:23], v[188:191], v[222:225], v[20:23]
	s_addc_u32 s31, s31, 0
	v_mfma_f32_16x16x32_bf16 v[16:19], v[196:199], v[222:225], v[16:19]
	s_cmp_gt_u32 s75, 13
	v_mfma_f32_16x16x32_bf16 v[4:7], v[188:191], v[230:233], v[4:7]
	v_mfma_f32_16x16x32_bf16 v[0:3], v[196:199], v[230:233], v[0:3]
	v_mfma_f32_16x16x32_bf16 v[52:55], v[192:195], v[208:211], v[52:55]
	v_mfma_f32_16x16x32_bf16 v[48:51], v[200:203], v[208:211], v[48:51]
	v_mfma_f32_16x16x32_bf16 v[36:39], v[192:195], v[216:219], v[36:39]
	v_mfma_f32_16x16x32_bf16 v[32:35], v[200:203], v[216:219], v[32:35]
	v_mfma_f32_16x16x32_bf16 v[20:23], v[192:195], v[226:229], v[20:23]
	v_mfma_f32_16x16x32_bf16 v[16:19], v[200:203], v[226:229], v[16:19]
	v_mfma_f32_16x16x32_bf16 v[4:7], v[192:195], v[234:237], v[4:7]
	v_mfma_f32_16x16x32_bf16 v[0:3], v[200:203], v[234:237], v[0:3]
	s_setprio 0
	s_barrier
	s_cbranch_scc0 .LBB0_725

; #define PG8_STAGE(bufoff, gbase, voff) do { _Pragma("unroll") for (int _i = 0; _i < 2; ++_i) \
;         __builtin_amdgcn_global_load_lds((const unsigned*)((const char*)(gbase) + (voff)[_i]), (PG8_LAS unsigned*)(lds + (bufoff) + ldsw + _i * 8192), 16, 0, 0); } while (0)
; #define PG8_LDA(dst, b, h) do { _Pragma("unroll") for (int m = 0; m < 4; ++m) _Pragma("unroll") for (int k = 0; k < 2; ++k) dst[m][k] = *(const PG8_LAS bf16x8*)(lds + PG8_SA(b, h) + aoff + m * 2048 + k * 1024); } while (0)
; #define PG8_LDB(dst, b, h) do { _Pragma("unroll") for (int n = 0; n < 2; ++n) _Pragma("unroll") for (int k = 0; k < 2; ++k) dst[n][k] = *(const PG8_LAS bf16x8*)(lds + PG8_SB(b, h) + boff + n * 2048 + k * 1024); } while (0)
; #define PG8_MMA(ai, bj, At, Bt) do { __builtin_amdgcn_s_setprio(1); _Pragma("unroll") for (int m = 0; m < 4; ++m) _Pragma("unroll") for (int n = 0; n < 2; ++n) _Pragma("unroll") for (int k = 0; k < 2; ++k) \
;         acc[ai][bj][m][n] = __builtin_amdgcn_mfma_f32_16x16x32_bf16(Bt[n][k], At[m][k], acc[ai][bj][m][n], 0, 0, 0); __builtin_amdgcn_s_setprio(0); } while (0)
; #define PG8_WAIT_V(n) asm volatile("s_waitcnt vmcnt(" #n ")" ::: "memory")
; #define PG8_WAIT_L(n) asm volatile("s_waitcnt lgkmcnt(" #n ")" ::: "memory")
; template <class Epi, class Sched>
; __device__ __forceinline__ void gemm_phase(PG8_LAS unsigned char* lds, PG8_LAS unsigned char* xl, const Gemm g, const Sched& S, const Epi& E) {
;     ...
;         const bool has_next = S.next(ui + 1, nxt);
;         const char* nA = has_next ? (const char*)g.A + nxt.aoff : cA; const char* nB = has_next ? (const char*)g.Bt + nxt.boff : cB;
; #pragma unroll 1
;         for (int t = 0; t < nt; t += 2) {
;             const bool last = (t == nt - 2);
;             const char* a1 = cA + (size_t)(t + 1) * kstep;
;             const char* a2 = last ? nA : cA + (size_t)(t + 2) * kstep; const char* b2 = last ? nB : cB + (size_t)(t + 2) * kstep;
;             const char* a3 = a2 + kstep; const char* b3 = b2 + kstep;
;             PG8_LDB(B0, 0, 0); PG8_LDB(B1, 0, 1); PG8_SCHED; PG8_LDA(At, 0, 0); PG8_STAGE(PG8_SA(1, 1), a1 + hsA, voffA);
;             PG8_WAIT_V(8); PG8_WAIT_L(0); PG8_BAR; PG8_MMA(0, 0, At, B0); PG8_MMA(0, 1, At, B1); PG8_BAR; PG8_SCHED;
;             PG8_LDA(At, 0, 1); PG8_STAGE(PG8_SB(0, 0), b2, voffB); PG8_STAGE(PG8_SB(0, 1), b2 + hsB, voffB); PG8_STAGE(PG8_SA(0, 0), a2, voffA);
.LBB0_824:
	s_add_u32 s26, s37, s20
	s_addc_u32 s27, s42, s21
	s_and_b64 s[28:29], s[6:7], exec
	s_cselect_b32 s46, s27, s31
	s_cselect_b32 s47, s26, s30
	s_add_u32 s28, s43, s22
	s_addc_u32 s29, s50, s23
	s_and_b64 s[34:35], s[6:7], exec
	s_cselect_b32 s70, s29, s3
	s_cselect_b32 s72, s28, s2
	s_add_u32 s73, s2, 0x100
	s_addc_u32 s74, s3, 0
	s_add_u32 s2, s30, 0x40080
	v_mov_b32_e32 v0, 0
	s_addc_u32 s3, s31, 0
	s_mov_b32 s75, -2
	ds_read_b128 v[170:173], v164
	ds_read_b128 v[174:177], v164 offset:1024
	ds_read_b128 v[180:183], v164 offset:2048
	ds_read_b128 v[184:187], v164 offset:3072
	ds_read_b128 v[188:191], v165
	ds_read_b128 v[192:195], v165 offset:1024
	ds_read_b128 v[196:199], v165 offset:2048
	ds_read_b128 v[200:203], v165 offset:3072
	s_add_u32 s30, s2, 0xfffc0080
	s_addc_u32 s31, s3, -1
	s_cmp_eq_u32 s75, 12
	s_cselect_b32 s35, s46, s31
	s_cselect_b32 s34, s47, s30
	s_cselect_b32 s31, s70, s74
	s_cselect_b32 s30, s72, s73
	v_lshl_add_u64 v[238:239], s[2:3], 0, v[140:141]
	s_add_i32 m0, s55, 0xc000
	ds_read_b128 v[204:207], v166
	ds_read_b128 v[208:211], v166 offset:1024
	ds_read_b128 v[212:215], v166 offset:2048
	ds_read_b128 v[216:219], v166 offset:3072
	ds_read_b128 v[222:225], v166 offset:4096
	ds_read_b128 v[226:229], v166 offset:5120
	ds_read_b128 v[230:233], v166 offset:6144
	ds_read_b128 v[234:237], v166 offset:7168
	global_load_lds_dwordx4 v[238:239], off
	v_lshl_add_u64 v[238:239], s[2:3], 0, v[138:139]
	s_add_i32 m0, s55, 0xe000
	s_nop 0
	global_load_lds_dwordx4 v[238:239], off
	s_waitcnt vmcnt(8)
	s_waitcnt lgkmcnt(0)
	s_barrier
	s_setprio 1
	s_waitcnt lgkmcnt(0)
	v_mfma_f32_16x16x32_bf16 v[124:127], v[170:173], v[204:207], 0
	v_mfma_f32_16x16x32_bf16 v[116:119], v[180:183], v[204:207], 0
	v_mfma_f32_16x16x32_bf16 v[108:111], v[170:173], v[212:215], 0
	v_mfma_f32_16x16x32_bf16 v[100:103], v[180:183], v[212:215], 0
	v_mfma_f32_16x16x32_bf16 v[92:95], v[170:173], v[222:225], 0
	v_mfma_f32_16x16x32_bf16 v[84:87], v[180:183], v[222:225], 0
	v_mfma_f32_16x16x32_bf16 v[76:79], v[170:173], v[230:233], 0
	v_mfma_f32_16x16x32_bf16 v[68:71], v[180:183], v[230:233], 0
	v_mfma_f32_16x16x32_bf16 v[124:127], v[174:177], v[208:211], v[124:127]
	v_mfma_f32_16x16x32_bf16 v[116:119], v[184:187], v[208:211], v[116:119]
	v_mfma_f32_16x16x32_bf16 v[108:111], v[174:177], v[216:219], v[108:111]
	v_mfma_f32_16x16x32_bf16 v[100:103], v[184:187], v[216:219], v[100:103]
	v_mfma_f32_16x16x32_bf16 v[92:95], v[174:177], v[226:229], v[92:95]
	v_mfma_f32_16x16x32_bf16 v[84:87], v[184:187], v[226:229], v[84:87]
	v_mfma_f32_16x16x32_bf16 v[76:79], v[174:177], v[234:237], v[76:79]
	v_mfma_f32_16x16x32_bf16 v[68:71], v[184:187], v[234:237], v[68:71]
	s_setprio 0
	s_setprio 1
	v_mfma_f32_16x16x32_bf16 v[120:123], v[188:191], v[204:207], 0
	v_mfma_f32_16x16x32_bf16 v[112:115], v[196:199], v[204:207], 0
	v_mfma_f32_16x16x32_bf16 v[104:107], v[188:191], v[212:215], 0
	v_mfma_f32_16x16x32_bf16 v[96:99], v[196:199], v[212:215], 0
	v_mfma_f32_16x16x32_bf16 v[88:91], v[188:191], v[222:225], 0
	v_mfma_f32_16x16x32_bf16 v[80:83], v[196:199], v[222:225], 0
	v_mfma_f32_16x16x32_bf16 v[72:75], v[188:191], v[230:233], 0
	v_mfma_f32_16x16x32_bf16 v[64:67], v[196:199], v[230:233], 0
	v_mfma_f32_16x16x32_bf16 v[120:123], v[192:195], v[208:211], v[120:123]
	v_mfma_f32_16x16x32_bf16 v[112:115], v[200:203], v[208:211], v[112:115]
	v_mfma_f32_16x16x32_bf16 v[104:107], v[192:195], v[216:219], v[104:107]
	v_mfma_f32_16x16x32_bf16 v[96:99], v[200:203], v[216:219], v[96:99]
	v_mfma_f32_16x16x32_bf16 v[88:91], v[192:195], v[226:229], v[88:91]
	v_mfma_f32_16x16x32_bf16 v[80:83], v[200:203], v[226:229], v[80:83]
	v_mfma_f32_16x16x32_bf16 v[72:75], v[192:195], v[234:237], v[72:75]
	v_mfma_f32_16x16x32_bf16 v[64:67], v[200:203], v[234:237], v[64:67]
	s_setprio 0
	s_barrier
	s_add_i32 s68, s54, s51
	v_lshl_add_u64 v[238:239], s[30:31], 0, v[132:133]
	s_mov_b32 m0, s68
	ds_read_b128 v[204:207], v166 offset:16384
	ds_read_b128 v[208:211], v166 offset:17408
	ds_read_b128 v[212:215], v166 offset:18432
	ds_read_b128 v[216:219], v166 offset:19456
	ds_read_b128 v[222:225], v166 offset:20480
	ds_read_b128 v[226:229], v166 offset:21504
	ds_read_b128 v[230:233], v166 offset:22528
	ds_read_b128 v[234:237], v166 offset:23552
	global_load_lds_dwordx4 v[238:239], off
	s_add_i32 m0, s68, 0x2000
	s_add_u32 s76, s30, 0x40000
	v_lshl_add_u64 v[240:241], s[30:31], 0, v[128:129]
	s_addc_u32 s77, s31, 0
	s_add_i32 s68, s62, s51
	global_load_lds_dwordx4 v[240:241], off
	v_lshl_add_u64 v[242:243], s[76:77], 0, v[132:133]
	s_mov_b32 m0, s68
	v_lshl_add_u64 v[244:245], s[34:35], 0, v[130:131]
	global_load_lds_dwordx4 v[242:243], off
	v_lshl_add_u64 v[242:243], s[76:77], 0, v[128:129]
	s_add_i32 m0, s68, 0x2000
	s_nop 0
	global_load_lds_dwordx4 v[242:243], off
	v_lshl_add_u64 v[242:243], s[34:35], 0, v[134:135]
	s_mov_b32 m0, s55
	s_nop 0
	global_load_lds_dwordx4 v[242:243], off
	s_mov_b32 m0, s56
	s_nop 0
	global_load_lds_dwordx4 v[244:245], off
	s_waitcnt vmcnt(8)
	s_waitcnt lgkmcnt(0)
	s_barrier
; #define PG8_STAGE(bufoff, gbase, voff) do { _Pragma("unroll") for (int _i = 0; _i < 2; ++_i) \
;         __builtin_amdgcn_global_load_lds((const unsigned*)((const char*)(gbase) + (voff)[_i]), (PG8_LAS unsigned*)(lds + (bufoff) + ldsw + _i * 8192), 16, 0, 0); } while (0)
; #define PG8_LDA(dst, b, h) do { _Pragma("unroll") for (int m = 0; m < 4; ++m) _Pragma("unroll") for (int k = 0; k < 2; ++k) dst[m][k] = *(const PG8_LAS bf16x8*)(lds + PG8_SA(b, h) + aoff + m * 2048 + k * 1024); } while (0)
; #define PG8_LDB(dst, b, h) do { _Pragma("unroll") for (int n = 0; n < 2; ++n) _Pragma("unroll") for (int k = 0; k < 2; ++k) dst[n][k] = *(const PG8_LAS bf16x8*)(lds + PG8_SB(b, h) + boff + n * 2048 + k * 1024); } while (0)
; #define PG8_MMA(ai, bj, At, Bt) do { __builtin_amdgcn_s_setprio(1); _Pragma("unroll") for (int m = 0; m < 4; ++m) _Pragma("unroll") for (int n = 0; n < 2; ++n) _Pragma("unroll") for (int k = 0; k < 2; ++k) \
;         acc[ai][bj][m][n] = __builtin_amdgcn_mfma_f32_16x16x32_bf16(Bt[n][k], At[m][k], acc[ai][bj][m][n], 0, 0, 0); __builtin_amdgcn_s_setprio(0); } while (0)
; #define PG8_WAIT_V(n) asm volatile("s_waitcnt vmcnt(" #n ")" ::: "memory")
; #define PG8_WAIT_L(n) asm volatile("s_waitcnt lgkmcnt(" #n ")" ::: "memory")
; #define PG8_BAR __builtin_amdgcn_s_barrier()
; #define PG8_SCHED __builtin_amdgcn_sched_barrier(0)
; template <class Epi, class Sched>
; __device__ __forceinline__ void gemm_phase(PG8_LAS unsigned char* lds, PG8_LAS unsigned char* xl, const Gemm g, const Sched& S, const Epi& E) {
;     ...
;             PG8_WAIT_V(8); PG8_WAIT_L(0); PG8_BAR; PG8_MMA(1, 0, At, B0); PG8_MMA(1, 1, At, B1); PG8_BAR; PG8_SCHED;
;             PG8_LDB(B0, 1, 0); PG8_LDB(B1, 1, 1); PG8_SCHED; PG8_LDA(At, 1, 0); PG8_STAGE(PG8_SA(0, 1), a2 + hsA, voffA);
;             PG8_WAIT_V(8); PG8_WAIT_L(0); PG8_BAR; PG8_MMA(0, 0, At, B0); PG8_MMA(0, 1, At, B1); PG8_BAR; PG8_SCHED;
	s_setprio 1
	s_waitcnt lgkmcnt(0)
	v_mfma_f32_16x16x32_bf16 v[60:63], v[170:173], v[204:207], 0
	v_mfma_f32_16x16x32_bf16 v[52:55], v[180:183], v[204:207], 0
	v_mfma_f32_16x16x32_bf16 v[44:47], v[170:173], v[212:215], 0
	v_mfma_f32_16x16x32_bf16 v[36:39], v[180:183], v[212:215], 0
	v_mfma_f32_16x16x32_bf16 v[28:31], v[170:173], v[222:225], 0
	v_mfma_f32_16x16x32_bf16 v[20:23], v[180:183], v[222:225], 0
	v_mfma_f32_16x16x32_bf16 v[12:15], v[170:173], v[230:233], 0
	v_mfma_f32_16x16x32_bf16 v[4:7], v[180:183], v[230:233], 0
	v_mfma_f32_16x16x32_bf16 v[60:63], v[174:177], v[208:211], v[60:63]
	v_mfma_f32_16x16x32_bf16 v[52:55], v[184:187], v[208:211], v[52:55]
	v_mfma_f32_16x16x32_bf16 v[44:47], v[174:177], v[216:219], v[44:47]
	v_mfma_f32_16x16x32_bf16 v[36:39], v[184:187], v[216:219], v[36:39]
	v_mfma_f32_16x16x32_bf16 v[28:31], v[174:177], v[226:229], v[28:31]
	v_mfma_f32_16x16x32_bf16 v[20:23], v[184:187], v[226:229], v[20:23]
	v_mfma_f32_16x16x32_bf16 v[12:15], v[174:177], v[234:237], v[12:15]
	v_mfma_f32_16x16x32_bf16 v[4:7], v[184:187], v[234:237], v[4:7]
	s_setprio 0
	s_setprio 1
	v_mfma_f32_16x16x32_bf16 v[56:59], v[188:191], v[204:207], 0
	v_mfma_f32_16x16x32_bf16 v[48:51], v[196:199], v[204:207], 0
	v_mfma_f32_16x16x32_bf16 v[40:43], v[188:191], v[212:215], 0
	v_mfma_f32_16x16x32_bf16 v[32:35], v[196:199], v[212:215], 0
	v_mfma_f32_16x16x32_bf16 v[24:27], v[188:191], v[222:225], 0
	v_mfma_f32_16x16x32_bf16 v[16:19], v[196:199], v[222:225], 0
	v_mfma_f32_16x16x32_bf16 v[8:11], v[188:191], v[230:233], 0
	v_mfma_f32_16x16x32_bf16 v[0:3], v[196:199], v[230:233], 0
	v_mfma_f32_16x16x32_bf16 v[56:59], v[192:195], v[208:211], v[56:59]
	v_mfma_f32_16x16x32_bf16 v[48:51], v[200:203], v[208:211], v[48:51]
	v_mfma_f32_16x16x32_bf16 v[40:43], v[192:195], v[216:219], v[40:43]
	v_mfma_f32_16x16x32_bf16 v[32:35], v[200:203], v[216:219], v[32:35]
	v_mfma_f32_16x16x32_bf16 v[24:27], v[192:195], v[226:229], v[24:27]
	v_mfma_f32_16x16x32_bf16 v[16:19], v[200:203], v[226:229], v[16:19]
	v_mfma_f32_16x16x32_bf16 v[8:11], v[192:195], v[234:237], v[8:11]
	v_mfma_f32_16x16x32_bf16 v[0:3], v[200:203], v[234:237], v[0:3]
	s_setprio 0
	s_barrier
	s_add_i32 s68, 0, 0x18000
	v_add_u32_e32 v169, s68, v147
	s_add_i32 s76, 0, 0x1c000
	ds_read_b128 v[170:173], v169
	ds_read_b128 v[174:177], v169 offset:1024
	ds_read_b128 v[180:183], v169 offset:2048
	ds_read_b128 v[184:187], v169 offset:3072
	v_add_u32_e32 v169, s76, v147
	ds_read_b128 v[188:191], v169
	ds_read_b128 v[192:195], v169 offset:1024
	ds_read_b128 v[196:199], v169 offset:2048
	ds_read_b128 v[200:203], v169 offset:3072
	s_add_u32 s34, s34, 0x40000
	s_addc_u32 s35, s35, 0
	s_mov_b32 m0, s57
	v_lshl_add_u64 v[246:247], s[34:35], 0, v[134:135]
	ds_read_b128 v[204:207], v166 offset:32768
	ds_read_b128 v[208:211], v166 offset:33792
	ds_read_b128 v[212:215], v166 offset:34816
	ds_read_b128 v[216:219], v166 offset:35840
	ds_read_b128 v[222:225], v166 offset:36864
	ds_read_b128 v[226:229], v166 offset:37888
	ds_read_b128 v[230:233], v166 offset:38912
	ds_read_b128 v[234:237], v166 offset:39936
	global_load_lds_dwordx4 v[246:247], off
	v_lshl_add_u64 v[246:247], s[34:35], 0, v[130:131]
	s_mov_b32 m0, s58
	s_nop 0
	global_load_lds_dwordx4 v[246:247], off
	s_waitcnt vmcnt(8)
	s_waitcnt lgkmcnt(0)
	s_barrier
	s_setprio 1
	s_waitcnt lgkmcnt(0)
	v_mfma_f32_16x16x32_bf16 v[124:127], v[170:173], v[204:207], v[124:127]
	v_mfma_f32_16x16x32_bf16 v[116:119], v[180:183], v[204:207], v[116:119]
	v_mfma_f32_16x16x32_bf16 v[108:111], v[170:173], v[212:215], v[108:111]
	v_mfma_f32_16x16x32_bf16 v[100:103], v[180:183], v[212:215], v[100:103]
	v_mfma_f32_16x16x32_bf16 v[92:95], v[170:173], v[222:225], v[92:95]
	v_mfma_f32_16x16x32_bf16 v[84:87], v[180:183], v[222:225], v[84:87]
	v_mfma_f32_16x16x32_bf16 v[76:79], v[170:173], v[230:233], v[76:79]
	v_mfma_f32_16x16x32_bf16 v[68:71], v[180:183], v[230:233], v[68:71]
	v_mfma_f32_16x16x32_bf16 v[124:127], v[174:177], v[208:211], v[124:127]
	v_mfma_f32_16x16x32_bf16 v[116:119], v[184:187], v[208:211], v[116:119]
	v_mfma_f32_16x16x32_bf16 v[108:111], v[174:177], v[216:219], v[108:111]
	v_mfma_f32_16x16x32_bf16 v[100:103], v[184:187], v[216:219], v[100:103]
	v_mfma_f32_16x16x32_bf16 v[92:95], v[174:177], v[226:229], v[92:95]
	v_mfma_f32_16x16x32_bf16 v[84:87], v[184:187], v[226:229], v[84:87]
	v_mfma_f32_16x16x32_bf16 v[76:79], v[174:177], v[234:237], v[76:79]
	v_mfma_f32_16x16x32_bf16 v[68:71], v[184:187], v[234:237], v[68:71]
	s_setprio 0
	s_setprio 1
	v_mfma_f32_16x16x32_bf16 v[120:123], v[188:191], v[204:207], v[120:123]
	v_mfma_f32_16x16x32_bf16 v[112:115], v[196:199], v[204:207], v[112:115]
	v_mfma_f32_16x16x32_bf16 v[104:107], v[188:191], v[212:215], v[104:107]
	v_mfma_f32_16x16x32_bf16 v[96:99], v[196:199], v[212:215], v[96:99]
	v_mfma_f32_16x16x32_bf16 v[88:91], v[188:191], v[222:225], v[88:91]
	v_mfma_f32_16x16x32_bf16 v[80:83], v[196:199], v[222:225], v[80:83]
	v_mfma_f32_16x16x32_bf16 v[72:75], v[188:191], v[230:233], v[72:75]
	v_mfma_f32_16x16x32_bf16 v[64:67], v[196:199], v[230:233], v[64:67]
	v_mfma_f32_16x16x32_bf16 v[120:123], v[192:195], v[208:211], v[120:123]
	v_mfma_f32_16x16x32_bf16 v[112:115], v[200:203], v[208:211], v[112:115]
	v_mfma_f32_16x16x32_bf16 v[104:107], v[192:195], v[216:219], v[104:107]
	v_mfma_f32_16x16x32_bf16 v[96:99], v[200:203], v[216:219], v[96:99]
	v_mfma_f32_16x16x32_bf16 v[88:91], v[192:195], v[226:229], v[88:91]
	v_mfma_f32_16x16x32_bf16 v[80:83], v[200:203], v[226:229], v[80:83]
	v_mfma_f32_16x16x32_bf16 v[72:75], v[192:195], v[234:237], v[72:75]
	v_mfma_f32_16x16x32_bf16 v[64:67], v[200:203], v[234:237], v[64:67]
	s_setprio 0
	s_barrier
; #define PG8_STAGE(bufoff, gbase, voff) do { _Pragma("unroll") for (int _i = 0; _i < 2; ++_i) \
;         __builtin_amdgcn_global_load_lds((const unsigned*)((const char*)(gbase) + (voff)[_i]), (PG8_LAS unsigned*)(lds + (bufoff) + ldsw + _i * 8192), 16, 0, 0); } while (0)
; #define PG8_LDA(dst, b, h) do { _Pragma("unroll") for (int m = 0; m < 4; ++m) _Pragma("unroll") for (int k = 0; k < 2; ++k) dst[m][k] = *(const PG8_LAS bf16x8*)(lds + PG8_SA(b, h) + aoff + m * 2048 + k * 1024); } while (0)
; #define PG8_LDB(dst, b, h) do { _Pragma("unroll") for (int n = 0; n < 2; ++n) _Pragma("unroll") for (int k = 0; k < 2; ++k) dst[n][k] = *(const PG8_LAS bf16x8*)(lds + PG8_SB(b, h) + boff + n * 2048 + k * 1024); } while (0)
; #define PG8_MMA(ai, bj, At, Bt) do { __builtin_amdgcn_s_setprio(1); _Pragma("unroll") for (int m = 0; m < 4; ++m) _Pragma("unroll") for (int n = 0; n < 2; ++n) _Pragma("unroll") for (int k = 0; k < 2; ++k) \
;         acc[ai][bj][m][n] = __builtin_amdgcn_mfma_f32_16x16x32_bf16(Bt[n][k], At[m][k], acc[ai][bj][m][n], 0, 0, 0); __builtin_amdgcn_s_setprio(0); } while (0)
; #define PG8_WAIT_V(n) asm volatile("s_waitcnt vmcnt(" #n ")" ::: "memory")
; #define PG8_WAIT_L(n) asm volatile("s_waitcnt lgkmcnt(" #n ")" ::: "memory")
; #define PG8_BAR __builtin_amdgcn_s_barrier()
; #define PG8_SCHED __builtin_amdgcn_sched_barrier(0)
; template <class Epi, class Sched>
; __device__ __forceinline__ void gemm_phase(PG8_LAS unsigned char* lds, PG8_LAS unsigned char* xl, const Gemm g, const Sched& S, const Epi& E) {
;     ...
;         for (int t = 0; t < nt; t += 2) {
;             const bool last = (t == nt - 2);
;             const char* a1 = cA + (size_t)(t + 1) * kstep;
;             const char* a2 = last ? nA : cA + (size_t)(t + 2) * kstep; const char* b2 = last ? nB : cB + (size_t)(t + 2) * kstep;
;             const char* a3 = a2 + kstep; const char* b3 = b2 + kstep;
;             PG8_LDB(B0, 0, 0); PG8_LDB(B1, 0, 1); PG8_SCHED; PG8_LDA(At, 0, 0); PG8_STAGE(PG8_SA(1, 1), a1 + hsA, voffA);
;     ...
;             PG8_LDA(At, 1, 1); PG8_STAGE(PG8_SB(1, 0), b3, voffB); PG8_STAGE(PG8_SB(1, 1), b3 + hsB, voffB); PG8_STAGE(PG8_SA(1, 0), a3, voffA);
;             PG8_WAIT_V(8); PG8_WAIT_L(0); PG8_BAR; PG8_MMA(1, 0, At, B0); PG8_MMA(1, 1, At, B1); PG8_BAR; PG8_SCHED;
	s_add_i32 s34, s68, s51
	v_lshl_add_u64 v[238:239], v[238:239], 0, s[16:17]
	s_mov_b32 m0, s34
	ds_read_b128 v[204:207], v166 offset:49152
	ds_read_b128 v[208:211], v166 offset:50176
	ds_read_b128 v[212:215], v166 offset:51200
	ds_read_b128 v[216:219], v166 offset:52224
	ds_read_b128 v[222:225], v166 offset:53248
	ds_read_b128 v[226:229], v166 offset:54272
	ds_read_b128 v[230:233], v166 offset:55296
	ds_read_b128 v[234:237], v166 offset:56320
	global_load_lds_dwordx4 v[238:239], off
	s_add_i32 m0, s34, 0x2000
	s_add_u32 s30, s30, 0x40080
	v_lshl_add_u64 v[238:239], v[240:241], 0, s[16:17]
	s_addc_u32 s31, s31, 0
	s_add_i32 s34, s76, s51
	global_load_lds_dwordx4 v[238:239], off
	v_lshl_add_u64 v[238:239], s[30:31], 0, v[132:133]
	s_mov_b32 m0, s34
	s_nop 0
	global_load_lds_dwordx4 v[238:239], off
	v_lshl_add_u64 v[238:239], s[30:31], 0, v[128:129]
	s_add_i32 m0, s34, 0x2000
	s_nop 0
	global_load_lds_dwordx4 v[238:239], off
	v_lshl_add_u64 v[238:239], v[242:243], 0, s[16:17]
	s_mov_b32 m0, s59
	s_nop 0
	global_load_lds_dwordx4 v[238:239], off
	v_lshl_add_u64 v[238:239], v[244:245], 0, s[16:17]
	s_mov_b32 m0, s61
	s_nop 0
	global_load_lds_dwordx4 v[238:239], off
	s_waitcnt vmcnt(8)
	s_waitcnt lgkmcnt(0)
	s_barrier
	s_setprio 1
	s_waitcnt lgkmcnt(0)
	v_mfma_f32_16x16x32_bf16 v[60:63], v[170:173], v[204:207], v[60:63]
	v_mfma_f32_16x16x32_bf16 v[52:55], v[180:183], v[204:207], v[52:55]
	v_mfma_f32_16x16x32_bf16 v[44:47], v[170:173], v[212:215], v[44:47]
	v_mfma_f32_16x16x32_bf16 v[36:39], v[180:183], v[212:215], v[36:39]
	v_mfma_f32_16x16x32_bf16 v[28:31], v[170:173], v[222:225], v[28:31]
	v_mfma_f32_16x16x32_bf16 v[20:23], v[180:183], v[222:225], v[20:23]
	v_mfma_f32_16x16x32_bf16 v[12:15], v[170:173], v[230:233], v[12:15]
	v_mfma_f32_16x16x32_bf16 v[4:7], v[180:183], v[230:233], v[4:7]
	v_mfma_f32_16x16x32_bf16 v[60:63], v[174:177], v[208:211], v[60:63]
	v_mfma_f32_16x16x32_bf16 v[52:55], v[184:187], v[208:211], v[52:55]
	v_mfma_f32_16x16x32_bf16 v[44:47], v[174:177], v[216:219], v[44:47]
	v_mfma_f32_16x16x32_bf16 v[36:39], v[184:187], v[216:219], v[36:39]
	v_mfma_f32_16x16x32_bf16 v[28:31], v[174:177], v[226:229], v[28:31]
	v_mfma_f32_16x16x32_bf16 v[20:23], v[184:187], v[226:229], v[20:23]
	v_mfma_f32_16x16x32_bf16 v[12:15], v[174:177], v[234:237], v[12:15]
	v_mfma_f32_16x16x32_bf16 v[4:7], v[184:187], v[234:237], v[4:7]
	s_setprio 0
	s_setprio 1
	v_mfma_f32_16x16x32_bf16 v[56:59], v[188:191], v[204:207], v[56:59]
	s_add_i32 s75, s75, 2
	v_mfma_f32_16x16x32_bf16 v[48:51], v[196:199], v[204:207], v[48:51]
	s_add_u32 s73, s73, 0x100
	v_mfma_f32_16x16x32_bf16 v[40:43], v[188:191], v[212:215], v[40:43]
	s_addc_u32 s74, s74, 0
	v_mfma_f32_16x16x32_bf16 v[32:35], v[196:199], v[212:215], v[32:35]
	s_add_u32 s2, s2, 0x100
	v_mfma_f32_16x16x32_bf16 v[24:27], v[188:191], v[222:225], v[24:27]
	s_addc_u32 s3, s3, 0
	v_mfma_f32_16x16x32_bf16 v[16:19], v[196:199], v[222:225], v[16:19]
	s_cmp_gt_u32 s75, 13
	v_mfma_f32_16x16x32_bf16 v[8:11], v[188:191], v[230:233], v[8:11]
	v_mfma_f32_16x16x32_bf16 v[0:3], v[196:199], v[230:233], v[0:3]
	v_mfma_f32_16x16x32_bf16 v[56:59], v[192:195], v[208:211], v[56:59]
	v_mfma_f32_16x16x32_bf16 v[48:51], v[200:203], v[208:211], v[48:51]
	v_mfma_f32_16x16x32_bf16 v[40:43], v[192:195], v[216:219], v[40:43]
	v_mfma_f32_16x16x32_bf16 v[32:35], v[200:203], v[216:219], v[32:35]
	v_mfma_f32_16x16x32_bf16 v[24:27], v[192:195], v[226:229], v[24:27]
	v_mfma_f32_16x16x32_bf16 v[16:19], v[200:203], v[226:229], v[16:19]
	v_mfma_f32_16x16x32_bf16 v[8:11], v[192:195], v[234:237], v[8:11]
	v_mfma_f32_16x16x32_bf16 v[0:3], v[200:203], v[234:237], v[0:3]
	s_setprio 0
	s_barrier
	s_cbranch_scc1 .Lpeel_after_P8
.LBB0_825:
	ds_read_b128 v[170:173], v164
	ds_read_b128 v[174:177], v164 offset:1024
	ds_read_b128 v[180:183], v164 offset:2048
	ds_read_b128 v[184:187], v164 offset:3072
	ds_read_b128 v[188:191], v165
	ds_read_b128 v[192:195], v165 offset:1024
	ds_read_b128 v[196:199], v165 offset:2048
	ds_read_b128 v[200:203], v165 offset:3072
	s_add_u32 s30, s2, 0xfffc0080
	s_addc_u32 s31, s3, -1
	s_cmp_eq_u32 s75, 12
	s_cselect_b32 s35, s46, s31
	s_cselect_b32 s34, s47, s30
	s_cselect_b32 s31, s70, s74
	s_cselect_b32 s30, s72, s73
	v_lshl_add_u64 v[238:239], s[2:3], 0, v[140:141]
	s_add_i32 m0, s55, 0xc000
	ds_read_b128 v[204:207], v166
	ds_read_b128 v[208:211], v166 offset:1024
	ds_read_b128 v[212:215], v166 offset:2048
	ds_read_b128 v[216:219], v166 offset:3072
	ds_read_b128 v[222:225], v166 offset:4096
	ds_read_b128 v[226:229], v166 offset:5120
	ds_read_b128 v[230:233], v166 offset:6144
	ds_read_b128 v[234:237], v166 offset:7168
	global_load_lds_dwordx4 v[238:239], off
	v_lshl_add_u64 v[238:239], s[2:3], 0, v[138:139]
	s_add_i32 m0, s55, 0xe000
	s_nop 0
	global_load_lds_dwordx4 v[238:239], off
	s_waitcnt vmcnt(8)
	s_waitcnt lgkmcnt(0)
	s_barrier
; #define PG8_STAGE(bufoff, gbase, voff) do { _Pragma("unroll") for (int _i = 0; _i < 2; ++_i) \
;         __builtin_amdgcn_global_load_lds((const unsigned*)((const char*)(gbase) + (voff)[_i]), (PG8_LAS unsigned*)(lds + (bufoff) + ldsw + _i * 8192), 16, 0, 0); } while (0)
; #define PG8_LDA(dst, b, h) do { _Pragma("unroll") for (int m = 0; m < 4; ++m) _Pragma("unroll") for (int k = 0; k < 2; ++k) dst[m][k] = *(const PG8_LAS bf16x8*)(lds + PG8_SA(b, h) + aoff + m * 2048 + k * 1024); } while (0)
; #define PG8_MMA(ai, bj, At, Bt) do { __builtin_amdgcn_s_setprio(1); _Pragma("unroll") for (int m = 0; m < 4; ++m) _Pragma("unroll") for (int n = 0; n < 2; ++n) _Pragma("unroll") for (int k = 0; k < 2; ++k) \
;         acc[ai][bj][m][n] = __builtin_amdgcn_mfma_f32_16x16x32_bf16(Bt[n][k], At[m][k], acc[ai][bj][m][n], 0, 0, 0); __builtin_amdgcn_s_setprio(0); } while (0)
; #define PG8_WAIT_V(n) asm volatile("s_waitcnt vmcnt(" #n ")" ::: "memory")
; #define PG8_WAIT_L(n) asm volatile("s_waitcnt lgkmcnt(" #n ")" ::: "memory")
; #define PG8_BAR __builtin_amdgcn_s_barrier()
; #define PG8_SCHED __builtin_amdgcn_sched_barrier(0)
; template <class Epi, class Sched>
; __device__ __forceinline__ void gemm_phase(PG8_LAS unsigned char* lds, PG8_LAS unsigned char* xl, const Gemm g, const Sched& S, const Epi& E) {
;     ...
;             PG8_WAIT_V(8); PG8_WAIT_L(0); PG8_BAR; PG8_MMA(0, 0, At, B0); PG8_MMA(0, 1, At, B1); PG8_BAR; PG8_SCHED;
;             PG8_LDA(At, 0, 1); PG8_STAGE(PG8_SB(0, 0), b2, voffB); PG8_STAGE(PG8_SB(0, 1), b2 + hsB, voffB); PG8_STAGE(PG8_SA(0, 0), a2, voffA);
;             PG8_WAIT_V(8); PG8_WAIT_L(0); PG8_BAR; PG8_MMA(1, 0, At, B0); PG8_MMA(1, 1, At, B1); PG8_BAR; PG8_SCHED;
	s_setprio 1
	s_waitcnt lgkmcnt(0)
	v_mfma_f32_16x16x32_bf16 v[124:127], v[170:173], v[204:207], v[124:127]
	v_mfma_f32_16x16x32_bf16 v[116:119], v[180:183], v[204:207], v[116:119]
	v_mfma_f32_16x16x32_bf16 v[108:111], v[170:173], v[212:215], v[108:111]
	v_mfma_f32_16x16x32_bf16 v[100:103], v[180:183], v[212:215], v[100:103]
	v_mfma_f32_16x16x32_bf16 v[92:95], v[170:173], v[222:225], v[92:95]
	v_mfma_f32_16x16x32_bf16 v[84:87], v[180:183], v[222:225], v[84:87]
	v_mfma_f32_16x16x32_bf16 v[76:79], v[170:173], v[230:233], v[76:79]
	v_mfma_f32_16x16x32_bf16 v[68:71], v[180:183], v[230:233], v[68:71]
	v_mfma_f32_16x16x32_bf16 v[124:127], v[174:177], v[208:211], v[124:127]
	v_mfma_f32_16x16x32_bf16 v[116:119], v[184:187], v[208:211], v[116:119]
	v_mfma_f32_16x16x32_bf16 v[108:111], v[174:177], v[216:219], v[108:111]
	v_mfma_f32_16x16x32_bf16 v[100:103], v[184:187], v[216:219], v[100:103]
	v_mfma_f32_16x16x32_bf16 v[92:95], v[174:177], v[226:229], v[92:95]
	v_mfma_f32_16x16x32_bf16 v[84:87], v[184:187], v[226:229], v[84:87]
	v_mfma_f32_16x16x32_bf16 v[76:79], v[174:177], v[234:237], v[76:79]
	v_mfma_f32_16x16x32_bf16 v[68:71], v[184:187], v[234:237], v[68:71]
	s_setprio 0
	s_setprio 1
	v_mfma_f32_16x16x32_bf16 v[120:123], v[188:191], v[204:207], v[120:123]
	v_mfma_f32_16x16x32_bf16 v[112:115], v[196:199], v[204:207], v[112:115]
	v_mfma_f32_16x16x32_bf16 v[104:107], v[188:191], v[212:215], v[104:107]
	v_mfma_f32_16x16x32_bf16 v[96:99], v[196:199], v[212:215], v[96:99]
	v_mfma_f32_16x16x32_bf16 v[88:91], v[188:191], v[222:225], v[88:91]
	v_mfma_f32_16x16x32_bf16 v[80:83], v[196:199], v[222:225], v[80:83]
	v_mfma_f32_16x16x32_bf16 v[72:75], v[188:191], v[230:233], v[72:75]
	v_mfma_f32_16x16x32_bf16 v[64:67], v[196:199], v[230:233], v[64:67]
	v_mfma_f32_16x16x32_bf16 v[120:123], v[192:195], v[208:211], v[120:123]
	v_mfma_f32_16x16x32_bf16 v[112:115], v[200:203], v[208:211], v[112:115]
	v_mfma_f32_16x16x32_bf16 v[104:107], v[192:195], v[216:219], v[104:107]
	v_mfma_f32_16x16x32_bf16 v[96:99], v[200:203], v[216:219], v[96:99]
	v_mfma_f32_16x16x32_bf16 v[88:91], v[192:195], v[226:229], v[88:91]
	v_mfma_f32_16x16x32_bf16 v[80:83], v[200:203], v[226:229], v[80:83]
	v_mfma_f32_16x16x32_bf16 v[72:75], v[192:195], v[234:237], v[72:75]
	v_mfma_f32_16x16x32_bf16 v[64:67], v[200:203], v[234:237], v[64:67]
	s_setprio 0
	s_barrier
	s_add_i32 s68, s54, s51
	v_lshl_add_u64 v[238:239], s[30:31], 0, v[132:133]
	s_mov_b32 m0, s68
	ds_read_b128 v[204:207], v166 offset:16384
	ds_read_b128 v[208:211], v166 offset:17408
	ds_read_b128 v[212:215], v166 offset:18432
	ds_read_b128 v[216:219], v166 offset:19456
	ds_read_b128 v[222:225], v166 offset:20480
	ds_read_b128 v[226:229], v166 offset:21504
	ds_read_b128 v[230:233], v166 offset:22528
	ds_read_b128 v[234:237], v166 offset:23552
	global_load_lds_dwordx4 v[238:239], off
	s_add_i32 m0, s68, 0x2000
	s_add_u32 s76, s30, 0x40000
	v_lshl_add_u64 v[240:241], s[30:31], 0, v[128:129]
	s_addc_u32 s77, s31, 0
	s_add_i32 s68, s62, s51
	global_load_lds_dwordx4 v[240:241], off
	v_lshl_add_u64 v[242:243], s[76:77], 0, v[132:133]
	s_mov_b32 m0, s68
	v_lshl_add_u64 v[244:245], s[34:35], 0, v[130:131]
	global_load_lds_dwordx4 v[242:243], off
	v_lshl_add_u64 v[242:243], s[76:77], 0, v[128:129]
	s_add_i32 m0, s68, 0x2000
	s_nop 0
	global_load_lds_dwordx4 v[242:243], off
	v_lshl_add_u64 v[242:243], s[34:35], 0, v[134:135]
	s_mov_b32 m0, s55
	s_nop 0
	global_load_lds_dwordx4 v[242:243], off
	s_mov_b32 m0, s56
	s_nop 0
	global_load_lds_dwordx4 v[244:245], off
	s_waitcnt vmcnt(8)
	s_waitcnt lgkmcnt(0)
	s_barrier
	s_setprio 1
	s_waitcnt lgkmcnt(0)
	v_mfma_f32_16x16x32_bf16 v[60:63], v[170:173], v[204:207], v[60:63]
	v_mfma_f32_16x16x32_bf16 v[52:55], v[180:183], v[204:207], v[52:55]
	v_mfma_f32_16x16x32_bf16 v[44:47], v[170:173], v[212:215], v[44:47]
	v_mfma_f32_16x16x32_bf16 v[36:39], v[180:183], v[212:215], v[36:39]
	v_mfma_f32_16x16x32_bf16 v[28:31], v[170:173], v[222:225], v[28:31]
	v_mfma_f32_16x16x32_bf16 v[20:23], v[180:183], v[222:225], v[20:23]
	v_mfma_f32_16x16x32_bf16 v[12:15], v[170:173], v[230:233], v[12:15]
	v_mfma_f32_16x16x32_bf16 v[4:7], v[180:183], v[230:233], v[4:7]
	v_mfma_f32_16x16x32_bf16 v[60:63], v[174:177], v[208:211], v[60:63]
	v_mfma_f32_16x16x32_bf16 v[52:55], v[184:187], v[208:211], v[52:55]
	v_mfma_f32_16x16x32_bf16 v[44:47], v[174:177], v[216:219], v[44:47]
	v_mfma_f32_16x16x32_bf16 v[36:39], v[184:187], v[216:219], v[36:39]
	v_mfma_f32_16x16x32_bf16 v[28:31], v[174:177], v[226:229], v[28:31]
	v_mfma_f32_16x16x32_bf16 v[20:23], v[184:187], v[226:229], v[20:23]
	v_mfma_f32_16x16x32_bf16 v[12:15], v[174:177], v[234:237], v[12:15]
	v_mfma_f32_16x16x32_bf16 v[4:7], v[184:187], v[234:237], v[4:7]
	s_setprio 0
	s_setprio 1
	v_mfma_f32_16x16x32_bf16 v[56:59], v[188:191], v[204:207], v[56:59]
	v_mfma_f32_16x16x32_bf16 v[48:51], v[196:199], v[204:207], v[48:51]
	v_mfma_f32_16x16x32_bf16 v[40:43], v[188:191], v[212:215], v[40:43]
	v_mfma_f32_16x16x32_bf16 v[32:35], v[196:199], v[212:215], v[32:35]
	v_mfma_f32_16x16x32_bf16 v[24:27], v[188:191], v[222:225], v[24:27]
	v_mfma_f32_16x16x32_bf16 v[16:19], v[196:199], v[222:225], v[16:19]
	v_mfma_f32_16x16x32_bf16 v[8:11], v[188:191], v[230:233], v[8:11]
	v_mfma_f32_16x16x32_bf16 v[0:3], v[196:199], v[230:233], v[0:3]
	v_mfma_f32_16x16x32_bf16 v[56:59], v[192:195], v[208:211], v[56:59]
	v_mfma_f32_16x16x32_bf16 v[48:51], v[200:203], v[208:211], v[48:51]
	v_mfma_f32_16x16x32_bf16 v[40:43], v[192:195], v[216:219], v[40:43]
	v_mfma_f32_16x16x32_bf16 v[32:35], v[200:203], v[216:219], v[32:35]
	v_mfma_f32_16x16x32_bf16 v[24:27], v[192:195], v[226:229], v[24:27]
	v_mfma_f32_16x16x32_bf16 v[16:19], v[200:203], v[226:229], v[16:19]
	v_mfma_f32_16x16x32_bf16 v[8:11], v[192:195], v[234:237], v[8:11]
	v_mfma_f32_16x16x32_bf16 v[0:3], v[200:203], v[234:237], v[0:3]
	s_setprio 0
	s_barrier
; #define PG8_STAGE(bufoff, gbase, voff) do { _Pragma("unroll") for (int _i = 0; _i < 2; ++_i) \
;         __builtin_amdgcn_global_load_lds((const unsigned*)((const char*)(gbase) + (voff)[_i]), (PG8_LAS unsigned*)(lds + (bufoff) + ldsw + _i * 8192), 16, 0, 0); } while (0)
; #define PG8_LDA(dst, b, h) do { _Pragma("unroll") for (int m = 0; m < 4; ++m) _Pragma("unroll") for (int k = 0; k < 2; ++k) dst[m][k] = *(const PG8_LAS bf16x8*)(lds + PG8_SA(b, h) + aoff + m * 2048 + k * 1024); } while (0)
; #define PG8_LDB(dst, b, h) do { _Pragma("unroll") for (int n = 0; n < 2; ++n) _Pragma("unroll") for (int k = 0; k < 2; ++k) dst[n][k] = *(const PG8_LAS bf16x8*)(lds + PG8_SB(b, h) + boff + n * 2048 + k * 1024); } while (0)
; #define PG8_MMA(ai, bj, At, Bt) do { __builtin_amdgcn_s_setprio(1); _Pragma("unroll") for (int m = 0; m < 4; ++m) _Pragma("unroll") for (int n = 0; n < 2; ++n) _Pragma("unroll") for (int k = 0; k < 2; ++k) \
;         acc[ai][bj][m][n] = __builtin_amdgcn_mfma_f32_16x16x32_bf16(Bt[n][k], At[m][k], acc[ai][bj][m][n], 0, 0, 0); __builtin_amdgcn_s_setprio(0); } while (0)
; #define PG8_WAIT_V(n) asm volatile("s_waitcnt vmcnt(" #n ")" ::: "memory")
; #define PG8_WAIT_L(n) asm volatile("s_waitcnt lgkmcnt(" #n ")" ::: "memory")
; #define PG8_BAR __builtin_amdgcn_s_barrier()
; #define PG8_SCHED __builtin_amdgcn_sched_barrier(0)
; template <class Epi, class Sched>
; __device__ __forceinline__ void gemm_phase(PG8_LAS unsigned char* lds, PG8_LAS unsigned char* xl, const Gemm g, const Sched& S, const Epi& E) {
;     ...
;             PG8_LDB(B0, 1, 0); PG8_LDB(B1, 1, 1); PG8_SCHED; PG8_LDA(At, 1, 0); PG8_STAGE(PG8_SA(0, 1), a2 + hsA, voffA);
;             PG8_WAIT_V(8); PG8_WAIT_L(0); PG8_BAR; PG8_MMA(0, 0, At, B0); PG8_MMA(0, 1, At, B1); PG8_BAR; PG8_SCHED;
	s_add_i32 s68, 0, 0x18000
	v_add_u32_e32 v169, s68, v147
	s_add_i32 s76, 0, 0x1c000
	ds_read_b128 v[170:173], v169
	ds_read_b128 v[174:177], v169 offset:1024
	ds_read_b128 v[180:183], v169 offset:2048
	ds_read_b128 v[184:187], v169 offset:3072
	v_add_u32_e32 v169, s76, v147
	ds_read_b128 v[188:191], v169
	ds_read_b128 v[192:195], v169 offset:1024
	ds_read_b128 v[196:199], v169 offset:2048
	ds_read_b128 v[200:203], v169 offset:3072
	s_add_u32 s34, s34, 0x40000
	s_addc_u32 s35, s35, 0
	s_mov_b32 m0, s57
	v_lshl_add_u64 v[246:247], s[34:35], 0, v[134:135]
	ds_read_b128 v[204:207], v166 offset:32768
	ds_read_b128 v[208:211], v166 offset:33792
	ds_read_b128 v[212:215], v166 offset:34816
	ds_read_b128 v[216:219], v166 offset:35840
	ds_read_b128 v[222:225], v166 offset:36864
	ds_read_b128 v[226:229], v166 offset:37888
	ds_read_b128 v[230:233], v166 offset:38912
	ds_read_b128 v[234:237], v166 offset:39936
	global_load_lds_dwordx4 v[246:247], off
	v_lshl_add_u64 v[246:247], s[34:35], 0, v[130:131]
	s_mov_b32 m0, s58
	s_nop 0
	global_load_lds_dwordx4 v[246:247], off
	s_waitcnt vmcnt(8)
	s_waitcnt lgkmcnt(0)
	s_barrier
	s_setprio 1
	s_waitcnt lgkmcnt(0)
	v_mfma_f32_16x16x32_bf16 v[124:127], v[170:173], v[204:207], v[124:127]
	v_mfma_f32_16x16x32_bf16 v[116:119], v[180:183], v[204:207], v[116:119]
	v_mfma_f32_16x16x32_bf16 v[108:111], v[170:173], v[212:215], v[108:111]
	v_mfma_f32_16x16x32_bf16 v[100:103], v[180:183], v[212:215], v[100:103]
	v_mfma_f32_16x16x32_bf16 v[92:95], v[170:173], v[222:225], v[92:95]
	v_mfma_f32_16x16x32_bf16 v[84:87], v[180:183], v[222:225], v[84:87]
	v_mfma_f32_16x16x32_bf16 v[76:79], v[170:173], v[230:233], v[76:79]
	v_mfma_f32_16x16x32_bf16 v[68:71], v[180:183], v[230:233], v[68:71]
	v_mfma_f32_16x16x32_bf16 v[124:127], v[174:177], v[208:211], v[124:127]
	v_mfma_f32_16x16x32_bf16 v[116:119], v[184:187], v[208:211], v[116:119]
	v_mfma_f32_16x16x32_bf16 v[108:111], v[174:177], v[216:219], v[108:111]
	v_mfma_f32_16x16x32_bf16 v[100:103], v[184:187], v[216:219], v[100:103]
	v_mfma_f32_16x16x32_bf16 v[92:95], v[174:177], v[226:229], v[92:95]
	v_mfma_f32_16x16x32_bf16 v[84:87], v[184:187], v[226:229], v[84:87]
	v_mfma_f32_16x16x32_bf16 v[76:79], v[174:177], v[234:237], v[76:79]
	v_mfma_f32_16x16x32_bf16 v[68:71], v[184:187], v[234:237], v[68:71]
	s_setprio 0
	s_setprio 1
	v_mfma_f32_16x16x32_bf16 v[120:123], v[188:191], v[204:207], v[120:123]
	v_mfma_f32_16x16x32_bf16 v[112:115], v[196:199], v[204:207], v[112:115]
	v_mfma_f32_16x16x32_bf16 v[104:107], v[188:191], v[212:215], v[104:107]
	v_mfma_f32_16x16x32_bf16 v[96:99], v[196:199], v[212:215], v[96:99]
	v_mfma_f32_16x16x32_bf16 v[88:91], v[188:191], v[222:225], v[88:91]
	v_mfma_f32_16x16x32_bf16 v[80:83], v[196:199], v[222:225], v[80:83]
	v_mfma_f32_16x16x32_bf16 v[72:75], v[188:191], v[230:233], v[72:75]
	v_mfma_f32_16x16x32_bf16 v[64:67], v[196:199], v[230:233], v[64:67]
	v_mfma_f32_16x16x32_bf16 v[120:123], v[192:195], v[208:211], v[120:123]
	v_mfma_f32_16x16x32_bf16 v[112:115], v[200:203], v[208:211], v[112:115]
	v_mfma_f32_16x16x32_bf16 v[104:107], v[192:195], v[216:219], v[104:107]
	v_mfma_f32_16x16x32_bf16 v[96:99], v[200:203], v[216:219], v[96:99]
	v_mfma_f32_16x16x32_bf16 v[88:91], v[192:195], v[226:229], v[88:91]
	v_mfma_f32_16x16x32_bf16 v[80:83], v[200:203], v[226:229], v[80:83]
	v_mfma_f32_16x16x32_bf16 v[72:75], v[192:195], v[234:237], v[72:75]
	v_mfma_f32_16x16x32_bf16 v[64:67], v[200:203], v[234:237], v[64:67]
	s_setprio 0
	s_barrier
; #define PG8_STAGE(bufoff, gbase, voff) do { _Pragma("unroll") for (int _i = 0; _i < 2; ++_i) \
;         __builtin_amdgcn_global_load_lds((const unsigned*)((const char*)(gbase) + (voff)[_i]), (PG8_LAS unsigned*)(lds + (bufoff) + ldsw + _i * 8192), 16, 0, 0); } while (0)
; #define PG8_LDA(dst, b, h) do { _Pragma("unroll") for (int m = 0; m < 4; ++m) _Pragma("unroll") for (int k = 0; k < 2; ++k) dst[m][k] = *(const PG8_LAS bf16x8*)(lds + PG8_SA(b, h) + aoff + m * 2048 + k * 1024); } while (0)
; #define PG8_MMA(ai, bj, At, Bt) do { __builtin_amdgcn_s_setprio(1); _Pragma("unroll") for (int m = 0; m < 4; ++m) _Pragma("unroll") for (int n = 0; n < 2; ++n) _Pragma("unroll") for (int k = 0; k < 2; ++k) \
;         acc[ai][bj][m][n] = __builtin_amdgcn_mfma_f32_16x16x32_bf16(Bt[n][k], At[m][k], acc[ai][bj][m][n], 0, 0, 0); __builtin_amdgcn_s_setprio(0); } while (0)
; #define PG8_WAIT_V(n) asm volatile("s_waitcnt vmcnt(" #n ")" ::: "memory")
; #define PG8_WAIT_L(n) asm volatile("s_waitcnt lgkmcnt(" #n ")" ::: "memory")
; #define PG8_BAR __builtin_amdgcn_s_barrier()
; #define PG8_SCHED __builtin_amdgcn_sched_barrier(0)
; template <class Epi, class Sched>
; __device__ __forceinline__ void gemm_phase(PG8_LAS unsigned char* lds, PG8_LAS unsigned char* xl, const Gemm g, const Sched& S, const Epi& E) {
;     ...
;             PG8_LDA(At, 1, 1); PG8_STAGE(PG8_SB(1, 0), b3, voffB); PG8_STAGE(PG8_SB(1, 1), b3 + hsB, voffB); PG8_STAGE(PG8_SA(1, 0), a3, voffA);
;             PG8_WAIT_V(8); PG8_WAIT_L(0); PG8_BAR; PG8_MMA(1, 0, At, B0); PG8_MMA(1, 1, At, B1); PG8_BAR; PG8_SCHED;
;         }
	s_add_i32 s34, s68, s51
	v_lshl_add_u64 v[238:239], v[238:239], 0, s[16:17]
	s_mov_b32 m0, s34
	ds_read_b128 v[204:207], v166 offset:49152
	ds_read_b128 v[208:211], v166 offset:50176
	ds_read_b128 v[212:215], v166 offset:51200
	ds_read_b128 v[216:219], v166 offset:52224
	ds_read_b128 v[222:225], v166 offset:53248
	ds_read_b128 v[226:229], v166 offset:54272
	ds_read_b128 v[230:233], v166 offset:55296
	ds_read_b128 v[234:237], v166 offset:56320
	global_load_lds_dwordx4 v[238:239], off
	s_add_i32 m0, s34, 0x2000
	s_add_u32 s30, s30, 0x40080
	v_lshl_add_u64 v[238:239], v[240:241], 0, s[16:17]
	s_addc_u32 s31, s31, 0
	s_add_i32 s34, s76, s51
	global_load_lds_dwordx4 v[238:239], off
	v_lshl_add_u64 v[238:239], s[30:31], 0, v[132:133]
	s_mov_b32 m0, s34
	s_nop 0
	global_load_lds_dwordx4 v[238:239], off
	v_lshl_add_u64 v[238:239], s[30:31], 0, v[128:129]
	s_add_i32 m0, s34, 0x2000
	s_nop 0
	global_load_lds_dwordx4 v[238:239], off
	v_lshl_add_u64 v[238:239], v[242:243], 0, s[16:17]
	s_mov_b32 m0, s59
	s_nop 0
	global_load_lds_dwordx4 v[238:239], off
	v_lshl_add_u64 v[238:239], v[244:245], 0, s[16:17]
	s_mov_b32 m0, s61
	s_nop 0
	global_load_lds_dwordx4 v[238:239], off
	s_waitcnt vmcnt(8)
	s_waitcnt lgkmcnt(0)
	s_barrier
	s_setprio 1
	s_waitcnt lgkmcnt(0)
	v_mfma_f32_16x16x32_bf16 v[60:63], v[170:173], v[204:207], v[60:63]
	v_mfma_f32_16x16x32_bf16 v[52:55], v[180:183], v[204:207], v[52:55]
	v_mfma_f32_16x16x32_bf16 v[44:47], v[170:173], v[212:215], v[44:47]
	v_mfma_f32_16x16x32_bf16 v[36:39], v[180:183], v[212:215], v[36:39]
	v_mfma_f32_16x16x32_bf16 v[28:31], v[170:173], v[222:225], v[28:31]
	v_mfma_f32_16x16x32_bf16 v[20:23], v[180:183], v[222:225], v[20:23]
	v_mfma_f32_16x16x32_bf16 v[12:15], v[170:173], v[230:233], v[12:15]
	v_mfma_f32_16x16x32_bf16 v[4:7], v[180:183], v[230:233], v[4:7]
	v_mfma_f32_16x16x32_bf16 v[60:63], v[174:177], v[208:211], v[60:63]
	v_mfma_f32_16x16x32_bf16 v[52:55], v[184:187], v[208:211], v[52:55]
	v_mfma_f32_16x16x32_bf16 v[44:47], v[174:177], v[216:219], v[44:47]
	v_mfma_f32_16x16x32_bf16 v[36:39], v[184:187], v[216:219], v[36:39]
	v_mfma_f32_16x16x32_bf16 v[28:31], v[174:177], v[226:229], v[28:31]
	v_mfma_f32_16x16x32_bf16 v[20:23], v[184:187], v[226:229], v[20:23]
	v_mfma_f32_16x16x32_bf16 v[12:15], v[174:177], v[234:237], v[12:15]
	v_mfma_f32_16x16x32_bf16 v[4:7], v[184:187], v[234:237], v[4:7]
	s_setprio 0
	s_setprio 1
	v_mfma_f32_16x16x32_bf16 v[56:59], v[188:191], v[204:207], v[56:59]
	s_add_i32 s75, s75, 2
	v_mfma_f32_16x16x32_bf16 v[48:51], v[196:199], v[204:207], v[48:51]
	s_add_u32 s73, s73, 0x100
	v_mfma_f32_16x16x32_bf16 v[40:43], v[188:191], v[212:215], v[40:43]
	s_addc_u32 s74, s74, 0
	v_mfma_f32_16x16x32_bf16 v[32:35], v[196:199], v[212:215], v[32:35]
	s_add_u32 s2, s2, 0x100
	v_mfma_f32_16x16x32_bf16 v[24:27], v[188:191], v[222:225], v[24:27]
	s_addc_u32 s3, s3, 0
	v_mfma_f32_16x16x32_bf16 v[16:19], v[196:199], v[222:225], v[16:19]
	s_cmp_gt_u32 s75, 13
	v_mfma_f32_16x16x32_bf16 v[8:11], v[188:191], v[230:233], v[8:11]
	v_mfma_f32_16x16x32_bf16 v[0:3], v[196:199], v[230:233], v[0:3]
	v_mfma_f32_16x16x32_bf16 v[56:59], v[192:195], v[208:211], v[56:59]
	v_mfma_f32_16x16x32_bf16 v[48:51], v[200:203], v[208:211], v[48:51]
	v_mfma_f32_16x16x32_bf16 v[40:43], v[192:195], v[216:219], v[40:43]
	v_mfma_f32_16x16x32_bf16 v[32:35], v[200:203], v[216:219], v[32:35]
	v_mfma_f32_16x16x32_bf16 v[24:27], v[192:195], v[226:229], v[24:27]
	v_mfma_f32_16x16x32_bf16 v[16:19], v[200:203], v[226:229], v[16:19]
	v_mfma_f32_16x16x32_bf16 v[8:11], v[192:195], v[234:237], v[8:11]
	v_mfma_f32_16x16x32_bf16 v[0:3], v[200:203], v[234:237], v[0:3]
	s_setprio 0
	s_barrier
	s_cbranch_scc0 .LBB0_825

; #define PG8_STAGE(bufoff, gbase, voff) do { _Pragma("unroll") for (int _i = 0; _i < 2; ++_i) \
;         __builtin_amdgcn_global_load_lds((const unsigned*)((const char*)(gbase) + (voff)[_i]), (PG8_LAS unsigned*)(lds + (bufoff) + ldsw + _i * 8192), 16, 0, 0); } while (0)
; #define PG8_LDA(dst, b, h) do { _Pragma("unroll") for (int m = 0; m < 4; ++m) _Pragma("unroll") for (int k = 0; k < 2; ++k) dst[m][k] = *(const PG8_LAS bf16x8*)(lds + PG8_SA(b, h) + aoff + m * 2048 + k * 1024); } while (0)
; #define PG8_LDB(dst, b, h) do { _Pragma("unroll") for (int n = 0; n < 2; ++n) _Pragma("unroll") for (int k = 0; k < 2; ++k) dst[n][k] = *(const PG8_LAS bf16x8*)(lds + PG8_SB(b, h) + boff + n * 2048 + k * 1024); } while (0)
; #define PG8_MMA(ai, bj, At, Bt) do { __builtin_amdgcn_s_setprio(1); _Pragma("unroll") for (int m = 0; m < 4; ++m) _Pragma("unroll") for (int n = 0; n < 2; ++n) _Pragma("unroll") for (int k = 0; k < 2; ++k) \
;         acc[ai][bj][m][n] = __builtin_amdgcn_mfma_f32_16x16x32_bf16(Bt[n][k], At[m][k], acc[ai][bj][m][n], 0, 0, 0); __builtin_amdgcn_s_setprio(0); } while (0)
; #define PG8_WAIT_V(n) asm volatile("s_waitcnt vmcnt(" #n ")" ::: "memory")
; #define PG8_WAIT_L(n) asm volatile("s_waitcnt lgkmcnt(" #n ")" ::: "memory")
; #define PG8_BAR __builtin_amdgcn_s_barrier()
; #define PG8_SCHED __builtin_amdgcn_sched_barrier(0)
; template <class Epi, class Sched>
; __device__ __forceinline__ void gemm_phase(PG8_LAS unsigned char* lds, PG8_LAS unsigned char* xl, const Gemm g, const Sched& S, const Epi& E) {
;     ...
;             PG8_LDB(B0, 0, 0); PG8_LDB(B1, 0, 1); PG8_SCHED; PG8_LDA(At, 0, 0); PG8_STAGE(PG8_SA(1, 1), a1 + hsA, voffA);
;             PG8_WAIT_V(8); PG8_WAIT_L(0); PG8_BAR; PG8_MMA(0, 0, At, B0); PG8_MMA(0, 1, At, B1); PG8_BAR; PG8_SCHED;
;             PG8_LDA(At, 0, 1); PG8_STAGE(PG8_SB(0, 0), b2, voffB); PG8_STAGE(PG8_SB(0, 1), b2 + hsB, voffB); PG8_STAGE(PG8_SA(0, 0), a2, voffA);
;             PG8_WAIT_V(8); PG8_WAIT_L(0); PG8_BAR; PG8_MMA(1, 0, At, B0); PG8_MMA(1, 1, At, B1); PG8_BAR; PG8_SCHED;
;             PG8_LDB(B0, 1, 0); PG8_LDB(B1, 1, 1); PG8_SCHED; PG8_LDA(At, 1, 0); PG8_STAGE(PG8_SA(0, 1), a2 + hsA, voffA);
.LBB0_914:
	ds_read_b128 v[144:147], v151
	ds_read_b128 v[154:157], v151 offset:1024
	ds_read_b128 v[158:161], v151 offset:2048
	ds_read_b128 v[162:165], v151 offset:3072
	ds_read_b128 v[166:169], v152
	ds_read_b128 v[170:173], v152 offset:1024
	ds_read_b128 v[174:177], v152 offset:2048
	ds_read_b128 v[180:183], v152 offset:3072
	s_add_u32 s28, s26, 0x100
	s_addc_u32 s29, s27, 0
	s_cmp_eq_u32 s67, 40
	s_cselect_b32 s35, s61, s29
	s_cselect_b32 s34, s62, s28
	s_cselect_b32 s31, s63, s66
	s_cselect_b32 s30, s64, s65
	v_lshl_add_u64 v[216:217], s[26:27], 0, v[138:139]
	s_add_i32 m0, s42, 0xc000
	ds_read_b128 v[184:187], v153
	ds_read_b128 v[188:191], v153 offset:1024
	ds_read_b128 v[192:195], v153 offset:2048
	ds_read_b128 v[196:199], v153 offset:3072
	ds_read_b128 v[200:203], v153 offset:4096
	ds_read_b128 v[204:207], v153 offset:5120
	ds_read_b128 v[208:211], v153 offset:6144
	ds_read_b128 v[212:215], v153 offset:7168
	global_load_lds_dwordx4 v[216:217], off
	v_lshl_add_u64 v[216:217], s[26:27], 0, v[136:137]
	s_add_i32 m0, s42, 0xe000
	s_nop 0
	global_load_lds_dwordx4 v[216:217], off
	s_waitcnt vmcnt(8)
	s_waitcnt lgkmcnt(0)
	s_barrier
	s_setprio 1
	s_waitcnt lgkmcnt(0)
	v_mfma_f32_16x16x32_bf16 v[124:127], v[144:147], v[184:187], v[124:127]
	v_mfma_f32_16x16x32_bf16 v[120:123], v[158:161], v[184:187], v[120:123]
	v_mfma_f32_16x16x32_bf16 v[108:111], v[144:147], v[192:195], v[108:111]
	v_mfma_f32_16x16x32_bf16 v[104:107], v[158:161], v[192:195], v[104:107]
	v_mfma_f32_16x16x32_bf16 v[92:95], v[144:147], v[200:203], v[92:95]
	v_mfma_f32_16x16x32_bf16 v[88:91], v[158:161], v[200:203], v[88:91]
	v_mfma_f32_16x16x32_bf16 v[76:79], v[144:147], v[208:211], v[76:79]
	v_mfma_f32_16x16x32_bf16 v[72:75], v[158:161], v[208:211], v[72:75]
	v_mfma_f32_16x16x32_bf16 v[124:127], v[154:157], v[188:191], v[124:127]
	v_mfma_f32_16x16x32_bf16 v[120:123], v[162:165], v[188:191], v[120:123]
	v_mfma_f32_16x16x32_bf16 v[108:111], v[154:157], v[196:199], v[108:111]
	v_mfma_f32_16x16x32_bf16 v[104:107], v[162:165], v[196:199], v[104:107]
	v_mfma_f32_16x16x32_bf16 v[92:95], v[154:157], v[204:207], v[92:95]
	v_mfma_f32_16x16x32_bf16 v[88:91], v[162:165], v[204:207], v[88:91]
	v_mfma_f32_16x16x32_bf16 v[76:79], v[154:157], v[212:215], v[76:79]
	v_mfma_f32_16x16x32_bf16 v[72:75], v[162:165], v[212:215], v[72:75]
	s_setprio 0
	s_setprio 1
	v_mfma_f32_16x16x32_bf16 v[116:119], v[166:169], v[184:187], v[116:119]
	v_mfma_f32_16x16x32_bf16 v[112:115], v[174:177], v[184:187], v[112:115]
	v_mfma_f32_16x16x32_bf16 v[100:103], v[166:169], v[192:195], v[100:103]
	v_mfma_f32_16x16x32_bf16 v[96:99], v[174:177], v[192:195], v[96:99]
	v_mfma_f32_16x16x32_bf16 v[84:87], v[166:169], v[200:203], v[84:87]
	v_mfma_f32_16x16x32_bf16 v[80:83], v[174:177], v[200:203], v[80:83]
	v_mfma_f32_16x16x32_bf16 v[68:71], v[166:169], v[208:211], v[68:71]
	v_mfma_f32_16x16x32_bf16 v[64:67], v[174:177], v[208:211], v[64:67]
	v_mfma_f32_16x16x32_bf16 v[116:119], v[170:173], v[188:191], v[116:119]
	v_mfma_f32_16x16x32_bf16 v[112:115], v[180:183], v[188:191], v[112:115]
	v_mfma_f32_16x16x32_bf16 v[100:103], v[170:173], v[196:199], v[100:103]
	v_mfma_f32_16x16x32_bf16 v[96:99], v[180:183], v[196:199], v[96:99]
	v_mfma_f32_16x16x32_bf16 v[84:87], v[170:173], v[204:207], v[84:87]
	v_mfma_f32_16x16x32_bf16 v[80:83], v[180:183], v[204:207], v[80:83]
	v_mfma_f32_16x16x32_bf16 v[68:71], v[170:173], v[212:215], v[68:71]
	v_mfma_f32_16x16x32_bf16 v[64:67], v[180:183], v[212:215], v[64:67]
	s_setprio 0
	s_barrier
	s_add_i32 s26, s51, s37
	v_lshl_add_u64 v[216:217], s[30:31], 0, v[130:131]
	s_mov_b32 m0, s26
	ds_read_b128 v[184:187], v153 offset:16384
	ds_read_b128 v[188:191], v153 offset:17408
	ds_read_b128 v[192:195], v153 offset:18432
	ds_read_b128 v[196:199], v153 offset:19456
	ds_read_b128 v[200:203], v153 offset:20480
	ds_read_b128 v[204:207], v153 offset:21504
	ds_read_b128 v[208:211], v153 offset:22528
	ds_read_b128 v[212:215], v153 offset:23552
	global_load_lds_dwordx4 v[216:217], off
	s_add_i32 m0, s26, 0x2000
	s_add_u32 s26, s30, 0xb0000
	v_lshl_add_u64 v[218:219], s[30:31], 0, v[134:135]
	s_addc_u32 s27, s31, 0
	s_add_i32 s68, s52, s37
	global_load_lds_dwordx4 v[218:219], off
	v_lshl_add_u64 v[222:223], s[26:27], 0, v[130:131]
	s_mov_b32 m0, s68
	v_lshl_add_u64 v[224:225], s[34:35], 0, v[132:133]
	global_load_lds_dwordx4 v[222:223], off
	v_lshl_add_u64 v[222:223], s[26:27], 0, v[134:135]
	s_add_i32 m0, s68, 0x2000
	s_nop 0
	global_load_lds_dwordx4 v[222:223], off
	v_lshl_add_u64 v[222:223], s[34:35], 0, v[128:129]
	s_mov_b32 m0, s42
	s_nop 0
	global_load_lds_dwordx4 v[222:223], off
	s_mov_b32 m0, s43
	s_nop 0
	global_load_lds_dwordx4 v[224:225], off
	s_waitcnt vmcnt(8)
	s_waitcnt lgkmcnt(0)
	s_barrier
; #define PG8_STAGE(bufoff, gbase, voff) do { _Pragma("unroll") for (int _i = 0; _i < 2; ++_i) \
;         __builtin_amdgcn_global_load_lds((const unsigned*)((const char*)(gbase) + (voff)[_i]), (PG8_LAS unsigned*)(lds + (bufoff) + ldsw + _i * 8192), 16, 0, 0); } while (0)
; #define PG8_LDA(dst, b, h) do { _Pragma("unroll") for (int m = 0; m < 4; ++m) _Pragma("unroll") for (int k = 0; k < 2; ++k) dst[m][k] = *(const PG8_LAS bf16x8*)(lds + PG8_SA(b, h) + aoff + m * 2048 + k * 1024); } while (0)
; #define PG8_LDB(dst, b, h) do { _Pragma("unroll") for (int n = 0; n < 2; ++n) _Pragma("unroll") for (int k = 0; k < 2; ++k) dst[n][k] = *(const PG8_LAS bf16x8*)(lds + PG8_SB(b, h) + boff + n * 2048 + k * 1024); } while (0)
; #define PG8_MMA(ai, bj, At, Bt) do { __builtin_amdgcn_s_setprio(1); _Pragma("unroll") for (int m = 0; m < 4; ++m) _Pragma("unroll") for (int n = 0; n < 2; ++n) _Pragma("unroll") for (int k = 0; k < 2; ++k) \
;         acc[ai][bj][m][n] = __builtin_amdgcn_mfma_f32_16x16x32_bf16(Bt[n][k], At[m][k], acc[ai][bj][m][n], 0, 0, 0); __builtin_amdgcn_s_setprio(0); } while (0)
; #define PG8_WAIT_V(n) asm volatile("s_waitcnt vmcnt(" #n ")" ::: "memory")
; #define PG8_WAIT_L(n) asm volatile("s_waitcnt lgkmcnt(" #n ")" ::: "memory")
; #define PG8_BAR __builtin_amdgcn_s_barrier()
; #define PG8_SCHED __builtin_amdgcn_sched_barrier(0)
; template <class Epi, class Sched>
; __device__ __forceinline__ void gemm_phase(PG8_LAS unsigned char* lds, PG8_LAS unsigned char* xl, const Gemm g, const Sched& S, const Epi& E) {
;     ...
;             PG8_WAIT_V(8); PG8_WAIT_L(0); PG8_BAR; PG8_MMA(1, 0, At, B0); PG8_MMA(1, 1, At, B1); PG8_BAR; PG8_SCHED;
;             PG8_LDB(B0, 1, 0); PG8_LDB(B1, 1, 1); PG8_SCHED; PG8_LDA(At, 1, 0); PG8_STAGE(PG8_SA(0, 1), a2 + hsA, voffA);
;             PG8_WAIT_V(8); PG8_WAIT_L(0); PG8_BAR; PG8_MMA(0, 0, At, B0); PG8_MMA(0, 1, At, B1); PG8_BAR; PG8_SCHED;
	s_setprio 1
	s_waitcnt lgkmcnt(0)
	v_mfma_f32_16x16x32_bf16 v[60:63], v[144:147], v[184:187], v[60:63]
	v_mfma_f32_16x16x32_bf16 v[56:59], v[158:161], v[184:187], v[56:59]
	v_mfma_f32_16x16x32_bf16 v[44:47], v[144:147], v[192:195], v[44:47]
	v_mfma_f32_16x16x32_bf16 v[40:43], v[158:161], v[192:195], v[40:43]
	v_mfma_f32_16x16x32_bf16 v[28:31], v[144:147], v[200:203], v[28:31]
	v_mfma_f32_16x16x32_bf16 v[24:27], v[158:161], v[200:203], v[24:27]
	v_mfma_f32_16x16x32_bf16 v[12:15], v[144:147], v[208:211], v[12:15]
	v_mfma_f32_16x16x32_bf16 v[8:11], v[158:161], v[208:211], v[8:11]
	v_mfma_f32_16x16x32_bf16 v[60:63], v[154:157], v[188:191], v[60:63]
	v_mfma_f32_16x16x32_bf16 v[56:59], v[162:165], v[188:191], v[56:59]
	v_mfma_f32_16x16x32_bf16 v[44:47], v[154:157], v[196:199], v[44:47]
	v_mfma_f32_16x16x32_bf16 v[40:43], v[162:165], v[196:199], v[40:43]
	v_mfma_f32_16x16x32_bf16 v[28:31], v[154:157], v[204:207], v[28:31]
	v_mfma_f32_16x16x32_bf16 v[24:27], v[162:165], v[204:207], v[24:27]
	v_mfma_f32_16x16x32_bf16 v[12:15], v[154:157], v[212:215], v[12:15]
	v_mfma_f32_16x16x32_bf16 v[8:11], v[162:165], v[212:215], v[8:11]
	s_setprio 0
	s_setprio 1
	v_mfma_f32_16x16x32_bf16 v[52:55], v[166:169], v[184:187], v[52:55]
	v_mfma_f32_16x16x32_bf16 v[48:51], v[174:177], v[184:187], v[48:51]
	v_mfma_f32_16x16x32_bf16 v[36:39], v[166:169], v[192:195], v[36:39]
	v_mfma_f32_16x16x32_bf16 v[32:35], v[174:177], v[192:195], v[32:35]
	v_mfma_f32_16x16x32_bf16 v[20:23], v[166:169], v[200:203], v[20:23]
	v_mfma_f32_16x16x32_bf16 v[16:19], v[174:177], v[200:203], v[16:19]
	v_mfma_f32_16x16x32_bf16 v[4:7], v[166:169], v[208:211], v[4:7]
	v_mfma_f32_16x16x32_bf16 v[0:3], v[174:177], v[208:211], v[0:3]
	v_mfma_f32_16x16x32_bf16 v[52:55], v[170:173], v[188:191], v[52:55]
	v_mfma_f32_16x16x32_bf16 v[48:51], v[180:183], v[188:191], v[48:51]
	v_mfma_f32_16x16x32_bf16 v[36:39], v[170:173], v[196:199], v[36:39]
	v_mfma_f32_16x16x32_bf16 v[32:35], v[180:183], v[196:199], v[32:35]
	v_mfma_f32_16x16x32_bf16 v[20:23], v[170:173], v[204:207], v[20:23]
	v_mfma_f32_16x16x32_bf16 v[16:19], v[180:183], v[204:207], v[16:19]
	v_mfma_f32_16x16x32_bf16 v[4:7], v[170:173], v[212:215], v[4:7]
	v_mfma_f32_16x16x32_bf16 v[0:3], v[180:183], v[212:215], v[0:3]
	s_setprio 0
	s_barrier
	s_add_i32 s68, 0, 0x18000
	s_add_i32 s70, 0, 0x1c000
	v_add_u32_e32 v162, s68, v149
	v_add_u32_e32 v179, s70, v149
	ds_read_b128 v[144:147], v162
	ds_read_b128 v[154:157], v162 offset:1024
	ds_read_b128 v[158:161], v162 offset:2048
	ds_read_b128 v[162:165], v162 offset:3072
	ds_read_b128 v[166:169], v179
	ds_read_b128 v[170:173], v179 offset:1024
	ds_read_b128 v[174:177], v179 offset:2048
	ds_read_b128 v[180:183], v179 offset:3072
	s_add_u32 s26, s34, 0xb0000
	s_addc_u32 s27, s35, 0
	s_mov_b32 m0, s46
	v_lshl_add_u64 v[226:227], s[26:27], 0, v[128:129]
	ds_read_b128 v[184:187], v153 offset:32768
	ds_read_b128 v[188:191], v153 offset:33792
	ds_read_b128 v[192:195], v153 offset:34816
	ds_read_b128 v[196:199], v153 offset:35840
	ds_read_b128 v[200:203], v153 offset:36864
	ds_read_b128 v[204:207], v153 offset:37888
	ds_read_b128 v[208:211], v153 offset:38912
	ds_read_b128 v[212:215], v153 offset:39936
	global_load_lds_dwordx4 v[226:227], off
	v_lshl_add_u64 v[226:227], s[26:27], 0, v[132:133]
	s_mov_b32 m0, s47
	s_nop 0
	global_load_lds_dwordx4 v[226:227], off
	s_waitcnt vmcnt(8)
	s_waitcnt lgkmcnt(0)
	s_barrier
	s_setprio 1
	s_waitcnt lgkmcnt(0)
	v_mfma_f32_16x16x32_bf16 v[124:127], v[144:147], v[184:187], v[124:127]
	v_mfma_f32_16x16x32_bf16 v[120:123], v[158:161], v[184:187], v[120:123]
	v_mfma_f32_16x16x32_bf16 v[108:111], v[144:147], v[192:195], v[108:111]
	v_mfma_f32_16x16x32_bf16 v[104:107], v[158:161], v[192:195], v[104:107]
	v_mfma_f32_16x16x32_bf16 v[92:95], v[144:147], v[200:203], v[92:95]
	v_mfma_f32_16x16x32_bf16 v[88:91], v[158:161], v[200:203], v[88:91]
	v_mfma_f32_16x16x32_bf16 v[76:79], v[144:147], v[208:211], v[76:79]
	v_mfma_f32_16x16x32_bf16 v[72:75], v[158:161], v[208:211], v[72:75]
	v_mfma_f32_16x16x32_bf16 v[124:127], v[154:157], v[188:191], v[124:127]
	v_mfma_f32_16x16x32_bf16 v[120:123], v[162:165], v[188:191], v[120:123]
	v_mfma_f32_16x16x32_bf16 v[108:111], v[154:157], v[196:199], v[108:111]
	v_mfma_f32_16x16x32_bf16 v[104:107], v[162:165], v[196:199], v[104:107]
	v_mfma_f32_16x16x32_bf16 v[92:95], v[154:157], v[204:207], v[92:95]
	v_mfma_f32_16x16x32_bf16 v[88:91], v[162:165], v[204:207], v[88:91]
	v_mfma_f32_16x16x32_bf16 v[76:79], v[154:157], v[212:215], v[76:79]
	v_mfma_f32_16x16x32_bf16 v[72:75], v[162:165], v[212:215], v[72:75]
	s_setprio 0
	s_setprio 1
	v_mfma_f32_16x16x32_bf16 v[116:119], v[166:169], v[184:187], v[116:119]
	v_mfma_f32_16x16x32_bf16 v[112:115], v[174:177], v[184:187], v[112:115]
	v_mfma_f32_16x16x32_bf16 v[100:103], v[166:169], v[192:195], v[100:103]
	v_mfma_f32_16x16x32_bf16 v[96:99], v[174:177], v[192:195], v[96:99]
	v_mfma_f32_16x16x32_bf16 v[84:87], v[166:169], v[200:203], v[84:87]
	v_mfma_f32_16x16x32_bf16 v[80:83], v[174:177], v[200:203], v[80:83]
	v_mfma_f32_16x16x32_bf16 v[68:71], v[166:169], v[208:211], v[68:71]
	v_mfma_f32_16x16x32_bf16 v[64:67], v[174:177], v[208:211], v[64:67]
	v_mfma_f32_16x16x32_bf16 v[116:119], v[170:173], v[188:191], v[116:119]
	v_mfma_f32_16x16x32_bf16 v[112:115], v[180:183], v[188:191], v[112:115]
	v_mfma_f32_16x16x32_bf16 v[100:103], v[170:173], v[196:199], v[100:103]
	v_mfma_f32_16x16x32_bf16 v[96:99], v[180:183], v[196:199], v[96:99]
	v_mfma_f32_16x16x32_bf16 v[84:87], v[170:173], v[204:207], v[84:87]
	v_mfma_f32_16x16x32_bf16 v[80:83], v[180:183], v[204:207], v[80:83]
	v_mfma_f32_16x16x32_bf16 v[68:71], v[170:173], v[212:215], v[68:71]
	v_mfma_f32_16x16x32_bf16 v[64:67], v[180:183], v[212:215], v[64:67]
	s_setprio 0
	s_barrier
; #define PG8_STAGE(bufoff, gbase, voff) do { _Pragma("unroll") for (int _i = 0; _i < 2; ++_i) \
;         __builtin_amdgcn_global_load_lds((const unsigned*)((const char*)(gbase) + (voff)[_i]), (PG8_LAS unsigned*)(lds + (bufoff) + ldsw + _i * 8192), 16, 0, 0); } while (0)
; #define PG8_LDA(dst, b, h) do { _Pragma("unroll") for (int m = 0; m < 4; ++m) _Pragma("unroll") for (int k = 0; k < 2; ++k) dst[m][k] = *(const PG8_LAS bf16x8*)(lds + PG8_SA(b, h) + aoff + m * 2048 + k * 1024); } while (0)
; #define PG8_MMA(ai, bj, At, Bt) do { __builtin_amdgcn_s_setprio(1); _Pragma("unroll") for (int m = 0; m < 4; ++m) _Pragma("unroll") for (int n = 0; n < 2; ++n) _Pragma("unroll") for (int k = 0; k < 2; ++k) \
;         acc[ai][bj][m][n] = __builtin_amdgcn_mfma_f32_16x16x32_bf16(Bt[n][k], At[m][k], acc[ai][bj][m][n], 0, 0, 0); __builtin_amdgcn_s_setprio(0); } while (0)
; #define PG8_WAIT_V(n) asm volatile("s_waitcnt vmcnt(" #n ")" ::: "memory")
; #define PG8_WAIT_L(n) asm volatile("s_waitcnt lgkmcnt(" #n ")" ::: "memory")
; #define PG8_BAR __builtin_amdgcn_s_barrier()
; #define PG8_SCHED __builtin_amdgcn_sched_barrier(0)
; template <class Epi, class Sched>
; __device__ __forceinline__ void gemm_phase(PG8_LAS unsigned char* lds, PG8_LAS unsigned char* xl, const Gemm g, const Sched& S, const Epi& E) {
;     ...
;             PG8_LDA(At, 1, 1); PG8_STAGE(PG8_SB(1, 0), b3, voffB); PG8_STAGE(PG8_SB(1, 1), b3 + hsB, voffB); PG8_STAGE(PG8_SA(1, 0), a3, voffA);
;             PG8_WAIT_V(8); PG8_WAIT_L(0); PG8_BAR; PG8_MMA(1, 0, At, B0); PG8_MMA(1, 1, At, B1); PG8_BAR; PG8_SCHED;
;         }
;         if (wr == 0) PG8_BAR;
	s_add_i32 s26, s68, s37
	v_lshl_add_u64 v[216:217], v[216:217], 0, s[12:13]
	s_mov_b32 m0, s26
	ds_read_b128 v[184:187], v153 offset:49152
	ds_read_b128 v[188:191], v153 offset:50176
	ds_read_b128 v[192:195], v153 offset:51200
	ds_read_b128 v[196:199], v153 offset:52224
	ds_read_b128 v[200:203], v153 offset:53248
	ds_read_b128 v[204:207], v153 offset:54272
	ds_read_b128 v[208:211], v153 offset:55296
	ds_read_b128 v[212:215], v153 offset:56320
	global_load_lds_dwordx4 v[216:217], off
	s_add_i32 m0, s26, 0x2000
	s_add_u32 s26, s30, 0xb0080
	v_lshl_add_u64 v[216:217], v[218:219], 0, s[12:13]
	s_addc_u32 s27, s31, 0
	s_add_i32 s30, s70, s37
	global_load_lds_dwordx4 v[216:217], off
	v_lshl_add_u64 v[216:217], s[26:27], 0, v[130:131]
	s_mov_b32 m0, s30
	s_nop 0
	global_load_lds_dwordx4 v[216:217], off
	v_lshl_add_u64 v[216:217], s[26:27], 0, v[134:135]
	s_add_i32 m0, s30, 0x2000
	s_nop 0
	global_load_lds_dwordx4 v[216:217], off
	v_lshl_add_u64 v[216:217], v[222:223], 0, s[12:13]
	s_mov_b32 m0, s49
	s_nop 0
	global_load_lds_dwordx4 v[216:217], off
	v_lshl_add_u64 v[216:217], v[224:225], 0, s[12:13]
	s_mov_b32 m0, s50
	s_nop 0
	global_load_lds_dwordx4 v[216:217], off
	s_waitcnt vmcnt(8)
	s_waitcnt lgkmcnt(0)
	s_barrier
	s_setprio 1
	s_waitcnt lgkmcnt(0)
	v_mfma_f32_16x16x32_bf16 v[60:63], v[144:147], v[184:187], v[60:63]
	v_mfma_f32_16x16x32_bf16 v[56:59], v[158:161], v[184:187], v[56:59]
	v_mfma_f32_16x16x32_bf16 v[44:47], v[144:147], v[192:195], v[44:47]
	v_mfma_f32_16x16x32_bf16 v[40:43], v[158:161], v[192:195], v[40:43]
	v_mfma_f32_16x16x32_bf16 v[28:31], v[144:147], v[200:203], v[28:31]
	v_mfma_f32_16x16x32_bf16 v[24:27], v[158:161], v[200:203], v[24:27]
	v_mfma_f32_16x16x32_bf16 v[12:15], v[144:147], v[208:211], v[12:15]
	v_mfma_f32_16x16x32_bf16 v[8:11], v[158:161], v[208:211], v[8:11]
	v_mfma_f32_16x16x32_bf16 v[60:63], v[154:157], v[188:191], v[60:63]
	v_mfma_f32_16x16x32_bf16 v[56:59], v[162:165], v[188:191], v[56:59]
	v_mfma_f32_16x16x32_bf16 v[44:47], v[154:157], v[196:199], v[44:47]
	v_mfma_f32_16x16x32_bf16 v[40:43], v[162:165], v[196:199], v[40:43]
	v_mfma_f32_16x16x32_bf16 v[28:31], v[154:157], v[204:207], v[28:31]
	v_mfma_f32_16x16x32_bf16 v[24:27], v[162:165], v[204:207], v[24:27]
	v_mfma_f32_16x16x32_bf16 v[12:15], v[154:157], v[212:215], v[12:15]
	v_mfma_f32_16x16x32_bf16 v[8:11], v[162:165], v[212:215], v[8:11]
	s_setprio 0
	s_setprio 1
	v_mfma_f32_16x16x32_bf16 v[52:55], v[166:169], v[184:187], v[52:55]
	s_add_i32 s67, s67, 2
	v_mfma_f32_16x16x32_bf16 v[48:51], v[174:177], v[184:187], v[48:51]
	s_add_u32 s65, s65, 0x100
	v_mfma_f32_16x16x32_bf16 v[36:39], v[166:169], v[192:195], v[36:39]
	s_addc_u32 s66, s66, 0
	v_mfma_f32_16x16x32_bf16 v[32:35], v[174:177], v[192:195], v[32:35]
	s_cmp_gt_u32 s67, 41
	v_mfma_f32_16x16x32_bf16 v[20:23], v[166:169], v[200:203], v[20:23]
	s_mov_b64 s[26:27], s[28:29]
	v_mfma_f32_16x16x32_bf16 v[16:19], v[174:177], v[200:203], v[16:19]
	v_mfma_f32_16x16x32_bf16 v[4:7], v[166:169], v[208:211], v[4:7]
	v_mfma_f32_16x16x32_bf16 v[0:3], v[174:177], v[208:211], v[0:3]
	v_mfma_f32_16x16x32_bf16 v[52:55], v[170:173], v[188:191], v[52:55]
	v_mfma_f32_16x16x32_bf16 v[48:51], v[180:183], v[188:191], v[48:51]
	v_mfma_f32_16x16x32_bf16 v[36:39], v[170:173], v[196:199], v[36:39]
	v_mfma_f32_16x16x32_bf16 v[32:35], v[180:183], v[196:199], v[32:35]
	v_mfma_f32_16x16x32_bf16 v[20:23], v[170:173], v[204:207], v[20:23]
	v_mfma_f32_16x16x32_bf16 v[16:19], v[180:183], v[204:207], v[16:19]
	v_mfma_f32_16x16x32_bf16 v[4:7], v[170:173], v[212:215], v[4:7]
	v_mfma_f32_16x16x32_bf16 v[0:3], v[180:183], v[212:215], v[0:3]
	s_setprio 0
	s_barrier
	s_cbranch_scc0 .LBB0_914
	s_and_b64 vcc, exec, s[14:15]
	s_cbranch_vccz .LBB0_917
	s_barrier

; #define PG8_STAGE(bufoff, gbase, voff) do { _Pragma("unroll") for (int _i = 0; _i < 2; ++_i) \
;         __builtin_amdgcn_global_load_lds((const unsigned*)((const char*)(gbase) + (voff)[_i]), (PG8_LAS unsigned*)(lds + (bufoff) + ldsw + _i * 8192), 16, 0, 0); } while (0)
; #define PG8_LDA(dst, b, h) do { _Pragma("unroll") for (int m = 0; m < 4; ++m) _Pragma("unroll") for (int k = 0; k < 2; ++k) dst[m][k] = *(const PG8_LAS bf16x8*)(lds + PG8_SA(b, h) + aoff + m * 2048 + k * 1024); } while (0)
; #define PG8_LDB(dst, b, h) do { _Pragma("unroll") for (int n = 0; n < 2; ++n) _Pragma("unroll") for (int k = 0; k < 2; ++k) dst[n][k] = *(const PG8_LAS bf16x8*)(lds + PG8_SB(b, h) + boff + n * 2048 + k * 1024); } while (0)
; #define PG8_MMA(ai, bj, At, Bt) do { __builtin_amdgcn_s_setprio(1); _Pragma("unroll") for (int m = 0; m < 4; ++m) _Pragma("unroll") for (int n = 0; n < 2; ++n) _Pragma("unroll") for (int k = 0; k < 2; ++k) \
;         acc[ai][bj][m][n] = __builtin_amdgcn_mfma_f32_16x16x32_bf16(Bt[n][k], At[m][k], acc[ai][bj][m][n], 0, 0, 0); __builtin_amdgcn_s_setprio(0); } while (0)
; #define PG8_WAIT_V(n) asm volatile("s_waitcnt vmcnt(" #n ")" ::: "memory")
; #define PG8_BAR __builtin_amdgcn_s_barrier()
; template <class Epi, class Sched>
; __device__ __forceinline__ void gemm_phase(PG8_LAS unsigned char* lds, PG8_LAS unsigned char* xl, const Gemm g, const Sched& S, const Epi& E) {
;     ...
;     for (;;) {
;         const bool has_next = S.next(ui + 1, nxt);
;         const char* nA = has_next ? (const char*)g.A + nxt.aoff : cA; const char* nB = has_next ? (const char*)g.Bt + nxt.boff : cB;
; #pragma unroll 1
;         for (int t = 0; t < nt; t += 2) {
;             const bool last = (t == nt - 2);
;             const char* a1 = cA + (size_t)(t + 1) * kstep;
;             const char* a2 = last ? nA : cA + (size_t)(t + 2) * kstep; const char* b2 = last ? nB : cB + (size_t)(t + 2) * kstep;
;             const char* a3 = a2 + kstep; const char* b3 = b2 + kstep;
;             PG8_LDB(B0, 0, 0); PG8_LDB(B1, 0, 1); PG8_SCHED; PG8_LDA(At, 0, 0); PG8_STAGE(PG8_SA(1, 1), a1 + hsA, voffA);
;             PG8_WAIT_V(8); PG8_WAIT_L(0); PG8_BAR; PG8_MMA(0, 0, At, B0); PG8_MMA(0, 1, At, B1); PG8_BAR; PG8_SCHED;
;             PG8_LDA(At, 0, 1); PG8_STAGE(PG8_SB(0, 0), b2, voffB); PG8_STAGE(PG8_SB(0, 1), b2 + hsB, voffB); PG8_STAGE(PG8_SA(0, 0), a2, voffA);
.LBB0_941:
	s_add_u32 s34, s55, s28
	s_addc_u32 s35, s56, s29
	s_and_b64 s[36:37], s[10:11], exec
	s_cselect_b32 s33, s35, s3
	s_cselect_b32 s46, s34, s2
	s_add_u32 s36, s57, s30
	s_addc_u32 s37, s58, s31
	s_and_b64 s[50:51], s[10:11], exec
	s_cselect_b32 s47, s37, s49
	s_cselect_b32 s77, s36, s48
	s_add_u32 s78, s48, 0x100
	v_mov_b32_e32 v0, 0
	s_addc_u32 s79, s49, 0
	s_mov_b32 s80, -2
	ds_read_b128 v[144:147], v199
	ds_read_b128 v[148:151], v199 offset:1024
	ds_read_b128 v[152:155], v199 offset:2048
	ds_read_b128 v[156:159], v199 offset:3072
	ds_read_b128 v[160:163], v200
	ds_read_b128 v[164:167], v200 offset:1024
	ds_read_b128 v[168:171], v200 offset:2048
	ds_read_b128 v[172:175], v200 offset:3072
	s_add_u32 s48, s2, 0x100
	s_addc_u32 s49, s3, 0
	s_cmp_eq_u32 s80, 40
	s_cselect_b32 s53, s33, s49
	s_cselect_b32 s52, s46, s48
	s_cselect_b32 s51, s47, s79
	s_cselect_b32 s50, s77, s78
	v_lshl_add_u64 v[176:177], s[2:3], 0, v[138:139]
	s_add_i32 m0, s43, 0xc000
	ds_read_b128 v[214:217], v201
	ds_read_b128 v[222:225], v201 offset:1024
	ds_read_b128 v[226:229], v201 offset:2048
	ds_read_b128 v[230:233], v201 offset:3072
	ds_read_b128 v[234:237], v201 offset:4096
	ds_read_b128 v[238:241], v201 offset:5120
	ds_read_b128 v[242:245], v201 offset:6144
	ds_read_b128 v[246:249], v201 offset:7168
	global_load_lds_dwordx4 v[176:177], off
	v_lshl_add_u64 v[176:177], s[2:3], 0, v[136:137]
	s_add_i32 m0, s43, 0xe000
	s_nop 0
	global_load_lds_dwordx4 v[176:177], off
	s_waitcnt vmcnt(8)
	s_waitcnt lgkmcnt(0)
	s_barrier
	s_setprio 1
	s_waitcnt lgkmcnt(0)
	v_mfma_f32_16x16x32_bf16 v[124:127], v[144:147], v[214:217], 0
	v_mfma_f32_16x16x32_bf16 v[120:123], v[152:155], v[214:217], 0
	v_mfma_f32_16x16x32_bf16 v[108:111], v[144:147], v[226:229], 0
	v_mfma_f32_16x16x32_bf16 v[104:107], v[152:155], v[226:229], 0
	v_mfma_f32_16x16x32_bf16 v[92:95], v[144:147], v[234:237], 0
	v_mfma_f32_16x16x32_bf16 v[88:91], v[152:155], v[234:237], 0
	v_mfma_f32_16x16x32_bf16 v[76:79], v[144:147], v[242:245], 0
	v_mfma_f32_16x16x32_bf16 v[72:75], v[152:155], v[242:245], 0
	v_mfma_f32_16x16x32_bf16 v[124:127], v[148:151], v[222:225], v[124:127]
	v_mfma_f32_16x16x32_bf16 v[120:123], v[156:159], v[222:225], v[120:123]
	v_mfma_f32_16x16x32_bf16 v[108:111], v[148:151], v[230:233], v[108:111]
	v_mfma_f32_16x16x32_bf16 v[104:107], v[156:159], v[230:233], v[104:107]
	v_mfma_f32_16x16x32_bf16 v[92:95], v[148:151], v[238:241], v[92:95]
	v_mfma_f32_16x16x32_bf16 v[88:91], v[156:159], v[238:241], v[88:91]
	v_mfma_f32_16x16x32_bf16 v[76:79], v[148:151], v[246:249], v[76:79]
	v_mfma_f32_16x16x32_bf16 v[72:75], v[156:159], v[246:249], v[72:75]
	s_setprio 0
	s_setprio 1
	v_mfma_f32_16x16x32_bf16 v[116:119], v[160:163], v[214:217], 0
	v_mfma_f32_16x16x32_bf16 v[112:115], v[168:171], v[214:217], 0
	v_mfma_f32_16x16x32_bf16 v[100:103], v[160:163], v[226:229], 0
	v_mfma_f32_16x16x32_bf16 v[96:99], v[168:171], v[226:229], 0
	v_mfma_f32_16x16x32_bf16 v[84:87], v[160:163], v[234:237], 0
	v_mfma_f32_16x16x32_bf16 v[80:83], v[168:171], v[234:237], 0
	v_mfma_f32_16x16x32_bf16 v[68:71], v[160:163], v[242:245], 0
	v_mfma_f32_16x16x32_bf16 v[64:67], v[168:171], v[242:245], 0
	v_mfma_f32_16x16x32_bf16 v[116:119], v[164:167], v[222:225], v[116:119]
	v_mfma_f32_16x16x32_bf16 v[112:115], v[172:175], v[222:225], v[112:115]
	v_mfma_f32_16x16x32_bf16 v[100:103], v[164:167], v[230:233], v[100:103]
	v_mfma_f32_16x16x32_bf16 v[96:99], v[172:175], v[230:233], v[96:99]
	v_mfma_f32_16x16x32_bf16 v[84:87], v[164:167], v[238:241], v[84:87]
	v_mfma_f32_16x16x32_bf16 v[80:83], v[172:175], v[238:241], v[80:83]
	v_mfma_f32_16x16x32_bf16 v[68:71], v[164:167], v[246:249], v[68:71]
	v_mfma_f32_16x16x32_bf16 v[64:67], v[172:175], v[246:249], v[64:67]
	s_setprio 0
	s_barrier
	s_add_i32 s2, s70, s42
	v_lshl_add_u64 v[176:177], s[50:51], 0, v[130:131]
	s_mov_b32 m0, s2
	ds_read_b128 v[214:217], v201 offset:16384
	ds_read_b128 v[222:225], v201 offset:17408
	ds_read_b128 v[226:229], v201 offset:18432
	ds_read_b128 v[230:233], v201 offset:19456
	ds_read_b128 v[234:237], v201 offset:20480
	ds_read_b128 v[238:241], v201 offset:21504
	ds_read_b128 v[242:245], v201 offset:22528
	ds_read_b128 v[246:249], v201 offset:23552
	global_load_lds_dwordx4 v[176:177], off
	s_add_i32 m0, s2, 0x2000
	s_add_u32 s2, s50, 0xb0000
	v_lshl_add_u64 v[218:219], s[50:51], 0, v[134:135]
	s_addc_u32 s3, s51, 0
	s_add_i32 s68, s71, s42
	global_load_lds_dwordx4 v[218:219], off
	v_lshl_add_u64 v[250:251], s[2:3], 0, v[130:131]
	s_mov_b32 m0, s68
	v_lshl_add_u64 v[252:253], s[52:53], 0, v[132:133]
	global_load_lds_dwordx4 v[250:251], off
	v_lshl_add_u64 v[250:251], s[2:3], 0, v[134:135]
	s_add_i32 m0, s68, 0x2000
	s_nop 0
	global_load_lds_dwordx4 v[250:251], off
	v_lshl_add_u64 v[250:251], s[52:53], 0, v[128:129]
	s_mov_b32 m0, s43
	s_nop 0
	global_load_lds_dwordx4 v[250:251], off
	s_mov_b32 m0, s59
	s_nop 0
	global_load_lds_dwordx4 v[252:253], off
	s_waitcnt vmcnt(8)
	s_waitcnt lgkmcnt(0)
	s_barrier
; #define PG8_STAGE(bufoff, gbase, voff) do { _Pragma("unroll") for (int _i = 0; _i < 2; ++_i) \
;         __builtin_amdgcn_global_load_lds((const unsigned*)((const char*)(gbase) + (voff)[_i]), (PG8_LAS unsigned*)(lds + (bufoff) + ldsw + _i * 8192), 16, 0, 0); } while (0)
; #define PG8_LDA(dst, b, h) do { _Pragma("unroll") for (int m = 0; m < 4; ++m) _Pragma("unroll") for (int k = 0; k < 2; ++k) dst[m][k] = *(const PG8_LAS bf16x8*)(lds + PG8_SA(b, h) + aoff + m * 2048 + k * 1024); } while (0)
; #define PG8_LDB(dst, b, h) do { _Pragma("unroll") for (int n = 0; n < 2; ++n) _Pragma("unroll") for (int k = 0; k < 2; ++k) dst[n][k] = *(const PG8_LAS bf16x8*)(lds + PG8_SB(b, h) + boff + n * 2048 + k * 1024); } while (0)
; #define PG8_MMA(ai, bj, At, Bt) do { __builtin_amdgcn_s_setprio(1); _Pragma("unroll") for (int m = 0; m < 4; ++m) _Pragma("unroll") for (int n = 0; n < 2; ++n) _Pragma("unroll") for (int k = 0; k < 2; ++k) \
;         acc[ai][bj][m][n] = __builtin_amdgcn_mfma_f32_16x16x32_bf16(Bt[n][k], At[m][k], acc[ai][bj][m][n], 0, 0, 0); __builtin_amdgcn_s_setprio(0); } while (0)
; #define PG8_WAIT_V(n) asm volatile("s_waitcnt vmcnt(" #n ")" ::: "memory")
; #define PG8_WAIT_L(n) asm volatile("s_waitcnt lgkmcnt(" #n ")" ::: "memory")
; #define PG8_BAR __builtin_amdgcn_s_barrier()
; #define PG8_SCHED __builtin_amdgcn_sched_barrier(0)
; template <class Epi, class Sched>
; __device__ __forceinline__ void gemm_phase(PG8_LAS unsigned char* lds, PG8_LAS unsigned char* xl, const Gemm g, const Sched& S, const Epi& E) {
;     ...
;             PG8_WAIT_V(8); PG8_WAIT_L(0); PG8_BAR; PG8_MMA(1, 0, At, B0); PG8_MMA(1, 1, At, B1); PG8_BAR; PG8_SCHED;
;             PG8_LDB(B0, 1, 0); PG8_LDB(B1, 1, 1); PG8_SCHED; PG8_LDA(At, 1, 0); PG8_STAGE(PG8_SA(0, 1), a2 + hsA, voffA);
;             PG8_WAIT_V(8); PG8_WAIT_L(0); PG8_BAR; PG8_MMA(0, 0, At, B0); PG8_MMA(0, 1, At, B1); PG8_BAR; PG8_SCHED;
	s_setprio 1
	s_waitcnt lgkmcnt(0)
	v_mfma_f32_16x16x32_bf16 v[60:63], v[144:147], v[214:217], 0
	v_mfma_f32_16x16x32_bf16 v[56:59], v[152:155], v[214:217], 0
	v_mfma_f32_16x16x32_bf16 v[44:47], v[144:147], v[226:229], 0
	v_mfma_f32_16x16x32_bf16 v[40:43], v[152:155], v[226:229], 0
	v_mfma_f32_16x16x32_bf16 v[28:31], v[144:147], v[234:237], 0
	v_mfma_f32_16x16x32_bf16 v[24:27], v[152:155], v[234:237], 0
	v_mfma_f32_16x16x32_bf16 v[12:15], v[144:147], v[242:245], 0
	v_mfma_f32_16x16x32_bf16 v[8:11], v[152:155], v[242:245], 0
	v_mfma_f32_16x16x32_bf16 v[60:63], v[148:151], v[222:225], v[60:63]
	v_mfma_f32_16x16x32_bf16 v[56:59], v[156:159], v[222:225], v[56:59]
	v_mfma_f32_16x16x32_bf16 v[44:47], v[148:151], v[230:233], v[44:47]
	v_mfma_f32_16x16x32_bf16 v[40:43], v[156:159], v[230:233], v[40:43]
	v_mfma_f32_16x16x32_bf16 v[28:31], v[148:151], v[238:241], v[28:31]
	v_mfma_f32_16x16x32_bf16 v[24:27], v[156:159], v[238:241], v[24:27]
	v_mfma_f32_16x16x32_bf16 v[12:15], v[148:151], v[246:249], v[12:15]
	v_mfma_f32_16x16x32_bf16 v[8:11], v[156:159], v[246:249], v[8:11]
	s_setprio 0
	s_setprio 1
	v_mfma_f32_16x16x32_bf16 v[52:55], v[160:163], v[214:217], 0
	v_mfma_f32_16x16x32_bf16 v[48:51], v[168:171], v[214:217], 0
	v_mfma_f32_16x16x32_bf16 v[36:39], v[160:163], v[226:229], 0
	v_mfma_f32_16x16x32_bf16 v[32:35], v[168:171], v[226:229], 0
	v_mfma_f32_16x16x32_bf16 v[20:23], v[160:163], v[234:237], 0
	v_mfma_f32_16x16x32_bf16 v[16:19], v[168:171], v[234:237], 0
	v_mfma_f32_16x16x32_bf16 v[4:7], v[160:163], v[242:245], 0
	v_mfma_f32_16x16x32_bf16 v[0:3], v[168:171], v[242:245], 0
	v_mfma_f32_16x16x32_bf16 v[52:55], v[164:167], v[222:225], v[52:55]
	v_mfma_f32_16x16x32_bf16 v[48:51], v[172:175], v[222:225], v[48:51]
	v_mfma_f32_16x16x32_bf16 v[36:39], v[164:167], v[230:233], v[36:39]
	v_mfma_f32_16x16x32_bf16 v[32:35], v[172:175], v[230:233], v[32:35]
	v_mfma_f32_16x16x32_bf16 v[20:23], v[164:167], v[238:241], v[20:23]
	v_mfma_f32_16x16x32_bf16 v[16:19], v[172:175], v[238:241], v[16:19]
	v_mfma_f32_16x16x32_bf16 v[4:7], v[164:167], v[246:249], v[4:7]
	v_mfma_f32_16x16x32_bf16 v[0:3], v[172:175], v[246:249], v[0:3]
	s_setprio 0
	s_barrier
	s_add_i32 s68, 0, 0x18000
	s_add_i32 s81, 0, 0x1c000
	v_add_u32_e32 v156, s68, v181
	v_add_u32_e32 v172, s81, v181
	ds_read_b128 v[144:147], v156
	ds_read_b128 v[148:151], v156 offset:1024
	ds_read_b128 v[152:155], v156 offset:2048
	ds_read_b128 v[156:159], v156 offset:3072
	ds_read_b128 v[160:163], v172
	ds_read_b128 v[164:167], v172 offset:1024
	ds_read_b128 v[168:171], v172 offset:2048
	ds_read_b128 v[172:175], v172 offset:3072
	s_add_u32 s2, s52, 0xb0000
	s_addc_u32 s3, s53, 0
	s_mov_b32 m0, s60
	v_lshl_add_u64 v[212:213], s[2:3], 0, v[128:129]
	ds_read_b128 v[214:217], v201 offset:32768
	ds_read_b128 v[222:225], v201 offset:33792
	ds_read_b128 v[226:229], v201 offset:34816
	ds_read_b128 v[230:233], v201 offset:35840
	ds_read_b128 v[234:237], v201 offset:36864
	ds_read_b128 v[238:241], v201 offset:37888
	ds_read_b128 v[242:245], v201 offset:38912
	ds_read_b128 v[246:249], v201 offset:39936
	global_load_lds_dwordx4 v[212:213], off
	v_lshl_add_u64 v[212:213], s[2:3], 0, v[132:133]
	s_mov_b32 m0, s61
	s_nop 0
	global_load_lds_dwordx4 v[212:213], off
	s_waitcnt vmcnt(8)
	s_waitcnt lgkmcnt(0)
	s_barrier
	s_setprio 1
	s_waitcnt lgkmcnt(0)
	v_mfma_f32_16x16x32_bf16 v[124:127], v[144:147], v[214:217], v[124:127]
	v_mfma_f32_16x16x32_bf16 v[120:123], v[152:155], v[214:217], v[120:123]
	v_mfma_f32_16x16x32_bf16 v[108:111], v[144:147], v[226:229], v[108:111]
	v_mfma_f32_16x16x32_bf16 v[104:107], v[152:155], v[226:229], v[104:107]
	v_mfma_f32_16x16x32_bf16 v[92:95], v[144:147], v[234:237], v[92:95]
	v_mfma_f32_16x16x32_bf16 v[88:91], v[152:155], v[234:237], v[88:91]
	v_mfma_f32_16x16x32_bf16 v[76:79], v[144:147], v[242:245], v[76:79]
	v_mfma_f32_16x16x32_bf16 v[72:75], v[152:155], v[242:245], v[72:75]
	v_mfma_f32_16x16x32_bf16 v[124:127], v[148:151], v[222:225], v[124:127]
	v_mfma_f32_16x16x32_bf16 v[120:123], v[156:159], v[222:225], v[120:123]
	v_mfma_f32_16x16x32_bf16 v[108:111], v[148:151], v[230:233], v[108:111]
	v_mfma_f32_16x16x32_bf16 v[104:107], v[156:159], v[230:233], v[104:107]
	v_mfma_f32_16x16x32_bf16 v[92:95], v[148:151], v[238:241], v[92:95]
	v_mfma_f32_16x16x32_bf16 v[88:91], v[156:159], v[238:241], v[88:91]
	v_mfma_f32_16x16x32_bf16 v[76:79], v[148:151], v[246:249], v[76:79]
	v_mfma_f32_16x16x32_bf16 v[72:75], v[156:159], v[246:249], v[72:75]
	s_setprio 0
	s_setprio 1
	v_mfma_f32_16x16x32_bf16 v[116:119], v[160:163], v[214:217], v[116:119]
	v_mfma_f32_16x16x32_bf16 v[112:115], v[168:171], v[214:217], v[112:115]
	v_mfma_f32_16x16x32_bf16 v[100:103], v[160:163], v[226:229], v[100:103]
	v_mfma_f32_16x16x32_bf16 v[96:99], v[168:171], v[226:229], v[96:99]
	v_mfma_f32_16x16x32_bf16 v[84:87], v[160:163], v[234:237], v[84:87]
	v_mfma_f32_16x16x32_bf16 v[80:83], v[168:171], v[234:237], v[80:83]
	v_mfma_f32_16x16x32_bf16 v[68:71], v[160:163], v[242:245], v[68:71]
	v_mfma_f32_16x16x32_bf16 v[64:67], v[168:171], v[242:245], v[64:67]
	v_mfma_f32_16x16x32_bf16 v[116:119], v[164:167], v[222:225], v[116:119]
	v_mfma_f32_16x16x32_bf16 v[112:115], v[172:175], v[222:225], v[112:115]
	v_mfma_f32_16x16x32_bf16 v[100:103], v[164:167], v[230:233], v[100:103]
	v_mfma_f32_16x16x32_bf16 v[96:99], v[172:175], v[230:233], v[96:99]
	v_mfma_f32_16x16x32_bf16 v[84:87], v[164:167], v[238:241], v[84:87]
	v_mfma_f32_16x16x32_bf16 v[80:83], v[172:175], v[238:241], v[80:83]
	v_mfma_f32_16x16x32_bf16 v[68:71], v[164:167], v[246:249], v[68:71]
	v_mfma_f32_16x16x32_bf16 v[64:67], v[172:175], v[246:249], v[64:67]
	s_setprio 0
	s_barrier
; #define PG8_STAGE(bufoff, gbase, voff) do { _Pragma("unroll") for (int _i = 0; _i < 2; ++_i) \
;         __builtin_amdgcn_global_load_lds((const unsigned*)((const char*)(gbase) + (voff)[_i]), (PG8_LAS unsigned*)(lds + (bufoff) + ldsw + _i * 8192), 16, 0, 0); } while (0)
; #define PG8_LDA(dst, b, h) do { _Pragma("unroll") for (int m = 0; m < 4; ++m) _Pragma("unroll") for (int k = 0; k < 2; ++k) dst[m][k] = *(const PG8_LAS bf16x8*)(lds + PG8_SA(b, h) + aoff + m * 2048 + k * 1024); } while (0)
; #define PG8_LDB(dst, b, h) do { _Pragma("unroll") for (int n = 0; n < 2; ++n) _Pragma("unroll") for (int k = 0; k < 2; ++k) dst[n][k] = *(const PG8_LAS bf16x8*)(lds + PG8_SB(b, h) + boff + n * 2048 + k * 1024); } while (0)
; #define PG8_MMA(ai, bj, At, Bt) do { __builtin_amdgcn_s_setprio(1); _Pragma("unroll") for (int m = 0; m < 4; ++m) _Pragma("unroll") for (int n = 0; n < 2; ++n) _Pragma("unroll") for (int k = 0; k < 2; ++k) \
;         acc[ai][bj][m][n] = __builtin_amdgcn_mfma_f32_16x16x32_bf16(Bt[n][k], At[m][k], acc[ai][bj][m][n], 0, 0, 0); __builtin_amdgcn_s_setprio(0); } while (0)
; #define PG8_WAIT_V(n) asm volatile("s_waitcnt vmcnt(" #n ")" ::: "memory")
; #define PG8_WAIT_L(n) asm volatile("s_waitcnt lgkmcnt(" #n ")" ::: "memory")
; #define PG8_BAR __builtin_amdgcn_s_barrier()
; #define PG8_SCHED __builtin_amdgcn_sched_barrier(0)
; template <class Epi, class Sched>
; __device__ __forceinline__ void gemm_phase(PG8_LAS unsigned char* lds, PG8_LAS unsigned char* xl, const Gemm g, const Sched& S, const Epi& E) {
;     ...
;             PG8_LDB(B0, 0, 0); PG8_LDB(B1, 0, 1); PG8_SCHED; PG8_LDA(At, 0, 0); PG8_STAGE(PG8_SA(1, 1), a1 + hsA, voffA);
;             PG8_WAIT_V(8); PG8_WAIT_L(0); PG8_BAR; PG8_MMA(0, 0, At, B0); PG8_MMA(0, 1, At, B1); PG8_BAR; PG8_SCHED;
;     ...
;             PG8_LDA(At, 1, 1); PG8_STAGE(PG8_SB(1, 0), b3, voffB); PG8_STAGE(PG8_SB(1, 1), b3 + hsB, voffB); PG8_STAGE(PG8_SA(1, 0), a3, voffA);
;             PG8_WAIT_V(8); PG8_WAIT_L(0); PG8_BAR; PG8_MMA(1, 0, At, B0); PG8_MMA(1, 1, At, B1); PG8_BAR; PG8_SCHED;
;         }
	s_add_i32 s2, s68, s42
	v_lshl_add_u64 v[176:177], v[176:177], 0, s[22:23]
	s_mov_b32 m0, s2
	ds_read_b128 v[214:217], v201 offset:49152
	ds_read_b128 v[222:225], v201 offset:50176
	ds_read_b128 v[226:229], v201 offset:51200
	ds_read_b128 v[230:233], v201 offset:52224
	ds_read_b128 v[234:237], v201 offset:53248
	ds_read_b128 v[238:241], v201 offset:54272
	ds_read_b128 v[242:245], v201 offset:55296
	ds_read_b128 v[246:249], v201 offset:56320
	global_load_lds_dwordx4 v[176:177], off
	s_add_i32 m0, s2, 0x2000
	s_add_u32 s2, s50, 0xb0080
	v_lshl_add_u64 v[176:177], v[218:219], 0, s[22:23]
	s_addc_u32 s3, s51, 0
	s_add_i32 s50, s81, s42
	global_load_lds_dwordx4 v[176:177], off
	v_lshl_add_u64 v[176:177], s[2:3], 0, v[130:131]
	s_mov_b32 m0, s50
	s_nop 0
	global_load_lds_dwordx4 v[176:177], off
	v_lshl_add_u64 v[176:177], s[2:3], 0, v[134:135]
	s_add_i32 m0, s50, 0x2000
	s_nop 0
	global_load_lds_dwordx4 v[176:177], off
	v_lshl_add_u64 v[176:177], v[250:251], 0, s[22:23]
	s_mov_b32 m0, s65
	s_nop 0
	global_load_lds_dwordx4 v[176:177], off
	v_lshl_add_u64 v[176:177], v[252:253], 0, s[22:23]
	s_mov_b32 m0, s66
	s_nop 0
	global_load_lds_dwordx4 v[176:177], off
	s_waitcnt vmcnt(8)
	s_waitcnt lgkmcnt(0)
	s_barrier
	s_setprio 1
	s_waitcnt lgkmcnt(0)
	v_mfma_f32_16x16x32_bf16 v[60:63], v[144:147], v[214:217], v[60:63]
	v_mfma_f32_16x16x32_bf16 v[56:59], v[152:155], v[214:217], v[56:59]
	v_mfma_f32_16x16x32_bf16 v[44:47], v[144:147], v[226:229], v[44:47]
	v_mfma_f32_16x16x32_bf16 v[40:43], v[152:155], v[226:229], v[40:43]
	v_mfma_f32_16x16x32_bf16 v[28:31], v[144:147], v[234:237], v[28:31]
	v_mfma_f32_16x16x32_bf16 v[24:27], v[152:155], v[234:237], v[24:27]
	v_mfma_f32_16x16x32_bf16 v[12:15], v[144:147], v[242:245], v[12:15]
	v_mfma_f32_16x16x32_bf16 v[8:11], v[152:155], v[242:245], v[8:11]
	v_mfma_f32_16x16x32_bf16 v[60:63], v[148:151], v[222:225], v[60:63]
	v_mfma_f32_16x16x32_bf16 v[56:59], v[156:159], v[222:225], v[56:59]
	v_mfma_f32_16x16x32_bf16 v[44:47], v[148:151], v[230:233], v[44:47]
	v_mfma_f32_16x16x32_bf16 v[40:43], v[156:159], v[230:233], v[40:43]
	v_mfma_f32_16x16x32_bf16 v[28:31], v[148:151], v[238:241], v[28:31]
	v_mfma_f32_16x16x32_bf16 v[24:27], v[156:159], v[238:241], v[24:27]
	v_mfma_f32_16x16x32_bf16 v[12:15], v[148:151], v[246:249], v[12:15]
	v_mfma_f32_16x16x32_bf16 v[8:11], v[156:159], v[246:249], v[8:11]
	s_setprio 0
	s_setprio 1
	v_mfma_f32_16x16x32_bf16 v[52:55], v[160:163], v[214:217], v[52:55]
	s_add_i32 s80, s80, 2
	v_mfma_f32_16x16x32_bf16 v[48:51], v[168:171], v[214:217], v[48:51]
	s_add_u32 s78, s78, 0x100
	v_mfma_f32_16x16x32_bf16 v[36:39], v[160:163], v[226:229], v[36:39]
	s_addc_u32 s79, s79, 0
	v_mfma_f32_16x16x32_bf16 v[32:35], v[168:171], v[226:229], v[32:35]
	s_cmp_gt_u32 s80, 41
	v_mfma_f32_16x16x32_bf16 v[20:23], v[160:163], v[234:237], v[20:23]
	s_mov_b64 s[2:3], s[48:49]
	v_mfma_f32_16x16x32_bf16 v[16:19], v[168:171], v[234:237], v[16:19]
	v_mfma_f32_16x16x32_bf16 v[4:7], v[160:163], v[242:245], v[4:7]
	v_mfma_f32_16x16x32_bf16 v[0:3], v[168:171], v[242:245], v[0:3]
	v_mfma_f32_16x16x32_bf16 v[52:55], v[164:167], v[222:225], v[52:55]
	v_mfma_f32_16x16x32_bf16 v[48:51], v[172:175], v[222:225], v[48:51]
	v_mfma_f32_16x16x32_bf16 v[36:39], v[164:167], v[230:233], v[36:39]
	v_mfma_f32_16x16x32_bf16 v[32:35], v[172:175], v[230:233], v[32:35]
	v_mfma_f32_16x16x32_bf16 v[20:23], v[164:167], v[238:241], v[20:23]
	v_mfma_f32_16x16x32_bf16 v[16:19], v[172:175], v[238:241], v[16:19]
	v_mfma_f32_16x16x32_bf16 v[4:7], v[164:167], v[246:249], v[4:7]
	v_mfma_f32_16x16x32_bf16 v[0:3], v[172:175], v[246:249], v[0:3]
	s_setprio 0
	s_barrier
	s_cbranch_scc1 .Lpeel_after_P9
.LBB0_942:
	ds_read_b128 v[144:147], v199
	ds_read_b128 v[148:151], v199 offset:1024
	ds_read_b128 v[152:155], v199 offset:2048
	ds_read_b128 v[156:159], v199 offset:3072
	ds_read_b128 v[160:163], v200
	ds_read_b128 v[164:167], v200 offset:1024
	ds_read_b128 v[168:171], v200 offset:2048
	ds_read_b128 v[172:175], v200 offset:3072
	s_add_u32 s48, s2, 0x100
	s_addc_u32 s49, s3, 0
	s_cmp_eq_u32 s80, 40
	s_cselect_b32 s53, s33, s49
	s_cselect_b32 s52, s46, s48
	s_cselect_b32 s51, s47, s79
	s_cselect_b32 s50, s77, s78
	v_lshl_add_u64 v[176:177], s[2:3], 0, v[138:139]
	s_add_i32 m0, s43, 0xc000
	ds_read_b128 v[214:217], v201
	ds_read_b128 v[222:225], v201 offset:1024
	ds_read_b128 v[226:229], v201 offset:2048
	ds_read_b128 v[230:233], v201 offset:3072
	ds_read_b128 v[234:237], v201 offset:4096
	ds_read_b128 v[238:241], v201 offset:5120
	ds_read_b128 v[242:245], v201 offset:6144
	ds_read_b128 v[246:249], v201 offset:7168
	global_load_lds_dwordx4 v[176:177], off
	v_lshl_add_u64 v[176:177], s[2:3], 0, v[136:137]
	s_add_i32 m0, s43, 0xe000
	s_nop 0
	global_load_lds_dwordx4 v[176:177], off
	s_waitcnt vmcnt(8)
	s_waitcnt lgkmcnt(0)
	s_barrier
; #define PG8_STAGE(bufoff, gbase, voff) do { _Pragma("unroll") for (int _i = 0; _i < 2; ++_i) \
;         __builtin_amdgcn_global_load_lds((const unsigned*)((const char*)(gbase) + (voff)[_i]), (PG8_LAS unsigned*)(lds + (bufoff) + ldsw + _i * 8192), 16, 0, 0); } while (0)
; #define PG8_LDA(dst, b, h) do { _Pragma("unroll") for (int m = 0; m < 4; ++m) _Pragma("unroll") for (int k = 0; k < 2; ++k) dst[m][k] = *(const PG8_LAS bf16x8*)(lds + PG8_SA(b, h) + aoff + m * 2048 + k * 1024); } while (0)
; #define PG8_MMA(ai, bj, At, Bt) do { __builtin_amdgcn_s_setprio(1); _Pragma("unroll") for (int m = 0; m < 4; ++m) _Pragma("unroll") for (int n = 0; n < 2; ++n) _Pragma("unroll") for (int k = 0; k < 2; ++k) \
;         acc[ai][bj][m][n] = __builtin_amdgcn_mfma_f32_16x16x32_bf16(Bt[n][k], At[m][k], acc[ai][bj][m][n], 0, 0, 0); __builtin_amdgcn_s_setprio(0); } while (0)
; #define PG8_WAIT_V(n) asm volatile("s_waitcnt vmcnt(" #n ")" ::: "memory")
; #define PG8_WAIT_L(n) asm volatile("s_waitcnt lgkmcnt(" #n ")" ::: "memory")
; #define PG8_BAR __builtin_amdgcn_s_barrier()
; #define PG8_SCHED __builtin_amdgcn_sched_barrier(0)
; template <class Epi, class Sched>
; __device__ __forceinline__ void gemm_phase(PG8_LAS unsigned char* lds, PG8_LAS unsigned char* xl, const Gemm g, const Sched& S, const Epi& E) {
;     ...
;             PG8_WAIT_V(8); PG8_WAIT_L(0); PG8_BAR; PG8_MMA(0, 0, At, B0); PG8_MMA(0, 1, At, B1); PG8_BAR; PG8_SCHED;
;             PG8_LDA(At, 0, 1); PG8_STAGE(PG8_SB(0, 0), b2, voffB); PG8_STAGE(PG8_SB(0, 1), b2 + hsB, voffB); PG8_STAGE(PG8_SA(0, 0), a2, voffA);
;             PG8_WAIT_V(8); PG8_WAIT_L(0); PG8_BAR; PG8_MMA(1, 0, At, B0); PG8_MMA(1, 1, At, B1); PG8_BAR; PG8_SCHED;
	s_setprio 1
	s_waitcnt lgkmcnt(0)
	v_mfma_f32_16x16x32_bf16 v[124:127], v[144:147], v[214:217], v[124:127]
	v_mfma_f32_16x16x32_bf16 v[120:123], v[152:155], v[214:217], v[120:123]
	v_mfma_f32_16x16x32_bf16 v[108:111], v[144:147], v[226:229], v[108:111]
	v_mfma_f32_16x16x32_bf16 v[104:107], v[152:155], v[226:229], v[104:107]
	v_mfma_f32_16x16x32_bf16 v[92:95], v[144:147], v[234:237], v[92:95]
	v_mfma_f32_16x16x32_bf16 v[88:91], v[152:155], v[234:237], v[88:91]
	v_mfma_f32_16x16x32_bf16 v[76:79], v[144:147], v[242:245], v[76:79]
	v_mfma_f32_16x16x32_bf16 v[72:75], v[152:155], v[242:245], v[72:75]
	v_mfma_f32_16x16x32_bf16 v[124:127], v[148:151], v[222:225], v[124:127]
	v_mfma_f32_16x16x32_bf16 v[120:123], v[156:159], v[222:225], v[120:123]
	v_mfma_f32_16x16x32_bf16 v[108:111], v[148:151], v[230:233], v[108:111]
	v_mfma_f32_16x16x32_bf16 v[104:107], v[156:159], v[230:233], v[104:107]
	v_mfma_f32_16x16x32_bf16 v[92:95], v[148:151], v[238:241], v[92:95]
	v_mfma_f32_16x16x32_bf16 v[88:91], v[156:159], v[238:241], v[88:91]
	v_mfma_f32_16x16x32_bf16 v[76:79], v[148:151], v[246:249], v[76:79]
	v_mfma_f32_16x16x32_bf16 v[72:75], v[156:159], v[246:249], v[72:75]
	s_setprio 0
	s_setprio 1
	v_mfma_f32_16x16x32_bf16 v[116:119], v[160:163], v[214:217], v[116:119]
	v_mfma_f32_16x16x32_bf16 v[112:115], v[168:171], v[214:217], v[112:115]
	v_mfma_f32_16x16x32_bf16 v[100:103], v[160:163], v[226:229], v[100:103]
	v_mfma_f32_16x16x32_bf16 v[96:99], v[168:171], v[226:229], v[96:99]
	v_mfma_f32_16x16x32_bf16 v[84:87], v[160:163], v[234:237], v[84:87]
	v_mfma_f32_16x16x32_bf16 v[80:83], v[168:171], v[234:237], v[80:83]
	v_mfma_f32_16x16x32_bf16 v[68:71], v[160:163], v[242:245], v[68:71]
	v_mfma_f32_16x16x32_bf16 v[64:67], v[168:171], v[242:245], v[64:67]
	v_mfma_f32_16x16x32_bf16 v[116:119], v[164:167], v[222:225], v[116:119]
	v_mfma_f32_16x16x32_bf16 v[112:115], v[172:175], v[222:225], v[112:115]
	v_mfma_f32_16x16x32_bf16 v[100:103], v[164:167], v[230:233], v[100:103]
	v_mfma_f32_16x16x32_bf16 v[96:99], v[172:175], v[230:233], v[96:99]
	v_mfma_f32_16x16x32_bf16 v[84:87], v[164:167], v[238:241], v[84:87]
	v_mfma_f32_16x16x32_bf16 v[80:83], v[172:175], v[238:241], v[80:83]
	v_mfma_f32_16x16x32_bf16 v[68:71], v[164:167], v[246:249], v[68:71]
	v_mfma_f32_16x16x32_bf16 v[64:67], v[172:175], v[246:249], v[64:67]
	s_setprio 0
	s_barrier
	s_add_i32 s2, s70, s42
	v_lshl_add_u64 v[176:177], s[50:51], 0, v[130:131]
	s_mov_b32 m0, s2
	ds_read_b128 v[214:217], v201 offset:16384
	ds_read_b128 v[222:225], v201 offset:17408
	ds_read_b128 v[226:229], v201 offset:18432
	ds_read_b128 v[230:233], v201 offset:19456
	ds_read_b128 v[234:237], v201 offset:20480
	ds_read_b128 v[238:241], v201 offset:21504
	ds_read_b128 v[242:245], v201 offset:22528
	ds_read_b128 v[246:249], v201 offset:23552
	global_load_lds_dwordx4 v[176:177], off
	s_add_i32 m0, s2, 0x2000
	s_add_u32 s2, s50, 0xb0000
	v_lshl_add_u64 v[218:219], s[50:51], 0, v[134:135]
	s_addc_u32 s3, s51, 0
	s_add_i32 s68, s71, s42
	global_load_lds_dwordx4 v[218:219], off
	v_lshl_add_u64 v[250:251], s[2:3], 0, v[130:131]
	s_mov_b32 m0, s68
	v_lshl_add_u64 v[252:253], s[52:53], 0, v[132:133]
	global_load_lds_dwordx4 v[250:251], off
	v_lshl_add_u64 v[250:251], s[2:3], 0, v[134:135]
	s_add_i32 m0, s68, 0x2000
	s_nop 0
	global_load_lds_dwordx4 v[250:251], off
	v_lshl_add_u64 v[250:251], s[52:53], 0, v[128:129]
	s_mov_b32 m0, s43
	s_nop 0
	global_load_lds_dwordx4 v[250:251], off
	s_mov_b32 m0, s59
	s_nop 0
	global_load_lds_dwordx4 v[252:253], off
	s_waitcnt vmcnt(8)
	s_waitcnt lgkmcnt(0)
	s_barrier
	s_setprio 1
	s_waitcnt lgkmcnt(0)
	v_mfma_f32_16x16x32_bf16 v[60:63], v[144:147], v[214:217], v[60:63]
	v_mfma_f32_16x16x32_bf16 v[56:59], v[152:155], v[214:217], v[56:59]
	v_mfma_f32_16x16x32_bf16 v[44:47], v[144:147], v[226:229], v[44:47]
	v_mfma_f32_16x16x32_bf16 v[40:43], v[152:155], v[226:229], v[40:43]
	v_mfma_f32_16x16x32_bf16 v[28:31], v[144:147], v[234:237], v[28:31]
	v_mfma_f32_16x16x32_bf16 v[24:27], v[152:155], v[234:237], v[24:27]
	v_mfma_f32_16x16x32_bf16 v[12:15], v[144:147], v[242:245], v[12:15]
	v_mfma_f32_16x16x32_bf16 v[8:11], v[152:155], v[242:245], v[8:11]
	v_mfma_f32_16x16x32_bf16 v[60:63], v[148:151], v[222:225], v[60:63]
	v_mfma_f32_16x16x32_bf16 v[56:59], v[156:159], v[222:225], v[56:59]
	v_mfma_f32_16x16x32_bf16 v[44:47], v[148:151], v[230:233], v[44:47]
	v_mfma_f32_16x16x32_bf16 v[40:43], v[156:159], v[230:233], v[40:43]
	v_mfma_f32_16x16x32_bf16 v[28:31], v[148:151], v[238:241], v[28:31]
	v_mfma_f32_16x16x32_bf16 v[24:27], v[156:159], v[238:241], v[24:27]
	v_mfma_f32_16x16x32_bf16 v[12:15], v[148:151], v[246:249], v[12:15]
	v_mfma_f32_16x16x32_bf16 v[8:11], v[156:159], v[246:249], v[8:11]
	s_setprio 0
	s_setprio 1
	v_mfma_f32_16x16x32_bf16 v[52:55], v[160:163], v[214:217], v[52:55]
	v_mfma_f32_16x16x32_bf16 v[48:51], v[168:171], v[214:217], v[48:51]
	v_mfma_f32_16x16x32_bf16 v[36:39], v[160:163], v[226:229], v[36:39]
	v_mfma_f32_16x16x32_bf16 v[32:35], v[168:171], v[226:229], v[32:35]
	v_mfma_f32_16x16x32_bf16 v[20:23], v[160:163], v[234:237], v[20:23]
	v_mfma_f32_16x16x32_bf16 v[16:19], v[168:171], v[234:237], v[16:19]
	v_mfma_f32_16x16x32_bf16 v[4:7], v[160:163], v[242:245], v[4:7]
	v_mfma_f32_16x16x32_bf16 v[0:3], v[168:171], v[242:245], v[0:3]
	v_mfma_f32_16x16x32_bf16 v[52:55], v[164:167], v[222:225], v[52:55]
	v_mfma_f32_16x16x32_bf16 v[48:51], v[172:175], v[222:225], v[48:51]
	v_mfma_f32_16x16x32_bf16 v[36:39], v[164:167], v[230:233], v[36:39]
	v_mfma_f32_16x16x32_bf16 v[32:35], v[172:175], v[230:233], v[32:35]
	v_mfma_f32_16x16x32_bf16 v[20:23], v[164:167], v[238:241], v[20:23]
	v_mfma_f32_16x16x32_bf16 v[16:19], v[172:175], v[238:241], v[16:19]
	v_mfma_f32_16x16x32_bf16 v[4:7], v[164:167], v[246:249], v[4:7]
	v_mfma_f32_16x16x32_bf16 v[0:3], v[172:175], v[246:249], v[0:3]
	s_setprio 0
	s_barrier
; #define PG8_STAGE(bufoff, gbase, voff) do { _Pragma("unroll") for (int _i = 0; _i < 2; ++_i) \
;         __builtin_amdgcn_global_load_lds((const unsigned*)((const char*)(gbase) + (voff)[_i]), (PG8_LAS unsigned*)(lds + (bufoff) + ldsw + _i * 8192), 16, 0, 0); } while (0)
; #define PG8_LDA(dst, b, h) do { _Pragma("unroll") for (int m = 0; m < 4; ++m) _Pragma("unroll") for (int k = 0; k < 2; ++k) dst[m][k] = *(const PG8_LAS bf16x8*)(lds + PG8_SA(b, h) + aoff + m * 2048 + k * 1024); } while (0)
; #define PG8_LDB(dst, b, h) do { _Pragma("unroll") for (int n = 0; n < 2; ++n) _Pragma("unroll") for (int k = 0; k < 2; ++k) dst[n][k] = *(const PG8_LAS bf16x8*)(lds + PG8_SB(b, h) + boff + n * 2048 + k * 1024); } while (0)
; #define PG8_MMA(ai, bj, At, Bt) do { __builtin_amdgcn_s_setprio(1); _Pragma("unroll") for (int m = 0; m < 4; ++m) _Pragma("unroll") for (int n = 0; n < 2; ++n) _Pragma("unroll") for (int k = 0; k < 2; ++k) \
;         acc[ai][bj][m][n] = __builtin_amdgcn_mfma_f32_16x16x32_bf16(Bt[n][k], At[m][k], acc[ai][bj][m][n], 0, 0, 0); __builtin_amdgcn_s_setprio(0); } while (0)
; #define PG8_WAIT_V(n) asm volatile("s_waitcnt vmcnt(" #n ")" ::: "memory")
; #define PG8_WAIT_L(n) asm volatile("s_waitcnt lgkmcnt(" #n ")" ::: "memory")
; #define PG8_BAR __builtin_amdgcn_s_barrier()
; #define PG8_SCHED __builtin_amdgcn_sched_barrier(0)
; template <class Epi, class Sched>
; __device__ __forceinline__ void gemm_phase(PG8_LAS unsigned char* lds, PG8_LAS unsigned char* xl, const Gemm g, const Sched& S, const Epi& E) {
;     ...
;             PG8_LDB(B0, 1, 0); PG8_LDB(B1, 1, 1); PG8_SCHED; PG8_LDA(At, 1, 0); PG8_STAGE(PG8_SA(0, 1), a2 + hsA, voffA);
;             PG8_WAIT_V(8); PG8_WAIT_L(0); PG8_BAR; PG8_MMA(0, 0, At, B0); PG8_MMA(0, 1, At, B1); PG8_BAR; PG8_SCHED;
	s_add_i32 s68, 0, 0x18000
	s_add_i32 s81, 0, 0x1c000
	v_add_u32_e32 v156, s68, v181
	v_add_u32_e32 v172, s81, v181
	ds_read_b128 v[144:147], v156
	ds_read_b128 v[148:151], v156 offset:1024
	ds_read_b128 v[152:155], v156 offset:2048
	ds_read_b128 v[156:159], v156 offset:3072
	ds_read_b128 v[160:163], v172
	ds_read_b128 v[164:167], v172 offset:1024
	ds_read_b128 v[168:171], v172 offset:2048
	ds_read_b128 v[172:175], v172 offset:3072
	s_add_u32 s2, s52, 0xb0000
	s_addc_u32 s3, s53, 0
	s_mov_b32 m0, s60
	v_lshl_add_u64 v[212:213], s[2:3], 0, v[128:129]
	ds_read_b128 v[214:217], v201 offset:32768
	ds_read_b128 v[222:225], v201 offset:33792
	ds_read_b128 v[226:229], v201 offset:34816
	ds_read_b128 v[230:233], v201 offset:35840
	ds_read_b128 v[234:237], v201 offset:36864
	ds_read_b128 v[238:241], v201 offset:37888
	ds_read_b128 v[242:245], v201 offset:38912
	ds_read_b128 v[246:249], v201 offset:39936
	global_load_lds_dwordx4 v[212:213], off
	v_lshl_add_u64 v[212:213], s[2:3], 0, v[132:133]
	s_mov_b32 m0, s61
	s_nop 0
	global_load_lds_dwordx4 v[212:213], off
	s_waitcnt vmcnt(8)
	s_waitcnt lgkmcnt(0)
	s_barrier
	s_setprio 1
	s_waitcnt lgkmcnt(0)
	v_mfma_f32_16x16x32_bf16 v[124:127], v[144:147], v[214:217], v[124:127]
	v_mfma_f32_16x16x32_bf16 v[120:123], v[152:155], v[214:217], v[120:123]
	v_mfma_f32_16x16x32_bf16 v[108:111], v[144:147], v[226:229], v[108:111]
	v_mfma_f32_16x16x32_bf16 v[104:107], v[152:155], v[226:229], v[104:107]
	v_mfma_f32_16x16x32_bf16 v[92:95], v[144:147], v[234:237], v[92:95]
	v_mfma_f32_16x16x32_bf16 v[88:91], v[152:155], v[234:237], v[88:91]
	v_mfma_f32_16x16x32_bf16 v[76:79], v[144:147], v[242:245], v[76:79]
	v_mfma_f32_16x16x32_bf16 v[72:75], v[152:155], v[242:245], v[72:75]
	v_mfma_f32_16x16x32_bf16 v[124:127], v[148:151], v[222:225], v[124:127]
	v_mfma_f32_16x16x32_bf16 v[120:123], v[156:159], v[222:225], v[120:123]
	v_mfma_f32_16x16x32_bf16 v[108:111], v[148:151], v[230:233], v[108:111]
	v_mfma_f32_16x16x32_bf16 v[104:107], v[156:159], v[230:233], v[104:107]
	v_mfma_f32_16x16x32_bf16 v[92:95], v[148:151], v[238:241], v[92:95]
	v_mfma_f32_16x16x32_bf16 v[88:91], v[156:159], v[238:241], v[88:91]
	v_mfma_f32_16x16x32_bf16 v[76:79], v[148:151], v[246:249], v[76:79]
	v_mfma_f32_16x16x32_bf16 v[72:75], v[156:159], v[246:249], v[72:75]
	s_setprio 0
	s_setprio 1
	v_mfma_f32_16x16x32_bf16 v[116:119], v[160:163], v[214:217], v[116:119]
	v_mfma_f32_16x16x32_bf16 v[112:115], v[168:171], v[214:217], v[112:115]
	v_mfma_f32_16x16x32_bf16 v[100:103], v[160:163], v[226:229], v[100:103]
	v_mfma_f32_16x16x32_bf16 v[96:99], v[168:171], v[226:229], v[96:99]
	v_mfma_f32_16x16x32_bf16 v[84:87], v[160:163], v[234:237], v[84:87]
	v_mfma_f32_16x16x32_bf16 v[80:83], v[168:171], v[234:237], v[80:83]
	v_mfma_f32_16x16x32_bf16 v[68:71], v[160:163], v[242:245], v[68:71]
	v_mfma_f32_16x16x32_bf16 v[64:67], v[168:171], v[242:245], v[64:67]
	v_mfma_f32_16x16x32_bf16 v[116:119], v[164:167], v[222:225], v[116:119]
	v_mfma_f32_16x16x32_bf16 v[112:115], v[172:175], v[222:225], v[112:115]
	v_mfma_f32_16x16x32_bf16 v[100:103], v[164:167], v[230:233], v[100:103]
	v_mfma_f32_16x16x32_bf16 v[96:99], v[172:175], v[230:233], v[96:99]
	v_mfma_f32_16x16x32_bf16 v[84:87], v[164:167], v[238:241], v[84:87]
	v_mfma_f32_16x16x32_bf16 v[80:83], v[172:175], v[238:241], v[80:83]
	v_mfma_f32_16x16x32_bf16 v[68:71], v[164:167], v[246:249], v[68:71]
	v_mfma_f32_16x16x32_bf16 v[64:67], v[172:175], v[246:249], v[64:67]
	s_setprio 0
	s_barrier
; #define PG8_STAGE(bufoff, gbase, voff) do { _Pragma("unroll") for (int _i = 0; _i < 2; ++_i) \
;         __builtin_amdgcn_global_load_lds((const unsigned*)((const char*)(gbase) + (voff)[_i]), (PG8_LAS unsigned*)(lds + (bufoff) + ldsw + _i * 8192), 16, 0, 0); } while (0)
; #define PG8_LDA(dst, b, h) do { _Pragma("unroll") for (int m = 0; m < 4; ++m) _Pragma("unroll") for (int k = 0; k < 2; ++k) dst[m][k] = *(const PG8_LAS bf16x8*)(lds + PG8_SA(b, h) + aoff + m * 2048 + k * 1024); } while (0)
; #define PG8_MMA(ai, bj, At, Bt) do { __builtin_amdgcn_s_setprio(1); _Pragma("unroll") for (int m = 0; m < 4; ++m) _Pragma("unroll") for (int n = 0; n < 2; ++n) _Pragma("unroll") for (int k = 0; k < 2; ++k) \
;         acc[ai][bj][m][n] = __builtin_amdgcn_mfma_f32_16x16x32_bf16(Bt[n][k], At[m][k], acc[ai][bj][m][n], 0, 0, 0); __builtin_amdgcn_s_setprio(0); } while (0)
; #define PG8_WAIT_V(n) asm volatile("s_waitcnt vmcnt(" #n ")" ::: "memory")
; #define PG8_WAIT_L(n) asm volatile("s_waitcnt lgkmcnt(" #n ")" ::: "memory")
; #define PG8_BAR __builtin_amdgcn_s_barrier()
; #define PG8_SCHED __builtin_amdgcn_sched_barrier(0)
; template <class Epi, class Sched>
; __device__ __forceinline__ void gemm_phase(PG8_LAS unsigned char* lds, PG8_LAS unsigned char* xl, const Gemm g, const Sched& S, const Epi& E) {
;     ...
;             PG8_LDA(At, 1, 1); PG8_STAGE(PG8_SB(1, 0), b3, voffB); PG8_STAGE(PG8_SB(1, 1), b3 + hsB, voffB); PG8_STAGE(PG8_SA(1, 0), a3, voffA);
;             PG8_WAIT_V(8); PG8_WAIT_L(0); PG8_BAR; PG8_MMA(1, 0, At, B0); PG8_MMA(1, 1, At, B1); PG8_BAR; PG8_SCHED;
;         }
	s_add_i32 s2, s68, s42
	v_lshl_add_u64 v[176:177], v[176:177], 0, s[22:23]
	s_mov_b32 m0, s2
	ds_read_b128 v[214:217], v201 offset:49152
	ds_read_b128 v[222:225], v201 offset:50176
	ds_read_b128 v[226:229], v201 offset:51200
	ds_read_b128 v[230:233], v201 offset:52224
	ds_read_b128 v[234:237], v201 offset:53248
	ds_read_b128 v[238:241], v201 offset:54272
	ds_read_b128 v[242:245], v201 offset:55296
	ds_read_b128 v[246:249], v201 offset:56320
	global_load_lds_dwordx4 v[176:177], off
	s_add_i32 m0, s2, 0x2000
	s_add_u32 s2, s50, 0xb0080
	v_lshl_add_u64 v[176:177], v[218:219], 0, s[22:23]
	s_addc_u32 s3, s51, 0
	s_add_i32 s50, s81, s42
	global_load_lds_dwordx4 v[176:177], off
	v_lshl_add_u64 v[176:177], s[2:3], 0, v[130:131]
	s_mov_b32 m0, s50
	s_nop 0
	global_load_lds_dwordx4 v[176:177], off
	v_lshl_add_u64 v[176:177], s[2:3], 0, v[134:135]
	s_add_i32 m0, s50, 0x2000
	s_nop 0
	global_load_lds_dwordx4 v[176:177], off
	v_lshl_add_u64 v[176:177], v[250:251], 0, s[22:23]
	s_mov_b32 m0, s65
	s_nop 0
	global_load_lds_dwordx4 v[176:177], off
	v_lshl_add_u64 v[176:177], v[252:253], 0, s[22:23]
	s_mov_b32 m0, s66
	s_nop 0
	global_load_lds_dwordx4 v[176:177], off
	s_waitcnt vmcnt(8)
	s_waitcnt lgkmcnt(0)
	s_barrier
	s_setprio 1
	s_waitcnt lgkmcnt(0)
	v_mfma_f32_16x16x32_bf16 v[60:63], v[144:147], v[214:217], v[60:63]
	v_mfma_f32_16x16x32_bf16 v[56:59], v[152:155], v[214:217], v[56:59]
	v_mfma_f32_16x16x32_bf16 v[44:47], v[144:147], v[226:229], v[44:47]
	v_mfma_f32_16x16x32_bf16 v[40:43], v[152:155], v[226:229], v[40:43]
	v_mfma_f32_16x16x32_bf16 v[28:31], v[144:147], v[234:237], v[28:31]
	v_mfma_f32_16x16x32_bf16 v[24:27], v[152:155], v[234:237], v[24:27]
	v_mfma_f32_16x16x32_bf16 v[12:15], v[144:147], v[242:245], v[12:15]
	v_mfma_f32_16x16x32_bf16 v[8:11], v[152:155], v[242:245], v[8:11]
	v_mfma_f32_16x16x32_bf16 v[60:63], v[148:151], v[222:225], v[60:63]
	v_mfma_f32_16x16x32_bf16 v[56:59], v[156:159], v[222:225], v[56:59]
	v_mfma_f32_16x16x32_bf16 v[44:47], v[148:151], v[230:233], v[44:47]
	v_mfma_f32_16x16x32_bf16 v[40:43], v[156:159], v[230:233], v[40:43]
	v_mfma_f32_16x16x32_bf16 v[28:31], v[148:151], v[238:241], v[28:31]
	v_mfma_f32_16x16x32_bf16 v[24:27], v[156:159], v[238:241], v[24:27]
	v_mfma_f32_16x16x32_bf16 v[12:15], v[148:151], v[246:249], v[12:15]
	v_mfma_f32_16x16x32_bf16 v[8:11], v[156:159], v[246:249], v[8:11]
	s_setprio 0
	s_setprio 1
	v_mfma_f32_16x16x32_bf16 v[52:55], v[160:163], v[214:217], v[52:55]
	s_add_i32 s80, s80, 2
	v_mfma_f32_16x16x32_bf16 v[48:51], v[168:171], v[214:217], v[48:51]
	s_add_u32 s78, s78, 0x100
	v_mfma_f32_16x16x32_bf16 v[36:39], v[160:163], v[226:229], v[36:39]
	s_addc_u32 s79, s79, 0
	v_mfma_f32_16x16x32_bf16 v[32:35], v[168:171], v[226:229], v[32:35]
	s_cmp_gt_u32 s80, 41
	v_mfma_f32_16x16x32_bf16 v[20:23], v[160:163], v[234:237], v[20:23]
	s_mov_b64 s[2:3], s[48:49]
	v_mfma_f32_16x16x32_bf16 v[16:19], v[168:171], v[234:237], v[16:19]
	v_mfma_f32_16x16x32_bf16 v[4:7], v[160:163], v[242:245], v[4:7]
	v_mfma_f32_16x16x32_bf16 v[0:3], v[168:171], v[242:245], v[0:3]
	v_mfma_f32_16x16x32_bf16 v[52:55], v[164:167], v[222:225], v[52:55]
	v_mfma_f32_16x16x32_bf16 v[48:51], v[172:175], v[222:225], v[48:51]
	v_mfma_f32_16x16x32_bf16 v[36:39], v[164:167], v[230:233], v[36:39]
	v_mfma_f32_16x16x32_bf16 v[32:35], v[172:175], v[230:233], v[32:35]
	v_mfma_f32_16x16x32_bf16 v[20:23], v[164:167], v[238:241], v[20:23]
	v_mfma_f32_16x16x32_bf16 v[16:19], v[172:175], v[238:241], v[16:19]
	v_mfma_f32_16x16x32_bf16 v[4:7], v[164:167], v[246:249], v[4:7]
	v_mfma_f32_16x16x32_bf16 v[0:3], v[172:175], v[246:249], v[0:3]
	s_setprio 0
	s_barrier
	s_cbranch_scc0 .LBB0_942
